# hyena order loop: skip / short-conv weights / bias and the six q=0 short-conv inputs requested at the top of the order loop (ahead of the spectrum loads), copied in place before the epilogue (were two
# speedup vs baseline: 1.1804x; 1.0008x over previous
.LBB0_538:
	s_lshl_b32 s0, s16, 11
	s_add_u32 s0, s24, s0
	s_addc_u32 s1, s59, 0
	global_load_dword v221, v145, s[0:1]
	s_lshl_b32 s4, s16, 9
	s_add_i32 s4, s4, 0x200
	s_add_i32 s0, s4, s68
	s_ashr_i32 s1, s0, 31
	s_lshl_b32 s6, s4, 2
	s_add_u32 s4, s90, s6
	s_addc_u32 s5, s91, 0
	s_lshl_b64 s[0:1], s[0:1], 14
	v_mov_b32_e32 v163, s6
	s_add_u32 s8, s26, s0
	s_addc_u32 s9, s27, s1
	s_add_u32 s10, s30, s0
	s_addc_u32 s11, s31, s1
	v_lshlrev_b32_e32 v232, 1, v146
	v_min_i32_e32 v233, 0x1ffe, v146
	v_max_i32_e32 v234, 1, v146
	global_load_dword v222, v163, s[90:91]
	global_load_dword v223, v153, s[4:5] offset:2048
	global_load_dword v224, v154, s[4:5]
	global_load_dword v225, v163, s[94:95]
	v_lshlrev_b32_e32 v233, 1, v233
	v_lshlrev_b32_e32 v234, 1, v234
	global_load_ushort v226, v232, s[8:9]
	global_load_ushort v227, v233, s[8:9] offset:2
	global_load_ushort v228, v234, s[8:9] offset:-2
	global_load_ushort v229, v232, s[10:11]
	global_load_ushort v230, v233, s[10:11] offset:2
	global_load_ushort v231, v234, s[10:11] offset:-2
	s_lshl_b32 s98, s16, 16
	s_mov_b32 s99, 0
	v_lshl_add_u64 v[196:197], s[98:99], 0, v[28:29]
	global_load_dwordx4 v[164:167], v[196:197], off offset:-4096
	global_load_dwordx4 v[168:171], v[196:197], off offset:-3072
	global_load_dwordx4 v[172:175], v[196:197], off offset:-2048
	global_load_dwordx4 v[176:179], v[196:197], off offset:-1024
	global_load_dwordx4 v[180:183], v[196:197], off
	global_load_dwordx4 v[184:187], v[196:197], off offset:1024
	global_load_dwordx4 v[188:191], v[196:197], off offset:2048
	global_load_dwordx4 v[192:195], v[196:197], off offset:3072
	v_mov_b32_e32 v20, v46
	v_mov_b32_e32 v21, v48
	v_mov_b32_e32 v22, v51
	v_mov_b32_e32 v23, v53
	v_pk_add_f32 v[88:89], v[20:21], 0 op_sel_hi:[1,0]
	v_pk_mul_f32 v[20:21], v[20:21], s[58:59] op_sel_hi:[1,0]
	v_xor_b32_e32 v91, 0x80000000, v46
	v_mov_b32_e32 v90, v48
	v_pk_add_f32 v[92:93], v[50:51], 0 neg_lo:[1,1] neg_hi:[1,1]
	v_mov_b32_e32 v24, v50
	v_mov_b32_e32 v25, v52
	v_pk_fma_f32 v[20:21], v[90:91], s[46:47], v[20:21] op_sel_hi:[1,0,1] neg_lo:[0,0,1] neg_hi:[0,0,1]
	v_pk_add_f32 v[90:91], v[22:23], 0 op_sel_hi:[1,0]
	v_pk_mul_f32 v[22:23], v[22:23], s[62:63] op_sel_hi:[1,0]
	v_mov_b32_e32 v92, v53
	v_mov_b32_e32 v26, v55
	v_mov_b32_e32 v27, v57
	v_pk_fma_f32 v[22:23], v[92:93], s[60:61], v[22:23] op_sel_hi:[1,0,1] neg_lo:[0,0,1] neg_hi:[0,0,1]
	v_pk_add_f32 v[92:93], v[24:25], 0 op_sel_hi:[1,0]
	v_pk_mul_f32 v[24:25], v[24:25], s[66:67] op_sel_hi:[1,0]
	v_xor_b32_e32 v95, 0x80000000, v50
	v_mov_b32_e32 v94, v52
	v_pk_add_f32 v[96:97], v[54:55], 0 neg_lo:[1,1] neg_hi:[1,1]
	v_mov_b32_e32 v64, v54
	v_mov_b32_e32 v65, v56
	v_pk_fma_f32 v[24:25], v[94:95], s[64:65], v[24:25] op_sel_hi:[1,0,1] neg_lo:[0,0,1] neg_hi:[0,0,1]
	v_pk_add_f32 v[94:95], v[26:27], 0 op_sel_hi:[1,0]
	v_pk_mul_f32 v[26:27], v[26:27], s[70:71] op_sel_hi:[1,0]
	v_mov_b32_e32 v96, v57
	v_mov_b32_e32 v66, v59
	v_mov_b32_e32 v67, v61
	v_pk_fma_f32 v[26:27], v[96:97], s[70:71], v[26:27] op_sel_hi:[1,0,1] neg_lo:[0,0,1] neg_hi:[0,0,1]
	v_pk_add_f32 v[96:97], v[64:65], 0 op_sel_hi:[1,0]
	v_pk_mul_f32 v[64:65], v[64:65], s[64:65] op_sel_hi:[1,0]
	v_xor_b32_e32 v99, 0x80000000, v54
	v_mov_b32_e32 v98, v56
	v_pk_add_f32 v[100:101], v[58:59], 0 neg_lo:[1,1] neg_hi:[1,1]
	v_mov_b32_e32 v2, v32
	v_mov_b32_e32 v3, v34
	v_mov_b32_e32 v4, v33
	v_mov_b32_e32 v5, v35
	v_mov_b32_e32 v18, v47
	v_mov_b32_e32 v19, v49
	v_mov_b32_e32 v68, v58
	v_mov_b32_e32 v69, v60
	v_pk_fma_f32 v[64:65], v[98:99], s[66:67], v[64:65] op_sel_hi:[1,0,1] neg_lo:[0,0,1] neg_hi:[0,0,1]
	v_pk_add_f32 v[98:99], v[66:67], 0 op_sel_hi:[1,0]
	v_pk_mul_f32 v[66:67], v[66:67], s[60:61] op_sel_hi:[1,0]
	v_mov_b32_e32 v100, v61
	v_pk_add_f32 v[70:71], v[2:3], 0 op_sel_hi:[1,0]
	v_pk_add_f32 v[72:73], v[4:5], 0 op_sel_hi:[1,0]
	v_pk_add_f32 v[74:75], v[32:33], 0 neg_lo:[1,1] neg_hi:[1,1]
	v_pk_add_f32 v[18:19], v[18:19], 0 op_sel_hi:[1,0]
	v_pk_fma_f32 v[66:67], v[100:101], s[62:63], v[66:67] op_sel_hi:[1,0,1] neg_lo:[0,0,1] neg_hi:[0,0,1]
	v_pk_add_f32 v[100:101], v[68:69], 0 op_sel_hi:[1,0]
	v_pk_mul_f32 v[68:69], v[68:69], s[46:47] op_sel_hi:[1,0]
	v_xor_b32_e32 v103, 0x80000000, v58
	v_mov_b32_e32 v102, v60
	v_mov_b32_e32 v74, v35
	v_pk_fma_f32 v[68:69], v[102:103], s[58:59], v[68:69] op_sel_hi:[1,0,1] neg_lo:[0,0,1] neg_hi:[0,0,1]
	v_pk_add_f32 v[102:103], v[18:19], v[70:71]
	v_pk_add_f32 v[18:19], v[70:71], v[18:19] neg_lo:[0,1] neg_hi:[0,1]
	v_pk_add_f32 v[70:71], v[88:89], v[72:73]
	v_pk_add_f32 v[72:73], v[72:73], v[88:89] neg_lo:[0,1] neg_hi:[0,1]
	v_mov_b32_e32 v6, v37
	v_mov_b32_e32 v7, v31
	v_pk_mul_f32 v[74:75], v[74:75], s[58:59] op_sel_hi:[1,0]
	s_nop 0
	v_pk_fma_f32 v[4:5], v[4:5], s[46:47], v[74:75] op_sel_hi:[1,0,1]
	v_pk_add_f32 v[74:75], v[6:7], 0 op_sel_hi:[1,0]
	v_pk_add_f32 v[76:77], v[36:37], 0 neg_lo:[1,1] neg_hi:[1,1]
	v_pk_mul_f32 v[88:89], v[72:73], s[62:63] op_sel:[1,0] op_sel_hi:[0,0] neg_hi:[1,0]
	v_mov_b32_e32 v76, v31
	v_pk_fma_f32 v[72:73], v[72:73], s[60:61], v[88:89] op_sel_hi:[1,0,1]
	v_pk_add_f32 v[88:89], v[90:91], v[74:75]
	v_pk_add_f32 v[74:75], v[74:75], v[90:91] neg_lo:[0,1] neg_hi:[0,1]
	v_mov_b32_e32 v8, v36
	v_mov_b32_e32 v9, v30
	v_pk_mul_f32 v[76:77], v[76:77], s[62:63] op_sel_hi:[1,0]
	s_nop 0
	v_pk_fma_f32 v[6:7], v[6:7], s[60:61], v[76:77] op_sel_hi:[1,0,1]
	v_pk_add_f32 v[76:77], v[8:9], 0 op_sel_hi:[1,0]
	v_pk_mul_f32 v[90:91], v[74:75], s[70:71] op_sel:[1,0] op_sel_hi:[0,0] neg_hi:[1,0]
	v_xor_b32_e32 v79, 0x80000000, v36
	v_mov_b32_e32 v78, v30
	v_pk_add_f32 v[80:81], v[38:39], 0 neg_lo:[1,1] neg_hi:[1,1]
	v_pk_fma_f32 v[74:75], v[74:75], s[70:71], v[90:91] op_sel_hi:[1,0,1]
	v_pk_add_f32 v[90:91], v[92:93], v[76:77]
	v_pk_add_f32 v[76:77], v[76:77], v[92:93] neg_lo:[0,1] neg_hi:[0,1]
	v_mov_b32_e32 v10, v39
	v_mov_b32_e32 v11, v41
	v_pk_mul_f32 v[78:79], v[78:79], s[66:67] op_sel_hi:[1,0]
	v_mov_b32_e32 v80, v41
	v_mov_b32_e32 v12, v38
	v_mov_b32_e32 v13, v40
	v_pk_fma_f32 v[8:9], v[8:9], s[64:65], v[78:79] op_sel_hi:[1,0,1]
	v_pk_add_f32 v[78:79], v[10:11], 0 op_sel_hi:[1,0]
	v_pk_mul_f32 v[80:81], v[80:81], s[70:71] op_sel_hi:[1,0]
	v_pk_mul_f32 v[92:93], v[76:77], s[60:61] op_sel:[1,0] op_sel_hi:[0,0] neg_hi:[1,0]
	v_pk_fma_f32 v[10:11], v[10:11], s[70:71], v[80:81] op_sel_hi:[1,0,1]
	v_pk_add_f32 v[80:81], v[12:13], 0 op_sel_hi:[1,0]
	v_xor_b32_e32 v83, 0x80000000, v38
	v_mov_b32_e32 v82, v40
	v_pk_fma_f32 v[76:77], v[76:77], s[62:63], v[92:93] op_sel_hi:[1,0,1]
	v_pk_add_f32 v[92:93], v[94:95], v[78:79]
	v_pk_add_f32 v[78:79], v[78:79], v[94:95] neg_lo:[0,1] neg_hi:[0,1]
	v_mov_b32_e32 v14, v43
	v_mov_b32_e32 v15, v45
	v_pk_mul_f32 v[82:83], v[82:83], s[64:65] op_sel_hi:[1,0]
	v_pk_add_f32 v[84:85], v[42:43], 0 neg_lo:[1,1] neg_hi:[1,1]
	v_xor_b32_e32 v95, 0x80000000, v78
	v_mov_b32_e32 v94, v79
	v_pk_add_f32 v[78:79], v[96:97], v[80:81]
	v_pk_add_f32 v[80:81], v[80:81], v[96:97] neg_lo:[0,1] neg_hi:[0,1]
	v_pk_fma_f32 v[12:13], v[12:13], s[66:67], v[82:83] op_sel_hi:[1,0,1]
	v_pk_add_f32 v[82:83], v[14:15], 0 op_sel_hi:[1,0]
	v_mov_b32_e32 v84, v45
	v_pk_mul_f32 v[96:97], v[80:81], s[62:63] op_sel_hi:[1,0]
	v_xor_b32_e32 v105, 0x80000000, v80
	v_mov_b32_e32 v104, v81
	v_mov_b32_e32 v16, v42
	v_mov_b32_e32 v17, v44
	v_pk_mul_f32 v[84:85], v[84:85], s[60:61] op_sel_hi:[1,0]
	v_xor_b32_e32 v87, 0x80000000, v42
	v_mov_b32_e32 v86, v44
	v_pk_fma_f32 v[80:81], v[104:105], s[60:61], v[96:97] op_sel_hi:[1,0,1] neg_lo:[0,0,1] neg_hi:[0,0,1]
	v_pk_add_f32 v[96:97], v[98:99], v[82:83]
	v_pk_add_f32 v[82:83], v[82:83], v[98:99] neg_lo:[0,1] neg_hi:[0,1]
	v_pk_fma_f32 v[14:15], v[14:15], s[62:63], v[84:85] op_sel_hi:[1,0,1]
	v_pk_add_f32 v[84:85], v[16:17], 0 op_sel_hi:[1,0]
	v_pk_mul_f32 v[86:87], v[86:87], s[46:47] op_sel_hi:[1,0]
	v_pk_mul_f32 v[98:99], v[82:83], s[70:71] op_sel_hi:[1,0]
	v_xor_b32_e32 v105, 0x80000000, v82
	v_mov_b32_e32 v104, v83
	v_pk_fma_f32 v[16:17], v[16:17], s[58:59], v[86:87] op_sel_hi:[1,0,1]
	v_pk_add_f32 v[86:87], v[46:47], 0 neg_lo:[1,1] neg_hi:[1,1]
	v_pk_fma_f32 v[82:83], v[104:105], s[70:71], v[98:99] op_sel_hi:[1,0,1] neg_lo:[0,0,1] neg_hi:[0,0,1]
	v_pk_add_f32 v[98:99], v[100:101], v[84:85]
	v_pk_add_f32 v[84:85], v[84:85], v[100:101] neg_lo:[0,1] neg_hi:[0,1]
	v_mov_b32_e32 v86, v49
	v_pk_mul_f32 v[100:101], v[84:85], s[60:61] op_sel_hi:[1,0]
	v_xor_b32_e32 v105, 0x80000000, v84
	v_mov_b32_e32 v104, v85
	v_pk_fma_f32 v[84:85], v[104:105], s[62:63], v[100:101] op_sel_hi:[1,0,1] neg_lo:[0,0,1] neg_hi:[0,0,1]
	v_pk_add_f32 v[100:101], v[86:87], v[2:3]
	v_pk_add_f32 v[2:3], v[2:3], v[86:87] neg_lo:[0,1] neg_hi:[0,1]
	v_pk_add_f32 v[86:87], v[20:21], v[4:5]
	v_pk_add_f32 v[4:5], v[4:5], v[20:21] neg_lo:[0,1] neg_hi:[0,1]
	v_mov_b32_e32 v63, v146
	v_pk_mul_f32 v[20:21], v[4:5], s[62:63] op_sel:[1,0] op_sel_hi:[0,0] neg_hi:[1,0]
	s_nop 0
	v_pk_fma_f32 v[4:5], v[4:5], s[60:61], v[20:21] op_sel_hi:[1,0,1]
	v_pk_add_f32 v[20:21], v[22:23], v[6:7]
	v_pk_add_f32 v[6:7], v[6:7], v[22:23] neg_lo:[0,1] neg_hi:[0,1]
	s_barrier
	v_pk_mul_f32 v[22:23], v[6:7], s[70:71] op_sel:[1,0] op_sel_hi:[0,0] neg_hi:[1,0]
	s_nop 0
	v_pk_fma_f32 v[6:7], v[6:7], s[70:71], v[22:23] op_sel_hi:[1,0,1]
	v_pk_add_f32 v[22:23], v[24:25], v[8:9]
	v_pk_add_f32 v[8:9], v[8:9], v[24:25] neg_lo:[0,1] neg_hi:[0,1]
	s_add_i32 s19, 16, 0x11000
	v_pk_mul_f32 v[24:25], v[8:9], s[60:61] op_sel:[1,0] op_sel_hi:[0,0] neg_hi:[1,0]
	s_add_i32 s18, 16, 0x12000
	v_pk_fma_f32 v[8:9], v[8:9], s[62:63], v[24:25] op_sel_hi:[1,0,1]
	v_pk_add_f32 v[24:25], v[26:27], v[10:11]
	v_pk_add_f32 v[10:11], v[10:11], v[26:27] neg_lo:[0,1] neg_hi:[0,1]
	s_add_i32 s17, 16, 0x13000
	v_xor_b32_e32 v27, 0x80000000, v10
	v_mov_b32_e32 v26, v11
	v_pk_add_f32 v[10:11], v[64:65], v[12:13]
	v_pk_add_f32 v[12:13], v[12:13], v[64:65] neg_lo:[0,1] neg_hi:[0,1]
	s_add_i32 s13, 16, 0x14000
	v_pk_mul_f32 v[64:65], v[12:13], s[62:63] op_sel_hi:[1,0]
	v_xor_b32_e32 v105, 0x80000000, v12
	v_mov_b32_e32 v104, v13
	v_pk_fma_f32 v[12:13], v[104:105], s[60:61], v[64:65] op_sel_hi:[1,0,1] neg_lo:[0,0,1] neg_hi:[0,0,1]
	v_pk_add_f32 v[64:65], v[66:67], v[14:15]
	v_pk_add_f32 v[14:15], v[14:15], v[66:67] neg_lo:[0,1] neg_hi:[0,1]
	s_add_i32 s12, 16, 0x15000
	v_pk_mul_f32 v[66:67], v[14:15], s[70:71] op_sel_hi:[1,0]
	v_xor_b32_e32 v105, 0x80000000, v14
	v_mov_b32_e32 v104, v15
	v_pk_fma_f32 v[14:15], v[104:105], s[70:71], v[66:67] op_sel_hi:[1,0,1] neg_lo:[0,0,1] neg_hi:[0,0,1]
	v_pk_add_f32 v[66:67], v[68:69], v[16:17]
	v_pk_add_f32 v[16:17], v[16:17], v[68:69] neg_lo:[0,1] neg_hi:[0,1]
	s_add_i32 s11, 16, 0x16000
	v_pk_mul_f32 v[68:69], v[16:17], s[60:61] op_sel_hi:[1,0]
	v_xor_b32_e32 v105, 0x80000000, v16
	v_mov_b32_e32 v104, v17
	v_pk_fma_f32 v[16:17], v[104:105], s[62:63], v[68:69] op_sel_hi:[1,0,1] neg_lo:[0,0,1] neg_hi:[0,0,1]
	v_pk_add_f32 v[68:69], v[92:93], v[102:103]
	v_pk_add_f32 v[92:93], v[102:103], v[92:93] neg_lo:[0,1] neg_hi:[0,1]
	v_pk_add_f32 v[102:103], v[78:79], v[70:71]
	v_pk_add_f32 v[70:71], v[70:71], v[78:79] neg_lo:[0,1] neg_hi:[0,1]
	s_add_i32 s10, 16, 0x17000
	v_pk_mul_f32 v[78:79], v[70:71], s[70:71] op_sel:[1,0] op_sel_hi:[0,0] neg_hi:[1,0]
	s_add_i32 s9, 16, 0x18000
	v_pk_fma_f32 v[70:71], v[70:71], s[70:71], v[78:79] op_sel_hi:[1,0,1]
	v_pk_add_f32 v[78:79], v[96:97], v[88:89]
	v_pk_add_f32 v[88:89], v[88:89], v[96:97] neg_lo:[0,1] neg_hi:[0,1]
	s_add_i32 s8, 16, 0x19000
	v_xor_b32_e32 v97, 0x80000000, v88
	v_mov_b32_e32 v96, v89
	v_pk_add_f32 v[88:89], v[98:99], v[90:91]
	v_pk_add_f32 v[90:91], v[90:91], v[98:99] neg_lo:[0,1] neg_hi:[0,1]
	s_add_i32 s7, 16, 0x1a000
	v_pk_mul_f32 v[98:99], v[90:91], s[70:71] op_sel_hi:[1,0]
	v_xor_b32_e32 v105, 0x80000000, v90
	v_mov_b32_e32 v104, v91
	v_pk_fma_f32 v[90:91], v[104:105], s[70:71], v[98:99] op_sel_hi:[1,0,1] neg_lo:[0,0,1] neg_hi:[0,0,1]
	v_pk_add_f32 v[98:99], v[94:95], v[18:19]
	v_pk_add_f32 v[18:19], v[18:19], v[94:95] neg_lo:[0,1] neg_hi:[0,1]
	v_pk_add_f32 v[94:95], v[80:81], v[72:73]
	v_pk_add_f32 v[72:73], v[72:73], v[80:81] neg_lo:[0,1] neg_hi:[0,1]
	s_add_i32 s6, 16, 0x1b000
	v_pk_mul_f32 v[80:81], v[72:73], s[70:71] op_sel:[1,0] op_sel_hi:[0,0] neg_hi:[1,0]
	s_add_i32 s5, 16, 0x1c000
	v_pk_fma_f32 v[72:73], v[72:73], s[70:71], v[80:81] op_sel_hi:[1,0,1]
	v_pk_add_f32 v[80:81], v[82:83], v[74:75]
	v_pk_add_f32 v[74:75], v[74:75], v[82:83] neg_lo:[0,1] neg_hi:[0,1]
	s_add_i32 s4, 16, 0x1d000
	v_xor_b32_e32 v83, 0x80000000, v74
	v_mov_b32_e32 v82, v75
	v_pk_add_f32 v[74:75], v[84:85], v[76:77]
	v_pk_add_f32 v[76:77], v[76:77], v[84:85] neg_lo:[0,1] neg_hi:[0,1]
	v_pk_add_f32 v[106:107], v[18:19], v[82:83]
	v_pk_mul_f32 v[84:85], v[76:77], s[70:71] op_sel_hi:[1,0]
	v_xor_b32_e32 v105, 0x80000000, v76
	v_mov_b32_e32 v104, v77
	v_pk_fma_f32 v[76:77], v[104:105], s[70:71], v[84:85] op_sel_hi:[1,0,1] neg_lo:[0,0,1] neg_hi:[0,0,1]
	v_pk_add_f32 v[84:85], v[24:25], v[100:101]
	v_pk_add_f32 v[24:25], v[100:101], v[24:25] neg_lo:[0,1] neg_hi:[0,1]
	v_pk_add_f32 v[100:101], v[10:11], v[86:87]
	v_pk_add_f32 v[10:11], v[86:87], v[10:11] neg_lo:[0,1] neg_hi:[0,1]
	v_pk_add_f32 v[18:19], v[18:19], v[82:83] neg_lo:[0,1] neg_hi:[0,1]
	v_pk_mul_f32 v[86:87], v[10:11], s[70:71] op_sel:[1,0] op_sel_hi:[0,0] neg_hi:[1,0]
	v_pk_add_f32 v[82:83], v[76:77], v[72:73]
	v_pk_fma_f32 v[10:11], v[10:11], s[70:71], v[86:87] op_sel_hi:[1,0,1]
	v_pk_add_f32 v[86:87], v[64:65], v[20:21]
	v_pk_add_f32 v[20:21], v[20:21], v[64:65] neg_lo:[0,1] neg_hi:[0,1]
	v_pk_add_f32 v[72:73], v[72:73], v[76:77] neg_lo:[0,1] neg_hi:[0,1]
	v_xor_b32_e32 v65, 0x80000000, v20
	v_mov_b32_e32 v64, v21
	v_pk_add_f32 v[20:21], v[66:67], v[22:23]
	v_pk_add_f32 v[22:23], v[22:23], v[66:67] neg_lo:[0,1] neg_hi:[0,1]
	v_xor_b32_e32 v77, 0x80000000, v72
	v_pk_mul_f32 v[66:67], v[22:23], s[70:71] op_sel_hi:[1,0]
	v_xor_b32_e32 v105, 0x80000000, v22
	v_mov_b32_e32 v104, v23
	v_pk_fma_f32 v[22:23], v[104:105], s[70:71], v[66:67] op_sel_hi:[1,0,1] neg_lo:[0,0,1] neg_hi:[0,0,1]
	v_pk_add_f32 v[66:67], v[2:3], v[26:27]
	v_pk_add_f32 v[2:3], v[2:3], v[26:27] neg_lo:[0,1] neg_hi:[0,1]
	v_pk_add_f32 v[26:27], v[12:13], v[4:5]
	v_pk_add_f32 v[4:5], v[4:5], v[12:13] neg_lo:[0,1] neg_hi:[0,1]
	v_mov_b32_e32 v76, v73
	v_pk_mul_f32 v[12:13], v[4:5], s[70:71] op_sel:[1,0] op_sel_hi:[0,0] neg_hi:[1,0]
	v_pk_add_f32 v[72:73], v[84:85], v[86:87]
	v_pk_fma_f32 v[4:5], v[4:5], s[70:71], v[12:13] op_sel_hi:[1,0,1]
	v_pk_add_f32 v[12:13], v[14:15], v[6:7]
	v_pk_add_f32 v[6:7], v[6:7], v[14:15] neg_lo:[0,1] neg_hi:[0,1]
	v_pk_add_f32 v[84:85], v[84:85], v[86:87] neg_lo:[0,1] neg_hi:[0,1]
	v_xor_b32_e32 v15, 0x80000000, v6
	v_mov_b32_e32 v14, v7
	v_pk_add_f32 v[6:7], v[16:17], v[8:9]
	v_pk_add_f32 v[8:9], v[8:9], v[16:17] neg_lo:[0,1] neg_hi:[0,1]
	v_pk_add_f32 v[86:87], v[20:21], v[100:101]
	v_pk_mul_f32 v[16:17], v[8:9], s[70:71] op_sel_hi:[1,0]
	s_nop 0
	v_pk_fma_f32 v[8:9], v[8:9], s[70:71], v[16:17] op_sel:[1,0,0] op_sel_hi:[0,0,1] neg_lo:[0,0,1] neg_hi:[1,0,1]
	v_pk_add_f32 v[104:105], v[92:93], v[96:97]
	v_pk_add_f32 v[92:93], v[92:93], v[96:97] neg_lo:[0,1] neg_hi:[0,1]
	v_pk_add_f32 v[96:97], v[90:91], v[70:71]
	v_pk_add_f32 v[70:71], v[70:71], v[90:91] neg_lo:[0,1] neg_hi:[0,1]
	v_pk_add_f32 v[16:17], v[78:79], v[68:69]
	v_pk_add_f32 v[68:69], v[68:69], v[78:79] neg_lo:[0,1] neg_hi:[0,1]
	v_pk_add_f32 v[78:79], v[88:89], v[102:103]
	v_pk_add_f32 v[88:89], v[102:103], v[88:89] neg_lo:[0,1] neg_hi:[0,1]
	v_xor_b32_e32 v91, 0x80000000, v70
	v_mov_b32_e32 v90, v71
	v_pk_add_f32 v[70:71], v[98:99], v[80:81]
	v_pk_add_f32 v[98:99], v[98:99], v[80:81] neg_lo:[0,1] neg_hi:[0,1]
	v_pk_add_f32 v[80:81], v[74:75], v[94:95]
	v_pk_add_f32 v[74:75], v[94:95], v[74:75] neg_lo:[0,1] neg_hi:[0,1]
	v_pk_add_f32 v[20:21], v[100:101], v[20:21] neg_lo:[0,1] neg_hi:[0,1]
	v_pk_add_f32 v[108:109], v[24:25], v[64:65]
	v_pk_add_f32 v[24:25], v[24:25], v[64:65] neg_lo:[0,1] neg_hi:[0,1]
	v_pk_add_f32 v[64:65], v[22:23], v[10:11]
	v_pk_add_f32 v[10:11], v[10:11], v[22:23] neg_lo:[0,1] neg_hi:[0,1]
	v_pk_add_f32 v[114:115], v[6:7], v[26:27]
	v_pk_add_f32 v[6:7], v[26:27], v[6:7] neg_lo:[0,1] neg_hi:[0,1]
	v_xor_b32_e32 v103, 0x80000000, v88
	v_mov_b32_e32 v102, v89
	v_xor_b32_e32 v95, 0x80000000, v74
	v_mov_b32_e32 v94, v75
	v_xor_b32_e32 v101, 0x80000000, v20
	v_mov_b32_e32 v100, v21
	v_xor_b32_e32 v27, 0x80000000, v6
	v_mov_b32_e32 v26, v7
	v_pk_add_f32 v[6:7], v[2:3], v[14:15]
	v_pk_add_f32 v[116:117], v[2:3], v[14:15] neg_lo:[0,1] neg_hi:[0,1]
	v_pk_add_f32 v[2:3], v[4:5], v[8:9] neg_lo:[0,1] neg_hi:[0,1]
	v_pk_add_f32 v[112:113], v[66:67], v[12:13]
	v_pk_add_f32 v[66:67], v[66:67], v[12:13] neg_lo:[0,1] neg_hi:[0,1]
	v_pk_add_f32 v[118:119], v[8:9], v[4:5]
	v_xor_b32_e32 v121, 0x80000000, v2
	v_mov_b32_e32 v120, v3
	v_pk_add_f32 v[2:3], v[78:79], v[16:17]
	v_pk_add_f32 v[88:89], v[16:17], v[78:79] neg_lo:[0,1] neg_hi:[0,1]
	v_pk_add_f32 v[122:123], v[68:69], v[102:103]
	v_pk_add_f32 v[20:21], v[68:69], v[102:103] neg_lo:[0,1] neg_hi:[0,1]
	v_pk_add_f32 v[78:79], v[104:105], v[96:97]
	v_pk_add_f32 v[74:75], v[104:105], v[96:97] neg_lo:[0,1] neg_hi:[0,1]
	v_pk_add_f32 v[96:97], v[92:93], v[90:91]
	v_pk_add_f32 v[8:9], v[92:93], v[90:91] neg_lo:[0,1] neg_hi:[0,1]
	v_pk_add_f32 v[102:103], v[98:99], v[94:95]
	v_pk_add_f32 v[12:13], v[98:99], v[94:95] neg_lo:[0,1] neg_hi:[0,1]
	v_pk_add_f32 v[98:99], v[18:19], v[76:77]
	v_pk_add_f32 v[4:5], v[18:19], v[76:77] neg_lo:[0,1] neg_hi:[0,1]
	v_pk_add_f32 v[18:19], v[72:73], v[86:87]
	v_pk_add_f32 v[92:93], v[72:73], v[86:87] neg_lo:[0,1] neg_hi:[0,1]
	v_pk_add_f32 v[86:87], v[84:85], v[100:101]
	v_pk_add_f32 v[22:23], v[84:85], v[100:101] neg_lo:[0,1] neg_hi:[0,1]
	v_pk_add_f32 v[100:101], v[24:25], v[10:11] op_sel:[0,1] op_sel_hi:[1,0] neg_hi:[0,1]
	v_pk_add_f32 v[10:11], v[24:25], v[10:11] op_sel:[0,1] op_sel_hi:[1,0] neg_lo:[0,1]
	v_mov_b32_e32 v24, v63
	v_pk_add_f32 v[84:85], v[108:109], v[64:65]
	v_cvt_f32_i32_e32 v24, v24
	v_pk_add_f32 v[76:77], v[108:109], v[64:65] neg_lo:[0,1] neg_hi:[0,1]
	v_pk_add_f32 v[104:105], v[66:67], v[26:27]
	v_pk_add_f32 v[14:15], v[66:67], v[26:27] neg_lo:[0,1] neg_hi:[0,1]
	v_mul_f32_e32 v25, 0x38800000, v24
	v_cos_f32_e32 v24, v25
	v_sin_f32_e32 v25, v25
	s_nop 0
	s_nop 0
	v_add_f32_e32 v62, v24, v24
	v_pk_mul_f32 v[26:27], v[24:25], v[24:25]
	v_mul_f32_e32 v62, v25, v62
	s_nop 0
	s_nop 0
	v_mov_b32_e32 v108, v25
	v_pk_add_f32 v[26:27], v[26:27], v[26:27] op_sel:[0,1] op_sel_hi:[0,1] neg_lo:[0,1] neg_hi:[0,1]
	v_pk_mul_f32 v[72:73], v[24:25], v[62:63] op_sel:[1,0] op_sel_hi:[0,0] neg_lo:[1,0]
	v_pk_mul_f32 v[94:95], v[18:19], v[108:109] op_sel:[1,0] op_sel_hi:[0,0] neg_hi:[1,0]
	v_pk_add_f32 v[16:17], v[70:71], v[80:81]
	v_pk_fma_f32 v[72:73], v[24:25], v[26:27], v[72:73]
	v_pk_fma_f32 v[18:19], v[18:19], v[24:25], v[94:95] op_sel_hi:[1,0,1]
	v_pk_mul_f32 v[24:25], v[62:63], s[48:49] op_sel_hi:[0,1]
	v_pk_fma_f32 v[94:95], v[26:27], s[40:41], v[24:25]
	s_nop 0
	v_pk_mul_f32 v[24:25], v[16:17], v[94:95] op_sel:[1,1] op_sel_hi:[0,1] neg_hi:[1,0]
	v_pk_add_f32 v[64:65], v[112:113], v[114:115]
	v_pk_fma_f32 v[24:25], v[16:17], v[94:95], v[24:25] op_sel_hi:[1,0,1]
	v_pk_mul_f32 v[16:17], v[62:63], v[72:73] op_sel:[0,1] op_sel_hi:[0,0] neg_lo:[0,1]
	v_pk_fma_f32 v[108:109], v[26:27], v[72:73], v[16:17]
	v_pk_mul_f32 v[16:17], v[64:65], v[72:73] op_sel:[1,1] op_sel_hi:[0,1] neg_hi:[1,0]
	v_pk_add_f32 v[90:91], v[106:107], v[82:83]
	v_pk_fma_f32 v[16:17], v[64:65], v[72:73], v[16:17] op_sel_hi:[1,0,1]
	v_pk_mul_f32 v[64:65], v[62:63], v[94:95] op_sel:[0,1] op_sel_hi:[0,0] neg_lo:[0,1]
	v_pk_fma_f32 v[94:95], v[26:27], v[94:95], v[64:65]
	s_nop 0
	v_pk_mul_f32 v[64:65], v[78:79], v[94:95] op_sel:[1,1] op_sel_hi:[0,1] neg_hi:[1,0]
	v_pk_add_f32 v[66:67], v[6:7], v[118:119]
	v_pk_fma_f32 v[72:73], v[78:79], v[94:95], v[64:65] op_sel_hi:[1,0,1]
	v_pk_mul_f32 v[64:65], v[62:63], v[108:109] op_sel:[0,1] op_sel_hi:[0,0] neg_lo:[0,1]
	v_pk_fma_f32 v[110:111], v[26:27], v[108:109], v[64:65]
	v_pk_mul_f32 v[64:65], v[84:85], v[108:109] op_sel:[1,1] op_sel_hi:[0,1] neg_hi:[1,0]
	v_pk_mul_f32 v[78:79], v[62:63], v[94:95] op_sel:[0,1] op_sel_hi:[0,0] neg_lo:[0,1]
	v_pk_fma_f32 v[64:65], v[84:85], v[108:109], v[64:65] op_sel_hi:[1,0,1]
	v_pk_fma_f32 v[84:85], v[26:27], v[94:95], v[78:79]
	s_nop 0
	v_pk_mul_f32 v[78:79], v[90:91], v[84:85] op_sel:[1,1] op_sel_hi:[0,1] neg_hi:[1,0]
	v_pk_add_f32 v[68:69], v[106:107], v[82:83] neg_lo:[0,1] neg_hi:[0,1]
	v_pk_fma_f32 v[78:79], v[90:91], v[84:85], v[78:79] op_sel_hi:[1,0,1]
	v_pk_mul_f32 v[90:91], v[62:63], v[110:111] op_sel:[0,1] op_sel_hi:[0,0] neg_lo:[0,1]
	v_pk_fma_f32 v[94:95], v[26:27], v[110:111], v[90:91]
	v_pk_mul_f32 v[90:91], v[66:67], v[110:111] op_sel:[1,1] op_sel_hi:[0,1] neg_hi:[1,0]
	v_pk_add_f32 v[106:107], v[116:117], v[120:121]
	v_pk_fma_f32 v[66:67], v[66:67], v[110:111], v[90:91] op_sel_hi:[1,0,1]
	v_pk_mul_f32 v[90:91], v[62:63], v[84:85] op_sel:[0,1] op_sel_hi:[0,0] neg_lo:[0,1]
	v_pk_fma_f32 v[108:109], v[26:27], v[84:85], v[90:91]
	s_nop 0
	v_pk_mul_f32 v[84:85], v[122:123], v[108:109] op_sel:[1,1] op_sel_hi:[0,1] neg_hi:[1,0]
	v_pk_add_f32 v[80:81], v[70:71], v[80:81] neg_lo:[0,1] neg_hi:[0,1]
	v_pk_fma_f32 v[90:91], v[122:123], v[108:109], v[84:85] op_sel_hi:[1,0,1]
	v_pk_mul_f32 v[84:85], v[62:63], v[94:95] op_sel:[0,1] op_sel_hi:[0,0] neg_lo:[0,1]
	v_pk_fma_f32 v[110:111], v[26:27], v[94:95], v[84:85]
	v_pk_mul_f32 v[84:85], v[86:87], v[94:95] op_sel:[1,1] op_sel_hi:[0,1] neg_hi:[1,0]
	v_pk_add_f32 v[82:83], v[112:113], v[114:115] neg_lo:[0,1] neg_hi:[0,1]
	v_pk_fma_f32 v[84:85], v[86:87], v[94:95], v[84:85] op_sel_hi:[1,0,1]
	v_pk_mul_f32 v[86:87], v[62:63], v[108:109] op_sel:[0,1] op_sel_hi:[0,0] neg_lo:[0,1]
	v_pk_fma_f32 v[108:109], v[26:27], v[108:109], v[86:87]
	s_nop 0
	v_pk_mul_f32 v[86:87], v[102:103], v[108:109] op_sel:[1,1] op_sel_hi:[0,1] neg_hi:[1,0]
	v_pk_add_f32 v[70:71], v[6:7], v[118:119] neg_lo:[0,1] neg_hi:[0,1]
	v_pk_fma_f32 v[94:95], v[102:103], v[108:109], v[86:87] op_sel_hi:[1,0,1]
	v_pk_mul_f32 v[86:87], v[62:63], v[110:111] op_sel:[0,1] op_sel_hi:[0,0] neg_lo:[0,1]
	v_pk_fma_f32 v[102:103], v[26:27], v[110:111], v[86:87]
	v_pk_mul_f32 v[86:87], v[104:105], v[110:111] op_sel:[1,1] op_sel_hi:[0,1] neg_hi:[1,0]
	v_pk_add_f32 v[6:7], v[116:117], v[120:121] neg_lo:[0,1] neg_hi:[0,1]
	v_pk_fma_f32 v[86:87], v[104:105], v[110:111], v[86:87] op_sel_hi:[1,0,1]
	v_pk_mul_f32 v[104:105], v[62:63], v[108:109] op_sel:[0,1] op_sel_hi:[0,0] neg_lo:[0,1]
	v_pk_fma_f32 v[104:105], v[26:27], v[108:109], v[104:105]
	s_nop 0
	v_pk_mul_f32 v[108:109], v[96:97], v[104:105] op_sel:[1,1] op_sel_hi:[0,1] neg_hi:[1,0]
	s_nop 0
	v_pk_fma_f32 v[96:97], v[96:97], v[104:105], v[108:109] op_sel_hi:[1,0,1]
	v_pk_mul_f32 v[108:109], v[62:63], v[102:103] op_sel:[0,1] op_sel_hi:[0,0] neg_lo:[0,1]
	v_pk_mul_f32 v[110:111], v[100:101], v[102:103] op_sel:[1,1] op_sel_hi:[0,1] neg_hi:[1,0]
	v_pk_fma_f32 v[108:109], v[26:27], v[102:103], v[108:109]
	v_pk_fma_f32 v[100:101], v[100:101], v[102:103], v[110:111] op_sel_hi:[1,0,1]
	v_pk_mul_f32 v[102:103], v[62:63], v[104:105] op_sel:[0,1] op_sel_hi:[0,0] neg_lo:[0,1]
	v_pk_fma_f32 v[102:103], v[26:27], v[104:105], v[102:103]
	s_nop 0
	v_pk_mul_f32 v[104:105], v[98:99], v[102:103] op_sel:[1,1] op_sel_hi:[0,1] neg_hi:[1,0]
	s_nop 0
	v_pk_fma_f32 v[98:99], v[98:99], v[102:103], v[104:105] op_sel_hi:[1,0,1]
	v_pk_mul_f32 v[104:105], v[62:63], v[108:109] op_sel:[0,1] op_sel_hi:[0,0] neg_lo:[0,1]
	v_pk_mul_f32 v[110:111], v[106:107], v[108:109] op_sel:[1,1] op_sel_hi:[0,1] neg_hi:[1,0]
	v_pk_fma_f32 v[104:105], v[26:27], v[108:109], v[104:105]
	v_pk_fma_f32 v[106:107], v[106:107], v[108:109], v[110:111] op_sel_hi:[1,0,1]
	v_pk_mul_f32 v[108:109], v[62:63], v[102:103] op_sel:[0,1] op_sel_hi:[0,0] neg_lo:[0,1]
	v_pk_fma_f32 v[102:103], v[26:27], v[102:103], v[108:109]
	s_nop 0
	v_pk_mul_f32 v[108:109], v[88:89], v[102:103] op_sel:[1,1] op_sel_hi:[0,1] neg_hi:[1,0]
	s_nop 0
	v_pk_fma_f32 v[88:89], v[88:89], v[102:103], v[108:109] op_sel_hi:[1,0,1]
	v_pk_mul_f32 v[108:109], v[62:63], v[104:105] op_sel:[0,1] op_sel_hi:[0,0] neg_lo:[0,1]
	v_pk_mul_f32 v[110:111], v[92:93], v[104:105] op_sel:[1,1] op_sel_hi:[0,1] neg_hi:[1,0]
	v_pk_fma_f32 v[108:109], v[26:27], v[104:105], v[108:109]
	v_pk_fma_f32 v[92:93], v[92:93], v[104:105], v[110:111] op_sel_hi:[1,0,1]
	v_pk_mul_f32 v[104:105], v[62:63], v[102:103] op_sel:[0,1] op_sel_hi:[0,0] neg_lo:[0,1]
	v_pk_fma_f32 v[102:103], v[26:27], v[102:103], v[104:105]
	s_nop 0
	v_pk_mul_f32 v[104:105], v[80:81], v[102:103] op_sel:[1,1] op_sel_hi:[0,1] neg_hi:[1,0]
	s_nop 0
	v_pk_fma_f32 v[80:81], v[80:81], v[102:103], v[104:105] op_sel_hi:[1,0,1]
	v_pk_mul_f32 v[104:105], v[62:63], v[108:109] op_sel:[0,1] op_sel_hi:[0,0] neg_lo:[0,1]
	v_pk_mul_f32 v[110:111], v[82:83], v[108:109] op_sel:[1,1] op_sel_hi:[0,1] neg_hi:[1,0]
	v_pk_fma_f32 v[104:105], v[26:27], v[108:109], v[104:105]
	v_pk_fma_f32 v[82:83], v[82:83], v[108:109], v[110:111] op_sel_hi:[1,0,1]
	v_pk_mul_f32 v[108:109], v[62:63], v[102:103] op_sel:[0,1] op_sel_hi:[0,0] neg_lo:[0,1]
	v_pk_fma_f32 v[102:103], v[26:27], v[102:103], v[108:109]
	s_nop 0
	v_pk_mul_f32 v[108:109], v[74:75], v[102:103] op_sel:[1,1] op_sel_hi:[0,1] neg_hi:[1,0]
	s_nop 0
	v_pk_fma_f32 v[74:75], v[74:75], v[102:103], v[108:109] op_sel_hi:[1,0,1]
	v_pk_mul_f32 v[108:109], v[62:63], v[104:105] op_sel:[0,1] op_sel_hi:[0,0] neg_lo:[0,1]
	v_pk_mul_f32 v[110:111], v[76:77], v[104:105] op_sel:[1,1] op_sel_hi:[0,1] neg_hi:[1,0]
	v_pk_fma_f32 v[108:109], v[26:27], v[104:105], v[108:109]
	v_pk_fma_f32 v[76:77], v[76:77], v[104:105], v[110:111] op_sel_hi:[1,0,1]
	v_pk_mul_f32 v[104:105], v[62:63], v[102:103] op_sel:[0,1] op_sel_hi:[0,0] neg_lo:[0,1]
	v_pk_fma_f32 v[102:103], v[26:27], v[102:103], v[104:105]
	s_nop 0
	v_pk_mul_f32 v[104:105], v[68:69], v[102:103] op_sel:[1,1] op_sel_hi:[0,1] neg_hi:[1,0]
	s_nop 0
	v_pk_fma_f32 v[68:69], v[68:69], v[102:103], v[104:105] op_sel_hi:[1,0,1]
	v_pk_mul_f32 v[104:105], v[62:63], v[108:109] op_sel:[0,1] op_sel_hi:[0,0] neg_lo:[0,1]
	v_pk_mul_f32 v[110:111], v[70:71], v[108:109] op_sel:[1,1] op_sel_hi:[0,1] neg_hi:[1,0]
	v_pk_fma_f32 v[104:105], v[26:27], v[108:109], v[104:105]
	v_pk_fma_f32 v[70:71], v[70:71], v[108:109], v[110:111] op_sel_hi:[1,0,1]
	v_pk_mul_f32 v[108:109], v[62:63], v[102:103] op_sel:[0,1] op_sel_hi:[0,0] neg_lo:[0,1]
	v_pk_fma_f32 v[102:103], v[26:27], v[102:103], v[108:109]
	s_nop 0
	v_pk_mul_f32 v[108:109], v[20:21], v[102:103] op_sel:[1,1] op_sel_hi:[0,1] neg_hi:[1,0]
	s_nop 0
	v_pk_fma_f32 v[20:21], v[20:21], v[102:103], v[108:109] op_sel_hi:[1,0,1]
	v_pk_mul_f32 v[108:109], v[62:63], v[104:105] op_sel:[0,1] op_sel_hi:[0,0] neg_lo:[0,1]
	v_pk_mul_f32 v[110:111], v[22:23], v[104:105] op_sel:[1,1] op_sel_hi:[0,1] neg_hi:[1,0]
	v_pk_fma_f32 v[108:109], v[26:27], v[104:105], v[108:109]
	v_pk_fma_f32 v[22:23], v[22:23], v[104:105], v[110:111] op_sel_hi:[1,0,1]
	v_pk_mul_f32 v[104:105], v[62:63], v[102:103] op_sel:[0,1] op_sel_hi:[0,0] neg_lo:[0,1]
	v_pk_fma_f32 v[102:103], v[26:27], v[102:103], v[104:105]
	s_nop 0
	v_pk_mul_f32 v[104:105], v[12:13], v[102:103] op_sel:[1,1] op_sel_hi:[0,1] neg_hi:[1,0]
	s_nop 0
	v_pk_fma_f32 v[12:13], v[12:13], v[102:103], v[104:105] op_sel_hi:[1,0,1]
	v_pk_mul_f32 v[104:105], v[62:63], v[108:109] op_sel:[0,1] op_sel_hi:[0,0] neg_lo:[0,1]
	v_pk_mul_f32 v[110:111], v[14:15], v[108:109] op_sel:[1,1] op_sel_hi:[0,1] neg_hi:[1,0]
	v_pk_fma_f32 v[104:105], v[26:27], v[108:109], v[104:105]
	v_pk_fma_f32 v[14:15], v[14:15], v[108:109], v[110:111] op_sel_hi:[1,0,1]
	v_pk_mul_f32 v[108:109], v[62:63], v[102:103] op_sel:[0,1] op_sel_hi:[0,0] neg_lo:[0,1]
	v_pk_fma_f32 v[102:103], v[26:27], v[102:103], v[108:109]
	s_nop 0
	v_pk_mul_f32 v[108:109], v[8:9], v[102:103] op_sel:[1,1] op_sel_hi:[0,1] neg_hi:[1,0]
	s_nop 0
	v_pk_fma_f32 v[8:9], v[8:9], v[102:103], v[108:109] op_sel_hi:[1,0,1]
	v_pk_mul_f32 v[108:109], v[62:63], v[104:105] op_sel:[0,1] op_sel_hi:[0,0] neg_lo:[0,1]
	v_pk_mul_f32 v[110:111], v[10:11], v[104:105] op_sel:[1,1] op_sel_hi:[0,1] neg_hi:[1,0]
	v_pk_fma_f32 v[108:109], v[26:27], v[104:105], v[108:109]
	v_pk_fma_f32 v[10:11], v[10:11], v[104:105], v[110:111] op_sel_hi:[1,0,1]
	v_pk_mul_f32 v[104:105], v[62:63], v[102:103] op_sel:[0,1] op_sel_hi:[0,0] neg_lo:[0,1]
	v_pk_fma_f32 v[26:27], v[26:27], v[102:103], v[104:105]
	s_nop 0
	v_pk_mul_f32 v[102:103], v[4:5], v[26:27] op_sel:[1,1] op_sel_hi:[0,1] neg_hi:[1,0]
	s_add_i32 s1, 16, 0x1e000
	v_pk_fma_f32 v[4:5], v[4:5], v[26:27], v[102:103] op_sel_hi:[1,0,1]
	s_nop 0
	s_nop 0
	v_pk_mul_f32 v[26:27], v[6:7], v[108:109] op_sel:[1,1] op_sel_hi:[0,1] neg_hi:[1,0]
	s_add_i32 s0, 16, 0x1f000
	v_pk_fma_f32 v[6:7], v[6:7], v[108:109], v[26:27] op_sel_hi:[1,0,1]
	v_lshrrev_b32_e32 v26, 5, v63
	v_bitop3_b32 v26, v26, v63, 15 bitop3:0x6c
	v_lshlrev_b32_e32 v26, 3, v26
	v_bfe_u32 v27, v63, 5, 4
	v_add_u32_e32 v62, 16, v26
	ds_write_b64 v62, v[2:3]
	v_bitop3_b32 v2, v27, v63, 16 bitop3:0x36
	v_lshlrev_b32_e32 v2, 3, v2
	v_add_u32_e32 v3, 16, v2
	ds_write_b64 v3, v[88:89] offset:4096
	ds_write_b64 v62, v[90:91] offset:8192
	ds_write_b64 v3, v[20:21] offset:12288
	ds_write_b64 v62, v[72:73] offset:16384
	ds_write_b64 v3, v[74:75] offset:20480
	ds_write_b64 v62, v[96:97] offset:24576
	ds_write_b64 v3, v[8:9] offset:28672
	ds_write_b64 v62, v[24:25] offset:32768
	ds_write_b64 v3, v[80:81] offset:36864
	ds_write_b64 v62, v[94:95] offset:40960
	ds_write_b64 v3, v[12:13] offset:45056
	ds_write_b64 v62, v[78:79] offset:49152
	ds_write_b64 v3, v[68:69] offset:53248
	ds_write_b64 v62, v[98:99] offset:57344
	ds_write_b64 v3, v[4:5] offset:61440
	v_add_u32_e32 v3, s47, v26
	ds_write_b64 v3, v[18:19]
	v_add_u32_e32 v3, s19, v2
	ds_write_b64 v3, v[92:93]
	v_add_u32_e32 v3, s18, v26
	ds_write_b64 v3, v[84:85]
	v_add_u32_e32 v3, s17, v2
	ds_write_b64 v3, v[22:23]
	v_add_u32_e32 v3, s13, v26
	ds_write_b64 v3, v[64:65]
	v_add_u32_e32 v3, s12, v2
	ds_write_b64 v3, v[76:77]
	v_add_u32_e32 v3, s11, v26
	ds_write_b64 v3, v[100:101]
	v_add_u32_e32 v3, s10, v2
	ds_write_b64 v3, v[10:11]
	v_add_u32_e32 v3, s9, v26
	ds_write_b64 v3, v[16:17]
	v_add_u32_e32 v3, s8, v2
	ds_write_b64 v3, v[82:83]
	v_add_u32_e32 v3, s7, v26
	ds_write_b64 v3, v[86:87]
	v_add_u32_e32 v3, s6, v2
	ds_write_b64 v3, v[14:15]
	v_add_u32_e32 v3, s5, v26
	ds_write_b64 v3, v[66:67]
	v_add_u32_e32 v3, s4, v2
	ds_write_b64 v3, v[70:71]
	v_add_u32_e32 v3, s1, v26
	v_add_u32_e32 v2, s0, v2
	v_mov_b32_e32 v21, v146
	ds_write_b64 v3, v[106:107]
	ds_write_b64 v2, v[6:7]
	s_waitcnt lgkmcnt(0)
	s_barrier
	s_lshl_b32 s44, s16, 14
	v_lshlrev_b32_e32 v2, 5, v21
	v_and_b32_e32 v4, 0xfffffe00, v2
	v_and_b32_e32 v20, 15, v21
	v_and_or_b32 v2, v21, 16, v4
	v_bitop3_b32 v4, v4, 16, v21 bitop3:0x34
	v_bitop3_b32 v72, v21, 8, 15 bitop3:0x6c
	v_lshl_add_u32 v26, v2, 3, 16
	v_lshlrev_b32_e32 v5, 3, v20
	v_lshl_add_u32 v126, v4, 3, 16
	v_lshlrev_b32_e32 v74, 3, v72
	v_add_u32_e32 v27, v26, v5
	v_add_u32_e32 v96, v126, v5
	v_add_u32_e32 v111, v26, v74
	v_add_u32_e32 v112, v126, v74
	ds_read_b64 v[2:3], v27
	ds_read_b64 v[4:5], v96
	v_bitop3_b32 v6, v21, 1, 15 bitop3:0x6c
	ds_read_b64 v[72:73], v111 offset:2048
	ds_read_b64 v[74:75], v112 offset:2048
	v_bitop3_b32 v76, v21, 9, 15 bitop3:0x6c
	v_lshlrev_b32_e32 v8, 3, v6
	v_lshlrev_b32_e32 v78, 3, v76
	v_add_u32_e32 v97, v26, v8
	v_add_u32_e32 v113, v26, v78
	ds_read_b64 v[6:7], v97 offset:256
	ds_read_b64 v[76:77], v113 offset:2304
	v_add_u32_e32 v98, v126, v8
	v_add_u32_e32 v114, v126, v78
	ds_read_b64 v[8:9], v98 offset:256
	ds_read_b64 v[78:79], v114 offset:2304
	s_waitcnt lgkmcnt(5)
	v_pk_add_f32 v[136:137], v[2:3], v[72:73]
	v_pk_add_f32 v[2:3], v[2:3], v[72:73] neg_lo:[0,1] neg_hi:[0,1]
	s_waitcnt lgkmcnt(4)
	v_pk_add_f32 v[72:73], v[4:5], v[74:75]
	v_pk_add_f32 v[4:5], v[4:5], v[74:75] neg_lo:[0,1] neg_hi:[0,1]
	v_bitop3_b32 v10, v21, 2, 15 bitop3:0x6c
	v_bitop3_b32 v80, v21, 10, 15 bitop3:0x6c
	v_lshlrev_b32_e32 v12, 3, v10
	v_lshlrev_b32_e32 v82, 3, v80
	v_pk_mul_f32 v[74:75], v[4:5], s[58:59] op_sel:[1,0] op_sel_hi:[0,0] neg_hi:[1,0]
	v_add_u32_e32 v99, v26, v12
	v_add_u32_e32 v115, v26, v82
	v_pk_fma_f32 v[4:5], v[4:5], s[46:47], v[74:75] op_sel_hi:[1,0,1]
	s_waitcnt lgkmcnt(2)
	v_pk_add_f32 v[74:75], v[6:7], v[76:77]
	v_pk_add_f32 v[6:7], v[6:7], v[76:77] neg_lo:[0,1] neg_hi:[0,1]
	ds_read_b64 v[10:11], v99 offset:512
	ds_read_b64 v[80:81], v115 offset:2560
	v_pk_mul_f32 v[76:77], v[6:7], s[62:63] op_sel:[1,0] op_sel_hi:[0,0] neg_hi:[1,0]
	v_add_u32_e32 v100, v126, v12
	v_bitop3_b32 v14, v21, 3, 15 bitop3:0x6c
	v_add_u32_e32 v116, v126, v82
	v_bitop3_b32 v84, v21, 11, 15 bitop3:0x6c
	v_pk_fma_f32 v[6:7], v[6:7], s[60:61], v[76:77] op_sel_hi:[1,0,1]
	s_waitcnt lgkmcnt(2)
	v_pk_add_f32 v[76:77], v[8:9], v[78:79]
	v_pk_add_f32 v[8:9], v[8:9], v[78:79] neg_lo:[0,1] neg_hi:[0,1]
	ds_read_b64 v[12:13], v100 offset:512
	v_lshlrev_b32_e32 v16, 3, v14
	ds_read_b64 v[82:83], v116 offset:2560
	v_lshlrev_b32_e32 v86, 3, v84
	v_add_u32_e32 v101, v26, v16
	v_add_u32_e32 v102, v126, v16
	v_add_u32_e32 v117, v26, v86
	v_add_u32_e32 v118, v126, v86
	v_pk_mul_f32 v[78:79], v[8:9], s[66:67] op_sel:[1,0] op_sel_hi:[0,0] neg_hi:[1,0]
	ds_read_b64 v[14:15], v101 offset:768
	ds_read_b64 v[16:17], v102 offset:768
	ds_read_b64 v[84:85], v117 offset:2816
	ds_read_b64 v[86:87], v118 offset:2816
	v_pk_fma_f32 v[8:9], v[8:9], s[64:65], v[78:79] op_sel_hi:[1,0,1]
	s_waitcnt lgkmcnt(6)
	v_pk_add_f32 v[78:79], v[10:11], v[80:81]
	v_pk_add_f32 v[10:11], v[10:11], v[80:81] neg_lo:[0,1] neg_hi:[0,1]
	v_bitop3_b32 v18, v21, 4, 15 bitop3:0x6c
	v_pk_mul_f32 v[80:81], v[10:11], s[70:71] op_sel:[1,0] op_sel_hi:[0,0] neg_hi:[1,0]
	v_bitop3_b32 v88, v21, 12, 15 bitop3:0x6c
	v_pk_fma_f32 v[10:11], v[10:11], s[70:71], v[80:81] op_sel_hi:[1,0,1]
	s_waitcnt lgkmcnt(4)
	v_pk_add_f32 v[80:81], v[12:13], v[82:83]
	v_pk_add_f32 v[12:13], v[12:13], v[82:83] neg_lo:[0,1] neg_hi:[0,1]
	v_lshlrev_b32_e32 v22, 3, v18
	v_lshlrev_b32_e32 v90, 3, v88
	v_pk_mul_f32 v[82:83], v[12:13], s[64:65] op_sel:[1,0] op_sel_hi:[0,0] neg_hi:[1,0]
	v_add_u32_e32 v103, v26, v22
	v_add_u32_e32 v119, v26, v90
	v_pk_fma_f32 v[12:13], v[12:13], s[66:67], v[82:83] op_sel_hi:[1,0,1]
	s_waitcnt lgkmcnt(1)
	v_pk_add_f32 v[82:83], v[14:15], v[84:85]
	v_pk_add_f32 v[14:15], v[14:15], v[84:85] neg_lo:[0,1] neg_hi:[0,1]
	ds_read_b64 v[18:19], v103 offset:1024
	v_add_u32_e32 v104, v126, v22
	v_bitop3_b32 v24, v21, 5, 15 bitop3:0x6c
	ds_read_b64 v[88:89], v119 offset:3072
	v_add_u32_e32 v120, v126, v90
	v_bitop3_b32 v92, v21, 13, 15 bitop3:0x6c
	ds_read_b64 v[22:23], v104 offset:1024
	v_lshlrev_b32_e32 v62, 3, v24
	ds_read_b64 v[90:91], v120 offset:3072
	v_lshlrev_b32_e32 v94, 3, v92
	v_pk_mul_f32 v[84:85], v[14:15], s[60:61] op_sel:[1,0] op_sel_hi:[0,0] neg_hi:[1,0]
	v_add_u32_e32 v105, v26, v62
	v_add_u32_e32 v121, v26, v94
	v_pk_fma_f32 v[14:15], v[14:15], s[62:63], v[84:85] op_sel_hi:[1,0,1]
	s_waitcnt lgkmcnt(4)
	v_pk_add_f32 v[84:85], v[16:17], v[86:87]
	v_pk_add_f32 v[16:17], v[16:17], v[86:87] neg_lo:[0,1] neg_hi:[0,1]
	ds_read_b64 v[24:25], v105 offset:1280
	ds_read_b64 v[92:93], v121 offset:3328
	v_add_u32_e32 v106, v126, v62
	v_bitop3_b32 v64, v21, 6, 15 bitop3:0x6c
	v_add_u32_e32 v122, v126, v94
	v_bitop3_b32 v123, v21, 14, 15 bitop3:0x6c
	v_pk_mul_f32 v[86:87], v[16:17], s[46:47] op_sel:[1,0] op_sel_hi:[0,0] neg_hi:[1,0]
	ds_read_b64 v[62:63], v106 offset:1280
	v_lshlrev_b32_e32 v66, 3, v64
	ds_read_b64 v[94:95], v122 offset:3328
	v_lshlrev_b32_e32 v124, 3, v123
	v_pk_fma_f32 v[16:17], v[16:17], s[58:59], v[86:87] op_sel_hi:[1,0,1]
	s_waitcnt lgkmcnt(6)
	v_pk_add_f32 v[86:87], v[18:19], v[88:89]
	v_pk_add_f32 v[18:19], v[18:19], v[88:89] neg_lo:[0,1] neg_hi:[0,1]
	v_add_u32_e32 v107, v26, v66
	v_add_u32_e32 v123, v26, v124
	v_xor_b32_e32 v89, 0x80000000, v18
	v_mov_b32_e32 v88, v19
	s_waitcnt lgkmcnt(4)
	v_pk_add_f32 v[18:19], v[22:23], v[90:91]
	v_pk_add_f32 v[22:23], v[22:23], v[90:91] neg_lo:[0,1] neg_hi:[0,1]
	ds_read_b64 v[64:65], v107 offset:1536
	ds_read_b64 v[128:129], v123 offset:3584
	v_pk_mul_f32 v[90:91], v[22:23], s[58:59] op_sel_hi:[1,0]
	v_xor_b32_e32 v139, 0x80000000, v22
	v_mov_b32_e32 v138, v23
	v_add_u32_e32 v108, v126, v66
	v_bitop3_b32 v68, v21, 7, 15 bitop3:0x6c
	v_add_u32_e32 v124, v126, v124
	v_bitop3_b32 v21, v21, 15, v21 bitop3:0xc
	v_pk_fma_f32 v[22:23], v[138:139], s[46:47], v[90:91] op_sel_hi:[1,0,1] neg_lo:[0,0,1] neg_hi:[0,0,1]
	s_waitcnt lgkmcnt(4)
	v_pk_add_f32 v[90:91], v[24:25], v[92:93]
	v_pk_add_f32 v[24:25], v[24:25], v[92:93] neg_lo:[0,1] neg_hi:[0,1]
	ds_read_b64 v[66:67], v108 offset:1536
	v_lshlrev_b32_e32 v70, 3, v68
	ds_read_b64 v[130:131], v124 offset:3584
	v_lshlrev_b32_e32 v21, 3, v21
	v_pk_mul_f32 v[92:93], v[24:25], s[62:63] op_sel_hi:[1,0]
	v_xor_b32_e32 v139, 0x80000000, v24
	v_mov_b32_e32 v138, v25
	v_add_u32_e32 v109, v26, v70
	v_add_u32_e32 v125, v26, v21
	v_pk_fma_f32 v[24:25], v[138:139], s[60:61], v[92:93] op_sel_hi:[1,0,1] neg_lo:[0,0,1] neg_hi:[0,0,1]
	s_waitcnt lgkmcnt(4)
	v_pk_add_f32 v[92:93], v[62:63], v[94:95]
	v_pk_add_f32 v[62:63], v[62:63], v[94:95] neg_lo:[0,1] neg_hi:[0,1]
	ds_read_b64 v[68:69], v109 offset:1792
	v_add_u32_e32 v110, v126, v70
	ds_read_b64 v[132:133], v125 offset:3840
	v_add_u32_e32 v126, v126, v21
	v_pk_mul_f32 v[94:95], v[62:63], s[66:67] op_sel_hi:[1,0]
	v_xor_b32_e32 v139, 0x80000000, v62
	v_mov_b32_e32 v138, v63
	ds_read_b64 v[70:71], v110 offset:1792
	ds_read_b64 v[134:135], v126 offset:3840
	v_pk_fma_f32 v[62:63], v[138:139], s[64:65], v[94:95] op_sel_hi:[1,0,1] neg_lo:[0,0,1] neg_hi:[0,0,1]
	s_waitcnt lgkmcnt(6)
	v_pk_add_f32 v[94:95], v[64:65], v[128:129]
	v_pk_add_f32 v[64:65], v[64:65], v[128:129] neg_lo:[0,1] neg_hi:[0,1]
	v_lshl_add_u64 v[0:1], s[44:45], 2, v[28:29]
	v_pk_mul_f32 v[128:129], v[64:65], s[70:71] op_sel_hi:[1,0]
	v_xor_b32_e32 v139, 0x80000000, v64
	v_mov_b32_e32 v138, v65
	v_pk_fma_f32 v[64:65], v[138:139], s[70:71], v[128:129] op_sel_hi:[1,0,1] neg_lo:[0,0,1] neg_hi:[0,0,1]
	s_waitcnt lgkmcnt(4)
	v_pk_add_f32 v[128:129], v[66:67], v[130:131]
	v_pk_add_f32 v[66:67], v[66:67], v[130:131] neg_lo:[0,1] neg_hi:[0,1]
	v_cvt_f32_i32_e32 v20, v20
	v_pk_mul_f32 v[130:131], v[66:67], s[64:65] op_sel_hi:[1,0]
	v_xor_b32_e32 v139, 0x80000000, v66
	v_mov_b32_e32 v138, v67
	v_pk_fma_f32 v[66:67], v[138:139], s[66:67], v[130:131] op_sel_hi:[1,0,1] neg_lo:[0,0,1] neg_hi:[0,0,1]
	s_waitcnt lgkmcnt(2)
	v_pk_add_f32 v[130:131], v[68:69], v[132:133]
	v_pk_add_f32 v[68:69], v[68:69], v[132:133] neg_lo:[0,1] neg_hi:[0,1]
	v_mul_f32_e32 v21, 0x3b000000, v20
	v_pk_mul_f32 v[132:133], v[68:69], s[60:61] op_sel_hi:[1,0]
	v_xor_b32_e32 v139, 0x80000000, v68
	v_mov_b32_e32 v138, v69
	v_pk_fma_f32 v[68:69], v[138:139], s[62:63], v[132:133] op_sel_hi:[1,0,1] neg_lo:[0,0,1] neg_hi:[0,0,1]
	s_waitcnt lgkmcnt(0)
	v_pk_add_f32 v[132:133], v[70:71], v[134:135]
	v_pk_add_f32 v[70:71], v[70:71], v[134:135] neg_lo:[0,1] neg_hi:[0,1]
	v_cos_f32_e32 v20, v21
	v_pk_mul_f32 v[134:135], v[70:71], s[46:47] op_sel_hi:[1,0]
	v_xor_b32_e32 v139, 0x80000000, v70
	v_mov_b32_e32 v138, v71
	v_pk_fma_f32 v[70:71], v[138:139], s[58:59], v[134:135] op_sel_hi:[1,0,1] neg_lo:[0,0,1] neg_hi:[0,0,1]
	v_pk_add_f32 v[134:135], v[136:137], v[86:87]
	v_pk_add_f32 v[86:87], v[136:137], v[86:87] neg_lo:[0,1] neg_hi:[0,1]
	v_pk_add_f32 v[136:137], v[72:73], v[18:19]
	v_pk_add_f32 v[18:19], v[72:73], v[18:19] neg_lo:[0,1] neg_hi:[0,1]
	v_sin_f32_e32 v21, v21
	s_nop 0
	s_nop 0
	v_pk_mul_f32 v[72:73], v[18:19], s[62:63] op_sel:[1,0] op_sel_hi:[0,0] neg_hi:[1,0]
	v_add_f32_e32 v26, v20, v20
	v_pk_fma_f32 v[18:19], v[18:19], s[60:61], v[72:73] op_sel_hi:[1,0,1]
	v_pk_add_f32 v[72:73], v[74:75], v[90:91]
	v_pk_add_f32 v[74:75], v[74:75], v[90:91] neg_lo:[0,1] neg_hi:[0,1]
	v_mul_f32_e32 v26, v21, v26
	s_nop 0
	s_nop 0
	v_pk_mul_f32 v[90:91], v[74:75], s[70:71] op_sel:[1,0] op_sel_hi:[0,0] neg_hi:[1,0]
	s_lshl_b32 s44, s16, 9
	v_pk_fma_f32 v[74:75], v[74:75], s[70:71], v[90:91] op_sel_hi:[1,0,1]
	v_pk_add_f32 v[90:91], v[76:77], v[92:93]
	v_pk_add_f32 v[76:77], v[76:77], v[92:93] neg_lo:[0,1] neg_hi:[0,1]
	s_mov_b64 s[28:29], -1
	s_nop 0
	s_nop 0
	v_pk_mul_f32 v[92:93], v[76:77], s[60:61] op_sel:[1,0] op_sel_hi:[0,0] neg_hi:[1,0]
	s_nop 0
	v_pk_fma_f32 v[76:77], v[76:77], s[62:63], v[92:93] op_sel_hi:[1,0,1]
	v_pk_add_f32 v[92:93], v[78:79], v[94:95]
	v_pk_add_f32 v[78:79], v[78:79], v[94:95] neg_lo:[0,1] neg_hi:[0,1]
	s_nop 0
	v_xor_b32_e32 v95, 0x80000000, v78
	v_mov_b32_e32 v94, v79
	v_pk_add_f32 v[78:79], v[80:81], v[128:129]
	v_pk_add_f32 v[80:81], v[80:81], v[128:129] neg_lo:[0,1] neg_hi:[0,1]
	s_nop 0
	v_pk_mul_f32 v[128:129], v[80:81], s[62:63] op_sel_hi:[1,0]
	v_xor_b32_e32 v139, 0x80000000, v80
	v_mov_b32_e32 v138, v81
	v_pk_fma_f32 v[80:81], v[138:139], s[60:61], v[128:129] op_sel_hi:[1,0,1] neg_lo:[0,0,1] neg_hi:[0,0,1]
	v_pk_add_f32 v[128:129], v[82:83], v[130:131]
	v_pk_add_f32 v[82:83], v[82:83], v[130:131] neg_lo:[0,1] neg_hi:[0,1]
	s_nop 0
	v_pk_mul_f32 v[130:131], v[82:83], s[70:71] op_sel_hi:[1,0]
	v_xor_b32_e32 v139, 0x80000000, v82
	v_mov_b32_e32 v138, v83
	v_pk_fma_f32 v[82:83], v[138:139], s[70:71], v[130:131] op_sel_hi:[1,0,1] neg_lo:[0,0,1] neg_hi:[0,0,1]
	v_pk_add_f32 v[130:131], v[84:85], v[132:133]
	v_pk_add_f32 v[84:85], v[84:85], v[132:133] neg_lo:[0,1] neg_hi:[0,1]
	s_nop 0
	v_pk_mul_f32 v[132:133], v[84:85], s[60:61] op_sel_hi:[1,0]
	v_xor_b32_e32 v139, 0x80000000, v84
	v_mov_b32_e32 v138, v85
	v_pk_fma_f32 v[84:85], v[138:139], s[62:63], v[132:133] op_sel_hi:[1,0,1] neg_lo:[0,0,1] neg_hi:[0,0,1]
	v_pk_add_f32 v[132:133], v[2:3], v[88:89]
	v_pk_add_f32 v[2:3], v[2:3], v[88:89] neg_lo:[0,1] neg_hi:[0,1]
	v_pk_add_f32 v[88:89], v[4:5], v[22:23]
	v_pk_add_f32 v[4:5], v[4:5], v[22:23] neg_lo:[0,1] neg_hi:[0,1]
	s_nop 0
	v_pk_mul_f32 v[22:23], v[4:5], s[62:63] op_sel:[1,0] op_sel_hi:[0,0] neg_hi:[1,0]
	s_nop 0
	v_pk_fma_f32 v[4:5], v[4:5], s[60:61], v[22:23] op_sel_hi:[1,0,1]
	v_pk_add_f32 v[22:23], v[6:7], v[24:25]
	v_pk_add_f32 v[6:7], v[6:7], v[24:25] neg_lo:[0,1] neg_hi:[0,1]
	s_nop 0
	v_pk_mul_f32 v[24:25], v[6:7], s[70:71] op_sel:[1,0] op_sel_hi:[0,0] neg_hi:[1,0]
	s_nop 0
	v_pk_fma_f32 v[6:7], v[6:7], s[70:71], v[24:25] op_sel_hi:[1,0,1]
	v_pk_add_f32 v[24:25], v[8:9], v[62:63]
	v_pk_add_f32 v[8:9], v[8:9], v[62:63] neg_lo:[0,1] neg_hi:[0,1]
	s_nop 0
	v_pk_mul_f32 v[62:63], v[8:9], s[60:61] op_sel:[1,0] op_sel_hi:[0,0] neg_hi:[1,0]
	s_nop 0
	v_pk_fma_f32 v[8:9], v[8:9], s[62:63], v[62:63] op_sel_hi:[1,0,1]
	v_pk_add_f32 v[62:63], v[10:11], v[64:65]
	v_pk_add_f32 v[10:11], v[10:11], v[64:65] neg_lo:[0,1] neg_hi:[0,1]
	s_nop 0
	v_xor_b32_e32 v65, 0x80000000, v10
	v_mov_b32_e32 v64, v11
	v_pk_add_f32 v[10:11], v[12:13], v[66:67]
	v_pk_add_f32 v[12:13], v[12:13], v[66:67] neg_lo:[0,1] neg_hi:[0,1]
	s_nop 0
	v_pk_mul_f32 v[66:67], v[12:13], s[62:63] op_sel_hi:[1,0]
	v_xor_b32_e32 v139, 0x80000000, v12
	v_mov_b32_e32 v138, v13
	v_pk_fma_f32 v[12:13], v[138:139], s[60:61], v[66:67] op_sel_hi:[1,0,1] neg_lo:[0,0,1] neg_hi:[0,0,1]
	v_pk_add_f32 v[66:67], v[14:15], v[68:69]
	v_pk_add_f32 v[14:15], v[14:15], v[68:69] neg_lo:[0,1] neg_hi:[0,1]
	s_nop 0
	v_pk_mul_f32 v[68:69], v[14:15], s[70:71] op_sel_hi:[1,0]
	v_xor_b32_e32 v139, 0x80000000, v14
	v_mov_b32_e32 v138, v15
	v_pk_fma_f32 v[14:15], v[138:139], s[70:71], v[68:69] op_sel_hi:[1,0,1] neg_lo:[0,0,1] neg_hi:[0,0,1]
	v_pk_add_f32 v[68:69], v[16:17], v[70:71]
	v_pk_add_f32 v[16:17], v[16:17], v[70:71] neg_lo:[0,1] neg_hi:[0,1]
	s_nop 0
	v_pk_mul_f32 v[70:71], v[16:17], s[60:61] op_sel_hi:[1,0]
	v_xor_b32_e32 v139, 0x80000000, v16
	v_mov_b32_e32 v138, v17
	v_pk_fma_f32 v[16:17], v[138:139], s[62:63], v[70:71] op_sel_hi:[1,0,1] neg_lo:[0,0,1] neg_hi:[0,0,1]
	v_pk_add_f32 v[70:71], v[134:135], v[92:93]
	v_pk_add_f32 v[92:93], v[134:135], v[92:93] neg_lo:[0,1] neg_hi:[0,1]
	v_pk_add_f32 v[134:135], v[136:137], v[78:79]
	v_pk_add_f32 v[78:79], v[136:137], v[78:79] neg_lo:[0,1] neg_hi:[0,1]
	s_nop 0
	v_pk_mul_f32 v[136:137], v[78:79], s[70:71] op_sel:[1,0] op_sel_hi:[0,0] neg_hi:[1,0]
	s_nop 0
	v_pk_fma_f32 v[78:79], v[78:79], s[70:71], v[136:137] op_sel_hi:[1,0,1]
	v_pk_add_f32 v[136:137], v[72:73], v[128:129]
	v_pk_add_f32 v[72:73], v[72:73], v[128:129] neg_lo:[0,1] neg_hi:[0,1]
	s_nop 0
	v_xor_b32_e32 v129, 0x80000000, v72
	v_mov_b32_e32 v128, v73
	v_pk_add_f32 v[72:73], v[90:91], v[130:131]
	v_pk_add_f32 v[90:91], v[90:91], v[130:131] neg_lo:[0,1] neg_hi:[0,1]
	s_nop 0
	v_pk_mul_f32 v[130:131], v[90:91], s[70:71] op_sel_hi:[1,0]
	v_xor_b32_e32 v139, 0x80000000, v90
	v_mov_b32_e32 v138, v91
	v_pk_fma_f32 v[90:91], v[138:139], s[70:71], v[130:131] op_sel_hi:[1,0,1] neg_lo:[0,0,1] neg_hi:[0,0,1]
	v_pk_add_f32 v[130:131], v[86:87], v[94:95]
	v_pk_add_f32 v[86:87], v[86:87], v[94:95] neg_lo:[0,1] neg_hi:[0,1]
	v_pk_add_f32 v[94:95], v[18:19], v[80:81]
	v_pk_add_f32 v[18:19], v[18:19], v[80:81] neg_lo:[0,1] neg_hi:[0,1]
	s_nop 0
	v_pk_mul_f32 v[80:81], v[18:19], s[70:71] op_sel:[1,0] op_sel_hi:[0,0] neg_hi:[1,0]
	s_nop 0
	v_pk_fma_f32 v[18:19], v[18:19], s[70:71], v[80:81] op_sel_hi:[1,0,1]
	v_pk_add_f32 v[80:81], v[74:75], v[82:83]
	v_pk_add_f32 v[74:75], v[74:75], v[82:83] neg_lo:[0,1] neg_hi:[0,1]
	s_nop 0
	v_xor_b32_e32 v83, 0x80000000, v74
	v_mov_b32_e32 v82, v75
	v_pk_add_f32 v[74:75], v[76:77], v[84:85]
	v_pk_add_f32 v[76:77], v[76:77], v[84:85] neg_lo:[0,1] neg_hi:[0,1]
	s_nop 0
	v_pk_mul_f32 v[84:85], v[76:77], s[70:71] op_sel_hi:[1,0]
	v_xor_b32_e32 v139, 0x80000000, v76
	v_mov_b32_e32 v138, v77
	v_pk_fma_f32 v[76:77], v[138:139], s[70:71], v[84:85] op_sel_hi:[1,0,1] neg_lo:[0,0,1] neg_hi:[0,0,1]
	v_pk_add_f32 v[84:85], v[132:133], v[62:63]
	v_pk_add_f32 v[62:63], v[132:133], v[62:63] neg_lo:[0,1] neg_hi:[0,1]
	v_pk_add_f32 v[132:133], v[88:89], v[10:11]
	v_pk_add_f32 v[10:11], v[88:89], v[10:11] neg_lo:[0,1] neg_hi:[0,1]
	s_nop 0
	v_pk_mul_f32 v[88:89], v[10:11], s[70:71] op_sel:[1,0] op_sel_hi:[0,0] neg_hi:[1,0]
	s_nop 0
	v_pk_fma_f32 v[10:11], v[10:11], s[70:71], v[88:89] op_sel_hi:[1,0,1]
	v_pk_add_f32 v[88:89], v[22:23], v[66:67]
	v_pk_add_f32 v[22:23], v[22:23], v[66:67] neg_lo:[0,1] neg_hi:[0,1]
	s_nop 0
	v_xor_b32_e32 v67, 0x80000000, v22
	v_mov_b32_e32 v66, v23
	v_pk_add_f32 v[22:23], v[24:25], v[68:69]
	v_pk_add_f32 v[24:25], v[24:25], v[68:69] neg_lo:[0,1] neg_hi:[0,1]
	s_nop 0
	v_pk_mul_f32 v[68:69], v[24:25], s[70:71] op_sel_hi:[1,0]
	v_xor_b32_e32 v139, 0x80000000, v24
	v_mov_b32_e32 v138, v25
	v_pk_fma_f32 v[24:25], v[138:139], s[70:71], v[68:69] op_sel_hi:[1,0,1] neg_lo:[0,0,1] neg_hi:[0,0,1]
	v_pk_add_f32 v[68:69], v[2:3], v[64:65]
	v_pk_add_f32 v[2:3], v[2:3], v[64:65] neg_lo:[0,1] neg_hi:[0,1]
	v_pk_add_f32 v[64:65], v[4:5], v[12:13]
	v_pk_add_f32 v[4:5], v[4:5], v[12:13] neg_lo:[0,1] neg_hi:[0,1]
	s_nop 0
	v_pk_mul_f32 v[12:13], v[4:5], s[70:71] op_sel:[1,0] op_sel_hi:[0,0] neg_hi:[1,0]
	s_nop 0
	v_pk_fma_f32 v[4:5], v[4:5], s[70:71], v[12:13] op_sel_hi:[1,0,1]
	v_pk_add_f32 v[12:13], v[6:7], v[14:15]
	v_pk_add_f32 v[6:7], v[6:7], v[14:15] neg_lo:[0,1] neg_hi:[0,1]
	v_pk_add_f32 v[140:141], v[68:69], v[12:13]
	v_xor_b32_e32 v15, 0x80000000, v6
	v_mov_b32_e32 v14, v7
	v_pk_add_f32 v[6:7], v[8:9], v[16:17]
	v_pk_add_f32 v[8:9], v[8:9], v[16:17] neg_lo:[0,1] neg_hi:[0,1]
	v_pk_add_f32 v[142:143], v[64:65], v[6:7]
	v_pk_mul_f32 v[16:17], v[8:9], s[70:71] op_sel_hi:[1,0]
	s_nop 0
	v_pk_fma_f32 v[8:9], v[8:9], s[70:71], v[16:17] op_sel:[1,0,0] op_sel_hi:[0,0,1] neg_lo:[0,0,1] neg_hi:[1,0,1]
	v_pk_add_f32 v[16:17], v[70:71], v[136:137]
	v_pk_add_f32 v[70:71], v[70:71], v[136:137] neg_lo:[0,1] neg_hi:[0,1]
	v_pk_add_f32 v[136:137], v[134:135], v[72:73]
	v_pk_add_f32 v[72:73], v[134:135], v[72:73] neg_lo:[0,1] neg_hi:[0,1]
	v_pk_add_f32 v[138:139], v[84:85], v[88:89] neg_lo:[0,1] neg_hi:[0,1]
	v_xor_b32_e32 v135, 0x80000000, v72
	v_mov_b32_e32 v134, v73
	v_pk_add_f32 v[72:73], v[92:93], v[128:129]
	v_pk_add_f32 v[92:93], v[92:93], v[128:129] neg_lo:[0,1] neg_hi:[0,1]
	v_pk_add_f32 v[128:129], v[78:79], v[90:91]
	v_pk_add_f32 v[78:79], v[78:79], v[90:91] neg_lo:[0,1] neg_hi:[0,1]
	v_pk_add_f32 v[6:7], v[64:65], v[6:7] neg_lo:[0,1] neg_hi:[0,1]
	v_xor_b32_e32 v91, 0x80000000, v78
	v_mov_b32_e32 v90, v79
	v_pk_add_f32 v[78:79], v[130:131], v[80:81]
	v_pk_add_f32 v[130:131], v[130:131], v[80:81] neg_lo:[0,1] neg_hi:[0,1]
	v_pk_add_f32 v[80:81], v[94:95], v[74:75]
	v_pk_add_f32 v[74:75], v[94:95], v[74:75] neg_lo:[0,1] neg_hi:[0,1]
	v_xor_b32_e32 v149, 0x80000000, v6
	v_xor_b32_e32 v95, 0x80000000, v74
	v_mov_b32_e32 v94, v75
	v_pk_add_f32 v[74:75], v[86:87], v[82:83]
	v_pk_add_f32 v[82:83], v[86:87], v[82:83] neg_lo:[0,1] neg_hi:[0,1]
	v_pk_add_f32 v[86:87], v[18:19], v[76:77]
	v_pk_add_f32 v[18:19], v[18:19], v[76:77] neg_lo:[0,1] neg_hi:[0,1]
	v_mov_b32_e32 v148, v7
	v_xor_b32_e32 v77, 0x80000000, v18
	v_mov_b32_e32 v76, v19
	v_pk_add_f32 v[18:19], v[84:85], v[88:89]
	v_pk_add_f32 v[88:89], v[132:133], v[22:23]
	v_pk_add_f32 v[22:23], v[132:133], v[22:23] neg_lo:[0,1] neg_hi:[0,1]
	v_pk_add_f32 v[6:7], v[2:3], v[14:15]
	v_xor_b32_e32 v133, 0x80000000, v22
	v_mov_b32_e32 v132, v23
	v_pk_add_f32 v[22:23], v[62:63], v[66:67]
	v_pk_add_f32 v[62:63], v[62:63], v[66:67] neg_lo:[0,1] neg_hi:[0,1]
	v_pk_add_f32 v[66:67], v[10:11], v[24:25]
	v_pk_add_f32 v[10:11], v[10:11], v[24:25] neg_lo:[0,1] neg_hi:[0,1]
	v_pk_add_f32 v[150:151], v[2:3], v[14:15] neg_lo:[0,1] neg_hi:[0,1]
	v_pk_add_f32 v[2:3], v[4:5], v[8:9] neg_lo:[0,1] neg_hi:[0,1]
	v_pk_add_f32 v[68:69], v[68:69], v[12:13] neg_lo:[0,1] neg_hi:[0,1]
	v_pk_add_f32 v[156:157], v[4:5], v[8:9]
	v_xor_b32_e32 v159, 0x80000000, v2
	v_mov_b32_e32 v158, v3
	v_pk_add_f32 v[2:3], v[16:17], v[136:137]
	v_pk_add_f32 v[84:85], v[16:17], v[136:137] neg_lo:[0,1] neg_hi:[0,1]
	v_pk_add_f32 v[136:137], v[70:71], v[134:135]
	v_pk_add_f32 v[16:17], v[70:71], v[134:135] neg_lo:[0,1] neg_hi:[0,1]
	v_pk_add_f32 v[134:135], v[72:73], v[128:129]
	v_pk_add_f32 v[70:71], v[72:73], v[128:129] neg_lo:[0,1] neg_hi:[0,1]
	v_pk_add_f32 v[128:129], v[92:93], v[90:91]
	v_pk_add_f32 v[8:9], v[92:93], v[90:91] neg_lo:[0,1] neg_hi:[0,1]
	v_pk_add_f32 v[72:73], v[78:79], v[80:81]
	v_pk_add_f32 v[80:81], v[78:79], v[80:81] neg_lo:[0,1] neg_hi:[0,1]
	v_pk_add_f32 v[92:93], v[130:131], v[94:95]
	v_pk_add_f32 v[12:13], v[130:131], v[94:95] neg_lo:[0,1] neg_hi:[0,1]
	v_pk_add_f32 v[78:79], v[74:75], v[86:87]
	v_pk_add_f32 v[64:65], v[74:75], v[86:87] neg_lo:[0,1] neg_hi:[0,1]
	v_pk_add_f32 v[130:131], v[82:83], v[76:77]
	v_pk_add_f32 v[4:5], v[82:83], v[76:77] neg_lo:[0,1] neg_hi:[0,1]
	v_pk_add_f32 v[76:77], v[18:19], v[88:89]
	v_pk_add_f32 v[88:89], v[18:19], v[88:89] neg_lo:[0,1] neg_hi:[0,1]
	v_pk_add_f32 v[86:87], v[138:139], v[132:133]
	v_pk_add_f32 v[18:19], v[138:139], v[132:133] neg_lo:[0,1] neg_hi:[0,1]
	v_pk_add_f32 v[132:133], v[62:63], v[10:11] op_sel:[0,1] op_sel_hi:[1,0] neg_hi:[0,1]
	v_pk_add_f32 v[10:11], v[62:63], v[10:11] op_sel:[0,1] op_sel_hi:[1,0] neg_lo:[0,1]
	v_pk_mul_f32 v[24:25], v[20:21], v[20:21]
	s_nop 0
	v_pk_add_f32 v[24:25], v[24:25], v[24:25] op_sel:[0,1] op_sel_hi:[0,1] neg_lo:[0,1] neg_hi:[0,1]
	v_pk_mul_f32 v[62:63], v[20:21], v[26:27] op_sel:[1,0] op_sel_hi:[0,0] neg_lo:[1,0]
	v_pk_add_f32 v[90:91], v[22:23], v[66:67]
	v_pk_add_f32 v[74:75], v[22:23], v[66:67] neg_lo:[0,1] neg_hi:[0,1]
	v_pk_add_f32 v[22:23], v[140:141], v[142:143]
	v_pk_add_f32 v[82:83], v[140:141], v[142:143] neg_lo:[0,1] neg_hi:[0,1]
	v_pk_add_f32 v[138:139], v[68:69], v[148:149]
	v_pk_add_f32 v[14:15], v[68:69], v[148:149] neg_lo:[0,1] neg_hi:[0,1]
	v_pk_fma_f32 v[68:69], v[20:21], v[24:25], v[62:63]
	v_mov_b32_e32 v142, v21
	s_nop 0
	v_pk_mul_f32 v[62:63], v[142:143], v[76:77] op_sel:[0,1] op_sel_hi:[0,0] neg_hi:[0,1]
	v_pk_fma_f32 v[20:21], v[20:21], v[76:77], v[62:63] op_sel_hi:[0,1,1]
	v_pk_mul_f32 v[62:63], v[26:27], s[48:49] op_sel_hi:[0,1]
	v_pk_fma_f32 v[76:77], v[24:25], s[40:41], v[62:63]
	s_nop 0
	v_pk_mul_f32 v[62:63], v[76:77], v[72:73] op_sel:[1,1] op_sel_hi:[1,0] neg_hi:[0,1]
	v_pk_add_f32 v[94:95], v[6:7], v[156:157]
	v_pk_fma_f32 v[62:63], v[72:73], v[76:77], v[62:63] op_sel_hi:[1,0,1]
	v_pk_mul_f32 v[72:73], v[26:27], v[68:69] op_sel:[0,1] op_sel_hi:[0,0] neg_lo:[0,1]
	v_pk_fma_f32 v[142:143], v[24:25], v[68:69], v[72:73]
	v_pk_mul_f32 v[72:73], v[68:69], v[22:23] op_sel:[1,1] op_sel_hi:[1,0] neg_hi:[0,1]
	v_pk_add_f32 v[140:141], v[150:151], v[158:159]
	v_pk_fma_f32 v[22:23], v[68:69], v[22:23], v[72:73] op_sel_hi:[0,1,1]
	v_pk_mul_f32 v[68:69], v[26:27], v[76:77] op_sel:[0,1] op_sel_hi:[0,0] neg_lo:[0,1]
	v_pk_fma_f32 v[76:77], v[24:25], v[76:77], v[68:69]
	s_nop 0
	v_pk_mul_f32 v[68:69], v[134:135], v[76:77] op_sel:[1,1] op_sel_hi:[0,1] neg_hi:[1,0]
	v_pk_add_f32 v[66:67], v[6:7], v[156:157] neg_lo:[0,1] neg_hi:[0,1]
	v_pk_fma_f32 v[72:73], v[134:135], v[76:77], v[68:69] op_sel_hi:[1,0,1]
	v_pk_mul_f32 v[68:69], v[26:27], v[142:143] op_sel:[0,1] op_sel_hi:[0,0] neg_lo:[0,1]
	v_pk_fma_f32 v[134:135], v[24:25], v[142:143], v[68:69]
	v_pk_mul_f32 v[68:69], v[142:143], v[90:91] op_sel:[1,1] op_sel_hi:[1,0] neg_hi:[0,1]
	v_pk_add_f32 v[6:7], v[150:151], v[158:159] neg_lo:[0,1] neg_hi:[0,1]
	v_pk_fma_f32 v[68:69], v[90:91], v[142:143], v[68:69] op_sel_hi:[1,0,1]
	v_pk_mul_f32 v[90:91], v[26:27], v[76:77] op_sel:[0,1] op_sel_hi:[0,0] neg_lo:[0,1]
	v_pk_fma_f32 v[90:91], v[24:25], v[76:77], v[90:91]
	s_nop 0
	v_pk_mul_f32 v[76:77], v[78:79], v[90:91] op_sel:[1,1] op_sel_hi:[0,1] neg_hi:[1,0]
	s_nop 0
	v_pk_fma_f32 v[78:79], v[78:79], v[90:91], v[76:77] op_sel_hi:[1,0,1]
	v_pk_mul_f32 v[76:77], v[26:27], v[134:135] op_sel:[0,1] op_sel_hi:[0,0] neg_lo:[0,1]
	v_pk_fma_f32 v[142:143], v[24:25], v[134:135], v[76:77]
	v_pk_mul_f32 v[76:77], v[134:135], v[94:95] op_sel:[1,1] op_sel_hi:[1,0] neg_hi:[0,1]
	s_nop 0
	v_pk_fma_f32 v[76:77], v[94:95], v[134:135], v[76:77] op_sel_hi:[1,0,1]
	v_pk_mul_f32 v[94:95], v[26:27], v[90:91] op_sel:[0,1] op_sel_hi:[0,0] neg_lo:[0,1]
	v_pk_fma_f32 v[94:95], v[24:25], v[90:91], v[94:95]
	s_nop 0
	v_pk_mul_f32 v[90:91], v[136:137], v[94:95] op_sel:[1,1] op_sel_hi:[0,1] neg_hi:[1,0]
	v_xor_b32_e32 v134, 0x80000000, v143
	v_pk_fma_f32 v[90:91], v[136:137], v[94:95], v[90:91] op_sel_hi:[1,0,1]
	v_pk_mul_f32 v[136:137], v[86:87], v[142:143] op_sel:[1,1] op_sel_hi:[0,1] neg_hi:[1,0]
	v_mov_b32_e32 v135, v142
	v_pk_fma_f32 v[86:87], v[86:87], v[142:143], v[136:137] op_sel_hi:[1,0,1]
	v_pk_mul_f32 v[136:137], v[26:27], v[94:95] op_sel:[0,1] op_sel_hi:[0,0] neg_lo:[0,1]
	v_pk_mul_f32 v[134:135], v[26:27], v[134:135] op_sel_hi:[0,1]
	v_pk_fma_f32 v[136:137], v[24:25], v[94:95], v[136:137]
	v_pk_fma_f32 v[134:135], v[24:25], v[142:143], v[134:135]
	v_pk_mul_f32 v[94:95], v[92:93], v[136:137] op_sel:[1,1] op_sel_hi:[0,1] neg_hi:[1,0]
	s_nop 0
	v_pk_fma_f32 v[94:95], v[92:93], v[136:137], v[94:95] op_sel_hi:[1,0,1]
	v_pk_mul_f32 v[92:93], v[26:27], v[134:135] op_sel:[0,1] op_sel_hi:[0,0] neg_lo:[0,1]
	v_pk_fma_f32 v[142:143], v[24:25], v[134:135], v[92:93]
	v_pk_mul_f32 v[92:93], v[138:139], v[134:135] op_sel:[1,1] op_sel_hi:[0,1] neg_hi:[1,0]
	s_nop 0
	v_pk_fma_f32 v[92:93], v[138:139], v[134:135], v[92:93] op_sel_hi:[1,0,1]
	v_pk_mul_f32 v[134:135], v[26:27], v[136:137] op_sel:[0,1] op_sel_hi:[0,0] neg_lo:[0,1]
	s_nop 0
	v_pk_fma_f32 v[134:135], v[24:25], v[136:137], v[134:135]
	v_pk_mul_f32 v[138:139], v[132:133], v[142:143] op_sel:[1,1] op_sel_hi:[0,1] neg_hi:[1,0]
	v_pk_mul_f32 v[136:137], v[128:129], v[134:135] op_sel:[1,1] op_sel_hi:[0,1] neg_hi:[1,0]
	v_pk_fma_f32 v[132:133], v[132:133], v[142:143], v[138:139] op_sel_hi:[1,0,1]
	v_pk_fma_f32 v[128:129], v[128:129], v[134:135], v[136:137] op_sel_hi:[1,0,1]
	v_pk_mul_f32 v[138:139], v[26:27], v[134:135] op_sel:[0,1] op_sel_hi:[0,0] neg_lo:[0,1]
	v_pk_mul_f32 v[136:137], v[26:27], v[142:143] op_sel:[0,1] op_sel_hi:[0,0] neg_lo:[0,1]
	v_pk_fma_f32 v[134:135], v[24:25], v[134:135], v[138:139]
	v_pk_fma_f32 v[136:137], v[24:25], v[142:143], v[136:137]
	v_pk_mul_f32 v[138:139], v[130:131], v[134:135] op_sel:[1,1] op_sel_hi:[0,1] neg_hi:[1,0]
	s_nop 0
	v_pk_fma_f32 v[130:131], v[130:131], v[134:135], v[138:139] op_sel_hi:[1,0,1]
	v_pk_mul_f32 v[138:139], v[26:27], v[136:137] op_sel:[0,1] op_sel_hi:[0,0] neg_lo:[0,1]
	v_pk_mul_f32 v[142:143], v[140:141], v[136:137] op_sel:[1,1] op_sel_hi:[0,1] neg_hi:[1,0]
	v_pk_fma_f32 v[138:139], v[24:25], v[136:137], v[138:139]
	v_pk_fma_f32 v[136:137], v[140:141], v[136:137], v[142:143] op_sel_hi:[1,0,1]
	v_pk_mul_f32 v[140:141], v[26:27], v[134:135] op_sel:[0,1] op_sel_hi:[0,0] neg_lo:[0,1]
	v_pk_fma_f32 v[134:135], v[24:25], v[134:135], v[140:141]
	s_nop 0
	v_pk_mul_f32 v[140:141], v[84:85], v[134:135] op_sel:[1,1] op_sel_hi:[0,1] neg_hi:[1,0]
	s_nop 0
	v_pk_fma_f32 v[84:85], v[84:85], v[134:135], v[140:141] op_sel_hi:[1,0,1]
	v_pk_mul_f32 v[140:141], v[26:27], v[138:139] op_sel:[0,1] op_sel_hi:[0,0] neg_lo:[0,1]
	v_pk_mul_f32 v[142:143], v[88:89], v[138:139] op_sel:[1,1] op_sel_hi:[0,1] neg_hi:[1,0]
	v_pk_fma_f32 v[140:141], v[24:25], v[138:139], v[140:141]
	v_pk_fma_f32 v[88:89], v[88:89], v[138:139], v[142:143] op_sel_hi:[1,0,1]
	v_pk_mul_f32 v[138:139], v[26:27], v[134:135] op_sel:[0,1] op_sel_hi:[0,0] neg_lo:[0,1]
	v_pk_fma_f32 v[134:135], v[24:25], v[134:135], v[138:139]
	s_nop 0
	v_pk_mul_f32 v[138:139], v[80:81], v[134:135] op_sel:[1,1] op_sel_hi:[0,1] neg_hi:[1,0]
	s_nop 0
	v_pk_fma_f32 v[80:81], v[80:81], v[134:135], v[138:139] op_sel_hi:[1,0,1]
	v_pk_mul_f32 v[138:139], v[26:27], v[140:141] op_sel:[0,1] op_sel_hi:[0,0] neg_lo:[0,1]
	v_pk_mul_f32 v[142:143], v[82:83], v[140:141] op_sel:[1,1] op_sel_hi:[0,1] neg_hi:[1,0]
	v_pk_fma_f32 v[138:139], v[24:25], v[140:141], v[138:139]
	v_pk_fma_f32 v[82:83], v[82:83], v[140:141], v[142:143] op_sel_hi:[1,0,1]
	v_pk_mul_f32 v[140:141], v[26:27], v[134:135] op_sel:[0,1] op_sel_hi:[0,0] neg_lo:[0,1]
	v_pk_fma_f32 v[134:135], v[24:25], v[134:135], v[140:141]
	s_nop 0
	v_pk_mul_f32 v[140:141], v[70:71], v[134:135] op_sel:[1,1] op_sel_hi:[0,1] neg_hi:[1,0]
	s_nop 0
	v_pk_fma_f32 v[70:71], v[70:71], v[134:135], v[140:141] op_sel_hi:[1,0,1]
	v_pk_mul_f32 v[140:141], v[26:27], v[138:139] op_sel:[0,1] op_sel_hi:[0,0] neg_lo:[0,1]
	v_pk_mul_f32 v[142:143], v[74:75], v[138:139] op_sel:[1,1] op_sel_hi:[0,1] neg_hi:[1,0]
	v_pk_fma_f32 v[140:141], v[24:25], v[138:139], v[140:141]
	v_pk_fma_f32 v[74:75], v[74:75], v[138:139], v[142:143] op_sel_hi:[1,0,1]
	v_pk_mul_f32 v[138:139], v[26:27], v[134:135] op_sel:[0,1] op_sel_hi:[0,0] neg_lo:[0,1]
	v_pk_fma_f32 v[134:135], v[24:25], v[134:135], v[138:139]
	s_nop 0
	v_pk_mul_f32 v[138:139], v[64:65], v[134:135] op_sel:[1,1] op_sel_hi:[0,1] neg_hi:[1,0]
	s_nop 0
	v_pk_fma_f32 v[64:65], v[64:65], v[134:135], v[138:139] op_sel_hi:[1,0,1]
	v_pk_mul_f32 v[138:139], v[26:27], v[140:141] op_sel:[0,1] op_sel_hi:[0,0] neg_lo:[0,1]
	v_pk_mul_f32 v[142:143], v[66:67], v[140:141] op_sel:[1,1] op_sel_hi:[0,1] neg_hi:[1,0]
	v_pk_fma_f32 v[138:139], v[24:25], v[140:141], v[138:139]
	v_pk_fma_f32 v[66:67], v[66:67], v[140:141], v[142:143] op_sel_hi:[1,0,1]
	v_pk_mul_f32 v[140:141], v[26:27], v[134:135] op_sel:[0,1] op_sel_hi:[0,0] neg_lo:[0,1]
	v_pk_fma_f32 v[134:135], v[24:25], v[134:135], v[140:141]
	s_nop 0
	v_pk_mul_f32 v[140:141], v[16:17], v[134:135] op_sel:[1,1] op_sel_hi:[0,1] neg_hi:[1,0]
	s_nop 0
	v_pk_fma_f32 v[16:17], v[16:17], v[134:135], v[140:141] op_sel_hi:[1,0,1]
	v_pk_mul_f32 v[140:141], v[26:27], v[138:139] op_sel:[0,1] op_sel_hi:[0,0] neg_lo:[0,1]
	v_pk_mul_f32 v[142:143], v[18:19], v[138:139] op_sel:[1,1] op_sel_hi:[0,1] neg_hi:[1,0]
	v_pk_fma_f32 v[140:141], v[24:25], v[138:139], v[140:141]
	v_pk_fma_f32 v[18:19], v[18:19], v[138:139], v[142:143] op_sel_hi:[1,0,1]
	v_pk_mul_f32 v[138:139], v[26:27], v[134:135] op_sel:[0,1] op_sel_hi:[0,0] neg_lo:[0,1]
	v_pk_fma_f32 v[134:135], v[24:25], v[134:135], v[138:139]
	s_nop 0
	v_pk_mul_f32 v[138:139], v[12:13], v[134:135] op_sel:[1,1] op_sel_hi:[0,1] neg_hi:[1,0]
	s_nop 0
	v_pk_fma_f32 v[12:13], v[12:13], v[134:135], v[138:139] op_sel_hi:[1,0,1]
	v_pk_mul_f32 v[138:139], v[26:27], v[140:141] op_sel:[0,1] op_sel_hi:[0,0] neg_lo:[0,1]
	v_pk_mul_f32 v[142:143], v[14:15], v[140:141] op_sel:[1,1] op_sel_hi:[0,1] neg_hi:[1,0]
	v_pk_fma_f32 v[138:139], v[24:25], v[140:141], v[138:139]
	v_pk_fma_f32 v[14:15], v[14:15], v[140:141], v[142:143] op_sel_hi:[1,0,1]
	v_pk_mul_f32 v[140:141], v[26:27], v[134:135] op_sel:[0,1] op_sel_hi:[0,0] neg_lo:[0,1]
	v_pk_fma_f32 v[134:135], v[24:25], v[134:135], v[140:141]
	s_nop 0
	v_pk_mul_f32 v[140:141], v[8:9], v[134:135] op_sel:[1,1] op_sel_hi:[0,1] neg_hi:[1,0]
	s_nop 0
	v_pk_fma_f32 v[8:9], v[8:9], v[134:135], v[140:141] op_sel_hi:[1,0,1]
	v_pk_mul_f32 v[140:141], v[26:27], v[138:139] op_sel:[0,1] op_sel_hi:[0,0] neg_lo:[0,1]
	v_pk_mul_f32 v[142:143], v[10:11], v[138:139] op_sel:[1,1] op_sel_hi:[0,1] neg_hi:[1,0]
	v_pk_fma_f32 v[140:141], v[24:25], v[138:139], v[140:141]
	v_pk_fma_f32 v[10:11], v[10:11], v[138:139], v[142:143] op_sel_hi:[1,0,1]
	v_pk_mul_f32 v[138:139], v[26:27], v[134:135] op_sel:[0,1] op_sel_hi:[0,0] neg_lo:[0,1]
	v_pk_fma_f32 v[24:25], v[24:25], v[134:135], v[138:139]
	s_nop 0
	v_pk_mul_f32 v[134:135], v[4:5], v[24:25] op_sel:[1,1] op_sel_hi:[0,1] neg_hi:[1,0]
	s_nop 0
	v_pk_fma_f32 v[4:5], v[4:5], v[24:25], v[134:135] op_sel_hi:[1,0,1]
	v_pk_mul_f32 v[24:25], v[6:7], v[140:141] op_sel:[1,1] op_sel_hi:[0,1] neg_hi:[1,0]
	s_nop 0
	v_pk_fma_f32 v[6:7], v[6:7], v[140:141], v[24:25] op_sel_hi:[1,0,1]
	ds_write_b64 v27, v[2:3]
	ds_write_b64 v96, v[84:85]
	ds_write_b64 v97, v[90:91] offset:256
	ds_write_b64 v98, v[16:17] offset:256
	ds_write_b64 v99, v[72:73] offset:512
	ds_write_b64 v100, v[70:71] offset:512
	ds_write_b64 v101, v[128:129] offset:768
	ds_write_b64 v102, v[8:9] offset:768
	ds_write_b64 v103, v[62:63] offset:1024
	ds_write_b64 v104, v[80:81] offset:1024
	ds_write_b64 v105, v[94:95] offset:1280
	ds_write_b64 v106, v[12:13] offset:1280
	ds_write_b64 v107, v[78:79] offset:1536
	ds_write_b64 v108, v[64:65] offset:1536
	ds_write_b64 v109, v[130:131] offset:1792
	ds_write_b64 v110, v[4:5] offset:1792
	ds_write_b64 v111, v[20:21] offset:2048
	ds_write_b64 v112, v[88:89] offset:2048
	ds_write_b64 v113, v[86:87] offset:2304
	ds_write_b64 v114, v[18:19] offset:2304
	ds_write_b64 v115, v[68:69] offset:2560
	ds_write_b64 v116, v[74:75] offset:2560
	ds_write_b64 v117, v[132:133] offset:2816
	ds_write_b64 v118, v[10:11] offset:2816
	ds_write_b64 v119, v[22:23] offset:3072
	ds_write_b64 v120, v[82:83] offset:3072
	ds_write_b64 v121, v[92:93] offset:3328
	ds_write_b64 v122, v[14:15] offset:3328
	ds_write_b64 v123, v[76:77] offset:3584
	ds_write_b64 v124, v[66:67] offset:3584
	ds_write_b64 v125, v[136:137] offset:3840
	ds_write_b64 v126, v[6:7] offset:3840
	v_mov_b32_e32 v2, v146
	s_waitcnt lgkmcnt(0)
	s_barrier
	s_nop 0
	v_lshlrev_b32_e32 v3, 4, v2
	v_lshrrev_b32_e32 v4, 1, v2
	v_bfe_u32 v2, v2, 1, 4
	v_bitop3_b32 v5, v4, v3, 16 bitop3:0x6c
	v_lshl_add_u32 v5, v5, 3, 16
	v_lshlrev_b32_e32 v2, 3, v2
	v_add_u32_e32 v6, v5, v2
	ds_read_b64 v[12:13], v6
	v_bitop3_b32 v6, v4, 1, 15 bitop3:0x6c
	v_lshlrev_b32_e32 v8, 3, v6
	v_add_u32_e32 v6, v5, v8
	ds_read_b64 v[14:15], v6
	v_bitop3_b32 v6, v4, 2, 15 bitop3:0x6c
	v_lshlrev_b32_e32 v9, 3, v6
	v_add_u32_e32 v6, v5, v9
	ds_read_b64 v[16:17], v6
	v_bitop3_b32 v6, v4, 3, 15 bitop3:0x6c
	v_lshlrev_b32_e32 v10, 3, v6
	v_add_u32_e32 v6, v5, v10
	ds_read_b64 v[18:19], v6
	v_bitop3_b32 v6, v4, 4, 15 bitop3:0x6c
	v_lshlrev_b32_e32 v11, 3, v6
	v_add_u32_e32 v6, v5, v11
	ds_read_b64 v[20:21], v6
	v_bitop3_b32 v6, v4, 5, 15 bitop3:0x6c
	v_lshlrev_b32_e32 v82, 3, v6
	v_add_u32_e32 v6, v5, v82
	ds_read_b64 v[22:23], v6
	v_bitop3_b32 v6, v4, 6, 15 bitop3:0x6c
	v_lshlrev_b32_e32 v83, 3, v6
	v_add_u32_e32 v6, v5, v83
	ds_read_b64 v[24:25], v6
	v_bitop3_b32 v6, v4, 7, 15 bitop3:0x6c
	v_lshlrev_b32_e32 v84, 3, v6
	v_add_u32_e32 v6, v5, v84
	ds_read_b64 v[26:27], v6
	v_bitop3_b32 v6, v4, 8, 15 bitop3:0x6c
	v_lshlrev_b32_e32 v85, 3, v6
	v_add_u32_e32 v6, v5, v85
	ds_read_b64 v[62:63], v6
	v_bitop3_b32 v6, v4, 9, 15 bitop3:0x6c
	v_lshlrev_b32_e32 v86, 3, v6
	v_add_u32_e32 v6, v5, v86
	ds_read_b64 v[64:65], v6
	v_bitop3_b32 v6, v4, 10, 15 bitop3:0x6c
	v_lshlrev_b32_e32 v87, 3, v6
	v_add_u32_e32 v6, v5, v87
	ds_read_b64 v[66:67], v6
	v_bitop3_b32 v6, v4, 11, 15 bitop3:0x6c
	v_lshlrev_b32_e32 v88, 3, v6
	v_add_u32_e32 v6, v5, v88
	ds_read_b64 v[68:69], v6
	v_bitop3_b32 v6, v4, 12, 15 bitop3:0x6c
	v_lshlrev_b32_e32 v89, 3, v6
	v_add_u32_e32 v6, v5, v89
	ds_read_b64 v[70:71], v6
	v_bitop3_b32 v6, v4, 13, 15 bitop3:0x6c
	v_lshlrev_b32_e32 v90, 3, v6
	v_add_u32_e32 v6, v5, v90
	ds_read_b64 v[72:73], v6
	v_bitop3_b32 v6, v4, 14, 15 bitop3:0x6c
	v_lshlrev_b32_e32 v91, 3, v6
	v_add_u32_e32 v6, v5, v91
	v_add_u32_e32 v3, 0x2000, v3
	ds_read_b64 v[74:75], v6
	v_bitop3_b32 v6, v4, 15, v4 bitop3:0xc
	v_bitop3_b32 v3, v3, v4, 16 bitop3:0x78
	v_lshlrev_b32_e32 v106, 3, v6
	v_lshl_add_u32 v107, v3, 3, 16
	v_add_u32_e32 v5, v5, v106
	v_add_u32_e32 v2, v107, v2
	ds_read_b64 v[76:77], v5
	ds_read_b64 v[6:7], v2
	v_add_u32_e32 v2, v107, v8
	ds_read_b64 v[78:79], v2
	v_add_u32_e32 v2, v107, v9
	ds_read_b64 v[8:9], v2
	v_add_u32_e32 v2, v107, v10
	ds_read_b64 v[80:81], v2
	v_add_u32_e32 v2, v107, v11
	ds_read_b64 v[10:11], v2
	v_add_u32_e32 v2, v107, v82
	v_add_u32_e32 v82, v107, v84
	v_add_u32_e32 v84, v107, v85
	ds_read_b64 v[4:5], v2
	ds_read_b64 v[92:93], v84
	v_add_u32_e32 v2, v107, v83
	v_add_u32_e32 v84, v107, v86
	ds_read_b64 v[2:3], v2
	ds_read_b64 v[82:83], v82
	ds_read_b64 v[94:95], v84
	v_add_u32_e32 v84, v107, v87
	ds_read_b64 v[96:97], v84
	v_add_u32_e32 v84, v107, v88
	ds_read_b64 v[98:99], v84
	v_add_u32_e32 v84, v107, v89
	ds_read_b64 v[100:101], v84
	v_add_u32_e32 v84, v107, v90
	ds_read_b64 v[102:103], v84
	v_add_u32_e32 v84, v107, v91
	ds_read_b64 v[104:105], v84
	v_add_u32_e32 v84, v107, v106
	ds_read_b64 v[106:107], v84
	s_waitcnt lgkmcnt(14)
	v_pk_add_f32 v[84:85], v[12:13], v[62:63]
	v_pk_add_f32 v[12:13], v[12:13], v[62:63] neg_lo:[0,1] neg_hi:[0,1]
	v_pk_add_f32 v[62:63], v[14:15], v[64:65]
	v_pk_add_f32 v[14:15], v[14:15], v[64:65] neg_lo:[0,1] neg_hi:[0,1]
	s_nop 0
	v_pk_mul_f32 v[64:65], v[14:15], s[62:63] op_sel:[1,0] op_sel_hi:[0,0] neg_hi:[1,0]
	s_nop 0
	v_pk_fma_f32 v[14:15], v[14:15], s[60:61], v[64:65] op_sel_hi:[1,0,1]
	v_pk_add_f32 v[64:65], v[16:17], v[66:67]
	v_pk_add_f32 v[16:17], v[16:17], v[66:67] neg_lo:[0,1] neg_hi:[0,1]
	s_nop 0
	v_pk_mul_f32 v[66:67], v[16:17], s[70:71] op_sel:[1,0] op_sel_hi:[0,0] neg_hi:[1,0]
	s_nop 0
	v_pk_fma_f32 v[16:17], v[16:17], s[70:71], v[66:67] op_sel_hi:[1,0,1]
	v_pk_add_f32 v[66:67], v[18:19], v[68:69]
	v_pk_add_f32 v[18:19], v[18:19], v[68:69] neg_lo:[0,1] neg_hi:[0,1]
	s_nop 0
	v_pk_mul_f32 v[68:69], v[18:19], s[60:61] op_sel:[1,0] op_sel_hi:[0,0] neg_hi:[1,0]
	s_nop 0
	v_pk_fma_f32 v[18:19], v[18:19], s[62:63], v[68:69] op_sel_hi:[1,0,1]
	v_pk_add_f32 v[68:69], v[20:21], v[70:71]
	v_pk_add_f32 v[20:21], v[20:21], v[70:71] neg_lo:[0,1] neg_hi:[0,1]
	s_nop 0
	v_xor_b32_e32 v71, 0x80000000, v20
	v_mov_b32_e32 v70, v21
	v_pk_add_f32 v[20:21], v[22:23], v[72:73]
	v_pk_add_f32 v[22:23], v[22:23], v[72:73] neg_lo:[0,1] neg_hi:[0,1]
	s_nop 0
	v_pk_mul_f32 v[72:73], v[22:23], s[62:63] op_sel_hi:[1,0]
	v_xor_b32_e32 v87, 0x80000000, v22
	v_mov_b32_e32 v86, v23
	v_pk_fma_f32 v[22:23], v[86:87], s[60:61], v[72:73] op_sel_hi:[1,0,1] neg_lo:[0,0,1] neg_hi:[0,0,1]
	v_pk_add_f32 v[72:73], v[24:25], v[74:75]
	v_pk_add_f32 v[24:25], v[24:25], v[74:75] neg_lo:[0,1] neg_hi:[0,1]
	s_nop 0
	v_pk_mul_f32 v[74:75], v[24:25], s[70:71] op_sel_hi:[1,0]
	v_xor_b32_e32 v87, 0x80000000, v24
	v_mov_b32_e32 v86, v25
	v_pk_fma_f32 v[24:25], v[86:87], s[70:71], v[74:75] op_sel_hi:[1,0,1] neg_lo:[0,0,1] neg_hi:[0,0,1]
	v_pk_add_f32 v[74:75], v[26:27], v[76:77]
	v_pk_add_f32 v[26:27], v[26:27], v[76:77] neg_lo:[0,1] neg_hi:[0,1]
	s_nop 0
	v_pk_mul_f32 v[76:77], v[26:27], s[60:61] op_sel_hi:[1,0]
	v_xor_b32_e32 v87, 0x80000000, v26
	v_mov_b32_e32 v86, v27
	v_pk_fma_f32 v[26:27], v[86:87], s[62:63], v[76:77] op_sel_hi:[1,0,1] neg_lo:[0,0,1] neg_hi:[0,0,1]
	v_pk_add_f32 v[76:77], v[84:85], v[68:69]
	v_pk_add_f32 v[68:69], v[84:85], v[68:69] neg_lo:[0,1] neg_hi:[0,1]
	v_pk_add_f32 v[84:85], v[62:63], v[20:21]
	v_pk_add_f32 v[20:21], v[62:63], v[20:21] neg_lo:[0,1] neg_hi:[0,1]
	s_nop 0
	v_pk_mul_f32 v[62:63], v[20:21], s[70:71] op_sel:[1,0] op_sel_hi:[0,0] neg_hi:[1,0]
	s_nop 0
	v_pk_fma_f32 v[20:21], v[20:21], s[70:71], v[62:63] op_sel_hi:[1,0,1]
	v_pk_add_f32 v[62:63], v[64:65], v[72:73]
	v_pk_add_f32 v[64:65], v[64:65], v[72:73] neg_lo:[0,1] neg_hi:[0,1]
	s_nop 0
	v_xor_b32_e32 v73, 0x80000000, v64
	v_mov_b32_e32 v72, v65
	v_pk_add_f32 v[64:65], v[66:67], v[74:75]
	v_pk_add_f32 v[66:67], v[66:67], v[74:75] neg_lo:[0,1] neg_hi:[0,1]
	s_nop 0
	v_pk_mul_f32 v[74:75], v[66:67], s[70:71] op_sel_hi:[1,0]
	v_xor_b32_e32 v87, 0x80000000, v66
	v_mov_b32_e32 v86, v67
	v_pk_fma_f32 v[66:67], v[86:87], s[70:71], v[74:75] op_sel_hi:[1,0,1] neg_lo:[0,0,1] neg_hi:[0,0,1]
	v_pk_add_f32 v[74:75], v[12:13], v[70:71]
	v_pk_add_f32 v[12:13], v[12:13], v[70:71] neg_lo:[0,1] neg_hi:[0,1]
	v_pk_add_f32 v[70:71], v[14:15], v[22:23]
	v_pk_add_f32 v[14:15], v[14:15], v[22:23] neg_lo:[0,1] neg_hi:[0,1]
	s_nop 0
	v_pk_mul_f32 v[22:23], v[14:15], s[70:71] op_sel:[1,0] op_sel_hi:[0,0] neg_hi:[1,0]
	s_nop 0
	v_pk_fma_f32 v[14:15], v[14:15], s[70:71], v[22:23] op_sel_hi:[1,0,1]
	v_pk_add_f32 v[22:23], v[16:17], v[24:25]
	v_pk_add_f32 v[16:17], v[16:17], v[24:25] neg_lo:[0,1] neg_hi:[0,1]
	s_nop 0
	v_xor_b32_e32 v25, 0x80000000, v16
	v_mov_b32_e32 v24, v17
	v_pk_add_f32 v[16:17], v[18:19], v[26:27]
	v_pk_add_f32 v[18:19], v[18:19], v[26:27] neg_lo:[0,1] neg_hi:[0,1]
	v_pk_add_f32 v[108:109], v[12:13], v[24:25]
	v_pk_mul_f32 v[26:27], v[18:19], s[70:71] op_sel_hi:[1,0]
	s_nop 0
	v_pk_fma_f32 v[18:19], v[18:19], s[70:71], v[26:27] op_sel:[1,0,0] op_sel_hi:[0,0,1] neg_lo:[0,0,1] neg_hi:[1,0,1]
	v_pk_add_f32 v[26:27], v[76:77], v[62:63]
	v_pk_add_f32 v[62:63], v[76:77], v[62:63] neg_lo:[0,1] neg_hi:[0,1]
	v_pk_add_f32 v[76:77], v[84:85], v[64:65]
	v_pk_add_f32 v[64:65], v[84:85], v[64:65] neg_lo:[0,1] neg_hi:[0,1]
	v_pk_add_f32 v[110:111], v[12:13], v[24:25] neg_lo:[0,1] neg_hi:[0,1]
	v_xor_b32_e32 v85, 0x80000000, v64
	v_mov_b32_e32 v84, v65
	v_pk_add_f32 v[64:65], v[68:69], v[72:73]
	v_pk_add_f32 v[68:69], v[68:69], v[72:73] neg_lo:[0,1] neg_hi:[0,1]
	v_pk_add_f32 v[72:73], v[20:21], v[66:67]
	v_pk_add_f32 v[20:21], v[20:21], v[66:67] neg_lo:[0,1] neg_hi:[0,1]
	v_pk_add_f32 v[12:13], v[14:15], v[18:19] neg_lo:[0,1] neg_hi:[0,1]
	v_pk_add_f32 v[112:113], v[14:15], v[18:19]
	v_xor_b32_e32 v115, 0x80000000, v12
	v_mov_b32_e32 v114, v13
	v_pk_add_f32 v[12:13], v[26:27], v[76:77]
	v_pk_add_f32 v[14:15], v[26:27], v[76:77] neg_lo:[0,1] neg_hi:[0,1]
	v_pk_add_f32 v[24:25], v[68:69], v[20:21] op_sel:[0,1] op_sel_hi:[1,0] neg_hi:[0,1]
	v_pk_add_f32 v[26:27], v[68:69], v[20:21] op_sel:[0,1] op_sel_hi:[1,0] neg_lo:[0,1]
	s_waitcnt lgkmcnt(6)
	v_pk_add_f32 v[66:67], v[78:79], v[94:95] neg_lo:[0,1] neg_hi:[0,1]
	v_pk_add_f32 v[86:87], v[74:75], v[22:23]
	v_pk_mul_f32 v[76:77], v[66:67], s[62:63] op_sel:[1,0] op_sel_hi:[0,0] neg_hi:[1,0]
	v_pk_add_f32 v[74:75], v[74:75], v[22:23] neg_lo:[0,1] neg_hi:[0,1]
	v_pk_fma_f32 v[66:67], v[66:67], s[60:61], v[76:77] op_sel_hi:[1,0,1]
	s_waitcnt lgkmcnt(5)
	v_pk_add_f32 v[76:77], v[8:9], v[96:97]
	v_pk_add_f32 v[8:9], v[8:9], v[96:97] neg_lo:[0,1] neg_hi:[0,1]
	v_pk_add_f32 v[20:21], v[64:65], v[72:73]
	v_pk_add_f32 v[22:23], v[64:65], v[72:73] neg_lo:[0,1] neg_hi:[0,1]
	v_pk_add_f32 v[64:65], v[78:79], v[94:95]
	v_pk_mul_f32 v[78:79], v[8:9], s[70:71] op_sel:[1,0] op_sel_hi:[0,0] neg_hi:[1,0]
	v_pk_add_f32 v[88:89], v[70:71], v[16:17]
	v_pk_add_f32 v[16:17], v[70:71], v[16:17] neg_lo:[0,1] neg_hi:[0,1]
	v_pk_fma_f32 v[8:9], v[8:9], s[70:71], v[78:79] op_sel_hi:[1,0,1]
	s_waitcnt lgkmcnt(4)
	v_pk_add_f32 v[78:79], v[80:81], v[98:99]
	v_pk_add_f32 v[80:81], v[80:81], v[98:99] neg_lo:[0,1] neg_hi:[0,1]
	v_xor_b32_e32 v91, 0x80000000, v16
	v_mov_b32_e32 v90, v17
	v_pk_add_f32 v[16:17], v[62:63], v[84:85]
	v_pk_add_f32 v[18:19], v[62:63], v[84:85] neg_lo:[0,1] neg_hi:[0,1]
	v_pk_add_f32 v[62:63], v[6:7], v[92:93]
	v_pk_add_f32 v[6:7], v[6:7], v[92:93] neg_lo:[0,1] neg_hi:[0,1]
	v_pk_mul_f32 v[92:93], v[80:81], s[60:61] op_sel:[1,0] op_sel_hi:[0,0] neg_hi:[1,0]
	v_pk_add_f32 v[68:69], v[86:87], v[88:89]
	v_pk_fma_f32 v[80:81], v[80:81], s[62:63], v[92:93] op_sel_hi:[1,0,1]
	s_waitcnt lgkmcnt(3)
	v_pk_add_f32 v[92:93], v[10:11], v[100:101]
	v_pk_add_f32 v[10:11], v[10:11], v[100:101] neg_lo:[0,1] neg_hi:[0,1]
	v_pk_add_f32 v[70:71], v[86:87], v[88:89] neg_lo:[0,1] neg_hi:[0,1]
	v_xor_b32_e32 v95, 0x80000000, v10
	v_mov_b32_e32 v94, v11
	s_waitcnt lgkmcnt(2)
	v_pk_add_f32 v[10:11], v[4:5], v[102:103]
	v_pk_add_f32 v[4:5], v[4:5], v[102:103] neg_lo:[0,1] neg_hi:[0,1]
	v_pk_add_f32 v[84:85], v[108:109], v[112:113]
	v_pk_mul_f32 v[96:97], v[4:5], s[62:63] op_sel_hi:[1,0]
	s_nop 0
	v_pk_fma_f32 v[4:5], v[4:5], s[60:61], v[96:97] op_sel:[1,0,0] op_sel_hi:[0,0,1] neg_lo:[0,0,1] neg_hi:[1,0,1]
	s_waitcnt lgkmcnt(1)
	v_pk_add_f32 v[96:97], v[2:3], v[104:105]
	v_pk_add_f32 v[2:3], v[2:3], v[104:105] neg_lo:[0,1] neg_hi:[0,1]
	v_pk_add_f32 v[86:87], v[108:109], v[112:113] neg_lo:[0,1] neg_hi:[0,1]
	v_pk_mul_f32 v[98:99], v[2:3], s[70:71] op_sel_hi:[1,0]
	s_nop 0
	v_pk_fma_f32 v[2:3], v[2:3], s[70:71], v[98:99] op_sel:[1,0,0] op_sel_hi:[0,0,1] neg_lo:[0,0,1] neg_hi:[1,0,1]
	s_waitcnt lgkmcnt(0)
	v_pk_add_f32 v[98:99], v[82:83], v[106:107]
	v_pk_add_f32 v[82:83], v[82:83], v[106:107] neg_lo:[0,1] neg_hi:[0,1]
	v_pk_add_f32 v[72:73], v[74:75], v[90:91]
	v_pk_mul_f32 v[100:101], v[82:83], s[60:61] op_sel_hi:[1,0]
	v_xor_b32_e32 v103, 0x80000000, v82
	v_mov_b32_e32 v102, v83
	v_pk_fma_f32 v[82:83], v[102:103], s[62:63], v[100:101] op_sel_hi:[1,0,1] neg_lo:[0,0,1] neg_hi:[0,0,1]
	v_pk_add_f32 v[100:101], v[62:63], v[92:93]
	v_pk_add_f32 v[62:63], v[62:63], v[92:93] neg_lo:[0,1] neg_hi:[0,1]
	v_pk_add_f32 v[92:93], v[64:65], v[10:11]
	v_pk_add_f32 v[10:11], v[64:65], v[10:11] neg_lo:[0,1] neg_hi:[0,1]
	v_pk_add_f32 v[74:75], v[74:75], v[90:91] neg_lo:[0,1] neg_hi:[0,1]
	v_pk_mul_f32 v[64:65], v[10:11], s[70:71] op_sel:[1,0] op_sel_hi:[0,0] neg_hi:[1,0]
	v_pk_add_f32 v[88:89], v[110:111], v[114:115]
	v_pk_fma_f32 v[10:11], v[10:11], s[70:71], v[64:65] op_sel_hi:[1,0,1]
	v_pk_add_f32 v[64:65], v[76:77], v[96:97]
	v_pk_add_f32 v[76:77], v[76:77], v[96:97] neg_lo:[0,1] neg_hi:[0,1]
	v_pk_add_f32 v[90:91], v[110:111], v[114:115] neg_lo:[0,1] neg_hi:[0,1]
	v_xor_b32_e32 v97, 0x80000000, v76
	v_mov_b32_e32 v96, v77
	v_pk_add_f32 v[76:77], v[78:79], v[98:99]
	v_pk_add_f32 v[78:79], v[78:79], v[98:99] neg_lo:[0,1] neg_hi:[0,1]
	s_nop 0
	v_pk_mul_f32 v[98:99], v[78:79], s[70:71] op_sel_hi:[1,0]
	v_xor_b32_e32 v103, 0x80000000, v78
	v_mov_b32_e32 v102, v79
	v_pk_fma_f32 v[78:79], v[102:103], s[70:71], v[98:99] op_sel_hi:[1,0,1] neg_lo:[0,0,1] neg_hi:[0,0,1]
	v_pk_add_f32 v[98:99], v[6:7], v[94:95]
	v_pk_add_f32 v[6:7], v[6:7], v[94:95] neg_lo:[0,1] neg_hi:[0,1]
	v_pk_add_f32 v[94:95], v[66:67], v[4:5]
	v_pk_add_f32 v[4:5], v[66:67], v[4:5] neg_lo:[0,1] neg_hi:[0,1]
	s_nop 0
	v_pk_mul_f32 v[66:67], v[4:5], s[70:71] op_sel:[1,0] op_sel_hi:[0,0] neg_hi:[1,0]
	s_nop 0
	v_pk_fma_f32 v[4:5], v[4:5], s[70:71], v[66:67] op_sel_hi:[1,0,1]
	v_pk_add_f32 v[66:67], v[8:9], v[2:3]
	v_pk_add_f32 v[2:3], v[8:9], v[2:3] neg_lo:[0,1] neg_hi:[0,1]
	v_pk_add_f32 v[106:107], v[98:99], v[66:67] neg_lo:[0,1] neg_hi:[0,1]
	v_xor_b32_e32 v9, 0x80000000, v2
	v_mov_b32_e32 v8, v3
	v_pk_add_f32 v[2:3], v[80:81], v[82:83]
	v_pk_add_f32 v[80:81], v[80:81], v[82:83] neg_lo:[0,1] neg_hi:[0,1]
	v_pk_add_f32 v[108:109], v[94:95], v[2:3]
	v_pk_mul_f32 v[82:83], v[80:81], s[70:71] op_sel_hi:[1,0]
	s_nop 0
	v_pk_fma_f32 v[80:81], v[80:81], s[70:71], v[82:83] op_sel:[1,0,0] op_sel_hi:[0,0,1] neg_lo:[0,0,1] neg_hi:[1,0,1]
	v_pk_add_f32 v[82:83], v[100:101], v[64:65]
	v_pk_add_f32 v[64:65], v[100:101], v[64:65] neg_lo:[0,1] neg_hi:[0,1]
	v_pk_add_f32 v[100:101], v[92:93], v[76:77]
	v_pk_add_f32 v[76:77], v[92:93], v[76:77] neg_lo:[0,1] neg_hi:[0,1]
	v_pk_add_f32 v[102:103], v[10:11], v[78:79]
	v_xor_b32_e32 v93, 0x80000000, v76
	v_mov_b32_e32 v92, v77
	v_pk_add_f32 v[76:77], v[62:63], v[96:97]
	v_pk_add_f32 v[10:11], v[10:11], v[78:79] neg_lo:[0,1] neg_hi:[0,1]
	v_pk_add_f32 v[2:3], v[94:95], v[2:3] neg_lo:[0,1] neg_hi:[0,1]
	v_pk_add_f32 v[62:63], v[62:63], v[96:97] neg_lo:[0,1] neg_hi:[0,1]
	v_xor_b32_e32 v105, 0x80000000, v10
	v_mov_b32_e32 v104, v11
	v_pk_add_f32 v[10:11], v[98:99], v[66:67]
	v_xor_b32_e32 v111, 0x80000000, v2
	v_mov_b32_e32 v110, v3
	v_pk_add_f32 v[112:113], v[6:7], v[8:9]
	v_pk_add_f32 v[114:115], v[6:7], v[8:9] neg_lo:[0,1] neg_hi:[0,1]
	v_pk_add_f32 v[6:7], v[4:5], v[80:81]
	v_pk_add_f32 v[2:3], v[4:5], v[80:81] neg_lo:[0,1] neg_hi:[0,1]
	v_pk_add_f32 v[98:99], v[82:83], v[100:101]
	v_pk_add_f32 v[96:97], v[82:83], v[100:101] neg_lo:[0,1] neg_hi:[0,1]
	v_pk_add_f32 v[82:83], v[76:77], v[102:103]
	v_pk_add_f32 v[80:81], v[76:77], v[102:103] neg_lo:[0,1] neg_hi:[0,1]
	s_waitcnt vmcnt(7)
	v_mov_b64 v[100:101], v[164:165]
	v_mov_b64 v[102:103], v[166:167]
	v_pk_add_f32 v[78:79], v[62:63], v[104:105]
	v_pk_add_f32 v[76:77], v[62:63], v[104:105] neg_lo:[0,1] neg_hi:[0,1]
	v_xor_b32_e32 v5, 0x80000000, v2
	v_mov_b32_e32 v4, v3
	v_pk_add_f32 v[62:63], v[106:107], v[110:111]
	v_pk_add_f32 v[2:3], v[106:107], v[110:111] neg_lo:[0,1] neg_hi:[0,1]
	v_pk_add_f32 v[94:95], v[64:65], v[92:93]
	v_pk_add_f32 v[92:93], v[64:65], v[92:93] neg_lo:[0,1] neg_hi:[0,1]
	v_pk_add_f32 v[66:67], v[10:11], v[108:109]
	v_pk_add_f32 v[64:65], v[10:11], v[108:109] neg_lo:[0,1] neg_hi:[0,1]
	v_pk_add_f32 v[10:11], v[112:113], v[6:7]
	v_pk_add_f32 v[8:9], v[112:113], v[6:7] neg_lo:[0,1] neg_hi:[0,1]
	v_pk_add_f32 v[6:7], v[114:115], v[4:5]
	v_pk_add_f32 v[4:5], v[114:115], v[4:5] neg_lo:[0,1] neg_hi:[0,1]
	v_cvt_f32_f16_e32 v104, v100
	v_cvt_f32_f16_sdwa v100, v100 dst_sel:DWORD dst_unused:UNUSED_PAD src0_sel:WORD_1
	v_mul_f32_e32 v104, 0x38800000, v104
	v_mul_f32_e32 v100, 0x38800000, v100
	s_nop 0
	v_pk_mul_f32 v[106:107], v[12:13], v[100:101] op_sel:[1,0] op_sel_hi:[0,0] neg_lo:[1,0]
	v_cvt_f32_f16_e32 v100, v101
	v_cvt_f32_f16_sdwa v101, v101 dst_sel:DWORD dst_unused:UNUSED_PAD src0_sel:WORD_1
	v_pk_fma_f32 v[12:13], v[12:13], v[104:105], v[106:107] op_sel_hi:[1,0,1]
	v_xor_b32_e32 v106, 0x80000000, v15
	v_mov_b32_e32 v107, v14
	v_mul_f32_e32 v104, 0x38800000, v101
	v_mul_f32_e32 v100, 0x38800000, v100
	v_pk_mul_f32 v[104:105], v[106:107], v[104:105] op_sel_hi:[1,0]
	v_xor_b32_e32 v106, 0x80000000, v21
	v_pk_fma_f32 v[14:15], v[14:15], v[100:101], v[104:105] op_sel_hi:[1,0,1]
	v_cvt_f32_f16_sdwa v101, v102 dst_sel:DWORD dst_unused:UNUSED_PAD src0_sel:WORD_1
	v_cvt_f32_f16_e32 v100, v102
	s_nop 0
	s_nop 0
	v_mul_f32_e32 v102, 0x38800000, v101
	v_mul_f32_e32 v100, 0x38800000, v100
	v_pk_mul_f32 v[104:105], v[16:17], v[102:103] op_sel:[1,0] op_sel_hi:[0,0] neg_lo:[1,0]
	v_mov_b32_e32 v107, v20
	v_pk_fma_f32 v[16:17], v[16:17], v[100:101], v[104:105] op_sel_hi:[1,0,1]
	v_cvt_f32_f16_sdwa v101, v103 dst_sel:DWORD dst_unused:UNUSED_PAD src0_sel:WORD_1
	v_cvt_f32_f16_e32 v100, v103
	v_xor_b32_e32 v104, 0x80000000, v19
	v_mov_b32_e32 v105, v18
	v_mul_f32_e32 v102, 0x38800000, v101
	v_mul_f32_e32 v100, 0x38800000, v100
	v_pk_mul_f32 v[102:103], v[104:105], v[102:103] op_sel_hi:[1,0]
	s_nop 0
	v_pk_fma_f32 v[18:19], v[18:19], v[100:101], v[102:103] op_sel_hi:[1,0,1]
	s_waitcnt vmcnt(6)
	v_mov_b64 v[100:101], v[168:169]
	v_mov_b64 v[102:103], v[170:171]
	v_cvt_f32_f16_e32 v104, v100
	v_cvt_f32_f16_sdwa v100, v100 dst_sel:DWORD dst_unused:UNUSED_PAD src0_sel:WORD_1
	v_mul_f32_e32 v104, 0x38800000, v104
	v_mul_f32_e32 v100, 0x38800000, v100
	v_pk_mul_f32 v[106:107], v[106:107], v[100:101] op_sel_hi:[1,0]
	v_cvt_f32_f16_e32 v100, v101
	v_cvt_f32_f16_sdwa v101, v101 dst_sel:DWORD dst_unused:UNUSED_PAD src0_sel:WORD_1
	v_pk_fma_f32 v[20:21], v[20:21], v[104:105], v[106:107] op_sel_hi:[1,0,1]
	v_xor_b32_e32 v106, 0x80000000, v23
	v_mov_b32_e32 v107, v22
	v_mul_f32_e32 v104, 0x38800000, v101
	v_mul_f32_e32 v100, 0x38800000, v100
	v_pk_mul_f32 v[104:105], v[106:107], v[104:105] op_sel_hi:[1,0]
	v_xor_b32_e32 v106, 0x80000000, v69
	v_pk_fma_f32 v[22:23], v[22:23], v[100:101], v[104:105] op_sel_hi:[1,0,1]
	v_cvt_f32_f16_sdwa v101, v102 dst_sel:DWORD dst_unused:UNUSED_PAD src0_sel:WORD_1
	v_cvt_f32_f16_e32 v100, v102
	s_nop 0
	s_nop 0
	v_mul_f32_e32 v102, 0x38800000, v101
	v_mul_f32_e32 v100, 0x38800000, v100
	v_pk_mul_f32 v[104:105], v[24:25], v[102:103] op_sel:[1,0] op_sel_hi:[0,0] neg_lo:[1,0]
	v_mov_b32_e32 v107, v68
	v_pk_fma_f32 v[24:25], v[24:25], v[100:101], v[104:105] op_sel_hi:[1,0,1]
	v_cvt_f32_f16_sdwa v101, v103 dst_sel:DWORD dst_unused:UNUSED_PAD src0_sel:WORD_1
	v_cvt_f32_f16_e32 v100, v103
	v_xor_b32_e32 v104, 0x80000000, v27
	v_mov_b32_e32 v105, v26
	v_mul_f32_e32 v102, 0x38800000, v101
	v_mul_f32_e32 v100, 0x38800000, v100
	v_pk_mul_f32 v[102:103], v[104:105], v[102:103] op_sel_hi:[1,0]
	s_nop 0
	v_pk_fma_f32 v[26:27], v[26:27], v[100:101], v[102:103] op_sel_hi:[1,0,1]
	s_waitcnt vmcnt(5)
	v_mov_b64 v[100:101], v[172:173]
	v_mov_b64 v[102:103], v[174:175]
	v_cvt_f32_f16_e32 v104, v100
	v_cvt_f32_f16_sdwa v100, v100 dst_sel:DWORD dst_unused:UNUSED_PAD src0_sel:WORD_1
	v_mul_f32_e32 v104, 0x38800000, v104
	v_mul_f32_e32 v100, 0x38800000, v100
	v_pk_mul_f32 v[106:107], v[106:107], v[100:101] op_sel_hi:[1,0]
	v_cvt_f32_f16_e32 v100, v101
	v_cvt_f32_f16_sdwa v101, v101 dst_sel:DWORD dst_unused:UNUSED_PAD src0_sel:WORD_1
	v_pk_fma_f32 v[68:69], v[68:69], v[104:105], v[106:107] op_sel_hi:[1,0,1]
	v_xor_b32_e32 v106, 0x80000000, v71
	v_mov_b32_e32 v107, v70
	v_mul_f32_e32 v104, 0x38800000, v101
	v_mul_f32_e32 v100, 0x38800000, v100
	v_pk_mul_f32 v[104:105], v[106:107], v[104:105] op_sel_hi:[1,0]
	v_xor_b32_e32 v106, 0x80000000, v85
	v_pk_fma_f32 v[70:71], v[70:71], v[100:101], v[104:105] op_sel_hi:[1,0,1]
	v_cvt_f32_f16_sdwa v101, v102 dst_sel:DWORD dst_unused:UNUSED_PAD src0_sel:WORD_1
	v_cvt_f32_f16_e32 v100, v102
	s_nop 0
	s_nop 0
	v_mul_f32_e32 v102, 0x38800000, v101
	v_mul_f32_e32 v100, 0x38800000, v100
	v_pk_mul_f32 v[104:105], v[72:73], v[102:103] op_sel:[1,0] op_sel_hi:[0,0] neg_lo:[1,0]
	v_mov_b32_e32 v107, v84
	v_pk_fma_f32 v[72:73], v[72:73], v[100:101], v[104:105] op_sel_hi:[1,0,1]
	v_cvt_f32_f16_sdwa v101, v103 dst_sel:DWORD dst_unused:UNUSED_PAD src0_sel:WORD_1
	v_cvt_f32_f16_e32 v100, v103
	v_xor_b32_e32 v104, 0x80000000, v75
	v_mov_b32_e32 v105, v74
	v_mul_f32_e32 v102, 0x38800000, v101
	v_mul_f32_e32 v100, 0x38800000, v100
	v_pk_mul_f32 v[102:103], v[104:105], v[102:103] op_sel_hi:[1,0]
	s_nop 0
	v_pk_fma_f32 v[74:75], v[74:75], v[100:101], v[102:103] op_sel_hi:[1,0,1]
	s_waitcnt vmcnt(4)
	v_mov_b64 v[100:101], v[176:177]
	v_mov_b64 v[102:103], v[178:179]
	v_cvt_f32_f16_e32 v104, v100
	v_cvt_f32_f16_sdwa v100, v100 dst_sel:DWORD dst_unused:UNUSED_PAD src0_sel:WORD_1
	v_mul_f32_e32 v104, 0x38800000, v104
	v_mul_f32_e32 v100, 0x38800000, v100
	v_pk_mul_f32 v[106:107], v[106:107], v[100:101] op_sel_hi:[1,0]
	v_cvt_f32_f16_e32 v100, v101
	v_cvt_f32_f16_sdwa v101, v101 dst_sel:DWORD dst_unused:UNUSED_PAD src0_sel:WORD_1
	v_pk_fma_f32 v[84:85], v[84:85], v[104:105], v[106:107] op_sel_hi:[1,0,1]
	v_xor_b32_e32 v106, 0x80000000, v87
	v_mov_b32_e32 v107, v86
	v_mul_f32_e32 v104, 0x38800000, v101
	v_mul_f32_e32 v100, 0x38800000, v100
	v_pk_mul_f32 v[104:105], v[106:107], v[104:105] op_sel_hi:[1,0]
	v_xor_b32_e32 v106, 0x80000000, v99
	v_pk_fma_f32 v[86:87], v[86:87], v[100:101], v[104:105] op_sel_hi:[1,0,1]
	v_cvt_f32_f16_sdwa v101, v102 dst_sel:DWORD dst_unused:UNUSED_PAD src0_sel:WORD_1
	v_cvt_f32_f16_e32 v100, v102
	s_nop 0
	s_nop 0
	v_mul_f32_e32 v102, 0x38800000, v101
	v_mul_f32_e32 v100, 0x38800000, v100
	v_pk_mul_f32 v[104:105], v[88:89], v[102:103] op_sel:[1,0] op_sel_hi:[0,0] neg_lo:[1,0]
	v_mov_b32_e32 v107, v98
	v_pk_fma_f32 v[88:89], v[88:89], v[100:101], v[104:105] op_sel_hi:[1,0,1]
	v_cvt_f32_f16_sdwa v101, v103 dst_sel:DWORD dst_unused:UNUSED_PAD src0_sel:WORD_1
	v_cvt_f32_f16_e32 v100, v103
	v_xor_b32_e32 v104, 0x80000000, v91
	v_mov_b32_e32 v105, v90
	v_mul_f32_e32 v102, 0x38800000, v101
	v_mul_f32_e32 v100, 0x38800000, v100
	v_pk_mul_f32 v[102:103], v[104:105], v[102:103] op_sel_hi:[1,0]
	s_nop 0
	v_pk_fma_f32 v[90:91], v[90:91], v[100:101], v[102:103] op_sel_hi:[1,0,1]
	s_waitcnt vmcnt(3)
	v_mov_b64 v[100:101], v[180:181]
	v_mov_b64 v[102:103], v[182:183]
	v_cvt_f32_f16_e32 v104, v100
	v_cvt_f32_f16_sdwa v100, v100 dst_sel:DWORD dst_unused:UNUSED_PAD src0_sel:WORD_1
	v_mul_f32_e32 v104, 0x38800000, v104
	v_mul_f32_e32 v100, 0x38800000, v100
	v_pk_mul_f32 v[106:107], v[106:107], v[100:101] op_sel_hi:[1,0]
	v_cvt_f32_f16_e32 v100, v101
	v_cvt_f32_f16_sdwa v101, v101 dst_sel:DWORD dst_unused:UNUSED_PAD src0_sel:WORD_1
	v_pk_fma_f32 v[98:99], v[98:99], v[104:105], v[106:107] op_sel_hi:[1,0,1]
	v_xor_b32_e32 v106, 0x80000000, v97
	v_mov_b32_e32 v107, v96
	v_mul_f32_e32 v104, 0x38800000, v101
	v_mul_f32_e32 v100, 0x38800000, v100
	v_pk_mul_f32 v[104:105], v[106:107], v[104:105] op_sel_hi:[1,0]
	v_xor_b32_e32 v106, 0x80000000, v83
	v_pk_fma_f32 v[96:97], v[96:97], v[100:101], v[104:105] op_sel_hi:[1,0,1]
	v_cvt_f32_f16_sdwa v101, v102 dst_sel:DWORD dst_unused:UNUSED_PAD src0_sel:WORD_1
	v_cvt_f32_f16_e32 v100, v102
	s_nop 0
	s_nop 0
	v_mul_f32_e32 v102, 0x38800000, v101
	v_mul_f32_e32 v100, 0x38800000, v100
	v_pk_mul_f32 v[104:105], v[94:95], v[102:103] op_sel:[1,0] op_sel_hi:[0,0] neg_lo:[1,0]
	v_mov_b32_e32 v107, v82
	v_pk_fma_f32 v[94:95], v[94:95], v[100:101], v[104:105] op_sel_hi:[1,0,1]
	v_cvt_f32_f16_sdwa v101, v103 dst_sel:DWORD dst_unused:UNUSED_PAD src0_sel:WORD_1
	v_cvt_f32_f16_e32 v100, v103
	v_xor_b32_e32 v104, 0x80000000, v93
	v_mov_b32_e32 v105, v92
	v_mul_f32_e32 v102, 0x38800000, v101
	v_mul_f32_e32 v100, 0x38800000, v100
	v_pk_mul_f32 v[102:103], v[104:105], v[102:103] op_sel_hi:[1,0]
	s_nop 0
	v_pk_fma_f32 v[92:93], v[92:93], v[100:101], v[102:103] op_sel_hi:[1,0,1]
	s_waitcnt vmcnt(2)
	v_mov_b64 v[100:101], v[184:185]
	v_mov_b64 v[102:103], v[186:187]
	v_cvt_f32_f16_e32 v104, v100
	v_cvt_f32_f16_sdwa v100, v100 dst_sel:DWORD dst_unused:UNUSED_PAD src0_sel:WORD_1
	v_mul_f32_e32 v104, 0x38800000, v104
	v_mul_f32_e32 v100, 0x38800000, v100
	v_pk_mul_f32 v[106:107], v[106:107], v[100:101] op_sel_hi:[1,0]
	v_cvt_f32_f16_e32 v100, v101
	v_cvt_f32_f16_sdwa v101, v101 dst_sel:DWORD dst_unused:UNUSED_PAD src0_sel:WORD_1
	v_pk_fma_f32 v[82:83], v[82:83], v[104:105], v[106:107] op_sel_hi:[1,0,1]
	v_xor_b32_e32 v106, 0x80000000, v81
	v_mov_b32_e32 v107, v80
	v_mul_f32_e32 v104, 0x38800000, v101
	v_mul_f32_e32 v100, 0x38800000, v100
	v_pk_mul_f32 v[104:105], v[106:107], v[104:105] op_sel_hi:[1,0]
	v_xor_b32_e32 v106, 0x80000000, v67
	v_pk_fma_f32 v[80:81], v[80:81], v[100:101], v[104:105] op_sel_hi:[1,0,1]
	v_cvt_f32_f16_sdwa v101, v102 dst_sel:DWORD dst_unused:UNUSED_PAD src0_sel:WORD_1
	v_cvt_f32_f16_e32 v100, v102
	s_nop 0
	s_nop 0
	v_mul_f32_e32 v102, 0x38800000, v101
	v_mul_f32_e32 v100, 0x38800000, v100
	v_pk_mul_f32 v[104:105], v[78:79], v[102:103] op_sel:[1,0] op_sel_hi:[0,0] neg_lo:[1,0]
	v_mov_b32_e32 v107, v66
	v_pk_fma_f32 v[78:79], v[78:79], v[100:101], v[104:105] op_sel_hi:[1,0,1]
	v_cvt_f32_f16_sdwa v101, v103 dst_sel:DWORD dst_unused:UNUSED_PAD src0_sel:WORD_1
	v_cvt_f32_f16_e32 v100, v103
	v_xor_b32_e32 v104, 0x80000000, v77
	v_mov_b32_e32 v105, v76
	v_mul_f32_e32 v102, 0x38800000, v101
	v_mul_f32_e32 v100, 0x38800000, v100
	v_pk_mul_f32 v[102:103], v[104:105], v[102:103] op_sel_hi:[1,0]
	s_nop 0
	v_pk_fma_f32 v[76:77], v[76:77], v[100:101], v[102:103] op_sel_hi:[1,0,1]
	s_waitcnt vmcnt(1)
	v_mov_b64 v[100:101], v[188:189]
	v_mov_b64 v[102:103], v[190:191]
	v_cvt_f32_f16_e32 v104, v100
	v_cvt_f32_f16_sdwa v100, v100 dst_sel:DWORD dst_unused:UNUSED_PAD src0_sel:WORD_1
	v_mul_f32_e32 v104, 0x38800000, v104
	v_mul_f32_e32 v100, 0x38800000, v100
	v_pk_mul_f32 v[106:107], v[106:107], v[100:101] op_sel_hi:[1,0]
	v_cvt_f32_f16_e32 v100, v101
	v_cvt_f32_f16_sdwa v101, v101 dst_sel:DWORD dst_unused:UNUSED_PAD src0_sel:WORD_1
	v_pk_fma_f32 v[66:67], v[66:67], v[104:105], v[106:107] op_sel_hi:[1,0,1]
	v_xor_b32_e32 v106, 0x80000000, v65
	v_mov_b32_e32 v107, v64
	v_mul_f32_e32 v104, 0x38800000, v101
	v_mul_f32_e32 v100, 0x38800000, v100
	v_pk_mul_f32 v[104:105], v[106:107], v[104:105] op_sel_hi:[1,0]
	s_nop 0
	v_pk_fma_f32 v[64:65], v[64:65], v[100:101], v[104:105] op_sel_hi:[1,0,1]
	v_cvt_f32_f16_sdwa v101, v102 dst_sel:DWORD dst_unused:UNUSED_PAD src0_sel:WORD_1
	v_cvt_f32_f16_e32 v100, v102
	s_nop 0
	s_nop 0
	v_mul_f32_e32 v102, 0x38800000, v101
	v_mul_f32_e32 v100, 0x38800000, v100
	v_pk_mul_f32 v[104:105], v[62:63], v[102:103] op_sel:[1,0] op_sel_hi:[0,0] neg_lo:[1,0]
	s_nop 0
	v_pk_fma_f32 v[62:63], v[62:63], v[100:101], v[104:105] op_sel_hi:[1,0,1]
	v_cvt_f32_f16_sdwa v101, v103 dst_sel:DWORD dst_unused:UNUSED_PAD src0_sel:WORD_1
	v_cvt_f32_f16_e32 v100, v103
	v_xor_b32_e32 v104, 0x80000000, v3
	v_mov_b32_e32 v105, v2
	v_mul_f32_e32 v102, 0x38800000, v101
	v_mul_f32_e32 v100, 0x38800000, v100
	v_pk_mul_f32 v[102:103], v[104:105], v[102:103] op_sel_hi:[1,0]
	v_xor_b32_e32 v104, 0x80000000, v11
	v_pk_fma_f32 v[100:101], v[2:3], v[100:101], v[102:103] op_sel_hi:[1,0,1]
	s_waitcnt vmcnt(0)
	v_mov_b64 v[0:1], v[192:193]
	v_mov_b64 v[2:3], v[194:195]
	v_mov_b32_e32 v105, v10
	v_cvt_f32_f16_e32 v102, v0
	v_cvt_f32_f16_sdwa v0, v0 dst_sel:DWORD dst_unused:UNUSED_PAD src0_sel:WORD_1
	v_mul_f32_e32 v102, 0x38800000, v102
	v_mul_f32_e32 v0, 0x38800000, v0
	v_pk_mul_f32 v[104:105], v[104:105], v[0:1] op_sel_hi:[1,0]
	v_cvt_f32_f16_e32 v0, v1
	v_cvt_f32_f16_sdwa v1, v1 dst_sel:DWORD dst_unused:UNUSED_PAD src0_sel:WORD_1
	v_pk_fma_f32 v[10:11], v[10:11], v[102:103], v[104:105] op_sel_hi:[1,0,1]
	v_xor_b32_e32 v104, 0x80000000, v9
	v_mov_b32_e32 v105, v8
	v_mul_f32_e32 v102, 0x38800000, v1
	v_mul_f32_e32 v0, 0x38800000, v0
	v_pk_mul_f32 v[102:103], v[104:105], v[102:103] op_sel_hi:[1,0]
	s_nop 0
	v_pk_fma_f32 v[0:1], v[8:9], v[0:1], v[102:103] op_sel_hi:[1,0,1]
	v_cvt_f32_f16_e32 v8, v2
	v_cvt_f32_f16_sdwa v2, v2 dst_sel:DWORD dst_unused:UNUSED_PAD src0_sel:WORD_1
	s_nop 0
	s_nop 0
	v_mul_f32_e32 v8, 0x38800000, v8
	v_mul_f32_e32 v2, 0x38800000, v2
	s_nop 0
	v_pk_mul_f32 v[102:103], v[6:7], v[2:3] op_sel:[1,0] op_sel_hi:[0,0] neg_lo:[1,0]
	v_cvt_f32_f16_e32 v2, v3
	v_cvt_f32_f16_sdwa v3, v3 dst_sel:DWORD dst_unused:UNUSED_PAD src0_sel:WORD_1
	v_pk_fma_f32 v[6:7], v[6:7], v[8:9], v[102:103] op_sel_hi:[1,0,1]
	v_xor_b32_e32 v102, 0x80000000, v5
	v_mov_b32_e32 v103, v4
	v_mul_f32_e32 v8, 0x38800000, v3
	v_mul_f32_e32 v2, 0x38800000, v2
	v_pk_mul_f32 v[8:9], v[102:103], v[8:9] op_sel_hi:[1,0]
	v_mov_b32_e32 v102, v146
	v_pk_fma_f32 v[2:3], v[4:5], v[2:3], v[8:9] op_sel_hi:[1,0,1]
	v_pk_add_f32 v[4:5], v[12:13], v[14:15]
	v_pk_add_f32 v[8:9], v[12:13], v[14:15] neg_lo:[0,1] neg_hi:[0,1]
	v_pk_add_f32 v[12:13], v[16:17], v[18:19]
	v_pk_add_f32 v[14:15], v[16:17], v[18:19] neg_lo:[0,1] neg_hi:[0,1]
	v_pk_add_f32 v[16:17], v[20:21], v[22:23]
	v_pk_add_f32 v[18:19], v[20:21], v[22:23] neg_lo:[0,1] neg_hi:[0,1]
	v_pk_add_f32 v[20:21], v[24:25], v[26:27]
	v_pk_add_f32 v[22:23], v[24:25], v[26:27] neg_lo:[0,1] neg_hi:[0,1]
	v_pk_add_f32 v[24:25], v[68:69], v[70:71]
	v_pk_add_f32 v[26:27], v[68:69], v[70:71] neg_lo:[0,1] neg_hi:[0,1]
	v_pk_add_f32 v[68:69], v[72:73], v[74:75]
	v_pk_add_f32 v[70:71], v[72:73], v[74:75] neg_lo:[0,1] neg_hi:[0,1]
	v_pk_add_f32 v[72:73], v[84:85], v[86:87]
	v_pk_add_f32 v[74:75], v[84:85], v[86:87] neg_lo:[0,1] neg_hi:[0,1]
	v_pk_add_f32 v[84:85], v[88:89], v[90:91]
	v_pk_add_f32 v[86:87], v[88:89], v[90:91] neg_lo:[0,1] neg_hi:[0,1]
	v_pk_add_f32 v[88:89], v[4:5], v[12:13]
	v_pk_add_f32 v[4:5], v[4:5], v[12:13] neg_lo:[0,1] neg_hi:[0,1]
	v_xor_b32_e32 v12, 0x80000000, v15
	v_mov_b32_e32 v13, v14
	v_pk_add_f32 v[14:15], v[8:9], v[12:13]
	v_pk_add_f32 v[8:9], v[8:9], v[12:13] neg_lo:[0,1] neg_hi:[0,1]
	v_pk_add_f32 v[12:13], v[16:17], v[20:21]
	v_pk_add_f32 v[16:17], v[16:17], v[20:21] neg_lo:[0,1] neg_hi:[0,1]
	v_xor_b32_e32 v20, 0x80000000, v23
	v_mov_b32_e32 v21, v22
	v_pk_add_f32 v[22:23], v[18:19], v[20:21]
	v_pk_add_f32 v[18:19], v[18:19], v[20:21] neg_lo:[0,1] neg_hi:[0,1]
	v_pk_add_f32 v[20:21], v[24:25], v[68:69]
	v_pk_add_f32 v[24:25], v[24:25], v[68:69] neg_lo:[0,1] neg_hi:[0,1]
	v_xor_b32_e32 v68, 0x80000000, v71
	v_mov_b32_e32 v69, v70
	v_pk_add_f32 v[70:71], v[26:27], v[68:69]
	v_pk_add_f32 v[26:27], v[26:27], v[68:69] neg_lo:[0,1] neg_hi:[0,1]
	v_pk_add_f32 v[68:69], v[72:73], v[84:85]
	v_pk_add_f32 v[72:73], v[72:73], v[84:85] neg_lo:[0,1] neg_hi:[0,1]
	v_xor_b32_e32 v84, 0x80000000, v87
	v_mov_b32_e32 v85, v86
	v_pk_add_f32 v[86:87], v[74:75], v[84:85]
	v_pk_add_f32 v[74:75], v[74:75], v[84:85] neg_lo:[0,1] neg_hi:[0,1]
	v_pk_add_f32 v[84:85], v[88:89], v[12:13]
	v_pk_add_f32 v[12:13], v[88:89], v[12:13] neg_lo:[0,1] neg_hi:[0,1]
	v_pk_mul_f32 v[88:89], v[22:23], s[70:71] op_sel:[1,0] op_sel_hi:[0,0] neg_lo:[1,0]
	v_xor_b32_e32 v90, 0x80000000, v19
	v_pk_fma_f32 v[22:23], v[22:23], s[70:71], v[88:89] op_sel_hi:[1,0,1]
	v_mov_b32_e32 v91, v18
	v_pk_add_f32 v[88:89], v[14:15], v[22:23]
	v_pk_add_f32 v[14:15], v[14:15], v[22:23] neg_lo:[0,1] neg_hi:[0,1]
	v_xor_b32_e32 v22, 0x80000000, v17
	v_mov_b32_e32 v23, v16
	v_pk_add_f32 v[16:17], v[4:5], v[22:23]
	v_pk_add_f32 v[4:5], v[4:5], v[22:23] neg_lo:[0,1] neg_hi:[0,1]
	v_pk_mul_f32 v[22:23], v[18:19], s[70:71] op_sel_hi:[1,0]
	s_nop 0
	v_pk_fma_f32 v[18:19], v[90:91], s[70:71], v[22:23] op_sel_hi:[1,0,1] neg_lo:[0,0,1] neg_hi:[0,0,1]
	v_xor_b32_e32 v90, 0x80000000, v75
	v_pk_add_f32 v[22:23], v[8:9], v[18:19]
	v_pk_add_f32 v[8:9], v[8:9], v[18:19] neg_lo:[0,1] neg_hi:[0,1]
	v_pk_add_f32 v[18:19], v[20:21], v[68:69]
	v_pk_add_f32 v[20:21], v[20:21], v[68:69] neg_lo:[0,1] neg_hi:[0,1]
	v_pk_mul_f32 v[68:69], v[86:87], s[70:71] op_sel:[1,0] op_sel_hi:[0,0] neg_lo:[1,0]
	v_mov_b32_e32 v91, v74
	v_pk_fma_f32 v[68:69], v[86:87], s[70:71], v[68:69] op_sel_hi:[1,0,1]
	s_nop 0
	v_pk_add_f32 v[86:87], v[70:71], v[68:69]
	v_pk_add_f32 v[68:69], v[70:71], v[68:69] neg_lo:[0,1] neg_hi:[0,1]
	v_xor_b32_e32 v70, 0x80000000, v73
	v_mov_b32_e32 v71, v72
	v_pk_add_f32 v[72:73], v[24:25], v[70:71]
	v_pk_add_f32 v[24:25], v[24:25], v[70:71] neg_lo:[0,1] neg_hi:[0,1]
	v_pk_mul_f32 v[70:71], v[74:75], s[70:71] op_sel_hi:[1,0]
	s_nop 0
	v_pk_fma_f32 v[70:71], v[90:91], s[70:71], v[70:71] op_sel_hi:[1,0,1] neg_lo:[0,0,1] neg_hi:[0,0,1]
	v_xor_b32_e32 v90, 0x80000000, v69
	v_pk_add_f32 v[74:75], v[26:27], v[70:71]
	v_pk_add_f32 v[26:27], v[26:27], v[70:71] neg_lo:[0,1] neg_hi:[0,1]
	v_pk_add_f32 v[70:71], v[84:85], v[18:19]
	v_pk_add_f32 v[18:19], v[84:85], v[18:19] neg_lo:[0,1] neg_hi:[0,1]
	v_pk_mul_f32 v[84:85], v[86:87], s[62:63] op_sel:[1,0] op_sel_hi:[0,0] neg_lo:[1,0]
	v_mov_b32_e32 v91, v68
	v_pk_fma_f32 v[84:85], v[86:87], s[60:61], v[84:85] op_sel_hi:[1,0,1]
	s_nop 0
	v_pk_add_f32 v[86:87], v[88:89], v[84:85]
	v_pk_add_f32 v[84:85], v[88:89], v[84:85] neg_lo:[0,1] neg_hi:[0,1]
	v_pk_mul_f32 v[88:89], v[72:73], s[70:71] op_sel:[1,0] op_sel_hi:[0,0] neg_lo:[1,0]
	s_nop 0
	v_pk_fma_f32 v[72:73], v[72:73], s[70:71], v[88:89] op_sel_hi:[1,0,1]
	s_nop 0
	v_pk_add_f32 v[88:89], v[16:17], v[72:73]
	v_pk_add_f32 v[16:17], v[16:17], v[72:73] neg_lo:[0,1] neg_hi:[0,1]
	v_pk_mul_f32 v[72:73], v[74:75], s[60:61] op_sel:[1,0] op_sel_hi:[0,0] neg_lo:[1,0]
	s_nop 0
	v_pk_fma_f32 v[72:73], v[74:75], s[62:63], v[72:73] op_sel_hi:[1,0,1]
	s_nop 0
	v_pk_add_f32 v[74:75], v[22:23], v[72:73]
	v_pk_add_f32 v[22:23], v[22:23], v[72:73] neg_lo:[0,1] neg_hi:[0,1]
	v_xor_b32_e32 v72, 0x80000000, v21
	v_mov_b32_e32 v73, v20
	v_pk_add_f32 v[20:21], v[12:13], v[72:73]
	v_pk_add_f32 v[12:13], v[12:13], v[72:73] neg_lo:[0,1] neg_hi:[0,1]
	v_pk_mul_f32 v[72:73], v[68:69], s[62:63] op_sel_hi:[1,0]
	s_nop 0
	v_pk_fma_f32 v[68:69], v[90:91], s[60:61], v[72:73] op_sel_hi:[1,0,1] neg_lo:[0,0,1] neg_hi:[0,0,1]
	v_xor_b32_e32 v90, 0x80000000, v25
	v_pk_add_f32 v[72:73], v[14:15], v[68:69]
	v_pk_add_f32 v[14:15], v[14:15], v[68:69] neg_lo:[0,1] neg_hi:[0,1]
	v_pk_mul_f32 v[68:69], v[24:25], s[70:71] op_sel_hi:[1,0]
	v_mov_b32_e32 v91, v24
	v_pk_fma_f32 v[24:25], v[90:91], s[70:71], v[68:69] op_sel_hi:[1,0,1] neg_lo:[0,0,1] neg_hi:[0,0,1]
	s_nop 0
	v_pk_add_f32 v[68:69], v[4:5], v[24:25]
	v_pk_add_f32 v[4:5], v[4:5], v[24:25] neg_lo:[0,1] neg_hi:[0,1]
	v_pk_mul_f32 v[24:25], v[26:27], s[60:61] op_sel_hi:[1,0]
	s_nop 0
	v_pk_fma_f32 v[24:25], v[26:27], s[62:63], v[24:25] op_sel:[1,0,0] op_sel_hi:[0,0,1] neg_lo:[1,0,1] neg_hi:[0,0,1]
	v_pk_add_f32 v[90:91], v[98:99], v[96:97] neg_lo:[0,1] neg_hi:[0,1]
	v_pk_add_f32 v[26:27], v[8:9], v[24:25]
	v_pk_add_f32 v[8:9], v[8:9], v[24:25] neg_lo:[0,1] neg_hi:[0,1]
	v_pk_add_f32 v[24:25], v[98:99], v[96:97]
	v_pk_add_f32 v[96:97], v[94:95], v[92:93]
	v_pk_add_f32 v[92:93], v[94:95], v[92:93] neg_lo:[0,1] neg_hi:[0,1]
	v_pk_add_f32 v[94:95], v[82:83], v[80:81]
	v_pk_add_f32 v[80:81], v[82:83], v[80:81] neg_lo:[0,1] neg_hi:[0,1]
	v_pk_add_f32 v[82:83], v[78:79], v[76:77]
	v_pk_add_f32 v[76:77], v[78:79], v[76:77] neg_lo:[0,1] neg_hi:[0,1]
	v_pk_add_f32 v[98:99], v[10:11], v[0:1]
	v_pk_add_f32 v[0:1], v[10:11], v[0:1] neg_lo:[0,1] neg_hi:[0,1]
	v_pk_add_f32 v[10:11], v[6:7], v[2:3]
	v_pk_add_f32 v[2:3], v[6:7], v[2:3] neg_lo:[0,1] neg_hi:[0,1]
	v_pk_add_f32 v[6:7], v[24:25], v[96:97]
	v_pk_add_f32 v[24:25], v[24:25], v[96:97] neg_lo:[0,1] neg_hi:[0,1]
	v_xor_b32_e32 v96, 0x80000000, v93
	v_mov_b32_e32 v97, v92
	v_pk_add_f32 v[78:79], v[66:67], v[64:65]
	v_pk_add_f32 v[64:65], v[66:67], v[64:65] neg_lo:[0,1] neg_hi:[0,1]
	v_pk_add_f32 v[66:67], v[62:63], v[100:101]
	v_pk_add_f32 v[62:63], v[62:63], v[100:101] neg_lo:[0,1] neg_hi:[0,1]
	v_pk_add_f32 v[92:93], v[90:91], v[96:97]
	v_pk_add_f32 v[90:91], v[90:91], v[96:97] neg_lo:[0,1] neg_hi:[0,1]
	v_pk_add_f32 v[96:97], v[94:95], v[82:83]
	v_pk_add_f32 v[82:83], v[94:95], v[82:83] neg_lo:[0,1] neg_hi:[0,1]
	v_xor_b32_e32 v94, 0x80000000, v77
	v_mov_b32_e32 v95, v76
	v_pk_add_f32 v[76:77], v[80:81], v[94:95]
	v_pk_add_f32 v[80:81], v[80:81], v[94:95] neg_lo:[0,1] neg_hi:[0,1]
	v_pk_add_f32 v[94:95], v[78:79], v[66:67]
	v_pk_add_f32 v[66:67], v[78:79], v[66:67] neg_lo:[0,1] neg_hi:[0,1]
	v_xor_b32_e32 v78, 0x80000000, v63
	v_mov_b32_e32 v79, v62
	v_pk_add_f32 v[62:63], v[64:65], v[78:79]
	v_pk_add_f32 v[64:65], v[64:65], v[78:79] neg_lo:[0,1] neg_hi:[0,1]
	v_pk_add_f32 v[78:79], v[98:99], v[10:11]
	v_pk_add_f32 v[10:11], v[98:99], v[10:11] neg_lo:[0,1] neg_hi:[0,1]
	v_xor_b32_e32 v98, 0x80000000, v3
	v_mov_b32_e32 v99, v2
	v_pk_add_f32 v[2:3], v[0:1], v[98:99]
	v_pk_add_f32 v[0:1], v[0:1], v[98:99] neg_lo:[0,1] neg_hi:[0,1]
	v_pk_add_f32 v[98:99], v[6:7], v[96:97]
	v_pk_add_f32 v[6:7], v[6:7], v[96:97] neg_lo:[0,1] neg_hi:[0,1]
	v_pk_mul_f32 v[96:97], v[76:77], s[70:71] op_sel:[1,0] op_sel_hi:[0,0] neg_lo:[1,0]
	v_xor_b32_e32 v100, 0x80000000, v81
	v_pk_fma_f32 v[76:77], v[76:77], s[70:71], v[96:97] op_sel_hi:[1,0,1]
	v_mov_b32_e32 v101, v80
	v_pk_add_f32 v[96:97], v[92:93], v[76:77]
	v_pk_add_f32 v[76:77], v[92:93], v[76:77] neg_lo:[0,1] neg_hi:[0,1]
	v_xor_b32_e32 v92, 0x80000000, v83
	v_mov_b32_e32 v93, v82
	v_pk_add_f32 v[82:83], v[24:25], v[92:93]
	v_pk_add_f32 v[24:25], v[24:25], v[92:93] neg_lo:[0,1] neg_hi:[0,1]
	v_pk_mul_f32 v[92:93], v[80:81], s[70:71] op_sel_hi:[1,0]
	s_nop 0
	v_pk_fma_f32 v[80:81], v[100:101], s[70:71], v[92:93] op_sel_hi:[1,0,1] neg_lo:[0,0,1] neg_hi:[0,0,1]
	v_xor_b32_e32 v100, 0x80000000, v1
	v_pk_add_f32 v[92:93], v[90:91], v[80:81]
	v_pk_add_f32 v[80:81], v[90:91], v[80:81] neg_lo:[0,1] neg_hi:[0,1]
	v_pk_add_f32 v[90:91], v[94:95], v[78:79]
	v_pk_add_f32 v[78:79], v[94:95], v[78:79] neg_lo:[0,1] neg_hi:[0,1]
	v_pk_mul_f32 v[94:95], v[2:3], s[70:71] op_sel:[1,0] op_sel_hi:[0,0] neg_lo:[1,0]
	v_mov_b32_e32 v101, v0
	v_pk_fma_f32 v[2:3], v[2:3], s[70:71], v[94:95] op_sel_hi:[1,0,1]
	s_nop 0
	v_pk_add_f32 v[94:95], v[62:63], v[2:3]
	v_pk_add_f32 v[2:3], v[62:63], v[2:3] neg_lo:[0,1] neg_hi:[0,1]
	v_xor_b32_e32 v62, 0x80000000, v11
	v_mov_b32_e32 v63, v10
	v_pk_add_f32 v[10:11], v[66:67], v[62:63]
	v_pk_add_f32 v[62:63], v[66:67], v[62:63] neg_lo:[0,1] neg_hi:[0,1]
	v_pk_mul_f32 v[66:67], v[0:1], s[70:71] op_sel_hi:[1,0]
	s_nop 0
	v_pk_fma_f32 v[0:1], v[100:101], s[70:71], v[66:67] op_sel_hi:[1,0,1] neg_lo:[0,0,1] neg_hi:[0,0,1]
	v_xor_b32_e32 v100, 0x80000000, v3
	v_pk_add_f32 v[66:67], v[64:65], v[0:1]
	v_pk_add_f32 v[0:1], v[64:65], v[0:1] neg_lo:[0,1] neg_hi:[0,1]
	v_pk_add_f32 v[64:65], v[98:99], v[90:91]
	v_pk_add_f32 v[90:91], v[98:99], v[90:91] neg_lo:[0,1] neg_hi:[0,1]
	v_pk_mul_f32 v[98:99], v[94:95], s[62:63] op_sel:[1,0] op_sel_hi:[0,0] neg_lo:[1,0]
	v_mov_b32_e32 v101, v2
	v_pk_fma_f32 v[94:95], v[94:95], s[60:61], v[98:99] op_sel_hi:[1,0,1]
	s_nop 0
	v_pk_add_f32 v[98:99], v[96:97], v[94:95]
	v_pk_add_f32 v[94:95], v[96:97], v[94:95] neg_lo:[0,1] neg_hi:[0,1]
	v_pk_mul_f32 v[96:97], v[10:11], s[70:71] op_sel:[1,0] op_sel_hi:[0,0] neg_lo:[1,0]
	s_nop 0
	v_pk_fma_f32 v[10:11], v[10:11], s[70:71], v[96:97] op_sel_hi:[1,0,1]
	s_nop 0
	v_pk_add_f32 v[96:97], v[82:83], v[10:11]
	v_pk_add_f32 v[10:11], v[82:83], v[10:11] neg_lo:[0,1] neg_hi:[0,1]
	v_pk_mul_f32 v[82:83], v[66:67], s[60:61] op_sel:[1,0] op_sel_hi:[0,0] neg_lo:[1,0]
	s_nop 0
	v_pk_fma_f32 v[66:67], v[66:67], s[62:63], v[82:83] op_sel_hi:[1,0,1]
	s_nop 0
	v_pk_add_f32 v[82:83], v[92:93], v[66:67]
	v_pk_add_f32 v[66:67], v[92:93], v[66:67] neg_lo:[0,1] neg_hi:[0,1]
	v_xor_b32_e32 v92, 0x80000000, v79
	v_mov_b32_e32 v93, v78
	v_pk_add_f32 v[78:79], v[6:7], v[92:93]
	v_pk_add_f32 v[6:7], v[6:7], v[92:93] neg_lo:[0,1] neg_hi:[0,1]
	v_pk_mul_f32 v[92:93], v[2:3], s[62:63] op_sel_hi:[1,0]
	s_nop 0
	v_pk_fma_f32 v[2:3], v[100:101], s[60:61], v[92:93] op_sel_hi:[1,0,1] neg_lo:[0,0,1] neg_hi:[0,0,1]
	v_xor_b32_e32 v100, 0x80000000, v63
	v_pk_add_f32 v[92:93], v[76:77], v[2:3]
	v_pk_add_f32 v[2:3], v[76:77], v[2:3] neg_lo:[0,1] neg_hi:[0,1]
	v_pk_mul_f32 v[76:77], v[62:63], s[70:71] op_sel_hi:[1,0]
	v_mov_b32_e32 v101, v62
	v_pk_fma_f32 v[62:63], v[100:101], s[70:71], v[76:77] op_sel_hi:[1,0,1] neg_lo:[0,0,1] neg_hi:[0,0,1]
	v_xor_b32_e32 v100, 0x80000000, v1
	v_pk_add_f32 v[76:77], v[24:25], v[62:63]
	v_pk_add_f32 v[24:25], v[24:25], v[62:63] neg_lo:[0,1] neg_hi:[0,1]
	v_pk_mul_f32 v[62:63], v[0:1], s[60:61] op_sel_hi:[1,0]
	v_mov_b32_e32 v101, v0
	v_pk_fma_f32 v[0:1], v[100:101], s[62:63], v[62:63] op_sel_hi:[1,0,1] neg_lo:[0,0,1] neg_hi:[0,0,1]
	v_bfe_u32 v100, v102, 1, 4
	v_pk_add_f32 v[62:63], v[80:81], v[0:1]
	v_pk_add_f32 v[0:1], v[80:81], v[0:1] neg_lo:[0,1] neg_hi:[0,1]
	v_lshlrev_b32_e32 v80, 4, v102
	v_lshrrev_b32_e32 v81, 1, v102
	v_bitop3_b32 v101, v81, v80, 16 bitop3:0x6c
	v_lshl_add_u32 v101, v101, 3, 16
	v_lshlrev_b32_e32 v100, 3, v100
	v_add_u32_e32 v102, v101, v100
	ds_write_b64 v102, v[70:71]
	v_bitop3_b32 v70, v81, 1, 15 bitop3:0x6c
	v_lshlrev_b32_e32 v70, 3, v70
	v_add_u32_e32 v71, v101, v70
	ds_write_b64 v71, v[86:87]
	v_bitop3_b32 v71, v81, 2, 15 bitop3:0x6c
	v_lshlrev_b32_e32 v71, 3, v71
	v_add_u32_e32 v86, v101, v71
	ds_write_b64 v86, v[88:89]
	v_bitop3_b32 v86, v81, 3, 15 bitop3:0x6c
	v_lshlrev_b32_e32 v86, 3, v86
	v_add_u32_e32 v87, v101, v86
	ds_write_b64 v87, v[74:75]
	v_bitop3_b32 v74, v81, 4, 15 bitop3:0x6c
	v_lshlrev_b32_e32 v74, 3, v74
	v_add_u32_e32 v75, v101, v74
	ds_write_b64 v75, v[20:21]
	v_bitop3_b32 v20, v81, 5, 15 bitop3:0x6c
	v_lshlrev_b32_e32 v20, 3, v20
	v_add_u32_e32 v21, v101, v20
	ds_write_b64 v21, v[72:73]
	v_bitop3_b32 v21, v81, 6, 15 bitop3:0x6c
	v_lshlrev_b32_e32 v21, 3, v21
	v_add_u32_e32 v72, v101, v21
	ds_write_b64 v72, v[68:69]
	v_bitop3_b32 v68, v81, 7, 15 bitop3:0x6c
	v_lshlrev_b32_e32 v68, 3, v68
	v_add_u32_e32 v69, v101, v68
	ds_write_b64 v69, v[26:27]
	v_bitop3_b32 v26, v81, 8, 15 bitop3:0x6c
	v_lshlrev_b32_e32 v26, 3, v26
	v_add_u32_e32 v27, v101, v26
	ds_write_b64 v27, v[18:19]
	v_bitop3_b32 v18, v81, 9, 15 bitop3:0x6c
	v_lshlrev_b32_e32 v18, 3, v18
	v_add_u32_e32 v19, v101, v18
	ds_write_b64 v19, v[84:85]
	v_bitop3_b32 v19, v81, 10, 15 bitop3:0x6c
	v_lshlrev_b32_e32 v19, 3, v19
	v_add_u32_e32 v27, v101, v19
	ds_write_b64 v27, v[16:17]
	v_bitop3_b32 v16, v81, 11, 15 bitop3:0x6c
	v_lshlrev_b32_e32 v16, 3, v16
	v_add_u32_e32 v17, v101, v16
	ds_write_b64 v17, v[22:23]
	v_bitop3_b32 v17, v81, 12, 15 bitop3:0x6c
	v_lshlrev_b32_e32 v17, 3, v17
	v_add_u32_e32 v22, v101, v17
	ds_write_b64 v22, v[12:13]
	v_bitop3_b32 v12, v81, 13, 15 bitop3:0x6c
	v_lshlrev_b32_e32 v12, 3, v12
	v_add_u32_e32 v13, v101, v12
	ds_write_b64 v13, v[14:15]
	v_bitop3_b32 v13, v81, 14, 15 bitop3:0x6c
	v_lshlrev_b32_e32 v13, 3, v13
	v_add_u32_e32 v14, v101, v13
	ds_write_b64 v14, v[4:5]
	v_bitop3_b32 v4, v81, 15, v81 bitop3:0xc
	v_lshlrev_b32_e32 v4, 3, v4
	v_add_u32_e32 v5, v101, v4
	ds_write_b64 v5, v[8:9]
	v_add_u32_e32 v5, 0x2000, v80
	v_bitop3_b32 v5, v5, v81, 16 bitop3:0x78
	v_lshl_add_u32 v5, v5, 3, 16
	v_add_u32_e32 v8, v5, v100
	ds_write_b64 v8, v[64:65]
	v_add_u32_e32 v8, v5, v70
	ds_write_b64 v8, v[98:99]
	v_add_u32_e32 v8, v5, v71
	ds_write_b64 v8, v[96:97]
	v_add_u32_e32 v8, v5, v86
	ds_write_b64 v8, v[82:83]
	v_add_u32_e32 v8, v5, v74
	ds_write_b64 v8, v[78:79]
	v_add_u32_e32 v8, v5, v20
	ds_write_b64 v8, v[92:93]
	v_add_u32_e32 v8, v5, v21
	ds_write_b64 v8, v[76:77]
	v_add_u32_e32 v8, v5, v68
	ds_write_b64 v8, v[62:63]
	v_add_u32_e32 v8, v5, v26
	ds_write_b64 v8, v[90:91]
	v_add_u32_e32 v8, v5, v18
	ds_write_b64 v8, v[94:95]
	v_add_u32_e32 v8, v5, v19
	ds_write_b64 v8, v[10:11]
	v_add_u32_e32 v8, v5, v16
	ds_write_b64 v8, v[66:67]
	v_add_u32_e32 v8, v5, v17
	ds_write_b64 v8, v[6:7]
	v_add_u32_e32 v6, v5, v12
	ds_write_b64 v6, v[2:3]
	v_add_u32_e32 v2, v5, v13
	ds_write_b64 v2, v[24:25]
	v_add_u32_e32 v2, v5, v4
	v_mov_b32_e32 v22, v146
	ds_write_b64 v2, v[0:1]
	s_waitcnt lgkmcnt(0)
	s_barrier
	s_nop 0
	v_lshlrev_b32_e32 v0, 5, v22
	v_and_b32_e32 v2, 0xfffffe00, v0
	v_and_or_b32 v0, v22, 16, v2
	v_bitop3_b32 v2, v2, 16, v22 bitop3:0x34
	v_bitop3_b32 v6, v22, 4, 15 bitop3:0x6c
	v_bitop3_b32 v14, v22, 8, 15 bitop3:0x6c
	v_lshl_add_u32 v23, v0, 3, 16
	v_lshl_add_u32 v65, v2, 3, 16
	v_lshlrev_b32_e32 v6, 3, v6
	v_lshlrev_b32_e32 v14, 3, v14
	v_bitop3_b32 v2, v22, 1, 15 bitop3:0x6c
	v_add_u32_e32 v105, v23, v6
	v_add_u32_e32 v106, v65, v6
	v_bitop3_b32 v6, v22, 5, 15 bitop3:0x6c
	v_add_u32_e32 v113, v23, v14
	v_add_u32_e32 v114, v65, v14
	v_bitop3_b32 v14, v22, 9, 15 bitop3:0x6c
	v_lshlrev_b32_e32 v2, 3, v2
	v_lshlrev_b32_e32 v6, 3, v6
	v_lshlrev_b32_e32 v14, 3, v14
	v_add_u32_e32 v99, v23, v2
	v_add_u32_e32 v100, v65, v2
	v_bitop3_b32 v2, v22, 2, 15 bitop3:0x6c
	v_add_u32_e32 v107, v23, v6
	v_add_u32_e32 v108, v65, v6
	v_bitop3_b32 v6, v22, 6, 15 bitop3:0x6c
	v_add_u32_e32 v115, v23, v14
	v_add_u32_e32 v116, v65, v14
	v_bitop3_b32 v14, v22, 10, 15 bitop3:0x6c
	v_bitop3_b32 v26, v22, 12, 15 bitop3:0x6c
	v_lshlrev_b32_e32 v2, 3, v2
	v_lshlrev_b32_e32 v6, 3, v6
	v_lshlrev_b32_e32 v14, 3, v14
	v_lshlrev_b32_e32 v26, 3, v26
	v_and_b32_e32 v64, 15, v22
	v_add_u32_e32 v101, v23, v2
	v_add_u32_e32 v102, v65, v2
	v_bitop3_b32 v2, v22, 3, 15 bitop3:0x6c
	v_add_u32_e32 v109, v23, v6
	v_add_u32_e32 v110, v65, v6
	v_bitop3_b32 v6, v22, 7, 15 bitop3:0x6c
	v_add_u32_e32 v117, v23, v14
	v_add_u32_e32 v118, v65, v14
	v_bitop3_b32 v14, v22, 11, 15 bitop3:0x6c
	v_add_u32_e32 v121, v23, v26
	v_add_u32_e32 v122, v65, v26
	v_bitop3_b32 v26, v22, 13, 15 bitop3:0x6c
	v_bitop3_b32 v66, v22, 14, 15 bitop3:0x6c
	v_bitop3_b32 v22, v22, 15, v22 bitop3:0xc
	v_lshlrev_b32_e32 v3, 3, v64
	v_lshlrev_b32_e32 v2, 3, v2
	v_lshlrev_b32_e32 v6, 3, v6
	v_lshlrev_b32_e32 v14, 3, v14
	v_lshlrev_b32_e32 v26, 3, v26
	v_lshlrev_b32_e32 v66, 3, v66
	v_lshlrev_b32_e32 v22, 3, v22
	v_add_u32_e32 v67, v23, v3
	v_add_u32_e32 v98, v65, v3
	v_add_u32_e32 v103, v23, v2
	v_add_u32_e32 v104, v65, v2
	v_add_u32_e32 v111, v23, v6
	v_add_u32_e32 v112, v65, v6
	v_add_u32_e32 v119, v23, v14
	v_add_u32_e32 v120, v65, v14
	v_add_u32_e32 v123, v23, v26
	v_add_u32_e32 v124, v65, v26
	v_add_u32_e32 v125, v23, v66
	v_add_u32_e32 v126, v65, v66
	v_add_u32_e32 v127, v23, v22
	v_add_u32_e32 v128, v65, v22
	ds_read_b64 v[0:1], v67
	ds_read_b64 v[12:13], v98
	ds_read_b64 v[74:75], v99 offset:256
	ds_read_b64 v[4:5], v100 offset:256
	ds_read_b64 v[76:77], v101 offset:512
	ds_read_b64 v[10:11], v102 offset:512
	ds_read_b64 v[70:71], v103 offset:768
	ds_read_b64 v[2:3], v104 offset:768
	ds_read_b64 v[62:63], v105 offset:1024
	ds_read_b64 v[20:21], v106 offset:1024
	ds_read_b64 v[90:91], v107 offset:1280
	ds_read_b64 v[8:9], v108 offset:1280
	ds_read_b64 v[84:85], v109 offset:1536
	ds_read_b64 v[16:17], v110 offset:1536
	ds_read_b64 v[82:83], v111 offset:1792
	ds_read_b64 v[6:7], v112 offset:1792
	ds_read_b64 v[24:25], v113 offset:2048
	ds_read_b64 v[78:79], v114 offset:2048
	ds_read_b64 v[96:97], v115 offset:2304
	ds_read_b64 v[18:19], v116 offset:2304
	ds_read_b64 v[86:87], v117 offset:2560
	ds_read_b64 v[72:73], v118 offset:2560
	ds_read_b64 v[130:131], v119 offset:2816
	ds_read_b64 v[14:15], v120 offset:2816
	ds_read_b64 v[80:81], v121 offset:3072
	ds_read_b64 v[92:93], v122 offset:3072
	ds_read_b64 v[132:133], v123 offset:3328
	ds_read_b64 v[26:27], v124 offset:3328
	ds_read_b64 v[94:95], v125 offset:3584
	ds_read_b64 v[88:89], v126 offset:3584
	ds_read_b64 v[134:135], v127 offset:3840
	ds_read_b64 v[22:23], v128 offset:3840
	s_waitcnt lgkmcnt(14)
	s_nop 0
	v_cvt_f32_i32_e32 v64, v64
	s_nop 0
	v_mul_f32_e32 v64, 0x3b000000, v64
	v_cos_f32_e32 v68, v64
	v_sin_f32_e32 v69, v64
	v_add_f32_e32 v66, v68, v68
	v_pk_mul_f32 v[64:65], v[68:69], v[68:69]
	v_mul_f32_e32 v66, v69, v66
	s_nop 0
	s_nop 0
	v_mov_b32_e32 v140, v69
	v_pk_add_f32 v[64:65], v[64:65], v[64:65] op_sel:[0,1] op_sel_hi:[0,1] neg_lo:[0,1] neg_hi:[0,1]
	v_pk_mul_f32 v[136:137], v[68:69], v[66:67] op_sel:[1,0] op_sel_hi:[0,0] neg_lo:[1,0]
	v_pk_mul_f32 v[138:139], v[24:25], v[140:141] op_sel:[1,0] op_sel_hi:[0,0] neg_lo:[1,0]
	v_pk_fma_f32 v[136:137], v[68:69], v[64:65], v[136:137]
	v_pk_fma_f32 v[24:25], v[24:25], v[68:69], v[138:139] op_sel_hi:[1,0,1]
	v_pk_mul_f32 v[68:69], v[66:67], s[48:49] op_sel_hi:[0,1]
	v_pk_fma_f32 v[138:139], v[64:65], s[40:41], v[68:69]
	s_nop 0
	v_pk_mul_f32 v[68:69], v[62:63], v[138:139] op_sel:[1,1] op_sel_hi:[0,1] neg_lo:[1,0]
	s_nop 0
	v_pk_fma_f32 v[68:69], v[62:63], v[138:139], v[68:69] op_sel_hi:[1,0,1]
	v_pk_mul_f32 v[62:63], v[66:67], v[136:137] op_sel:[0,1] op_sel_hi:[0,0] neg_lo:[0,1]
	v_pk_fma_f32 v[140:141], v[64:65], v[136:137], v[62:63]
	s_waitcnt lgkmcnt(7)
	v_pk_mul_f32 v[62:63], v[80:81], v[136:137] op_sel:[1,1] op_sel_hi:[0,1] neg_lo:[1,0]
	s_nop 0
	v_pk_fma_f32 v[62:63], v[80:81], v[136:137], v[62:63] op_sel_hi:[1,0,1]
	v_pk_mul_f32 v[80:81], v[66:67], v[138:139] op_sel:[0,1] op_sel_hi:[0,0] neg_lo:[0,1]
	v_pk_fma_f32 v[136:137], v[64:65], v[138:139], v[80:81]
	s_nop 0
	v_pk_mul_f32 v[80:81], v[76:77], v[136:137] op_sel:[1,1] op_sel_hi:[0,1] neg_lo:[1,0]
	s_nop 0
	v_pk_fma_f32 v[80:81], v[76:77], v[136:137], v[80:81] op_sel_hi:[1,0,1]
	v_pk_mul_f32 v[76:77], v[66:67], v[140:141] op_sel:[0,1] op_sel_hi:[0,0] neg_lo:[0,1]
	v_pk_fma_f32 v[138:139], v[64:65], v[140:141], v[76:77]
	v_pk_mul_f32 v[76:77], v[86:87], v[140:141] op_sel:[1,1] op_sel_hi:[0,1] neg_lo:[1,0]
	s_nop 0
	v_pk_fma_f32 v[76:77], v[86:87], v[140:141], v[76:77] op_sel_hi:[1,0,1]
	v_pk_mul_f32 v[86:87], v[66:67], v[136:137] op_sel:[0,1] op_sel_hi:[0,0] neg_lo:[0,1]
	v_pk_fma_f32 v[136:137], v[64:65], v[136:137], v[86:87]
	s_nop 0
	v_pk_mul_f32 v[86:87], v[84:85], v[136:137] op_sel:[1,1] op_sel_hi:[0,1] neg_lo:[1,0]
	s_nop 0
	v_pk_fma_f32 v[86:87], v[84:85], v[136:137], v[86:87] op_sel_hi:[1,0,1]
	v_pk_mul_f32 v[84:85], v[66:67], v[138:139] op_sel:[0,1] op_sel_hi:[0,0] neg_lo:[0,1]
	v_pk_fma_f32 v[140:141], v[64:65], v[138:139], v[84:85]
	s_waitcnt lgkmcnt(3)
	v_pk_mul_f32 v[84:85], v[94:95], v[138:139] op_sel:[1,1] op_sel_hi:[0,1] neg_lo:[1,0]
	s_nop 0
	v_pk_fma_f32 v[84:85], v[94:95], v[138:139], v[84:85] op_sel_hi:[1,0,1]
	v_pk_mul_f32 v[94:95], v[66:67], v[136:137] op_sel:[0,1] op_sel_hi:[0,0] neg_lo:[0,1]
	v_pk_fma_f32 v[136:137], v[64:65], v[136:137], v[94:95]
	s_nop 0
	v_pk_mul_f32 v[94:95], v[74:75], v[136:137] op_sel:[1,1] op_sel_hi:[0,1] neg_lo:[1,0]
	s_nop 0
	v_pk_fma_f32 v[94:95], v[74:75], v[136:137], v[94:95] op_sel_hi:[1,0,1]
	v_pk_mul_f32 v[74:75], v[66:67], v[140:141] op_sel:[0,1] op_sel_hi:[0,0] neg_lo:[0,1]
	v_pk_fma_f32 v[138:139], v[64:65], v[140:141], v[74:75]
	v_pk_mul_f32 v[74:75], v[96:97], v[140:141] op_sel:[1,1] op_sel_hi:[0,1] neg_lo:[1,0]
	s_nop 0
	v_pk_fma_f32 v[74:75], v[96:97], v[140:141], v[74:75] op_sel_hi:[1,0,1]
	v_pk_mul_f32 v[96:97], v[66:67], v[136:137] op_sel:[0,1] op_sel_hi:[0,0] neg_lo:[0,1]
	v_pk_fma_f32 v[136:137], v[64:65], v[136:137], v[96:97]
	s_nop 0
	v_pk_mul_f32 v[96:97], v[90:91], v[136:137] op_sel:[1,1] op_sel_hi:[0,1] neg_lo:[1,0]
	s_nop 0
	v_pk_fma_f32 v[96:97], v[90:91], v[136:137], v[96:97] op_sel_hi:[1,0,1]
	v_pk_mul_f32 v[90:91], v[66:67], v[138:139] op_sel:[0,1] op_sel_hi:[0,0] neg_lo:[0,1]
	v_pk_fma_f32 v[140:141], v[64:65], v[138:139], v[90:91]
	v_pk_mul_f32 v[90:91], v[132:133], v[138:139] op_sel:[1,1] op_sel_hi:[0,1] neg_lo:[1,0]
	s_nop 0
	v_pk_fma_f32 v[90:91], v[132:133], v[138:139], v[90:91] op_sel_hi:[1,0,1]
	v_pk_mul_f32 v[132:133], v[66:67], v[136:137] op_sel:[0,1] op_sel_hi:[0,0] neg_lo:[0,1]
	s_nop 0
	v_pk_fma_f32 v[132:133], v[64:65], v[136:137], v[132:133]
	v_pk_mul_f32 v[138:139], v[130:131], v[140:141] op_sel:[1,1] op_sel_hi:[0,1] neg_lo:[1,0]
	v_pk_mul_f32 v[136:137], v[70:71], v[132:133] op_sel:[1,1] op_sel_hi:[0,1] neg_lo:[1,0]
	v_pk_fma_f32 v[130:131], v[130:131], v[140:141], v[138:139] op_sel_hi:[1,0,1]
	v_pk_fma_f32 v[70:71], v[70:71], v[132:133], v[136:137] op_sel_hi:[1,0,1]
	v_pk_mul_f32 v[138:139], v[66:67], v[132:133] op_sel:[0,1] op_sel_hi:[0,0] neg_lo:[0,1]
	v_pk_mul_f32 v[136:137], v[66:67], v[140:141] op_sel:[0,1] op_sel_hi:[0,0] neg_lo:[0,1]
	v_pk_fma_f32 v[132:133], v[64:65], v[132:133], v[138:139]
	v_pk_fma_f32 v[136:137], v[64:65], v[140:141], v[136:137]
	v_pk_mul_f32 v[138:139], v[82:83], v[132:133] op_sel:[1,1] op_sel_hi:[0,1] neg_lo:[1,0]
	s_waitcnt lgkmcnt(1)
	v_pk_fma_f32 v[82:83], v[82:83], v[132:133], v[138:139] op_sel_hi:[1,0,1]
	v_pk_mul_f32 v[138:139], v[66:67], v[136:137] op_sel:[0,1] op_sel_hi:[0,0] neg_lo:[0,1]
	v_pk_mul_f32 v[140:141], v[134:135], v[136:137] op_sel:[1,1] op_sel_hi:[0,1] neg_lo:[1,0]
	v_pk_fma_f32 v[138:139], v[64:65], v[136:137], v[138:139]
	v_pk_fma_f32 v[134:135], v[134:135], v[136:137], v[140:141] op_sel_hi:[1,0,1]
	v_pk_mul_f32 v[136:137], v[66:67], v[132:133] op_sel:[0,1] op_sel_hi:[0,0] neg_lo:[0,1]
	v_pk_fma_f32 v[132:133], v[64:65], v[132:133], v[136:137]
	s_nop 0
	v_pk_mul_f32 v[136:137], v[12:13], v[132:133] op_sel:[1,1] op_sel_hi:[0,1] neg_lo:[1,0]
	s_nop 0
	v_pk_fma_f32 v[12:13], v[12:13], v[132:133], v[136:137] op_sel_hi:[1,0,1]
	v_pk_mul_f32 v[136:137], v[66:67], v[138:139] op_sel:[0,1] op_sel_hi:[0,0] neg_lo:[0,1]
	v_pk_mul_f32 v[140:141], v[78:79], v[138:139] op_sel:[1,1] op_sel_hi:[0,1] neg_lo:[1,0]
	v_pk_fma_f32 v[136:137], v[64:65], v[138:139], v[136:137]
	v_pk_fma_f32 v[78:79], v[78:79], v[138:139], v[140:141] op_sel_hi:[1,0,1]
	v_pk_mul_f32 v[138:139], v[66:67], v[132:133] op_sel:[0,1] op_sel_hi:[0,0] neg_lo:[0,1]
	v_pk_fma_f32 v[132:133], v[64:65], v[132:133], v[138:139]
	s_nop 0
	v_pk_mul_f32 v[138:139], v[20:21], v[132:133] op_sel:[1,1] op_sel_hi:[0,1] neg_lo:[1,0]
	s_nop 0
	v_pk_fma_f32 v[20:21], v[20:21], v[132:133], v[138:139] op_sel_hi:[1,0,1]
	v_pk_mul_f32 v[138:139], v[66:67], v[136:137] op_sel:[0,1] op_sel_hi:[0,0] neg_lo:[0,1]
	v_pk_mul_f32 v[140:141], v[92:93], v[136:137] op_sel:[1,1] op_sel_hi:[0,1] neg_lo:[1,0]
	v_pk_fma_f32 v[138:139], v[64:65], v[136:137], v[138:139]
	v_pk_fma_f32 v[92:93], v[92:93], v[136:137], v[140:141] op_sel_hi:[1,0,1]
	v_pk_mul_f32 v[136:137], v[66:67], v[132:133] op_sel:[0,1] op_sel_hi:[0,0] neg_lo:[0,1]
	v_pk_fma_f32 v[132:133], v[64:65], v[132:133], v[136:137]
	s_nop 0
	v_pk_mul_f32 v[136:137], v[10:11], v[132:133] op_sel:[1,1] op_sel_hi:[0,1] neg_lo:[1,0]
	s_nop 0
	v_pk_fma_f32 v[10:11], v[10:11], v[132:133], v[136:137] op_sel_hi:[1,0,1]
	v_pk_mul_f32 v[136:137], v[66:67], v[138:139] op_sel:[0,1] op_sel_hi:[0,0] neg_lo:[0,1]
	v_pk_mul_f32 v[140:141], v[72:73], v[138:139] op_sel:[1,1] op_sel_hi:[0,1] neg_lo:[1,0]
	v_pk_fma_f32 v[136:137], v[64:65], v[138:139], v[136:137]
	v_pk_fma_f32 v[72:73], v[72:73], v[138:139], v[140:141] op_sel_hi:[1,0,1]
	v_pk_mul_f32 v[138:139], v[66:67], v[132:133] op_sel:[0,1] op_sel_hi:[0,0] neg_lo:[0,1]
	v_pk_fma_f32 v[132:133], v[64:65], v[132:133], v[138:139]
	s_nop 0
	v_pk_mul_f32 v[138:139], v[16:17], v[132:133] op_sel:[1,1] op_sel_hi:[0,1] neg_lo:[1,0]
	s_nop 0
	v_pk_fma_f32 v[16:17], v[16:17], v[132:133], v[138:139] op_sel_hi:[1,0,1]
	v_pk_mul_f32 v[138:139], v[66:67], v[136:137] op_sel:[0,1] op_sel_hi:[0,0] neg_lo:[0,1]
	v_pk_mul_f32 v[140:141], v[88:89], v[136:137] op_sel:[1,1] op_sel_hi:[0,1] neg_lo:[1,0]
	v_pk_fma_f32 v[138:139], v[64:65], v[136:137], v[138:139]
	v_pk_fma_f32 v[88:89], v[88:89], v[136:137], v[140:141] op_sel_hi:[1,0,1]
	v_pk_mul_f32 v[136:137], v[66:67], v[132:133] op_sel:[0,1] op_sel_hi:[0,0] neg_lo:[0,1]
	v_pk_fma_f32 v[132:133], v[64:65], v[132:133], v[136:137]
	s_nop 0
	v_pk_mul_f32 v[136:137], v[4:5], v[132:133] op_sel:[1,1] op_sel_hi:[0,1] neg_lo:[1,0]
	s_nop 0
	v_pk_fma_f32 v[4:5], v[4:5], v[132:133], v[136:137] op_sel_hi:[1,0,1]
	v_pk_mul_f32 v[136:137], v[66:67], v[138:139] op_sel:[0,1] op_sel_hi:[0,0] neg_lo:[0,1]
	v_pk_mul_f32 v[140:141], v[18:19], v[138:139] op_sel:[1,1] op_sel_hi:[0,1] neg_lo:[1,0]
	v_pk_fma_f32 v[136:137], v[64:65], v[138:139], v[136:137]
	v_pk_fma_f32 v[18:19], v[18:19], v[138:139], v[140:141] op_sel_hi:[1,0,1]
	v_pk_mul_f32 v[138:139], v[66:67], v[132:133] op_sel:[0,1] op_sel_hi:[0,0] neg_lo:[0,1]
	v_pk_fma_f32 v[132:133], v[64:65], v[132:133], v[138:139]
	s_nop 0
	v_pk_mul_f32 v[138:139], v[8:9], v[132:133] op_sel:[1,1] op_sel_hi:[0,1] neg_lo:[1,0]
	s_nop 0
	v_pk_fma_f32 v[8:9], v[8:9], v[132:133], v[138:139] op_sel_hi:[1,0,1]
	v_pk_mul_f32 v[138:139], v[66:67], v[136:137] op_sel:[0,1] op_sel_hi:[0,0] neg_lo:[0,1]
	v_pk_mul_f32 v[140:141], v[26:27], v[136:137] op_sel:[1,1] op_sel_hi:[0,1] neg_lo:[1,0]
	v_pk_fma_f32 v[138:139], v[64:65], v[136:137], v[138:139]
	v_pk_fma_f32 v[26:27], v[26:27], v[136:137], v[140:141] op_sel_hi:[1,0,1]
	v_pk_mul_f32 v[136:137], v[66:67], v[132:133] op_sel:[0,1] op_sel_hi:[0,0] neg_lo:[0,1]
	v_pk_fma_f32 v[132:133], v[64:65], v[132:133], v[136:137]
	s_nop 0
	v_pk_mul_f32 v[136:137], v[2:3], v[132:133] op_sel:[1,1] op_sel_hi:[0,1] neg_lo:[1,0]
	s_nop 0
	v_pk_fma_f32 v[2:3], v[2:3], v[132:133], v[136:137] op_sel_hi:[1,0,1]
	v_pk_mul_f32 v[136:137], v[66:67], v[138:139] op_sel:[0,1] op_sel_hi:[0,0] neg_lo:[0,1]
	v_pk_mul_f32 v[140:141], v[14:15], v[138:139] op_sel:[1,1] op_sel_hi:[0,1] neg_lo:[1,0]
	v_pk_fma_f32 v[136:137], v[64:65], v[138:139], v[136:137]
	v_pk_fma_f32 v[14:15], v[14:15], v[138:139], v[140:141] op_sel_hi:[1,0,1]
	v_pk_mul_f32 v[138:139], v[66:67], v[132:133] op_sel:[0,1] op_sel_hi:[0,0] neg_lo:[0,1]
	v_pk_fma_f32 v[64:65], v[64:65], v[132:133], v[138:139]
	s_nop 0
	v_pk_mul_f32 v[132:133], v[6:7], v[64:65] op_sel:[1,1] op_sel_hi:[0,1] neg_lo:[1,0]
	s_nop 0
	v_pk_fma_f32 v[6:7], v[6:7], v[64:65], v[132:133] op_sel_hi:[1,0,1]
	s_waitcnt lgkmcnt(0)
	v_pk_mul_f32 v[64:65], v[22:23], v[136:137] op_sel:[1,1] op_sel_hi:[0,1] neg_lo:[1,0]
	s_nop 0
	v_pk_fma_f32 v[22:23], v[22:23], v[136:137], v[64:65] op_sel_hi:[1,0,1]
	v_pk_add_f32 v[64:65], v[0:1], v[12:13]
	v_pk_add_f32 v[0:1], v[0:1], v[12:13] neg_lo:[0,1] neg_hi:[0,1]
	v_pk_add_f32 v[12:13], v[94:95], v[4:5]
	v_pk_add_f32 v[4:5], v[94:95], v[4:5] neg_lo:[0,1] neg_hi:[0,1]
	v_pk_add_f32 v[94:95], v[80:81], v[10:11]
	v_pk_add_f32 v[10:11], v[80:81], v[10:11] neg_lo:[0,1] neg_hi:[0,1]
	v_pk_add_f32 v[80:81], v[70:71], v[2:3]
	v_pk_add_f32 v[2:3], v[70:71], v[2:3] neg_lo:[0,1] neg_hi:[0,1]
	v_pk_add_f32 v[132:133], v[64:65], v[12:13]
	v_pk_add_f32 v[12:13], v[64:65], v[12:13] neg_lo:[0,1] neg_hi:[0,1]
	v_xor_b32_e32 v64, 0x80000000, v5
	v_mov_b32_e32 v65, v4
	v_pk_add_f32 v[70:71], v[68:69], v[20:21]
	v_pk_add_f32 v[20:21], v[68:69], v[20:21] neg_lo:[0,1] neg_hi:[0,1]
	v_pk_add_f32 v[68:69], v[96:97], v[8:9]
	v_pk_add_f32 v[8:9], v[96:97], v[8:9] neg_lo:[0,1] neg_hi:[0,1]
	v_pk_add_f32 v[4:5], v[0:1], v[64:65]
	v_pk_add_f32 v[0:1], v[0:1], v[64:65] neg_lo:[0,1] neg_hi:[0,1]
	v_pk_add_f32 v[64:65], v[94:95], v[80:81]
	v_pk_add_f32 v[80:81], v[94:95], v[80:81] neg_lo:[0,1] neg_hi:[0,1]
	v_xor_b32_e32 v94, 0x80000000, v3
	v_mov_b32_e32 v95, v2
	v_pk_add_f32 v[96:97], v[86:87], v[16:17]
	v_pk_add_f32 v[16:17], v[86:87], v[16:17] neg_lo:[0,1] neg_hi:[0,1]
	v_pk_add_f32 v[86:87], v[82:83], v[6:7]
	v_pk_add_f32 v[6:7], v[82:83], v[6:7] neg_lo:[0,1] neg_hi:[0,1]
	v_pk_add_f32 v[2:3], v[10:11], v[94:95]
	v_pk_add_f32 v[10:11], v[10:11], v[94:95] neg_lo:[0,1] neg_hi:[0,1]
	v_pk_add_f32 v[94:95], v[70:71], v[68:69]
	v_pk_add_f32 v[68:69], v[70:71], v[68:69] neg_lo:[0,1] neg_hi:[0,1]
	v_xor_b32_e32 v70, 0x80000000, v9
	v_mov_b32_e32 v71, v8
	v_pk_add_f32 v[82:83], v[24:25], v[78:79]
	v_pk_add_f32 v[24:25], v[24:25], v[78:79] neg_lo:[0,1] neg_hi:[0,1]
	v_pk_add_f32 v[78:79], v[74:75], v[18:19]
	v_pk_add_f32 v[18:19], v[74:75], v[18:19] neg_lo:[0,1] neg_hi:[0,1]
	v_pk_add_f32 v[8:9], v[20:21], v[70:71]
	v_pk_add_f32 v[20:21], v[20:21], v[70:71] neg_lo:[0,1] neg_hi:[0,1]
	v_pk_add_f32 v[70:71], v[96:97], v[86:87]
	v_pk_add_f32 v[86:87], v[96:97], v[86:87] neg_lo:[0,1] neg_hi:[0,1]
	v_xor_b32_e32 v96, 0x80000000, v7
	v_mov_b32_e32 v97, v6
	v_pk_add_f32 v[74:75], v[76:77], v[72:73]
	v_pk_add_f32 v[72:73], v[76:77], v[72:73] neg_lo:[0,1] neg_hi:[0,1]
	v_pk_add_f32 v[76:77], v[130:131], v[14:15]
	v_pk_add_f32 v[14:15], v[130:131], v[14:15] neg_lo:[0,1] neg_hi:[0,1]
	v_pk_add_f32 v[6:7], v[16:17], v[96:97]
	v_pk_add_f32 v[16:17], v[16:17], v[96:97] neg_lo:[0,1] neg_hi:[0,1]
	v_pk_add_f32 v[96:97], v[82:83], v[78:79]
	v_pk_add_f32 v[78:79], v[82:83], v[78:79] neg_lo:[0,1] neg_hi:[0,1]
	v_xor_b32_e32 v82, 0x80000000, v19
	v_mov_b32_e32 v83, v18
	v_pk_add_f32 v[130:131], v[62:63], v[92:93]
	v_pk_add_f32 v[62:63], v[62:63], v[92:93] neg_lo:[0,1] neg_hi:[0,1]
	v_pk_add_f32 v[92:93], v[90:91], v[26:27]
	v_pk_add_f32 v[26:27], v[90:91], v[26:27] neg_lo:[0,1] neg_hi:[0,1]
	v_pk_add_f32 v[18:19], v[24:25], v[82:83]
	v_pk_add_f32 v[24:25], v[24:25], v[82:83] neg_lo:[0,1] neg_hi:[0,1]
	v_pk_add_f32 v[82:83], v[74:75], v[76:77]
	v_pk_add_f32 v[74:75], v[74:75], v[76:77] neg_lo:[0,1] neg_hi:[0,1]
	v_xor_b32_e32 v76, 0x80000000, v15
	v_mov_b32_e32 v77, v14
	v_pk_add_f32 v[90:91], v[84:85], v[88:89]
	v_pk_add_f32 v[84:85], v[84:85], v[88:89] neg_lo:[0,1] neg_hi:[0,1]
	v_pk_add_f32 v[88:89], v[134:135], v[22:23]
	v_pk_add_f32 v[22:23], v[134:135], v[22:23] neg_lo:[0,1] neg_hi:[0,1]
	v_pk_add_f32 v[14:15], v[72:73], v[76:77]
	v_pk_add_f32 v[72:73], v[72:73], v[76:77] neg_lo:[0,1] neg_hi:[0,1]
	v_pk_add_f32 v[76:77], v[130:131], v[92:93]
	v_pk_add_f32 v[92:93], v[130:131], v[92:93] neg_lo:[0,1] neg_hi:[0,1]
	v_xor_b32_e32 v130, 0x80000000, v27
	v_mov_b32_e32 v131, v26
	v_pk_add_f32 v[26:27], v[62:63], v[130:131]
	v_pk_add_f32 v[62:63], v[62:63], v[130:131] neg_lo:[0,1] neg_hi:[0,1]
	v_pk_add_f32 v[130:131], v[90:91], v[88:89]
	v_pk_add_f32 v[88:89], v[90:91], v[88:89] neg_lo:[0,1] neg_hi:[0,1]
	v_xor_b32_e32 v90, 0x80000000, v23
	v_mov_b32_e32 v91, v22
	v_pk_add_f32 v[22:23], v[84:85], v[90:91]
	v_pk_add_f32 v[84:85], v[84:85], v[90:91] neg_lo:[0,1] neg_hi:[0,1]
	v_pk_add_f32 v[90:91], v[132:133], v[64:65]
	v_pk_add_f32 v[64:65], v[132:133], v[64:65] neg_lo:[0,1] neg_hi:[0,1]
	v_pk_mul_f32 v[132:133], v[2:3], s[70:71] op_sel:[1,0] op_sel_hi:[0,0] neg_lo:[1,0]
	v_xor_b32_e32 v134, 0x80000000, v11
	v_pk_fma_f32 v[2:3], v[2:3], s[70:71], v[132:133] op_sel_hi:[1,0,1]
	v_mov_b32_e32 v135, v10
	v_pk_add_f32 v[132:133], v[4:5], v[2:3]
	v_pk_add_f32 v[2:3], v[4:5], v[2:3] neg_lo:[0,1] neg_hi:[0,1]
	v_xor_b32_e32 v4, 0x80000000, v81
	v_mov_b32_e32 v5, v80
	v_pk_add_f32 v[80:81], v[12:13], v[4:5]
	v_pk_add_f32 v[4:5], v[12:13], v[4:5] neg_lo:[0,1] neg_hi:[0,1]
	v_pk_mul_f32 v[12:13], v[10:11], s[70:71] op_sel_hi:[1,0]
	s_nop 0
	v_pk_fma_f32 v[10:11], v[134:135], s[70:71], v[12:13] op_sel_hi:[1,0,1] neg_lo:[0,0,1] neg_hi:[0,0,1]
	v_xor_b32_e32 v134, 0x80000000, v17
	v_pk_add_f32 v[12:13], v[0:1], v[10:11]
	v_pk_add_f32 v[0:1], v[0:1], v[10:11] neg_lo:[0,1] neg_hi:[0,1]
	v_pk_add_f32 v[10:11], v[94:95], v[70:71]
	v_pk_add_f32 v[70:71], v[94:95], v[70:71] neg_lo:[0,1] neg_hi:[0,1]
	v_pk_mul_f32 v[94:95], v[6:7], s[70:71] op_sel:[1,0] op_sel_hi:[0,0] neg_lo:[1,0]
	v_mov_b32_e32 v135, v16
	v_pk_fma_f32 v[6:7], v[6:7], s[70:71], v[94:95] op_sel_hi:[1,0,1]
	s_nop 0
	v_pk_add_f32 v[94:95], v[8:9], v[6:7]
	v_pk_add_f32 v[6:7], v[8:9], v[6:7] neg_lo:[0,1] neg_hi:[0,1]
	v_xor_b32_e32 v8, 0x80000000, v87
	v_mov_b32_e32 v9, v86
	v_pk_add_f32 v[86:87], v[68:69], v[8:9]
	v_pk_add_f32 v[8:9], v[68:69], v[8:9] neg_lo:[0,1] neg_hi:[0,1]
	v_pk_mul_f32 v[68:69], v[16:17], s[70:71] op_sel_hi:[1,0]
	s_nop 0
	v_pk_fma_f32 v[16:17], v[134:135], s[70:71], v[68:69] op_sel_hi:[1,0,1] neg_lo:[0,0,1] neg_hi:[0,0,1]
	v_xor_b32_e32 v134, 0x80000000, v73
	v_pk_add_f32 v[68:69], v[20:21], v[16:17]
	v_pk_add_f32 v[16:17], v[20:21], v[16:17] neg_lo:[0,1] neg_hi:[0,1]
	v_pk_add_f32 v[20:21], v[96:97], v[82:83]
	v_pk_add_f32 v[82:83], v[96:97], v[82:83] neg_lo:[0,1] neg_hi:[0,1]
	v_pk_mul_f32 v[96:97], v[14:15], s[70:71] op_sel:[1,0] op_sel_hi:[0,0] neg_lo:[1,0]
	v_mov_b32_e32 v135, v72
	v_pk_fma_f32 v[14:15], v[14:15], s[70:71], v[96:97] op_sel_hi:[1,0,1]
	s_nop 0
	v_pk_add_f32 v[96:97], v[18:19], v[14:15]
	v_pk_add_f32 v[14:15], v[18:19], v[14:15] neg_lo:[0,1] neg_hi:[0,1]
	v_xor_b32_e32 v18, 0x80000000, v75
	v_mov_b32_e32 v19, v74
	v_pk_add_f32 v[74:75], v[78:79], v[18:19]
	v_pk_add_f32 v[18:19], v[78:79], v[18:19] neg_lo:[0,1] neg_hi:[0,1]
	v_pk_mul_f32 v[78:79], v[72:73], s[70:71] op_sel_hi:[1,0]
	s_nop 0
	v_pk_fma_f32 v[72:73], v[134:135], s[70:71], v[78:79] op_sel_hi:[1,0,1] neg_lo:[0,0,1] neg_hi:[0,0,1]
	v_xor_b32_e32 v134, 0x80000000, v85
	v_pk_add_f32 v[78:79], v[24:25], v[72:73]
	v_pk_add_f32 v[24:25], v[24:25], v[72:73] neg_lo:[0,1] neg_hi:[0,1]
	v_pk_add_f32 v[72:73], v[76:77], v[130:131]
	v_pk_add_f32 v[76:77], v[76:77], v[130:131] neg_lo:[0,1] neg_hi:[0,1]
	v_pk_mul_f32 v[130:131], v[22:23], s[70:71] op_sel:[1,0] op_sel_hi:[0,0] neg_lo:[1,0]
	v_mov_b32_e32 v135, v84
	v_pk_fma_f32 v[22:23], v[22:23], s[70:71], v[130:131] op_sel_hi:[1,0,1]
	s_nop 0
	v_pk_add_f32 v[130:131], v[26:27], v[22:23]
	v_pk_add_f32 v[22:23], v[26:27], v[22:23] neg_lo:[0,1] neg_hi:[0,1]
	v_xor_b32_e32 v26, 0x80000000, v89
	v_mov_b32_e32 v27, v88
	v_pk_add_f32 v[88:89], v[92:93], v[26:27]
	v_pk_add_f32 v[26:27], v[92:93], v[26:27] neg_lo:[0,1] neg_hi:[0,1]
	v_pk_mul_f32 v[92:93], v[84:85], s[70:71] op_sel_hi:[1,0]
	s_nop 0
	v_pk_fma_f32 v[84:85], v[134:135], s[70:71], v[92:93] op_sel_hi:[1,0,1] neg_lo:[0,0,1] neg_hi:[0,0,1]
	v_xor_b32_e32 v134, 0x80000000, v7
	v_pk_add_f32 v[92:93], v[62:63], v[84:85]
	v_pk_add_f32 v[62:63], v[62:63], v[84:85] neg_lo:[0,1] neg_hi:[0,1]
	v_pk_add_f32 v[84:85], v[90:91], v[10:11]
	v_pk_add_f32 v[10:11], v[90:91], v[10:11] neg_lo:[0,1] neg_hi:[0,1]
	v_pk_mul_f32 v[90:91], v[94:95], s[62:63] op_sel:[1,0] op_sel_hi:[0,0] neg_lo:[1,0]
	v_mov_b32_e32 v135, v6
	v_pk_fma_f32 v[90:91], v[94:95], s[60:61], v[90:91] op_sel_hi:[1,0,1]
	s_nop 0
	v_pk_add_f32 v[94:95], v[132:133], v[90:91]
	v_pk_add_f32 v[90:91], v[132:133], v[90:91] neg_lo:[0,1] neg_hi:[0,1]
	v_pk_mul_f32 v[132:133], v[86:87], s[70:71] op_sel:[1,0] op_sel_hi:[0,0] neg_lo:[1,0]
	s_nop 0
	v_pk_fma_f32 v[86:87], v[86:87], s[70:71], v[132:133] op_sel_hi:[1,0,1]
	s_nop 0
	v_pk_add_f32 v[132:133], v[80:81], v[86:87]
	v_pk_add_f32 v[80:81], v[80:81], v[86:87] neg_lo:[0,1] neg_hi:[0,1]
	v_pk_mul_f32 v[86:87], v[68:69], s[60:61] op_sel:[1,0] op_sel_hi:[0,0] neg_lo:[1,0]
	s_nop 0
	v_pk_fma_f32 v[68:69], v[68:69], s[62:63], v[86:87] op_sel_hi:[1,0,1]
	s_nop 0
	v_pk_add_f32 v[86:87], v[12:13], v[68:69]
	v_pk_add_f32 v[12:13], v[12:13], v[68:69] neg_lo:[0,1] neg_hi:[0,1]
	v_xor_b32_e32 v68, 0x80000000, v71
	v_mov_b32_e32 v69, v70
	v_pk_add_f32 v[70:71], v[64:65], v[68:69]
	v_pk_add_f32 v[64:65], v[64:65], v[68:69] neg_lo:[0,1] neg_hi:[0,1]
	v_pk_mul_f32 v[68:69], v[6:7], s[62:63] op_sel_hi:[1,0]
	s_nop 0
	v_pk_fma_f32 v[6:7], v[134:135], s[60:61], v[68:69] op_sel_hi:[1,0,1] neg_lo:[0,0,1] neg_hi:[0,0,1]
	v_xor_b32_e32 v134, 0x80000000, v9
	v_pk_add_f32 v[68:69], v[2:3], v[6:7]
	v_pk_add_f32 v[2:3], v[2:3], v[6:7] neg_lo:[0,1] neg_hi:[0,1]
	v_pk_mul_f32 v[6:7], v[8:9], s[70:71] op_sel_hi:[1,0]
	v_mov_b32_e32 v135, v8
	v_pk_fma_f32 v[6:7], v[134:135], s[70:71], v[6:7] op_sel_hi:[1,0,1] neg_lo:[0,0,1] neg_hi:[0,0,1]
	v_xor_b32_e32 v134, 0x80000000, v17
	v_pk_add_f32 v[8:9], v[4:5], v[6:7]
	v_pk_add_f32 v[4:5], v[4:5], v[6:7] neg_lo:[0,1] neg_hi:[0,1]
	v_pk_mul_f32 v[6:7], v[16:17], s[60:61] op_sel_hi:[1,0]
	v_mov_b32_e32 v135, v16
	v_pk_fma_f32 v[6:7], v[134:135], s[62:63], v[6:7] op_sel_hi:[1,0,1] neg_lo:[0,0,1] neg_hi:[0,0,1]
	v_xor_b32_e32 v134, 0x80000000, v23
	v_pk_add_f32 v[16:17], v[0:1], v[6:7]
	v_pk_add_f32 v[0:1], v[0:1], v[6:7] neg_lo:[0,1] neg_hi:[0,1]
	v_pk_add_f32 v[6:7], v[20:21], v[72:73]
	v_pk_add_f32 v[20:21], v[20:21], v[72:73] neg_lo:[0,1] neg_hi:[0,1]
	v_pk_mul_f32 v[72:73], v[130:131], s[62:63] op_sel:[1,0] op_sel_hi:[0,0] neg_lo:[1,0]
	v_mov_b32_e32 v135, v22
	v_pk_fma_f32 v[72:73], v[130:131], s[60:61], v[72:73] op_sel_hi:[1,0,1]
	s_nop 0
	v_pk_add_f32 v[130:131], v[96:97], v[72:73]
	v_pk_add_f32 v[72:73], v[96:97], v[72:73] neg_lo:[0,1] neg_hi:[0,1]
	v_pk_mul_f32 v[96:97], v[88:89], s[70:71] op_sel:[1,0] op_sel_hi:[0,0] neg_lo:[1,0]
	s_nop 0
	v_pk_fma_f32 v[88:89], v[88:89], s[70:71], v[96:97] op_sel_hi:[1,0,1]
	s_nop 0
	v_pk_add_f32 v[96:97], v[74:75], v[88:89]
	v_pk_add_f32 v[74:75], v[74:75], v[88:89] neg_lo:[0,1] neg_hi:[0,1]
	v_pk_mul_f32 v[88:89], v[92:93], s[60:61] op_sel:[1,0] op_sel_hi:[0,0] neg_lo:[1,0]
	s_nop 0
	v_pk_fma_f32 v[88:89], v[92:93], s[62:63], v[88:89] op_sel_hi:[1,0,1]
	s_nop 0
	v_pk_add_f32 v[92:93], v[78:79], v[88:89]
	v_pk_add_f32 v[78:79], v[78:79], v[88:89] neg_lo:[0,1] neg_hi:[0,1]
	v_xor_b32_e32 v88, 0x80000000, v77
	v_mov_b32_e32 v89, v76
	v_pk_add_f32 v[76:77], v[82:83], v[88:89]
	v_pk_add_f32 v[82:83], v[82:83], v[88:89] neg_lo:[0,1] neg_hi:[0,1]
	v_pk_mul_f32 v[88:89], v[22:23], s[62:63] op_sel_hi:[1,0]
	s_nop 0
	v_pk_fma_f32 v[22:23], v[134:135], s[60:61], v[88:89] op_sel_hi:[1,0,1] neg_lo:[0,0,1] neg_hi:[0,0,1]
	v_xor_b32_e32 v134, 0x80000000, v27
	v_pk_add_f32 v[88:89], v[14:15], v[22:23]
	v_pk_add_f32 v[14:15], v[14:15], v[22:23] neg_lo:[0,1] neg_hi:[0,1]
	v_pk_mul_f32 v[22:23], v[26:27], s[70:71] op_sel_hi:[1,0]
	v_mov_b32_e32 v135, v26
	v_pk_fma_f32 v[22:23], v[134:135], s[70:71], v[22:23] op_sel_hi:[1,0,1] neg_lo:[0,0,1] neg_hi:[0,0,1]
	v_xor_b32_e32 v134, 0x80000000, v63
	v_pk_add_f32 v[26:27], v[18:19], v[22:23]
	v_pk_add_f32 v[18:19], v[18:19], v[22:23] neg_lo:[0,1] neg_hi:[0,1]
	v_pk_mul_f32 v[22:23], v[62:63], s[60:61] op_sel_hi:[1,0]
	v_mov_b32_e32 v135, v62
	v_pk_fma_f32 v[22:23], v[134:135], s[62:63], v[22:23] op_sel_hi:[1,0,1] neg_lo:[0,0,1] neg_hi:[0,0,1]
	v_xor_b32_e32 v134, 0x80000000, v73
	v_pk_add_f32 v[62:63], v[24:25], v[22:23]
	v_pk_add_f32 v[22:23], v[24:25], v[22:23] neg_lo:[0,1] neg_hi:[0,1]
	v_pk_add_f32 v[24:25], v[84:85], v[6:7]
	v_pk_add_f32 v[6:7], v[84:85], v[6:7] neg_lo:[0,1] neg_hi:[0,1]
	v_pk_mul_f32 v[84:85], v[130:131], s[58:59] op_sel:[1,0] op_sel_hi:[0,0] neg_lo:[1,0]
	v_mov_b32_e32 v135, v72
	v_pk_fma_f32 v[84:85], v[130:131], s[46:47], v[84:85] op_sel_hi:[1,0,1]
	s_nop 0
	v_pk_add_f32 v[130:131], v[94:95], v[84:85]
	v_pk_add_f32 v[84:85], v[94:95], v[84:85] neg_lo:[0,1] neg_hi:[0,1]
	v_pk_mul_f32 v[94:95], v[96:97], s[62:63] op_sel:[1,0] op_sel_hi:[0,0] neg_lo:[1,0]
	s_nop 0
	v_pk_fma_f32 v[94:95], v[96:97], s[60:61], v[94:95] op_sel_hi:[1,0,1]
	s_nop 0
	v_pk_add_f32 v[96:97], v[132:133], v[94:95]
	v_pk_add_f32 v[94:95], v[132:133], v[94:95] neg_lo:[0,1] neg_hi:[0,1]
	v_pk_mul_f32 v[132:133], v[92:93], s[66:67] op_sel:[1,0] op_sel_hi:[0,0] neg_lo:[1,0]
	s_nop 0
	v_pk_fma_f32 v[92:93], v[92:93], s[64:65], v[132:133] op_sel_hi:[1,0,1]
	s_nop 0
	v_pk_add_f32 v[132:133], v[86:87], v[92:93]
	v_pk_add_f32 v[86:87], v[86:87], v[92:93] neg_lo:[0,1] neg_hi:[0,1]
	v_pk_mul_f32 v[92:93], v[76:77], s[70:71] op_sel:[1,0] op_sel_hi:[0,0] neg_lo:[1,0]
	s_nop 0
	v_pk_fma_f32 v[76:77], v[76:77], s[70:71], v[92:93] op_sel_hi:[1,0,1]
	s_nop 0
	v_pk_add_f32 v[92:93], v[70:71], v[76:77]
	v_pk_add_f32 v[70:71], v[70:71], v[76:77] neg_lo:[0,1] neg_hi:[0,1]
	v_pk_mul_f32 v[76:77], v[88:89], s[64:65] op_sel:[1,0] op_sel_hi:[0,0] neg_lo:[1,0]
	s_nop 0
	v_pk_fma_f32 v[76:77], v[88:89], s[66:67], v[76:77] op_sel_hi:[1,0,1]
	s_nop 0
	v_pk_add_f32 v[88:89], v[68:69], v[76:77]
	v_pk_add_f32 v[68:69], v[68:69], v[76:77] neg_lo:[0,1] neg_hi:[0,1]
	v_pk_mul_f32 v[76:77], v[26:27], s[60:61] op_sel:[1,0] op_sel_hi:[0,0] neg_lo:[1,0]
	s_nop 0
	v_pk_fma_f32 v[26:27], v[26:27], s[62:63], v[76:77] op_sel_hi:[1,0,1]
	s_nop 0
	v_pk_add_f32 v[76:77], v[8:9], v[26:27]
	v_pk_add_f32 v[8:9], v[8:9], v[26:27] neg_lo:[0,1] neg_hi:[0,1]
	v_pk_mul_f32 v[26:27], v[62:63], s[46:47] op_sel:[1,0] op_sel_hi:[0,0] neg_lo:[1,0]
	s_nop 0
	v_pk_fma_f32 v[26:27], v[62:63], s[58:59], v[26:27] op_sel_hi:[1,0,1]
	s_nop 0
	v_pk_add_f32 v[62:63], v[16:17], v[26:27]
	v_pk_add_f32 v[16:17], v[16:17], v[26:27] neg_lo:[0,1] neg_hi:[0,1]
	v_xor_b32_e32 v26, 0x80000000, v21
	v_mov_b32_e32 v27, v20
	v_pk_add_f32 v[20:21], v[10:11], v[26:27]
	v_pk_add_f32 v[10:11], v[10:11], v[26:27] neg_lo:[0,1] neg_hi:[0,1]
	v_pk_mul_f32 v[26:27], v[72:73], s[58:59] op_sel_hi:[1,0]
	s_nop 0
	v_pk_fma_f32 v[26:27], v[134:135], s[46:47], v[26:27] op_sel_hi:[1,0,1] neg_lo:[0,0,1] neg_hi:[0,0,1]
	v_xor_b32_e32 v134, 0x80000000, v75
	v_pk_add_f32 v[72:73], v[90:91], v[26:27]
	v_pk_add_f32 v[26:27], v[90:91], v[26:27] neg_lo:[0,1] neg_hi:[0,1]
	v_pk_mul_f32 v[90:91], v[74:75], s[62:63] op_sel_hi:[1,0]
	v_mov_b32_e32 v135, v74
	v_pk_fma_f32 v[74:75], v[134:135], s[60:61], v[90:91] op_sel_hi:[1,0,1] neg_lo:[0,0,1] neg_hi:[0,0,1]
	v_xor_b32_e32 v134, 0x80000000, v79
	v_pk_add_f32 v[90:91], v[80:81], v[74:75]
	v_pk_add_f32 v[74:75], v[80:81], v[74:75] neg_lo:[0,1] neg_hi:[0,1]
	v_pk_mul_f32 v[80:81], v[78:79], s[66:67] op_sel_hi:[1,0]
	v_mov_b32_e32 v135, v78
	v_pk_fma_f32 v[78:79], v[134:135], s[64:65], v[80:81] op_sel_hi:[1,0,1] neg_lo:[0,0,1] neg_hi:[0,0,1]
	v_xor_b32_e32 v134, 0x80000000, v83
	v_pk_add_f32 v[80:81], v[12:13], v[78:79]
	v_pk_add_f32 v[12:13], v[12:13], v[78:79] neg_lo:[0,1] neg_hi:[0,1]
	v_pk_mul_f32 v[78:79], v[82:83], s[70:71] op_sel_hi:[1,0]
	v_mov_b32_e32 v135, v82
	v_pk_fma_f32 v[78:79], v[134:135], s[70:71], v[78:79] op_sel_hi:[1,0,1] neg_lo:[0,0,1] neg_hi:[0,0,1]
	v_xor_b32_e32 v134, 0x80000000, v15
	v_pk_add_f32 v[82:83], v[64:65], v[78:79]
	v_pk_add_f32 v[64:65], v[64:65], v[78:79] neg_lo:[0,1] neg_hi:[0,1]
	v_pk_mul_f32 v[78:79], v[14:15], s[64:65] op_sel_hi:[1,0]
	v_mov_b32_e32 v135, v14
	v_pk_fma_f32 v[14:15], v[134:135], s[66:67], v[78:79] op_sel_hi:[1,0,1] neg_lo:[0,0,1] neg_hi:[0,0,1]
	v_xor_b32_e32 v134, 0x80000000, v19
	v_pk_add_f32 v[78:79], v[2:3], v[14:15]
	v_pk_add_f32 v[2:3], v[2:3], v[14:15] neg_lo:[0,1] neg_hi:[0,1]
	v_pk_mul_f32 v[14:15], v[18:19], s[60:61] op_sel_hi:[1,0]
	v_mov_b32_e32 v135, v18
	v_pk_fma_f32 v[14:15], v[134:135], s[62:63], v[14:15] op_sel_hi:[1,0,1] neg_lo:[0,0,1] neg_hi:[0,0,1]
	v_xor_b32_e32 v134, 0x80000000, v23
	v_pk_add_f32 v[18:19], v[4:5], v[14:15]
	v_pk_add_f32 v[4:5], v[4:5], v[14:15] neg_lo:[0,1] neg_hi:[0,1]
	v_pk_mul_f32 v[14:15], v[22:23], s[46:47] op_sel_hi:[1,0]
	v_mov_b32_e32 v135, v22
	v_pk_fma_f32 v[14:15], v[134:135], s[58:59], v[14:15] op_sel_hi:[1,0,1] neg_lo:[0,0,1] neg_hi:[0,0,1]
	s_nop 0
	v_pk_add_f32 v[22:23], v[0:1], v[14:15]
	v_pk_add_f32 v[0:1], v[0:1], v[14:15] neg_lo:[0,1] neg_hi:[0,1]
	ds_write_b64 v67, v[24:25]
	ds_write_b64 v98, v[130:131]
	ds_write_b64 v99, v[96:97] offset:256
	ds_write_b64 v100, v[132:133] offset:256
	ds_write_b64 v101, v[92:93] offset:512
	ds_write_b64 v102, v[88:89] offset:512
	ds_write_b64 v103, v[76:77] offset:768
	ds_write_b64 v104, v[62:63] offset:768
	ds_write_b64 v105, v[20:21] offset:1024
	ds_write_b64 v106, v[72:73] offset:1024
	ds_write_b64 v107, v[90:91] offset:1280
	ds_write_b64 v108, v[80:81] offset:1280
	ds_write_b64 v109, v[82:83] offset:1536
	ds_write_b64 v110, v[78:79] offset:1536
	ds_write_b64 v111, v[18:19] offset:1792
	ds_write_b64 v112, v[22:23] offset:1792
	ds_write_b64 v113, v[6:7] offset:2048
	ds_write_b64 v114, v[84:85] offset:2048
	ds_write_b64 v115, v[94:95] offset:2304
	ds_write_b64 v116, v[86:87] offset:2304
	ds_write_b64 v117, v[70:71] offset:2560
	ds_write_b64 v118, v[68:69] offset:2560
	ds_write_b64 v119, v[8:9] offset:2816
	ds_write_b64 v120, v[16:17] offset:2816
	ds_write_b64 v121, v[10:11] offset:3072
	ds_write_b64 v122, v[26:27] offset:3072
	ds_write_b64 v123, v[74:75] offset:3328
	ds_write_b64 v124, v[12:13] offset:3328
	ds_write_b64 v125, v[64:65] offset:3584
	ds_write_b64 v126, v[2:3] offset:3584
	ds_write_b64 v127, v[4:5] offset:3840
	ds_write_b64 v128, v[0:1] offset:3840
	v_mov_b32_e32 v74, v146
	s_waitcnt lgkmcnt(0)
	s_barrier
	s_nop 0
	v_lshrrev_b32_e32 v0, 5, v74
	v_bfe_u32 v4, v74, 5, 4
	v_bitop3_b32 v0, v0, v74, 15 bitop3:0x6c
	v_bitop3_b32 v4, v4, v74, 16 bitop3:0x36
	v_lshlrev_b32_e32 v66, 3, v0
	v_lshlrev_b32_e32 v67, 3, v4
	v_add_u32_e32 v5, 16, v66
	v_add_u32_e32 v4, 16, v67
	v_add_u32_e32 v62, s47, v66
	v_add_u32_e32 v70, s9, v66
	ds_read2st64_b64 v[0:3], v5 offset1:16
	ds_read2st64_b64 v[16:19], v4 offset0:8 offset1:24
	ds_read2st64_b64 v[24:27], v5 offset0:32 offset1:48
	ds_read2st64_b64 v[8:11], v4 offset0:40 offset1:56
	ds_read2st64_b64 v[92:95], v5 offset0:64 offset1:80
	ds_read2st64_b64 v[12:15], v4 offset0:72 offset1:88
	ds_read2st64_b64 v[20:23], v5 offset0:96 offset1:112
	ds_read2st64_b64 v[4:7], v4 offset0:104 offset1:120
	ds_read_b64 v[68:69], v62
	ds_read_b64 v[72:73], v70
	v_add_u32_e32 v62, s19, v67
	v_add_u32_e32 v70, s8, v67
	ds_read_b64 v[84:85], v62
	ds_read_b64 v[90:91], v70
	v_add_u32_e32 v62, s18, v66
	v_add_u32_e32 v70, s7, v66
	ds_read_b64 v[96:97], v62
	ds_read_b64 v[100:101], v70
	v_add_u32_e32 v62, s17, v67
	v_add_u32_e32 v70, s6, v67
	ds_read_b64 v[64:65], v62
	ds_read_b64 v[70:71], v70
	v_add_u32_e32 v62, s13, v66
	v_add_u32_e32 v75, s5, v66
	ds_read_b64 v[86:87], v62
	ds_read_b64 v[102:103], v75
	v_add_u32_e32 v62, s12, v67
	v_add_u32_e32 v75, s4, v67
	ds_read_b64 v[80:81], v62
	ds_read_b64 v[88:89], v75
	v_add_u32_e32 v62, s11, v66
	v_add_u32_e32 v66, s1, v66
	ds_read_b64 v[98:99], v62
	ds_read_b64 v[104:105], v66
	v_add_u32_e32 v62, s10, v67
	v_add_u32_e32 v66, s0, v67
	ds_read_b64 v[62:63], v62
	ds_read_b64 v[66:67], v66
	s_waitcnt lgkmcnt(14)
	s_nop 0
	v_cvt_f32_i32_e32 v74, v74
	s_nop 0
	s_lshl_b64 s[0:1], s[44:45], 2
	s_add_u32 s0, s24, s0
	v_mul_f32_e32 v74, 0x38800000, v74
	v_cos_f32_e32 v78, v74
	v_sin_f32_e32 v79, v74
	s_addc_u32 s1, s59, s1
	s_and_b64 vcc, s[14:15], exec
	v_add_f32_e32 v76, v78, v78
	v_pk_mul_f32 v[74:75], v[78:79], v[78:79]
	v_mul_f32_e32 v76, v79, v76
	s_nop 0
	s_nop 0
	v_mov_b32_e32 v108, v79
	v_pk_add_f32 v[74:75], v[74:75], v[74:75] op_sel:[0,1] op_sel_hi:[0,1] neg_lo:[0,1] neg_hi:[0,1]
	v_pk_mul_f32 v[82:83], v[78:79], v[76:77] op_sel:[1,0] op_sel_hi:[0,0] neg_lo:[1,0]
	v_pk_mul_f32 v[106:107], v[68:69], v[108:109] op_sel:[1,0] op_sel_hi:[0,0] neg_lo:[1,0]
	v_pk_fma_f32 v[82:83], v[78:79], v[74:75], v[82:83]
	v_pk_fma_f32 v[68:69], v[68:69], v[78:79], v[106:107] op_sel_hi:[1,0,1]
	v_pk_mul_f32 v[78:79], v[76:77], s[48:49] op_sel_hi:[0,1]
	v_pk_fma_f32 v[106:107], v[74:75], s[40:41], v[78:79]
	s_nop 0
	v_pk_mul_f32 v[78:79], v[92:93], v[106:107] op_sel:[1,1] op_sel_hi:[0,1] neg_lo:[1,0]
	s_nop 0
	v_pk_fma_f32 v[78:79], v[92:93], v[106:107], v[78:79] op_sel_hi:[1,0,1]
	v_pk_mul_f32 v[92:93], v[76:77], v[82:83] op_sel:[0,1] op_sel_hi:[0,0] neg_lo:[0,1]
	v_pk_mul_f32 v[108:109], v[72:73], v[82:83] op_sel:[1,1] op_sel_hi:[0,1] neg_lo:[1,0]
	v_pk_fma_f32 v[92:93], v[74:75], v[82:83], v[92:93]
	v_pk_fma_f32 v[72:73], v[72:73], v[82:83], v[108:109] op_sel_hi:[1,0,1]
	v_pk_mul_f32 v[82:83], v[76:77], v[106:107] op_sel:[0,1] op_sel_hi:[0,0] neg_lo:[0,1]
	v_pk_fma_f32 v[106:107], v[74:75], v[106:107], v[82:83]
	s_nop 0
	v_pk_mul_f32 v[82:83], v[24:25], v[106:107] op_sel:[1,1] op_sel_hi:[0,1] neg_lo:[1,0]
	s_nop 0
	v_pk_fma_f32 v[82:83], v[24:25], v[106:107], v[82:83] op_sel_hi:[1,0,1]
	v_pk_mul_f32 v[24:25], v[76:77], v[92:93] op_sel:[0,1] op_sel_hi:[0,0] neg_lo:[0,1]
	v_pk_fma_f32 v[108:109], v[74:75], v[92:93], v[24:25]
	s_waitcnt lgkmcnt(7)
	v_pk_mul_f32 v[24:25], v[86:87], v[92:93] op_sel:[1,1] op_sel_hi:[0,1] neg_lo:[1,0]
	s_nop 0
	v_pk_fma_f32 v[24:25], v[86:87], v[92:93], v[24:25] op_sel_hi:[1,0,1]
	v_pk_mul_f32 v[86:87], v[76:77], v[106:107] op_sel:[0,1] op_sel_hi:[0,0] neg_lo:[0,1]
	v_pk_fma_f32 v[92:93], v[74:75], v[106:107], v[86:87]
	s_nop 0
	v_pk_mul_f32 v[86:87], v[20:21], v[92:93] op_sel:[1,1] op_sel_hi:[0,1] neg_lo:[1,0]
	s_nop 0
	v_pk_fma_f32 v[86:87], v[20:21], v[92:93], v[86:87] op_sel_hi:[1,0,1]
	v_pk_mul_f32 v[20:21], v[76:77], v[108:109] op_sel:[0,1] op_sel_hi:[0,0] neg_lo:[0,1]
	v_pk_fma_f32 v[106:107], v[74:75], v[108:109], v[20:21]
	s_waitcnt lgkmcnt(6)
	v_pk_mul_f32 v[20:21], v[102:103], v[108:109] op_sel:[1,1] op_sel_hi:[0,1] neg_lo:[1,0]
	s_nop 0
	v_pk_fma_f32 v[20:21], v[102:103], v[108:109], v[20:21] op_sel_hi:[1,0,1]
	v_pk_mul_f32 v[102:103], v[76:77], v[92:93] op_sel:[0,1] op_sel_hi:[0,0] neg_lo:[0,1]
	v_pk_fma_f32 v[102:103], v[74:75], v[92:93], v[102:103]
	s_nop 0
	v_pk_mul_f32 v[92:93], v[2:3], v[102:103] op_sel:[1,1] op_sel_hi:[0,1] neg_lo:[1,0]
	s_nop 0
	v_pk_fma_f32 v[92:93], v[2:3], v[102:103], v[92:93] op_sel_hi:[1,0,1]
	v_pk_mul_f32 v[2:3], v[76:77], v[106:107] op_sel:[0,1] op_sel_hi:[0,0] neg_lo:[0,1]
	v_pk_fma_f32 v[108:109], v[74:75], v[106:107], v[2:3]
	v_pk_mul_f32 v[2:3], v[96:97], v[106:107] op_sel:[1,1] op_sel_hi:[0,1] neg_lo:[1,0]
	s_nop 0
	v_pk_fma_f32 v[2:3], v[96:97], v[106:107], v[2:3] op_sel_hi:[1,0,1]
	v_pk_mul_f32 v[96:97], v[76:77], v[102:103] op_sel:[0,1] op_sel_hi:[0,0] neg_lo:[0,1]
	v_pk_fma_f32 v[102:103], v[74:75], v[102:103], v[96:97]
	s_nop 0
	v_pk_mul_f32 v[96:97], v[94:95], v[102:103] op_sel:[1,1] op_sel_hi:[0,1] neg_lo:[1,0]
	s_nop 0
	v_pk_fma_f32 v[96:97], v[94:95], v[102:103], v[96:97] op_sel_hi:[1,0,1]
	v_pk_mul_f32 v[94:95], v[76:77], v[108:109] op_sel:[0,1] op_sel_hi:[0,0] neg_lo:[0,1]
	v_pk_fma_f32 v[106:107], v[74:75], v[108:109], v[94:95]
	v_pk_mul_f32 v[94:95], v[100:101], v[108:109] op_sel:[1,1] op_sel_hi:[0,1] neg_lo:[1,0]
	s_nop 0
	v_pk_fma_f32 v[94:95], v[100:101], v[108:109], v[94:95] op_sel_hi:[1,0,1]
	v_pk_mul_f32 v[100:101], v[76:77], v[102:103] op_sel:[0,1] op_sel_hi:[0,0] neg_lo:[0,1]
	v_pk_fma_f32 v[100:101], v[74:75], v[102:103], v[100:101]
	s_nop 0
	v_pk_mul_f32 v[102:103], v[26:27], v[100:101] op_sel:[1,1] op_sel_hi:[0,1] neg_lo:[1,0]
	s_waitcnt lgkmcnt(3)
	v_pk_fma_f32 v[26:27], v[26:27], v[100:101], v[102:103] op_sel_hi:[1,0,1]
	v_pk_mul_f32 v[102:103], v[76:77], v[106:107] op_sel:[0,1] op_sel_hi:[0,0] neg_lo:[0,1]
	v_pk_mul_f32 v[108:109], v[98:99], v[106:107] op_sel:[1,1] op_sel_hi:[0,1] neg_lo:[1,0]
	v_pk_fma_f32 v[102:103], v[74:75], v[106:107], v[102:103]
	v_pk_fma_f32 v[98:99], v[98:99], v[106:107], v[108:109] op_sel_hi:[1,0,1]
	v_pk_mul_f32 v[106:107], v[76:77], v[100:101] op_sel:[0,1] op_sel_hi:[0,0] neg_lo:[0,1]
	v_pk_fma_f32 v[100:101], v[74:75], v[100:101], v[106:107]
	s_nop 0
	v_pk_mul_f32 v[106:107], v[22:23], v[100:101] op_sel:[1,1] op_sel_hi:[0,1] neg_lo:[1,0]
	s_waitcnt lgkmcnt(2)
	v_pk_fma_f32 v[22:23], v[22:23], v[100:101], v[106:107] op_sel_hi:[1,0,1]
	v_pk_mul_f32 v[106:107], v[76:77], v[102:103] op_sel:[0,1] op_sel_hi:[0,0] neg_lo:[0,1]
	v_pk_mul_f32 v[108:109], v[104:105], v[102:103] op_sel:[1,1] op_sel_hi:[0,1] neg_lo:[1,0]
	v_pk_fma_f32 v[106:107], v[74:75], v[102:103], v[106:107]
	v_pk_fma_f32 v[102:103], v[104:105], v[102:103], v[108:109] op_sel_hi:[1,0,1]
	v_pk_mul_f32 v[104:105], v[76:77], v[100:101] op_sel:[0,1] op_sel_hi:[0,0] neg_lo:[0,1]
	v_pk_fma_f32 v[100:101], v[74:75], v[100:101], v[104:105]
	s_nop 0
	v_pk_mul_f32 v[104:105], v[16:17], v[100:101] op_sel:[1,1] op_sel_hi:[0,1] neg_lo:[1,0]
	s_nop 0
	v_pk_fma_f32 v[16:17], v[16:17], v[100:101], v[104:105] op_sel_hi:[1,0,1]
	v_pk_mul_f32 v[104:105], v[76:77], v[106:107] op_sel:[0,1] op_sel_hi:[0,0] neg_lo:[0,1]
	v_pk_mul_f32 v[108:109], v[84:85], v[106:107] op_sel:[1,1] op_sel_hi:[0,1] neg_lo:[1,0]
	v_pk_fma_f32 v[104:105], v[74:75], v[106:107], v[104:105]
	v_pk_fma_f32 v[84:85], v[84:85], v[106:107], v[108:109] op_sel_hi:[1,0,1]
	v_pk_mul_f32 v[106:107], v[76:77], v[100:101] op_sel:[0,1] op_sel_hi:[0,0] neg_lo:[0,1]
	v_pk_fma_f32 v[100:101], v[74:75], v[100:101], v[106:107]
	s_nop 0
	v_pk_mul_f32 v[106:107], v[12:13], v[100:101] op_sel:[1,1] op_sel_hi:[0,1] neg_lo:[1,0]
	s_nop 0
	v_pk_fma_f32 v[12:13], v[12:13], v[100:101], v[106:107] op_sel_hi:[1,0,1]
	v_pk_mul_f32 v[106:107], v[76:77], v[104:105] op_sel:[0,1] op_sel_hi:[0,0] neg_lo:[0,1]
	v_pk_mul_f32 v[108:109], v[90:91], v[104:105] op_sel:[1,1] op_sel_hi:[0,1] neg_lo:[1,0]
	v_pk_fma_f32 v[106:107], v[74:75], v[104:105], v[106:107]
	v_pk_fma_f32 v[90:91], v[90:91], v[104:105], v[108:109] op_sel_hi:[1,0,1]
	v_pk_mul_f32 v[104:105], v[76:77], v[100:101] op_sel:[0,1] op_sel_hi:[0,0] neg_lo:[0,1]
	v_pk_fma_f32 v[100:101], v[74:75], v[100:101], v[104:105]
	s_nop 0
	v_pk_mul_f32 v[104:105], v[8:9], v[100:101] op_sel:[1,1] op_sel_hi:[0,1] neg_lo:[1,0]
	s_nop 0
	v_pk_fma_f32 v[8:9], v[8:9], v[100:101], v[104:105] op_sel_hi:[1,0,1]
	v_pk_mul_f32 v[104:105], v[76:77], v[106:107] op_sel:[0,1] op_sel_hi:[0,0] neg_lo:[0,1]
	v_pk_mul_f32 v[108:109], v[80:81], v[106:107] op_sel:[1,1] op_sel_hi:[0,1] neg_lo:[1,0]
	v_pk_fma_f32 v[104:105], v[74:75], v[106:107], v[104:105]
	v_pk_fma_f32 v[80:81], v[80:81], v[106:107], v[108:109] op_sel_hi:[1,0,1]
	v_pk_mul_f32 v[106:107], v[76:77], v[100:101] op_sel:[0,1] op_sel_hi:[0,0] neg_lo:[0,1]
	v_pk_fma_f32 v[100:101], v[74:75], v[100:101], v[106:107]
	s_nop 0
	v_pk_mul_f32 v[106:107], v[4:5], v[100:101] op_sel:[1,1] op_sel_hi:[0,1] neg_lo:[1,0]
	s_nop 0
	v_pk_fma_f32 v[4:5], v[4:5], v[100:101], v[106:107] op_sel_hi:[1,0,1]
	v_pk_mul_f32 v[106:107], v[76:77], v[104:105] op_sel:[0,1] op_sel_hi:[0,0] neg_lo:[0,1]
	v_pk_mul_f32 v[108:109], v[88:89], v[104:105] op_sel:[1,1] op_sel_hi:[0,1] neg_lo:[1,0]
	v_pk_fma_f32 v[106:107], v[74:75], v[104:105], v[106:107]
	v_pk_fma_f32 v[88:89], v[88:89], v[104:105], v[108:109] op_sel_hi:[1,0,1]
	v_pk_mul_f32 v[104:105], v[76:77], v[100:101] op_sel:[0,1] op_sel_hi:[0,0] neg_lo:[0,1]
	v_pk_fma_f32 v[100:101], v[74:75], v[100:101], v[104:105]
	s_nop 0
	v_pk_mul_f32 v[104:105], v[18:19], v[100:101] op_sel:[1,1] op_sel_hi:[0,1] neg_lo:[1,0]
	s_nop 0
	v_pk_fma_f32 v[18:19], v[18:19], v[100:101], v[104:105] op_sel_hi:[1,0,1]
	v_pk_mul_f32 v[104:105], v[76:77], v[106:107] op_sel:[0,1] op_sel_hi:[0,0] neg_lo:[0,1]
	v_pk_mul_f32 v[108:109], v[64:65], v[106:107] op_sel:[1,1] op_sel_hi:[0,1] neg_lo:[1,0]
	v_pk_fma_f32 v[104:105], v[74:75], v[106:107], v[104:105]
	v_pk_fma_f32 v[64:65], v[64:65], v[106:107], v[108:109] op_sel_hi:[1,0,1]
	v_pk_mul_f32 v[106:107], v[76:77], v[100:101] op_sel:[0,1] op_sel_hi:[0,0] neg_lo:[0,1]
	v_pk_fma_f32 v[100:101], v[74:75], v[100:101], v[106:107]
	s_nop 0
	v_pk_mul_f32 v[106:107], v[14:15], v[100:101] op_sel:[1,1] op_sel_hi:[0,1] neg_lo:[1,0]
	s_nop 0
	v_pk_fma_f32 v[14:15], v[14:15], v[100:101], v[106:107] op_sel_hi:[1,0,1]
	v_pk_mul_f32 v[106:107], v[76:77], v[104:105] op_sel:[0,1] op_sel_hi:[0,0] neg_lo:[0,1]
	v_pk_mul_f32 v[108:109], v[70:71], v[104:105] op_sel:[1,1] op_sel_hi:[0,1] neg_lo:[1,0]
	v_pk_fma_f32 v[106:107], v[74:75], v[104:105], v[106:107]
	v_pk_fma_f32 v[70:71], v[70:71], v[104:105], v[108:109] op_sel_hi:[1,0,1]
	v_pk_mul_f32 v[104:105], v[76:77], v[100:101] op_sel:[0,1] op_sel_hi:[0,0] neg_lo:[0,1]
	v_pk_fma_f32 v[100:101], v[74:75], v[100:101], v[104:105]
	s_nop 0
	v_pk_mul_f32 v[104:105], v[10:11], v[100:101] op_sel:[1,1] op_sel_hi:[0,1] neg_lo:[1,0]
	s_waitcnt lgkmcnt(1)
	v_pk_fma_f32 v[10:11], v[10:11], v[100:101], v[104:105] op_sel_hi:[1,0,1]
	v_pk_mul_f32 v[104:105], v[76:77], v[106:107] op_sel:[0,1] op_sel_hi:[0,0] neg_lo:[0,1]
	v_pk_mul_f32 v[108:109], v[62:63], v[106:107] op_sel:[1,1] op_sel_hi:[0,1] neg_lo:[1,0]
	v_pk_fma_f32 v[104:105], v[74:75], v[106:107], v[104:105]
	v_pk_fma_f32 v[62:63], v[62:63], v[106:107], v[108:109] op_sel_hi:[1,0,1]
	v_pk_mul_f32 v[76:77], v[76:77], v[100:101] op_sel:[0,1] op_sel_hi:[0,0] neg_lo:[0,1]
	v_pk_fma_f32 v[74:75], v[74:75], v[100:101], v[76:77]
	s_nop 0
	v_pk_mul_f32 v[76:77], v[6:7], v[74:75] op_sel:[1,1] op_sel_hi:[0,1] neg_lo:[1,0]
	s_nop 0
	v_pk_fma_f32 v[6:7], v[6:7], v[74:75], v[76:77] op_sel_hi:[1,0,1]
	s_waitcnt lgkmcnt(0)
	v_pk_mul_f32 v[74:75], v[66:67], v[104:105] op_sel:[1,1] op_sel_hi:[0,1] neg_lo:[1,0]
	v_pk_add_f32 v[76:77], v[82:83], v[8:9]
	v_pk_fma_f32 v[66:67], v[66:67], v[104:105], v[74:75] op_sel_hi:[1,0,1]
	v_pk_add_f32 v[74:75], v[0:1], v[16:17]
	v_pk_add_f32 v[0:1], v[0:1], v[16:17] neg_lo:[0,1] neg_hi:[0,1]
	v_pk_add_f32 v[16:17], v[92:93], v[18:19]
	v_pk_add_f32 v[18:19], v[92:93], v[18:19] neg_lo:[0,1] neg_hi:[0,1]
	v_pk_add_f32 v[8:9], v[82:83], v[8:9] neg_lo:[0,1] neg_hi:[0,1]
	v_pk_add_f32 v[82:83], v[26:27], v[10:11]
	v_pk_add_f32 v[10:11], v[26:27], v[10:11] neg_lo:[0,1] neg_hi:[0,1]
	v_pk_add_f32 v[92:93], v[86:87], v[4:5]
	v_pk_add_f32 v[4:5], v[86:87], v[4:5] neg_lo:[0,1] neg_hi:[0,1]
	v_pk_add_f32 v[86:87], v[22:23], v[6:7]
	v_pk_add_f32 v[6:7], v[22:23], v[6:7] neg_lo:[0,1] neg_hi:[0,1]
	v_pk_add_f32 v[22:23], v[68:69], v[84:85]
	v_pk_add_f32 v[68:69], v[68:69], v[84:85] neg_lo:[0,1] neg_hi:[0,1]
	v_pk_add_f32 v[84:85], v[2:3], v[64:65]
	v_pk_add_f32 v[2:3], v[2:3], v[64:65] neg_lo:[0,1] neg_hi:[0,1]
	v_pk_add_f32 v[64:65], v[24:25], v[80:81]
	v_pk_add_f32 v[24:25], v[24:25], v[80:81] neg_lo:[0,1] neg_hi:[0,1]
	v_pk_add_f32 v[80:81], v[98:99], v[62:63]
	v_pk_add_f32 v[62:63], v[98:99], v[62:63] neg_lo:[0,1] neg_hi:[0,1]
	v_pk_add_f32 v[98:99], v[74:75], v[16:17]
	v_pk_add_f32 v[16:17], v[74:75], v[16:17] neg_lo:[0,1] neg_hi:[0,1]
	v_xor_b32_e32 v74, 0x80000000, v19
	v_mov_b32_e32 v75, v18
	v_pk_add_f32 v[26:27], v[78:79], v[12:13]
	v_pk_add_f32 v[12:13], v[78:79], v[12:13] neg_lo:[0,1] neg_hi:[0,1]
	v_pk_add_f32 v[78:79], v[96:97], v[14:15]
	v_pk_add_f32 v[14:15], v[96:97], v[14:15] neg_lo:[0,1] neg_hi:[0,1]
	v_pk_add_f32 v[18:19], v[0:1], v[74:75]
	v_pk_add_f32 v[0:1], v[0:1], v[74:75] neg_lo:[0,1] neg_hi:[0,1]
	v_pk_add_f32 v[74:75], v[76:77], v[82:83]
	v_pk_add_f32 v[76:77], v[76:77], v[82:83] neg_lo:[0,1] neg_hi:[0,1]
	v_xor_b32_e32 v82, 0x80000000, v11
	v_mov_b32_e32 v83, v10
	v_pk_add_f32 v[10:11], v[8:9], v[82:83]
	v_pk_add_f32 v[8:9], v[8:9], v[82:83] neg_lo:[0,1] neg_hi:[0,1]
	v_pk_add_f32 v[82:83], v[26:27], v[78:79]
	v_pk_add_f32 v[26:27], v[26:27], v[78:79] neg_lo:[0,1] neg_hi:[0,1]
	v_xor_b32_e32 v78, 0x80000000, v15
	v_mov_b32_e32 v79, v14
	v_pk_add_f32 v[14:15], v[12:13], v[78:79]
	v_pk_add_f32 v[12:13], v[12:13], v[78:79] neg_lo:[0,1] neg_hi:[0,1]
	v_pk_add_f32 v[78:79], v[92:93], v[86:87]
	v_pk_add_f32 v[86:87], v[92:93], v[86:87] neg_lo:[0,1] neg_hi:[0,1]
	v_xor_b32_e32 v92, 0x80000000, v7
	v_mov_b32_e32 v93, v6
	v_pk_add_f32 v[6:7], v[4:5], v[92:93]
	v_pk_add_f32 v[4:5], v[4:5], v[92:93] neg_lo:[0,1] neg_hi:[0,1]
	v_pk_add_f32 v[92:93], v[22:23], v[84:85]
	v_pk_add_f32 v[22:23], v[22:23], v[84:85] neg_lo:[0,1] neg_hi:[0,1]
	v_xor_b32_e32 v84, 0x80000000, v3
	v_mov_b32_e32 v85, v2
	v_pk_add_f32 v[96:97], v[72:73], v[90:91]
	v_pk_add_f32 v[72:73], v[72:73], v[90:91] neg_lo:[0,1] neg_hi:[0,1]
	v_pk_add_f32 v[90:91], v[94:95], v[70:71]
	v_pk_add_f32 v[70:71], v[94:95], v[70:71] neg_lo:[0,1] neg_hi:[0,1]
	v_pk_add_f32 v[2:3], v[68:69], v[84:85]
	v_pk_add_f32 v[68:69], v[68:69], v[84:85] neg_lo:[0,1] neg_hi:[0,1]
	v_pk_add_f32 v[84:85], v[64:65], v[80:81]
	v_pk_add_f32 v[64:65], v[64:65], v[80:81] neg_lo:[0,1] neg_hi:[0,1]
	v_xor_b32_e32 v80, 0x80000000, v63
	v_mov_b32_e32 v81, v62
	v_pk_add_f32 v[94:95], v[20:21], v[88:89]
	v_pk_add_f32 v[20:21], v[20:21], v[88:89] neg_lo:[0,1] neg_hi:[0,1]
	v_pk_add_f32 v[88:89], v[102:103], v[66:67]
	v_pk_add_f32 v[66:67], v[102:103], v[66:67] neg_lo:[0,1] neg_hi:[0,1]
	v_pk_add_f32 v[62:63], v[24:25], v[80:81]
	v_pk_add_f32 v[24:25], v[24:25], v[80:81] neg_lo:[0,1] neg_hi:[0,1]
	v_pk_add_f32 v[80:81], v[96:97], v[90:91]
	v_pk_add_f32 v[90:91], v[96:97], v[90:91] neg_lo:[0,1] neg_hi:[0,1]
	v_xor_b32_e32 v96, 0x80000000, v71
	v_mov_b32_e32 v97, v70
	v_pk_add_f32 v[70:71], v[72:73], v[96:97]
	v_pk_add_f32 v[72:73], v[72:73], v[96:97] neg_lo:[0,1] neg_hi:[0,1]
	v_pk_add_f32 v[96:97], v[94:95], v[88:89]
	v_pk_add_f32 v[88:89], v[94:95], v[88:89] neg_lo:[0,1] neg_hi:[0,1]
	v_xor_b32_e32 v94, 0x80000000, v67
	v_mov_b32_e32 v95, v66
	v_pk_add_f32 v[66:67], v[20:21], v[94:95]
	v_pk_add_f32 v[20:21], v[20:21], v[94:95] neg_lo:[0,1] neg_hi:[0,1]
	v_pk_add_f32 v[94:95], v[98:99], v[74:75]
	v_pk_add_f32 v[74:75], v[98:99], v[74:75] neg_lo:[0,1] neg_hi:[0,1]
	v_pk_mul_f32 v[98:99], v[10:11], s[70:71] op_sel:[1,0] op_sel_hi:[0,0] neg_lo:[1,0]
	v_xor_b32_e32 v100, 0x80000000, v9
	v_pk_fma_f32 v[10:11], v[10:11], s[70:71], v[98:99] op_sel_hi:[1,0,1]
	v_mov_b32_e32 v101, v8
	v_pk_add_f32 v[98:99], v[18:19], v[10:11]
	v_pk_add_f32 v[10:11], v[18:19], v[10:11] neg_lo:[0,1] neg_hi:[0,1]
	v_xor_b32_e32 v18, 0x80000000, v77
	v_mov_b32_e32 v19, v76
	v_pk_add_f32 v[76:77], v[16:17], v[18:19]
	v_pk_add_f32 v[16:17], v[16:17], v[18:19] neg_lo:[0,1] neg_hi:[0,1]
	v_pk_mul_f32 v[18:19], v[8:9], s[70:71] op_sel_hi:[1,0]
	s_nop 0
	v_pk_fma_f32 v[8:9], v[100:101], s[70:71], v[18:19] op_sel_hi:[1,0,1] neg_lo:[0,0,1] neg_hi:[0,0,1]
	v_xor_b32_e32 v100, 0x80000000, v5
	v_pk_add_f32 v[18:19], v[0:1], v[8:9]
	v_pk_add_f32 v[0:1], v[0:1], v[8:9] neg_lo:[0,1] neg_hi:[0,1]
	v_pk_add_f32 v[8:9], v[82:83], v[78:79]
	v_pk_add_f32 v[78:79], v[82:83], v[78:79] neg_lo:[0,1] neg_hi:[0,1]
	v_pk_mul_f32 v[82:83], v[6:7], s[70:71] op_sel:[1,0] op_sel_hi:[0,0] neg_lo:[1,0]
	v_mov_b32_e32 v101, v4
	v_pk_fma_f32 v[6:7], v[6:7], s[70:71], v[82:83] op_sel_hi:[1,0,1]
	s_nop 0
	v_pk_add_f32 v[82:83], v[14:15], v[6:7]
	v_pk_add_f32 v[6:7], v[14:15], v[6:7] neg_lo:[0,1] neg_hi:[0,1]
	v_xor_b32_e32 v14, 0x80000000, v87
	v_mov_b32_e32 v15, v86
	v_pk_add_f32 v[86:87], v[26:27], v[14:15]
	v_pk_add_f32 v[14:15], v[26:27], v[14:15] neg_lo:[0,1] neg_hi:[0,1]
	v_pk_mul_f32 v[26:27], v[4:5], s[70:71] op_sel_hi:[1,0]
	s_nop 0
	v_pk_fma_f32 v[4:5], v[100:101], s[70:71], v[26:27] op_sel_hi:[1,0,1] neg_lo:[0,0,1] neg_hi:[0,0,1]
	v_xor_b32_e32 v100, 0x80000000, v25
	v_pk_add_f32 v[26:27], v[12:13], v[4:5]
	v_pk_add_f32 v[4:5], v[12:13], v[4:5] neg_lo:[0,1] neg_hi:[0,1]
	v_pk_add_f32 v[12:13], v[92:93], v[84:85]
	v_pk_add_f32 v[84:85], v[92:93], v[84:85] neg_lo:[0,1] neg_hi:[0,1]
	v_pk_mul_f32 v[92:93], v[62:63], s[70:71] op_sel:[1,0] op_sel_hi:[0,0] neg_lo:[1,0]
	v_mov_b32_e32 v101, v24
	v_pk_fma_f32 v[62:63], v[62:63], s[70:71], v[92:93] op_sel_hi:[1,0,1]
	s_nop 0
	v_pk_add_f32 v[92:93], v[2:3], v[62:63]
	v_pk_add_f32 v[2:3], v[2:3], v[62:63] neg_lo:[0,1] neg_hi:[0,1]
	v_xor_b32_e32 v62, 0x80000000, v65
	v_mov_b32_e32 v63, v64
	v_pk_add_f32 v[64:65], v[22:23], v[62:63]
	v_pk_add_f32 v[22:23], v[22:23], v[62:63] neg_lo:[0,1] neg_hi:[0,1]
	v_pk_mul_f32 v[62:63], v[24:25], s[70:71] op_sel_hi:[1,0]
	s_nop 0
	v_pk_fma_f32 v[24:25], v[100:101], s[70:71], v[62:63] op_sel_hi:[1,0,1] neg_lo:[0,0,1] neg_hi:[0,0,1]
	v_xor_b32_e32 v100, 0x80000000, v21
	v_pk_add_f32 v[62:63], v[68:69], v[24:25]
	v_pk_add_f32 v[24:25], v[68:69], v[24:25] neg_lo:[0,1] neg_hi:[0,1]
	v_pk_add_f32 v[68:69], v[80:81], v[96:97]
	v_pk_add_f32 v[80:81], v[80:81], v[96:97] neg_lo:[0,1] neg_hi:[0,1]
	v_pk_mul_f32 v[96:97], v[66:67], s[70:71] op_sel:[1,0] op_sel_hi:[0,0] neg_lo:[1,0]
	v_mov_b32_e32 v101, v20
	v_pk_fma_f32 v[66:67], v[66:67], s[70:71], v[96:97] op_sel_hi:[1,0,1]
	s_nop 0
	v_pk_add_f32 v[96:97], v[70:71], v[66:67]
	v_pk_add_f32 v[66:67], v[70:71], v[66:67] neg_lo:[0,1] neg_hi:[0,1]
	v_xor_b32_e32 v70, 0x80000000, v89
	v_mov_b32_e32 v71, v88
	v_pk_add_f32 v[88:89], v[90:91], v[70:71]
	v_pk_add_f32 v[70:71], v[90:91], v[70:71] neg_lo:[0,1] neg_hi:[0,1]
	v_pk_mul_f32 v[90:91], v[20:21], s[70:71] op_sel_hi:[1,0]
	s_nop 0
	v_pk_fma_f32 v[20:21], v[100:101], s[70:71], v[90:91] op_sel_hi:[1,0,1] neg_lo:[0,0,1] neg_hi:[0,0,1]
	s_nop 0
	v_pk_add_f32 v[90:91], v[72:73], v[20:21]
	v_pk_add_f32 v[20:21], v[72:73], v[20:21] neg_lo:[0,1] neg_hi:[0,1]
	v_pk_add_f32 v[72:73], v[94:95], v[8:9]
	v_pk_add_f32 v[8:9], v[94:95], v[8:9] neg_lo:[0,1] neg_hi:[0,1]
	v_pk_mul_f32 v[94:95], v[82:83], s[62:63] op_sel:[1,0] op_sel_hi:[0,0] neg_lo:[1,0]
	s_nop 0
	v_pk_fma_f32 v[82:83], v[82:83], s[60:61], v[94:95] op_sel_hi:[1,0,1]
	s_nop 0
	v_pk_add_f32 v[94:95], v[98:99], v[82:83]
	v_pk_add_f32 v[82:83], v[98:99], v[82:83] neg_lo:[0,1] neg_hi:[0,1]
	v_pk_mul_f32 v[98:99], v[86:87], s[70:71] op_sel:[1,0] op_sel_hi:[0,0] neg_lo:[1,0]
	s_nop 0
	v_pk_fma_f32 v[86:87], v[86:87], s[70:71], v[98:99] op_sel_hi:[1,0,1]
	s_nop 0
	v_pk_add_f32 v[98:99], v[76:77], v[86:87]
	v_pk_add_f32 v[86:87], v[76:77], v[86:87] neg_lo:[0,1] neg_hi:[0,1]
	v_pk_mul_f32 v[76:77], v[26:27], s[60:61] op_sel:[1,0] op_sel_hi:[0,0] neg_lo:[1,0]
	s_nop 0
	v_pk_fma_f32 v[26:27], v[26:27], s[62:63], v[76:77] op_sel_hi:[1,0,1]
	v_xor_b32_e32 v76, 0x80000000, v67
	v_pk_add_f32 v[100:101], v[18:19], v[26:27]
	v_pk_add_f32 v[26:27], v[18:19], v[26:27] neg_lo:[0,1] neg_hi:[0,1]
	v_pk_add_f32 v[102:103], v[74:75], v[78:79] op_sel:[0,1] op_sel_hi:[1,0] neg_lo:[0,1]
	v_pk_add_f32 v[104:105], v[74:75], v[78:79] op_sel:[0,1] op_sel_hi:[1,0] neg_hi:[0,1]
	v_pk_mul_f32 v[18:19], v[6:7], s[62:63] op_sel_hi:[1,0]
	v_xor_b32_e32 v74, 0x80000000, v7
	v_mov_b32_e32 v75, v6
	v_pk_fma_f32 v[6:7], v[74:75], s[60:61], v[18:19] op_sel_hi:[1,0,1] neg_lo:[0,0,1] neg_hi:[0,0,1]
	v_xor_b32_e32 v74, 0x80000000, v15
	v_pk_add_f32 v[18:19], v[10:11], v[6:7]
	v_pk_add_f32 v[6:7], v[10:11], v[6:7] neg_lo:[0,1] neg_hi:[0,1]
	v_pk_mul_f32 v[10:11], v[14:15], s[70:71] op_sel_hi:[1,0]
	v_mov_b32_e32 v75, v14
	v_pk_fma_f32 v[10:11], v[74:75], s[70:71], v[10:11] op_sel_hi:[1,0,1] neg_lo:[0,0,1] neg_hi:[0,0,1]
	v_xor_b32_e32 v74, 0x80000000, v5
	v_pk_add_f32 v[14:15], v[16:17], v[10:11]
	v_pk_add_f32 v[10:11], v[16:17], v[10:11] neg_lo:[0,1] neg_hi:[0,1]
	v_pk_mul_f32 v[16:17], v[4:5], s[60:61] op_sel_hi:[1,0]
	v_mov_b32_e32 v75, v4
	v_pk_fma_f32 v[4:5], v[74:75], s[62:63], v[16:17] op_sel_hi:[1,0,1] neg_lo:[0,0,1] neg_hi:[0,0,1]
	v_xor_b32_e32 v74, 0x80000000, v89
	v_pk_add_f32 v[16:17], v[0:1], v[4:5]
	v_pk_add_f32 v[106:107], v[0:1], v[4:5] neg_lo:[0,1] neg_hi:[0,1]
	v_pk_add_f32 v[0:1], v[12:13], v[68:69]
	v_pk_add_f32 v[4:5], v[12:13], v[68:69] neg_lo:[0,1] neg_hi:[0,1]
	v_mov_b32_e32 v75, v88
	v_pk_mul_f32 v[12:13], v[96:97], s[62:63] op_sel:[1,0] op_sel_hi:[0,0] neg_lo:[1,0]
	v_pk_mul_f32 v[74:75], v[74:75], s[70:71] op_sel_hi:[1,0]
	v_pk_fma_f32 v[12:13], v[96:97], s[60:61], v[12:13] op_sel_hi:[1,0,1]
	v_pk_fma_f32 v[74:75], v[88:89], s[70:71], v[74:75] op_sel_hi:[1,0,1]
	v_pk_add_f32 v[68:69], v[92:93], v[12:13]
	v_pk_add_f32 v[12:13], v[92:93], v[12:13] neg_lo:[0,1] neg_hi:[0,1]
	v_pk_add_f32 v[88:89], v[64:65], v[74:75]
	v_pk_add_f32 v[92:93], v[64:65], v[74:75] neg_lo:[0,1] neg_hi:[0,1]
	v_pk_mul_f32 v[64:65], v[90:91], s[60:61] op_sel:[1,0] op_sel_hi:[0,0] neg_lo:[1,0]
	v_pk_add_f32 v[78:79], v[72:73], v[0:1]
	v_pk_fma_f32 v[64:65], v[90:91], s[62:63], v[64:65] op_sel_hi:[1,0,1]
	s_nop 0
	v_pk_add_f32 v[74:75], v[62:63], v[64:65]
	v_pk_add_f32 v[90:91], v[62:63], v[64:65] neg_lo:[0,1] neg_hi:[0,1]
	v_pk_mul_f32 v[0:1], v[68:69], s[58:59] op_sel:[1,0] op_sel_hi:[0,0] neg_lo:[1,0]
	v_pk_add_f32 v[64:65], v[84:85], v[80:81] op_sel:[0,1] op_sel_hi:[1,0] neg_lo:[0,1]
	v_pk_add_f32 v[80:81], v[84:85], v[80:81] op_sel:[0,1] op_sel_hi:[1,0] neg_hi:[0,1]
	v_pk_mul_f32 v[62:63], v[66:67], s[62:63] op_sel_hi:[1,0]
	v_mov_b32_e32 v77, v66
	v_pk_fma_f32 v[0:1], v[68:69], s[46:47], v[0:1] op_sel_hi:[1,0,1]
	v_pk_fma_f32 v[62:63], v[76:77], s[60:61], v[62:63] op_sel_hi:[1,0,1] neg_lo:[0,0,1] neg_hi:[0,0,1]
	v_pk_add_f32 v[76:77], v[94:95], v[0:1]
	v_pk_mul_f32 v[0:1], v[88:89], s[62:63] op_sel:[1,0] op_sel_hi:[0,0] neg_lo:[1,0]
	v_pk_add_f32 v[84:85], v[2:3], v[62:63]
	v_pk_fma_f32 v[0:1], v[88:89], s[60:61], v[0:1] op_sel_hi:[1,0,1]
	v_pk_add_f32 v[2:3], v[2:3], v[62:63] neg_lo:[0,1] neg_hi:[0,1]
	v_pk_add_f32 v[72:73], v[98:99], v[0:1]
	v_pk_mul_f32 v[0:1], v[74:75], s[66:67] op_sel:[1,0] op_sel_hi:[0,0] neg_lo:[1,0]
	v_pk_mul_f32 v[62:63], v[70:71], s[70:71] op_sel_hi:[1,0]
	v_pk_fma_f32 v[0:1], v[74:75], s[64:65], v[0:1] op_sel_hi:[1,0,1]
	v_xor_b32_e32 v66, 0x80000000, v71
	v_pk_add_f32 v[74:75], v[100:101], v[0:1]
	v_pk_mul_f32 v[0:1], v[64:65], s[70:71] op_sel:[1,0] op_sel_hi:[0,0] neg_lo:[1,0]
	v_mov_b32_e32 v67, v70
	v_pk_fma_f32 v[0:1], v[64:65], s[70:71], v[0:1] op_sel_hi:[1,0,1]
	v_pk_fma_f32 v[62:63], v[66:67], s[70:71], v[62:63] op_sel_hi:[1,0,1] neg_lo:[0,0,1] neg_hi:[0,0,1]
	v_pk_add_f32 v[66:67], v[102:103], v[0:1]
	v_pk_mul_f32 v[0:1], v[84:85], s[64:65] op_sel:[1,0] op_sel_hi:[0,0] neg_lo:[1,0]
	v_pk_add_f32 v[70:71], v[22:23], v[62:63]
	v_pk_fma_f32 v[0:1], v[84:85], s[66:67], v[0:1] op_sel_hi:[1,0,1]
	v_pk_add_f32 v[96:97], v[22:23], v[62:63] neg_lo:[0,1] neg_hi:[0,1]
	v_pk_mul_f32 v[22:23], v[20:21], s[60:61] op_sel_hi:[1,0]
	v_pk_add_f32 v[68:69], v[18:19], v[0:1]
	v_pk_fma_f32 v[20:21], v[20:21], s[62:63], v[22:23] op_sel:[1,0,0] op_sel_hi:[0,0,1] neg_lo:[1,0,1] neg_hi:[0,0,1]
	v_pk_mul_f32 v[0:1], v[70:71], s[60:61] op_sel:[1,0] op_sel_hi:[0,0] neg_lo:[1,0]
	v_pk_add_f32 v[22:23], v[24:25], v[20:21]
	v_pk_fma_f32 v[0:1], v[70:71], s[62:63], v[0:1] op_sel_hi:[1,0,1]
	v_pk_add_f32 v[108:109], v[24:25], v[20:21] neg_lo:[0,1] neg_hi:[0,1]
	v_pk_add_f32 v[62:63], v[14:15], v[0:1]
	v_pk_mul_f32 v[0:1], v[22:23], s[46:47] op_sel:[1,0] op_sel_hi:[0,0] neg_lo:[1,0]
	s_nop 0
	v_pk_fma_f32 v[0:1], v[22:23], s[58:59], v[0:1] op_sel_hi:[1,0,1]
	s_nop 0
	v_pk_add_f32 v[64:65], v[16:17], v[0:1]
	v_pk_add_f32 v[22:23], v[8:9], v[4:5] op_sel:[0,1] op_sel_hi:[1,0] neg_lo:[0,1]
	v_pk_mul_f32 v[0:1], v[12:13], s[58:59] op_sel_hi:[1,0]
	v_xor_b32_e32 v4, 0x80000000, v13
	v_mov_b32_e32 v5, v12
	v_pk_fma_f32 v[0:1], v[4:5], s[46:47], v[0:1] op_sel_hi:[1,0,1] neg_lo:[0,0,1] neg_hi:[0,0,1]
	v_xor_b32_e32 v4, 0x80000000, v93
	v_pk_add_f32 v[24:25], v[82:83], v[0:1]
	v_pk_mul_f32 v[0:1], v[92:93], s[62:63] op_sel_hi:[1,0]
	v_mov_b32_e32 v5, v92
	v_pk_fma_f32 v[0:1], v[4:5], s[60:61], v[0:1] op_sel_hi:[1,0,1] neg_lo:[0,0,1] neg_hi:[0,0,1]
	v_xor_b32_e32 v4, 0x80000000, v91
	v_pk_add_f32 v[18:19], v[86:87], v[0:1]
	v_pk_mul_f32 v[0:1], v[90:91], s[66:67] op_sel_hi:[1,0]
	v_mov_b32_e32 v5, v90
	v_pk_fma_f32 v[0:1], v[4:5], s[64:65], v[0:1] op_sel_hi:[1,0,1] neg_lo:[0,0,1] neg_hi:[0,0,1]
	s_nop 0
	v_pk_add_f32 v[20:21], v[26:27], v[0:1]
	v_pk_mul_f32 v[0:1], v[80:81], s[70:71] op_sel_hi:[1,0]
	s_nop 0
	v_pk_fma_f32 v[0:1], v[80:81], s[70:71], v[0:1] op_sel:[1,0,0] op_sel_hi:[0,0,1] neg_lo:[1,0,1] neg_hi:[0,0,1]
	v_xor_b32_e32 v8, 0x80000000, v3
	v_pk_add_f32 v[4:5], v[104:105], v[0:1]
	v_pk_mul_f32 v[0:1], v[2:3], s[64:65] op_sel_hi:[1,0]
	v_mov_b32_e32 v9, v2
	v_pk_fma_f32 v[0:1], v[8:9], s[66:67], v[0:1] op_sel_hi:[1,0,1] neg_lo:[0,0,1] neg_hi:[0,0,1]
	s_nop 0
	v_pk_add_f32 v[6:7], v[6:7], v[0:1]
	v_pk_mul_f32 v[0:1], v[96:97], s[60:61] op_sel_hi:[1,0]
	s_nop 0
	v_pk_fma_f32 v[0:1], v[96:97], s[62:63], v[0:1] op_sel:[1,0,0] op_sel_hi:[0,0,1] neg_lo:[1,0,1] neg_hi:[0,0,1]
	v_pk_mul_f32 v[2:3], v[108:109], s[46:47] op_sel_hi:[1,0]
	v_pk_add_f32 v[0:1], v[10:11], v[0:1]
	v_xor_b32_e32 v8, 0x80000000, v109
	v_mov_b32_e32 v9, v108
	v_mov_b32_e32 v10, v146
	v_pk_fma_f32 v[2:3], v[8:9], s[58:59], v[2:3] op_sel_hi:[1,0,1] neg_lo:[0,0,1] neg_hi:[0,0,1]
	v_mov_b32_e32 v8, v221
	s_movk_i32 s0, 0x200
	s_cselect_b32 s4, s0, 0x400
	s_add_i32 s0, s4, s68
	s_ashr_i32 s1, s0, 31
	s_lshl_b32 s6, s4, 2
	s_add_u32 s4, s90, s6
	s_addc_u32 s5, s91, 0
	s_lshl_b64 s[0:1], s[0:1], 14
	v_min_i32_e32 v70, 0x1ffe, v10
	v_mov_b32_e32 v9, s6
	s_add_u32 s36, s26, s0
	v_ashrrev_i32_e32 v11, 31, v10
	v_ashrrev_i32_e32 v71, 31, v70
	v_mov_b32_e32 v16, v222
	v_mov_b32_e32 v14, v223
	v_mov_b32_e32 v17, v224
	v_mov_b32_e32 v12, v225
	s_addc_u32 s37, s27, s1
	v_max_i32_e32 v9, 1, v10
	v_lshlrev_b64 v[82:83], 1, v[10:11]
	v_lshlrev_b64 v[84:85], 1, v[70:71]
	v_lshl_add_u64 v[26:27], s[36:37], 0, v[82:83]
	v_lshlrev_b32_e32 v9, 1, v9
	v_lshl_add_u64 v[70:71], s[36:37], 0, v[84:85]
	v_mov_b32_e32 v13, v226
	s_add_u32 s88, s30, s0
	v_mov_b32_e32 v70, v227
	s_addc_u32 s89, s31, s1
	v_mov_b32_e32 v15, v228
	v_cmp_lt_i32_e64 s[0:1], 0, v10
	v_cmp_gt_i32_e64 s[4:5], s74, v10
	v_pk_add_f32 v[2:3], v[106:107], v[2:3]
	v_cndmask_b32_e64 v81, 0, 1.0, s[0:1]
	v_cndmask_b32_e64 v86, 0, 1.0, s[4:5]
	v_add_u32_e32 v92, 0x200, v10
	v_cmp_lt_i32_e64 s[20:21], s25, v10
	v_cmp_gt_i32_e64 s[18:19], s42, v10
	v_add_u32_e32 v90, 0x400, v10
	v_cmp_lt_i32_e64 s[16:17], s33, v10
	v_cmp_gt_i32_e64 s[0:1], s51, v10
	v_add_u32_e32 v88, 0x600, v10
	v_cmp_lt_i32_e64 s[12:13], s43, v10
	v_cmp_gt_i32_e64 s[10:11], s50, v10
	v_cmp_lt_i32_e64 s[8:9], s2, v10
	v_cmp_gt_i32_e64 s[6:7], s38, v10
	v_cmp_lt_i32_e64 s[4:5], s65, v10
	v_cmp_gt_i32_e64 s[22:23], s34, v10
	s_waitcnt vmcnt(2)
	v_lshlrev_b32_e32 v13, 16, v13
	s_waitcnt vmcnt(1)
	v_lshlrev_b32_e32 v70, 16, v70
	v_mul_f32_e32 v70, v86, v70
	s_waitcnt vmcnt(0)
	v_lshlrev_b32_e32 v15, 16, v15
	v_mul_f32_e32 v15, v81, v15
	v_mul_f32_e32 v15, v16, v15
	v_fmac_f32_e32 v15, v14, v13
	v_fmac_f32_e32 v15, v17, v70
	v_lshl_add_u64 v[70:71], s[88:89], 0, v[82:83]
	v_lshl_add_u64 v[82:83], s[88:89], 0, v[84:85]
	v_add_f32_e32 v80, v12, v15
	v_mov_b32_e32 v13, v229
	v_mov_b32_e32 v15, v230
	v_add_u32_e32 v84, 0x800, v10
	v_mov_b32_e32 v9, v231
	v_add_u32_e32 v82, 0xa00, v10
	s_waitcnt vmcnt(2)
	v_lshlrev_b32_e32 v13, 16, v13
	s_waitcnt vmcnt(1)
	v_lshlrev_b32_e32 v15, 16, v15
	v_mul_f32_e32 v15, v86, v15
	s_waitcnt vmcnt(0)
	v_lshlrev_b32_e32 v9, 16, v9
	v_mul_f32_e32 v9, v81, v9
	v_mul_f32_e32 v9, v16, v9
	v_fmac_f32_e32 v9, v14, v13
	v_fmac_f32_e32 v9, v17, v15
	v_add_f32_e32 v86, v12, v9
	s_cbranch_vccnz .LBB0_540
	v_readlane_b32 s98, v252, 56
	s_lshl_b64 s[0:1], s[92:93], 1
	s_add_u32 s4, s0, s30
	s_addc_u32 s5, s1, s31
	s_add_u32 s0, s0, s26
	s_addc_u32 s1, s1, s27
	s_add_u32 s18, s96, 0x800000
	s_addc_u32 s19, s97, 0
	s_cmpk_gt_i32 s98, 0xff
	s_cbranch_scc1 .Lhy_ep1_comb_L0
	v_lshlrev_b32_e32 v109, 1, v10
	v_add_u32_e32 v254, 0x1e00, v10
	v_add_u32_e32 v253, 0x1000, v109
	v_cmp_gt_i32_e32 vcc, 0x1fff, v254
	v_add_u32_e32 v251, 0x2000, v109
	v_add_u32_e32 v250, 0x3000, v109
	v_min_i32_e32 v254, 0x1ffe, v254
	v_cndmask_b32_e64 v255, 0, 1.0, vcc
	v_lshlrev_b32_e32 v254, 1, v254
	global_load_ushort v9, v109, s[0:1]
	global_load_ushort v11, v109, s[4:5]
	global_load_ushort v13, v109, s[36:37] offset:1022
	global_load_ushort v15, v109, s[36:37] offset:1024
	global_load_ushort v81, v109, s[36:37] offset:1026
	global_load_ushort v83, v109, s[88:89] offset:1022
	global_load_ushort v85, v109, s[88:89] offset:1024
	global_load_ushort v87, v109, s[88:89] offset:1026
	global_load_ushort v89, v109, s[0:1] offset:1024
	global_load_ushort v91, v109, s[4:5] offset:1024
	global_load_ushort v93, v109, s[36:37] offset:2046
	global_load_ushort v94, v109, s[36:37] offset:2048
	global_load_ushort v95, v109, s[36:37] offset:2050
	global_load_ushort v96, v109, s[88:89] offset:2046
	global_load_ushort v97, v109, s[88:89] offset:2048
	global_load_ushort v98, v109, s[88:89] offset:2050
	global_load_ushort v99, v109, s[0:1] offset:2048
	global_load_ushort v100, v109, s[4:5] offset:2048
	global_load_ushort v101, v109, s[36:37] offset:3070
	global_load_ushort v102, v109, s[36:37] offset:3072
	global_load_ushort v103, v109, s[36:37] offset:3074
	global_load_ushort v104, v109, s[88:89] offset:3070
	global_load_ushort v105, v109, s[88:89] offset:3072
	global_load_ushort v106, v109, s[88:89] offset:3074
	global_load_ushort v107, v109, s[0:1] offset:3072
	global_load_ushort v108, v109, s[4:5] offset:3072
	global_load_ushort v111, v253, s[36:37] offset:-2
	global_load_ushort v112, v253, s[36:37]
	global_load_ushort v113, v253, s[36:37] offset:2
	global_load_ushort v114, v253, s[88:89] offset:-2
	global_load_ushort v115, v253, s[88:89]
	global_load_ushort v116, v253, s[88:89] offset:2
	global_load_ushort v117, v253, s[0:1]
	global_load_ushort v118, v253, s[4:5]
	global_load_ushort v119, v253, s[36:37] offset:1022
	global_load_ushort v120, v253, s[36:37] offset:1024
	global_load_ushort v121, v253, s[36:37] offset:1026
	global_load_ushort v122, v253, s[88:89] offset:1022
	global_load_ushort v123, v253, s[88:89] offset:1024
	global_load_ushort v124, v253, s[88:89] offset:1026
	global_load_ushort v125, v253, s[0:1] offset:1024
	global_load_ushort v126, v253, s[4:5] offset:1024
	global_load_ushort v127, v253, s[36:37] offset:2046
	global_load_ushort v128, v253, s[36:37] offset:2048
	global_load_ushort v129, v253, s[36:37] offset:2050
	global_load_ushort v130, v253, s[88:89] offset:2046
	global_load_ushort v131, v253, s[88:89] offset:2048
	global_load_ushort v132, v253, s[88:89] offset:2050
	global_load_ushort v133, v253, s[0:1] offset:2048
	global_load_ushort v134, v253, s[4:5] offset:2048
	global_load_ushort v135, v253, s[36:37] offset:3070
	global_load_ushort v136, v253, s[36:37] offset:3072
	global_load_ushort v137, v253, s[36:37] offset:3074
	global_load_ushort v138, v253, s[88:89] offset:3070
	global_load_ushort v139, v253, s[88:89] offset:3072
	global_load_ushort v140, v253, s[88:89] offset:3074
	global_load_ushort v141, v253, s[0:1] offset:3072
	global_load_ushort v142, v253, s[4:5] offset:3072
	global_load_ushort v143, v251, s[36:37] offset:-2
	global_load_ushort v163, v251, s[36:37]
	global_load_ushort v164, v251, s[36:37] offset:2
	global_load_ushort v165, v251, s[88:89] offset:-2
	global_load_ushort v166, v251, s[88:89]
	global_load_ushort v167, v251, s[88:89] offset:2
	global_load_ushort v168, v251, s[0:1]
	global_load_ushort v169, v251, s[4:5]
	global_load_ushort v170, v251, s[36:37] offset:1022
	global_load_ushort v171, v251, s[36:37] offset:1024
	global_load_ushort v172, v251, s[36:37] offset:1026
	global_load_ushort v173, v251, s[88:89] offset:1022
	global_load_ushort v174, v251, s[88:89] offset:1024
	global_load_ushort v175, v251, s[88:89] offset:1026
	global_load_ushort v176, v251, s[0:1] offset:1024
	global_load_ushort v177, v251, s[4:5] offset:1024
	global_load_ushort v178, v251, s[36:37] offset:2046
	global_load_ushort v179, v251, s[36:37] offset:2048
	global_load_ushort v180, v251, s[36:37] offset:2050
	global_load_ushort v181, v251, s[88:89] offset:2046
	global_load_ushort v182, v251, s[88:89] offset:2048
	global_load_ushort v183, v251, s[88:89] offset:2050
	global_load_ushort v184, v251, s[0:1] offset:2048
	global_load_ushort v185, v251, s[4:5] offset:2048
	global_load_ushort v186, v251, s[36:37] offset:3070
	global_load_ushort v187, v251, s[36:37] offset:3072
	global_load_ushort v188, v251, s[36:37] offset:3074
	global_load_ushort v189, v251, s[88:89] offset:3070
	global_load_ushort v190, v251, s[88:89] offset:3072
	global_load_ushort v191, v251, s[88:89] offset:3074
	global_load_ushort v192, v251, s[0:1] offset:3072
	global_load_ushort v193, v251, s[4:5] offset:3072
	global_load_ushort v194, v250, s[36:37] offset:-2
	global_load_ushort v195, v250, s[36:37]
	global_load_ushort v196, v250, s[36:37] offset:2
	global_load_ushort v197, v250, s[88:89] offset:-2
	global_load_ushort v221, v250, s[88:89]
	global_load_ushort v222, v250, s[88:89] offset:2
	global_load_ushort v223, v250, s[0:1]
	global_load_ushort v224, v250, s[4:5]
	global_load_ushort v225, v250, s[36:37] offset:1022
	global_load_ushort v226, v250, s[36:37] offset:1024
	global_load_ushort v227, v250, s[36:37] offset:1026
	global_load_ushort v228, v250, s[88:89] offset:1022
	global_load_ushort v229, v250, s[88:89] offset:1024
	global_load_ushort v230, v250, s[88:89] offset:1026
	global_load_ushort v231, v250, s[0:1] offset:1024
	global_load_ushort v232, v250, s[4:5] offset:1024
	global_load_ushort v233, v250, s[36:37] offset:2046
	global_load_ushort v234, v250, s[36:37] offset:2048
	global_load_ushort v235, v250, s[36:37] offset:2050
	global_load_ushort v236, v250, s[88:89] offset:2046
	global_load_ushort v237, v250, s[88:89] offset:2048
	global_load_ushort v238, v250, s[88:89] offset:2050
	global_load_ushort v239, v250, s[0:1] offset:2048
	global_load_ushort v240, v250, s[4:5] offset:2048
	global_load_ushort v241, v250, s[36:37] offset:3070
	global_load_ushort v242, v250, s[36:37] offset:3072
	global_load_ushort v243, v254, s[36:37] offset:2
	global_load_ushort v244, v250, s[88:89] offset:3070
	global_load_ushort v245, v250, s[88:89] offset:3072
	global_load_ushort v246, v254, s[88:89] offset:2
	global_load_ushort v247, v250, s[0:1] offset:3072
	global_load_ushort v248, v250, s[4:5] offset:3072
	s_waitcnt vmcnt(63)
	v_fma_f32 v27, v32, v8, v78
	v_mul_f32_e32 v70, v80, v27
	v_lshlrev_b32_e32 v9, 16, v9
	v_mul_f32_e32 v84, 0xbfb8aa3b, v9
	v_exp_f32_e32 v84, v84
	s_nop 0
	v_add_f32_e32 v84, 1.0, v84
	v_div_scale_f32 v71, s[28:29], v84, v84, v9
	v_rcp_f32_e32 v82, v71
	s_nop 0
	v_fma_f32 v92, -v71, v82, 1.0
	v_fmac_f32_e32 v82, v92, v82
	v_div_scale_f32 v88, vcc, v9, v84, v9
	v_mul_f32_e32 v90, v88, v82
	v_fma_f32 v92, -v71, v90, v88
	v_fmac_f32_e32 v90, v92, v82
	v_fma_f32 v71, -v71, v90, v88
	v_div_fmas_f32 v71, v71, v82, v90
	v_div_fixup_f32 v9, v71, v84, v9
	v_mul_f32_e32 v70, v70, v9
	v_fma_f32 v27, v34, v8, v79
	v_mul_f32_e32 v110, v86, v27
	v_lshlrev_b32_e32 v11, 16, v11
	v_mul_f32_e32 v84, 0xbfb8aa3b, v11
	v_exp_f32_e32 v84, v84
	s_nop 0
	v_add_f32_e32 v84, 1.0, v84
	v_div_scale_f32 v71, s[28:29], v84, v84, v11
	v_rcp_f32_e32 v82, v71
	s_nop 0
	v_fma_f32 v92, -v71, v82, 1.0
	v_fmac_f32_e32 v82, v92, v82
	v_div_scale_f32 v88, vcc, v11, v84, v11
	v_mul_f32_e32 v90, v88, v82
	v_fma_f32 v92, -v71, v90, v88
	v_fmac_f32_e32 v90, v92, v82
	v_fma_f32 v71, -v71, v90, v88
	v_div_fmas_f32 v71, v71, v82, v90
	v_div_fixup_f32 v11, v71, v84, v11
	v_mul_f32_e32 v110, v110, v11
	v_cvt_pk_bf16_f32 v198, v70, v110
	v_lshlrev_b32_e32 v15, 16, v15
	v_lshlrev_b32_e32 v81, 16, v81
	v_lshlrev_b32_e32 v13, 16, v13
	v_mul_f32_e32 v13, v16, v13
	v_fmac_f32_e32 v13, v14, v15
	v_fmac_f32_e32 v13, v17, v81
	v_add_f32_e32 v13, v12, v13
	v_fma_f32 v27, v33, v8, v76
	v_mul_f32_e32 v70, v27, v13
	v_lshlrev_b32_e32 v89, 16, v89
	v_mul_f32_e32 v84, 0xbfb8aa3b, v89
	v_exp_f32_e32 v84, v84
	s_nop 0
	v_add_f32_e32 v84, 1.0, v84
	v_div_scale_f32 v71, s[28:29], v84, v84, v89
	v_rcp_f32_e32 v82, v71
	s_nop 0
	v_fma_f32 v92, -v71, v82, 1.0
	v_fmac_f32_e32 v82, v92, v82
	v_div_scale_f32 v88, vcc, v89, v84, v89
	v_mul_f32_e32 v90, v88, v82
	v_fma_f32 v92, -v71, v90, v88
	v_fmac_f32_e32 v90, v92, v82
	v_fma_f32 v71, -v71, v90, v88
	v_div_fmas_f32 v71, v71, v82, v90
	v_div_fixup_f32 v89, v71, v84, v89
	v_mul_f32_e32 v70, v70, v89
	v_lshlrev_b32_e32 v85, 16, v85
	v_lshlrev_b32_e32 v87, 16, v87
	v_lshlrev_b32_e32 v83, 16, v83
	v_mul_f32_e32 v83, v16, v83
	v_fmac_f32_e32 v83, v14, v85
	v_fmac_f32_e32 v83, v17, v87
	v_add_f32_e32 v83, v12, v83
	v_fma_f32 v27, v35, v8, v77
	v_mul_f32_e32 v110, v27, v83
	v_lshlrev_b32_e32 v91, 16, v91
	v_mul_f32_e32 v84, 0xbfb8aa3b, v91
	v_exp_f32_e32 v84, v84
	s_nop 0
	v_add_f32_e32 v84, 1.0, v84
	v_div_scale_f32 v71, s[28:29], v84, v84, v91
	v_rcp_f32_e32 v82, v71
	s_nop 0
	v_fma_f32 v92, -v71, v82, 1.0
	v_fmac_f32_e32 v82, v92, v82
	v_div_scale_f32 v88, vcc, v91, v84, v91
	v_mul_f32_e32 v90, v88, v82
	v_fma_f32 v92, -v71, v90, v88
	v_fmac_f32_e32 v90, v92, v82
	v_fma_f32 v71, -v71, v90, v88
	v_div_fmas_f32 v71, v71, v82, v90
	v_div_fixup_f32 v91, v71, v84, v91
	v_mul_f32_e32 v110, v110, v91
	v_cvt_pk_bf16_f32 v199, v70, v110
	v_lshlrev_b32_e32 v94, 16, v94
	v_lshlrev_b32_e32 v95, 16, v95
	v_lshlrev_b32_e32 v93, 16, v93
	v_mul_f32_e32 v93, v16, v93
	v_fmac_f32_e32 v93, v14, v94
	v_fmac_f32_e32 v93, v17, v95
	v_add_f32_e32 v93, v12, v93
	v_fma_f32 v27, v37, v8, v72
	v_mul_f32_e32 v70, v27, v93
	v_lshlrev_b32_e32 v99, 16, v99
	v_mul_f32_e32 v84, 0xbfb8aa3b, v99
	v_exp_f32_e32 v84, v84
	s_nop 0
	v_add_f32_e32 v84, 1.0, v84
	v_div_scale_f32 v71, s[28:29], v84, v84, v99
	v_rcp_f32_e32 v82, v71
	s_nop 0
	v_fma_f32 v92, -v71, v82, 1.0
	v_fmac_f32_e32 v82, v92, v82
	v_div_scale_f32 v88, vcc, v99, v84, v99
	v_mul_f32_e32 v90, v88, v82
	v_fma_f32 v92, -v71, v90, v88
	v_fmac_f32_e32 v90, v92, v82
	v_fma_f32 v71, -v71, v90, v88
	v_div_fmas_f32 v71, v71, v82, v90
	v_div_fixup_f32 v99, v71, v84, v99
	v_mul_f32_e32 v70, v70, v99
	v_lshlrev_b32_e32 v97, 16, v97
	v_lshlrev_b32_e32 v98, 16, v98
	v_lshlrev_b32_e32 v96, 16, v96
	v_mul_f32_e32 v96, v16, v96
	v_fmac_f32_e32 v96, v14, v97
	v_fmac_f32_e32 v96, v17, v98
	v_add_f32_e32 v96, v12, v96
	v_fma_f32 v27, v31, v8, v73
	v_mul_f32_e32 v110, v27, v96
	v_lshlrev_b32_e32 v100, 16, v100
	v_mul_f32_e32 v84, 0xbfb8aa3b, v100
	v_exp_f32_e32 v84, v84
	s_nop 0
	v_add_f32_e32 v84, 1.0, v84
	v_div_scale_f32 v71, s[28:29], v84, v84, v100
	v_rcp_f32_e32 v82, v71
	s_nop 0
	v_fma_f32 v92, -v71, v82, 1.0
	v_fmac_f32_e32 v82, v92, v82
	v_div_scale_f32 v88, vcc, v100, v84, v100
	v_mul_f32_e32 v90, v88, v82
	v_fma_f32 v92, -v71, v90, v88
	v_fmac_f32_e32 v90, v92, v82
	v_fma_f32 v71, -v71, v90, v88
	v_div_fmas_f32 v71, v71, v82, v90
	v_div_fixup_f32 v100, v71, v84, v100
	v_mul_f32_e32 v110, v110, v100
	v_cvt_pk_bf16_f32 v200, v70, v110
	v_lshlrev_b32_e32 v102, 16, v102
	v_lshlrev_b32_e32 v103, 16, v103
	v_lshlrev_b32_e32 v101, 16, v101
	v_mul_f32_e32 v101, v16, v101
	v_fmac_f32_e32 v101, v14, v102
	v_fmac_f32_e32 v101, v17, v103
	v_add_f32_e32 v101, v12, v101
	v_fma_f32 v27, v36, v8, v74
	v_mul_f32_e32 v70, v27, v101
	v_lshlrev_b32_e32 v107, 16, v107
	v_mul_f32_e32 v84, 0xbfb8aa3b, v107
	v_exp_f32_e32 v84, v84
	s_nop 0
	v_add_f32_e32 v84, 1.0, v84
	v_div_scale_f32 v71, s[28:29], v84, v84, v107
	v_rcp_f32_e32 v82, v71
	s_nop 0
	v_fma_f32 v92, -v71, v82, 1.0
	v_fmac_f32_e32 v82, v92, v82
	v_div_scale_f32 v88, vcc, v107, v84, v107
	v_mul_f32_e32 v90, v88, v82
	v_fma_f32 v92, -v71, v90, v88
	v_fmac_f32_e32 v90, v92, v82
	v_fma_f32 v71, -v71, v90, v88
	v_div_fmas_f32 v71, v71, v82, v90
	v_div_fixup_f32 v107, v71, v84, v107
	v_mul_f32_e32 v70, v70, v107
	v_lshlrev_b32_e32 v105, 16, v105
	v_lshlrev_b32_e32 v106, 16, v106
	v_lshlrev_b32_e32 v104, 16, v104
	v_mul_f32_e32 v104, v16, v104
	v_fmac_f32_e32 v104, v14, v105
	v_fmac_f32_e32 v104, v17, v106
	v_add_f32_e32 v104, v12, v104
	v_fma_f32 v27, v30, v8, v75
	v_mul_f32_e32 v110, v27, v104
	v_lshlrev_b32_e32 v108, 16, v108
	v_mul_f32_e32 v84, 0xbfb8aa3b, v108
	v_exp_f32_e32 v84, v84
	s_nop 0
	v_add_f32_e32 v84, 1.0, v84
	v_div_scale_f32 v71, s[28:29], v84, v84, v108
	v_rcp_f32_e32 v82, v71
	s_nop 0
	v_fma_f32 v92, -v71, v82, 1.0
	v_fmac_f32_e32 v82, v92, v82
	v_div_scale_f32 v88, vcc, v108, v84, v108
	v_mul_f32_e32 v90, v88, v82
	v_fma_f32 v92, -v71, v90, v88
	v_fmac_f32_e32 v90, v92, v82
	v_fma_f32 v71, -v71, v90, v88
	v_div_fmas_f32 v71, v71, v82, v90
	v_div_fixup_f32 v108, v71, v84, v108
	v_mul_f32_e32 v110, v110, v108
	v_cvt_pk_bf16_f32 v201, v70, v110
	s_waitcnt vmcnt(63)
	v_lshlrev_b32_e32 v112, 16, v112
	v_lshlrev_b32_e32 v113, 16, v113
	v_lshlrev_b32_e32 v111, 16, v111
	v_mul_f32_e32 v111, v16, v111
	v_fmac_f32_e32 v111, v14, v112
	v_fmac_f32_e32 v111, v17, v113
	v_add_f32_e32 v111, v12, v111
	v_fma_f32 v27, v39, v8, v66
	v_mul_f32_e32 v70, v27, v111
	v_lshlrev_b32_e32 v117, 16, v117
	v_mul_f32_e32 v84, 0xbfb8aa3b, v117
	v_exp_f32_e32 v84, v84
	s_nop 0
	v_add_f32_e32 v84, 1.0, v84
	v_div_scale_f32 v71, s[28:29], v84, v84, v117
	v_rcp_f32_e32 v82, v71
	s_nop 0
	v_fma_f32 v92, -v71, v82, 1.0
	v_fmac_f32_e32 v82, v92, v82
	v_div_scale_f32 v88, vcc, v117, v84, v117
	v_mul_f32_e32 v90, v88, v82
	v_fma_f32 v92, -v71, v90, v88
	v_fmac_f32_e32 v90, v92, v82
	v_fma_f32 v71, -v71, v90, v88
	v_div_fmas_f32 v71, v71, v82, v90
	v_div_fixup_f32 v117, v71, v84, v117
	v_mul_f32_e32 v70, v70, v117
	v_lshlrev_b32_e32 v115, 16, v115
	v_lshlrev_b32_e32 v116, 16, v116
	v_lshlrev_b32_e32 v114, 16, v114
	v_mul_f32_e32 v114, v16, v114
	v_fmac_f32_e32 v114, v14, v115
	v_fmac_f32_e32 v114, v17, v116
	v_add_f32_e32 v114, v12, v114
	v_fma_f32 v27, v41, v8, v67
	v_mul_f32_e32 v110, v27, v114
	v_lshlrev_b32_e32 v118, 16, v118
	v_mul_f32_e32 v84, 0xbfb8aa3b, v118
	v_exp_f32_e32 v84, v84
	s_nop 0
	v_add_f32_e32 v84, 1.0, v84
	v_div_scale_f32 v71, s[28:29], v84, v84, v118
	v_rcp_f32_e32 v82, v71
	s_nop 0
	v_fma_f32 v92, -v71, v82, 1.0
	v_fmac_f32_e32 v82, v92, v82
	v_div_scale_f32 v88, vcc, v118, v84, v118
	v_mul_f32_e32 v90, v88, v82
	v_fma_f32 v92, -v71, v90, v88
	v_fmac_f32_e32 v90, v92, v82
	v_fma_f32 v71, -v71, v90, v88
	v_div_fmas_f32 v71, v71, v82, v90
	v_div_fixup_f32 v118, v71, v84, v118
	v_mul_f32_e32 v110, v110, v118
	v_cvt_pk_bf16_f32 v202, v70, v110
	v_lshlrev_b32_e32 v120, 16, v120
	v_lshlrev_b32_e32 v121, 16, v121
	v_lshlrev_b32_e32 v119, 16, v119
	v_mul_f32_e32 v119, v16, v119
	v_fmac_f32_e32 v119, v14, v120
	v_fmac_f32_e32 v119, v17, v121
	v_add_f32_e32 v119, v12, v119
	v_fma_f32 v27, v38, v8, v68
	v_mul_f32_e32 v70, v27, v119
	v_lshlrev_b32_e32 v125, 16, v125
	v_mul_f32_e32 v84, 0xbfb8aa3b, v125
	v_exp_f32_e32 v84, v84
	s_nop 0
	v_add_f32_e32 v84, 1.0, v84
	v_div_scale_f32 v71, s[28:29], v84, v84, v125
	v_rcp_f32_e32 v82, v71
	s_nop 0
	v_fma_f32 v92, -v71, v82, 1.0
	v_fmac_f32_e32 v82, v92, v82
	v_div_scale_f32 v88, vcc, v125, v84, v125
	v_mul_f32_e32 v90, v88, v82
	v_fma_f32 v92, -v71, v90, v88
	v_fmac_f32_e32 v90, v92, v82
	v_fma_f32 v71, -v71, v90, v88
	v_div_fmas_f32 v71, v71, v82, v90
	v_div_fixup_f32 v125, v71, v84, v125
	v_mul_f32_e32 v70, v70, v125
	v_lshlrev_b32_e32 v123, 16, v123
	v_lshlrev_b32_e32 v124, 16, v124
	v_lshlrev_b32_e32 v122, 16, v122
	v_mul_f32_e32 v122, v16, v122
	v_fmac_f32_e32 v122, v14, v123
	v_fmac_f32_e32 v122, v17, v124
	v_add_f32_e32 v122, v12, v122
	v_fma_f32 v27, v40, v8, v69
	v_mul_f32_e32 v110, v27, v122
	v_lshlrev_b32_e32 v126, 16, v126
	v_mul_f32_e32 v84, 0xbfb8aa3b, v126
	v_exp_f32_e32 v84, v84
	s_nop 0
	v_add_f32_e32 v84, 1.0, v84
	v_div_scale_f32 v71, s[28:29], v84, v84, v126
	v_rcp_f32_e32 v82, v71
	s_nop 0
	v_fma_f32 v92, -v71, v82, 1.0
	v_fmac_f32_e32 v82, v92, v82
	v_div_scale_f32 v88, vcc, v126, v84, v126
	v_mul_f32_e32 v90, v88, v82
	v_fma_f32 v92, -v71, v90, v88
	v_fmac_f32_e32 v90, v92, v82
	v_fma_f32 v71, -v71, v90, v88
	v_div_fmas_f32 v71, v71, v82, v90
	v_div_fixup_f32 v126, v71, v84, v126
	v_mul_f32_e32 v110, v110, v126
	v_cvt_pk_bf16_f32 v203, v70, v110
	v_lshlrev_b32_e32 v128, 16, v128
	v_lshlrev_b32_e32 v129, 16, v129
	v_lshlrev_b32_e32 v127, 16, v127
	v_mul_f32_e32 v127, v16, v127
	v_fmac_f32_e32 v127, v14, v128
	v_fmac_f32_e32 v127, v17, v129
	v_add_f32_e32 v127, v12, v127
	v_fma_f32 v27, v43, v8, v62
	v_mul_f32_e32 v70, v27, v127
	v_lshlrev_b32_e32 v133, 16, v133
	v_mul_f32_e32 v84, 0xbfb8aa3b, v133
	v_exp_f32_e32 v84, v84
	s_nop 0
	v_add_f32_e32 v84, 1.0, v84
	v_div_scale_f32 v71, s[28:29], v84, v84, v133
	v_rcp_f32_e32 v82, v71
	s_nop 0
	v_fma_f32 v92, -v71, v82, 1.0
	v_fmac_f32_e32 v82, v92, v82
	v_div_scale_f32 v88, vcc, v133, v84, v133
	v_mul_f32_e32 v90, v88, v82
	v_fma_f32 v92, -v71, v90, v88
	v_fmac_f32_e32 v90, v92, v82
	v_fma_f32 v71, -v71, v90, v88
	v_div_fmas_f32 v71, v71, v82, v90
	v_div_fixup_f32 v133, v71, v84, v133
	v_mul_f32_e32 v70, v70, v133
	v_lshlrev_b32_e32 v131, 16, v131
	v_lshlrev_b32_e32 v132, 16, v132
	v_lshlrev_b32_e32 v130, 16, v130
	v_mul_f32_e32 v130, v16, v130
	v_fmac_f32_e32 v130, v14, v131
	v_fmac_f32_e32 v130, v17, v132
	v_add_f32_e32 v130, v12, v130
	v_fma_f32 v27, v45, v8, v63
	v_mul_f32_e32 v110, v27, v130
	v_lshlrev_b32_e32 v134, 16, v134
	v_mul_f32_e32 v84, 0xbfb8aa3b, v134
	v_exp_f32_e32 v84, v84
	s_nop 0
	v_add_f32_e32 v84, 1.0, v84
	v_div_scale_f32 v71, s[28:29], v84, v84, v134
	v_rcp_f32_e32 v82, v71
	s_nop 0
	v_fma_f32 v92, -v71, v82, 1.0
	v_fmac_f32_e32 v82, v92, v82
	v_div_scale_f32 v88, vcc, v134, v84, v134
	v_mul_f32_e32 v90, v88, v82
	v_fma_f32 v92, -v71, v90, v88
	v_fmac_f32_e32 v90, v92, v82
	v_fma_f32 v71, -v71, v90, v88
	v_div_fmas_f32 v71, v71, v82, v90
	v_div_fixup_f32 v134, v71, v84, v134
	v_mul_f32_e32 v110, v110, v134
	v_cvt_pk_bf16_f32 v204, v70, v110
	v_lshlrev_b32_e32 v136, 16, v136
	v_lshlrev_b32_e32 v137, 16, v137
	v_lshlrev_b32_e32 v135, 16, v135
	v_mul_f32_e32 v135, v16, v135
	v_fmac_f32_e32 v135, v14, v136
	v_fmac_f32_e32 v135, v17, v137
	v_add_f32_e32 v135, v12, v135
	v_fma_f32 v27, v42, v8, v64
	v_mul_f32_e32 v70, v27, v135
	v_lshlrev_b32_e32 v141, 16, v141
	v_mul_f32_e32 v84, 0xbfb8aa3b, v141
	v_exp_f32_e32 v84, v84
	s_nop 0
	v_add_f32_e32 v84, 1.0, v84
	v_div_scale_f32 v71, s[28:29], v84, v84, v141
	v_rcp_f32_e32 v82, v71
	s_nop 0
	v_fma_f32 v92, -v71, v82, 1.0
	v_fmac_f32_e32 v82, v92, v82
	v_div_scale_f32 v88, vcc, v141, v84, v141
	v_mul_f32_e32 v90, v88, v82
	v_fma_f32 v92, -v71, v90, v88
	v_fmac_f32_e32 v90, v92, v82
	v_fma_f32 v71, -v71, v90, v88
	v_div_fmas_f32 v71, v71, v82, v90
	v_div_fixup_f32 v141, v71, v84, v141
	v_mul_f32_e32 v70, v70, v141
	v_lshlrev_b32_e32 v139, 16, v139
	v_lshlrev_b32_e32 v140, 16, v140
	v_lshlrev_b32_e32 v138, 16, v138
	v_mul_f32_e32 v138, v16, v138
	v_fmac_f32_e32 v138, v14, v139
	v_fmac_f32_e32 v138, v17, v140
	v_add_f32_e32 v138, v12, v138
	v_fma_f32 v27, v44, v8, v65
	v_mul_f32_e32 v110, v27, v138
	v_lshlrev_b32_e32 v142, 16, v142
	v_mul_f32_e32 v84, 0xbfb8aa3b, v142
	v_exp_f32_e32 v84, v84
	s_nop 0
	v_add_f32_e32 v84, 1.0, v84
	v_div_scale_f32 v71, s[28:29], v84, v84, v142
	v_rcp_f32_e32 v82, v71
	s_nop 0
	v_fma_f32 v92, -v71, v82, 1.0
	v_fmac_f32_e32 v82, v92, v82
	v_div_scale_f32 v88, vcc, v142, v84, v142
	v_mul_f32_e32 v90, v88, v82
	v_fma_f32 v92, -v71, v90, v88
	v_fmac_f32_e32 v90, v92, v82
	v_fma_f32 v71, -v71, v90, v88
	v_div_fmas_f32 v71, v71, v82, v90
	v_div_fixup_f32 v142, v71, v84, v142
	v_mul_f32_e32 v110, v110, v142
	v_cvt_pk_bf16_f32 v205, v70, v110
	s_waitcnt vmcnt(32)
	v_lshlrev_b32_e32 v163, 16, v163
	v_lshlrev_b32_e32 v164, 16, v164
	v_lshlrev_b32_e32 v143, 16, v143
	v_mul_f32_e32 v143, v16, v143
	v_fmac_f32_e32 v143, v14, v163
	v_fmac_f32_e32 v143, v17, v164
	v_add_f32_e32 v143, v12, v143
	v_fma_f32 v27, v47, v8, v22
	v_mul_f32_e32 v70, v27, v143
	v_lshlrev_b32_e32 v168, 16, v168
	v_mul_f32_e32 v84, 0xbfb8aa3b, v168
	v_exp_f32_e32 v84, v84
	s_nop 0
	v_add_f32_e32 v84, 1.0, v84
	v_div_scale_f32 v71, s[28:29], v84, v84, v168
	v_rcp_f32_e32 v82, v71
	s_nop 0
	v_fma_f32 v92, -v71, v82, 1.0
	v_fmac_f32_e32 v82, v92, v82
	v_div_scale_f32 v88, vcc, v168, v84, v168
	v_mul_f32_e32 v90, v88, v82
	v_fma_f32 v92, -v71, v90, v88
	v_fmac_f32_e32 v90, v92, v82
	v_fma_f32 v71, -v71, v90, v88
	v_div_fmas_f32 v71, v71, v82, v90
	v_div_fixup_f32 v168, v71, v84, v168
	v_mul_f32_e32 v70, v70, v168
	v_lshlrev_b32_e32 v166, 16, v166
	v_lshlrev_b32_e32 v167, 16, v167
	v_lshlrev_b32_e32 v165, 16, v165
	v_mul_f32_e32 v165, v16, v165
	v_fmac_f32_e32 v165, v14, v166
	v_fmac_f32_e32 v165, v17, v167
	v_add_f32_e32 v165, v12, v165
	v_fma_f32 v27, v49, v8, v23
	v_mul_f32_e32 v110, v27, v165
	v_lshlrev_b32_e32 v169, 16, v169
	v_mul_f32_e32 v84, 0xbfb8aa3b, v169
	v_exp_f32_e32 v84, v84
	s_nop 0
	v_add_f32_e32 v84, 1.0, v84
	v_div_scale_f32 v71, s[28:29], v84, v84, v169
	v_rcp_f32_e32 v82, v71
	s_nop 0
	v_fma_f32 v92, -v71, v82, 1.0
	v_fmac_f32_e32 v82, v92, v82
	v_div_scale_f32 v88, vcc, v169, v84, v169
	v_mul_f32_e32 v90, v88, v82
	v_fma_f32 v92, -v71, v90, v88
	v_fmac_f32_e32 v90, v92, v82
	v_fma_f32 v71, -v71, v90, v88
	v_div_fmas_f32 v71, v71, v82, v90
	v_div_fixup_f32 v169, v71, v84, v169
	v_mul_f32_e32 v110, v110, v169
	v_cvt_pk_bf16_f32 v206, v70, v110
	v_lshlrev_b32_e32 v171, 16, v171
	v_lshlrev_b32_e32 v172, 16, v172
	v_lshlrev_b32_e32 v170, 16, v170
	v_mul_f32_e32 v170, v16, v170
	v_fmac_f32_e32 v170, v14, v171
	v_fmac_f32_e32 v170, v17, v172
	v_add_f32_e32 v170, v12, v170
	v_fma_f32 v27, v46, v8, v24
	v_mul_f32_e32 v70, v27, v170
	v_lshlrev_b32_e32 v176, 16, v176
	v_mul_f32_e32 v84, 0xbfb8aa3b, v176
	v_exp_f32_e32 v84, v84
	s_nop 0
	v_add_f32_e32 v84, 1.0, v84
	v_div_scale_f32 v71, s[28:29], v84, v84, v176
	v_rcp_f32_e32 v82, v71
	s_nop 0
	v_fma_f32 v92, -v71, v82, 1.0
	v_fmac_f32_e32 v82, v92, v82
	v_div_scale_f32 v88, vcc, v176, v84, v176
	v_mul_f32_e32 v90, v88, v82
	v_fma_f32 v92, -v71, v90, v88
	v_fmac_f32_e32 v90, v92, v82
	v_fma_f32 v71, -v71, v90, v88
	v_div_fmas_f32 v71, v71, v82, v90
	v_div_fixup_f32 v176, v71, v84, v176
	v_mul_f32_e32 v70, v70, v176
	v_lshlrev_b32_e32 v174, 16, v174
	v_lshlrev_b32_e32 v175, 16, v175
	v_lshlrev_b32_e32 v173, 16, v173
	v_mul_f32_e32 v173, v16, v173
	v_fmac_f32_e32 v173, v14, v174
	v_fmac_f32_e32 v173, v17, v175
	v_add_f32_e32 v173, v12, v173
	v_fma_f32 v27, v48, v8, v25
	v_mul_f32_e32 v110, v27, v173
	v_lshlrev_b32_e32 v177, 16, v177
	v_mul_f32_e32 v84, 0xbfb8aa3b, v177
	v_exp_f32_e32 v84, v84
	s_nop 0
	v_add_f32_e32 v84, 1.0, v84
	v_div_scale_f32 v71, s[28:29], v84, v84, v177
	v_rcp_f32_e32 v82, v71
	s_nop 0
	v_fma_f32 v92, -v71, v82, 1.0
	v_fmac_f32_e32 v82, v92, v82
	v_div_scale_f32 v88, vcc, v177, v84, v177
	v_mul_f32_e32 v90, v88, v82
	v_fma_f32 v92, -v71, v90, v88
	v_fmac_f32_e32 v90, v92, v82
	v_fma_f32 v71, -v71, v90, v88
	v_div_fmas_f32 v71, v71, v82, v90
	v_div_fixup_f32 v177, v71, v84, v177
	v_mul_f32_e32 v110, v110, v177
	v_cvt_pk_bf16_f32 v207, v70, v110
	v_lshlrev_b32_e32 v179, 16, v179
	v_lshlrev_b32_e32 v180, 16, v180
	v_lshlrev_b32_e32 v178, 16, v178
	v_mul_f32_e32 v178, v16, v178
	v_fmac_f32_e32 v178, v14, v179
	v_fmac_f32_e32 v178, v17, v180
	v_add_f32_e32 v178, v12, v178
	v_fma_f32 v27, v51, v8, v18
	v_mul_f32_e32 v70, v27, v178
	v_lshlrev_b32_e32 v184, 16, v184
	v_mul_f32_e32 v84, 0xbfb8aa3b, v184
	v_exp_f32_e32 v84, v84
	s_nop 0
	v_add_f32_e32 v84, 1.0, v84
	v_div_scale_f32 v71, s[28:29], v84, v84, v184
	v_rcp_f32_e32 v82, v71
	s_nop 0
	v_fma_f32 v92, -v71, v82, 1.0
	v_fmac_f32_e32 v82, v92, v82
	v_div_scale_f32 v88, vcc, v184, v84, v184
	v_mul_f32_e32 v90, v88, v82
	v_fma_f32 v92, -v71, v90, v88
	v_fmac_f32_e32 v90, v92, v82
	v_fma_f32 v71, -v71, v90, v88
	v_div_fmas_f32 v71, v71, v82, v90
	v_div_fixup_f32 v184, v71, v84, v184
	v_mul_f32_e32 v70, v70, v184
	v_lshlrev_b32_e32 v182, 16, v182
	v_lshlrev_b32_e32 v183, 16, v183
	v_lshlrev_b32_e32 v181, 16, v181
	v_mul_f32_e32 v181, v16, v181
	v_fmac_f32_e32 v181, v14, v182
	v_fmac_f32_e32 v181, v17, v183
	v_add_f32_e32 v181, v12, v181
	v_fma_f32 v27, v53, v8, v19
	v_mul_f32_e32 v110, v27, v181
	v_lshlrev_b32_e32 v185, 16, v185
	v_mul_f32_e32 v84, 0xbfb8aa3b, v185
	v_exp_f32_e32 v84, v84
	s_nop 0
	v_add_f32_e32 v84, 1.0, v84
	v_div_scale_f32 v71, s[28:29], v84, v84, v185
	v_rcp_f32_e32 v82, v71
	s_nop 0
	v_fma_f32 v92, -v71, v82, 1.0
	v_fmac_f32_e32 v82, v92, v82
	v_div_scale_f32 v88, vcc, v185, v84, v185
	v_mul_f32_e32 v90, v88, v82
	v_fma_f32 v92, -v71, v90, v88
	v_fmac_f32_e32 v90, v92, v82
	v_fma_f32 v71, -v71, v90, v88
	v_div_fmas_f32 v71, v71, v82, v90
	v_div_fixup_f32 v185, v71, v84, v185
	v_mul_f32_e32 v110, v110, v185
	v_cvt_pk_bf16_f32 v208, v70, v110
	v_lshlrev_b32_e32 v187, 16, v187
	v_lshlrev_b32_e32 v188, 16, v188
	v_lshlrev_b32_e32 v186, 16, v186
	v_mul_f32_e32 v186, v16, v186
	v_fmac_f32_e32 v186, v14, v187
	v_fmac_f32_e32 v186, v17, v188
	v_add_f32_e32 v186, v12, v186
	v_fma_f32 v27, v50, v8, v20
	v_mul_f32_e32 v70, v27, v186
	v_lshlrev_b32_e32 v192, 16, v192
	v_mul_f32_e32 v84, 0xbfb8aa3b, v192
	v_exp_f32_e32 v84, v84
	s_nop 0
	v_add_f32_e32 v84, 1.0, v84
	v_div_scale_f32 v71, s[28:29], v84, v84, v192
	v_rcp_f32_e32 v82, v71
	s_nop 0
	v_fma_f32 v92, -v71, v82, 1.0
	v_fmac_f32_e32 v82, v92, v82
	v_div_scale_f32 v88, vcc, v192, v84, v192
	v_mul_f32_e32 v90, v88, v82
	v_fma_f32 v92, -v71, v90, v88
	v_fmac_f32_e32 v90, v92, v82
	v_fma_f32 v71, -v71, v90, v88
	v_div_fmas_f32 v71, v71, v82, v90
	v_div_fixup_f32 v192, v71, v84, v192
	v_mul_f32_e32 v70, v70, v192
	v_lshlrev_b32_e32 v190, 16, v190
	v_lshlrev_b32_e32 v191, 16, v191
	v_lshlrev_b32_e32 v189, 16, v189
	v_mul_f32_e32 v189, v16, v189
	v_fmac_f32_e32 v189, v14, v190
	v_fmac_f32_e32 v189, v17, v191
	v_add_f32_e32 v189, v12, v189
	v_fma_f32 v27, v52, v8, v21
	v_mul_f32_e32 v110, v27, v189
	v_lshlrev_b32_e32 v193, 16, v193
	v_mul_f32_e32 v84, 0xbfb8aa3b, v193
	v_exp_f32_e32 v84, v84
	s_nop 0
	v_add_f32_e32 v84, 1.0, v84
	v_div_scale_f32 v71, s[28:29], v84, v84, v193
	v_rcp_f32_e32 v82, v71
	s_nop 0
	v_fma_f32 v92, -v71, v82, 1.0
	v_fmac_f32_e32 v82, v92, v82
	v_div_scale_f32 v88, vcc, v193, v84, v193
	v_mul_f32_e32 v90, v88, v82
	v_fma_f32 v92, -v71, v90, v88
	v_fmac_f32_e32 v90, v92, v82
	v_fma_f32 v71, -v71, v90, v88
	v_div_fmas_f32 v71, v71, v82, v90
	v_div_fixup_f32 v193, v71, v84, v193
	v_mul_f32_e32 v110, v110, v193
	v_cvt_pk_bf16_f32 v209, v70, v110
	s_waitcnt vmcnt(0)
	v_lshlrev_b32_e32 v195, 16, v195
	v_lshlrev_b32_e32 v196, 16, v196
	v_lshlrev_b32_e32 v194, 16, v194
	v_mul_f32_e32 v194, v16, v194
	v_fmac_f32_e32 v194, v14, v195
	v_fmac_f32_e32 v194, v17, v196
	v_add_f32_e32 v194, v12, v194
	v_fma_f32 v27, v55, v8, v4
	v_mul_f32_e32 v70, v27, v194
	v_lshlrev_b32_e32 v223, 16, v223
	v_mul_f32_e32 v84, 0xbfb8aa3b, v223
	v_exp_f32_e32 v84, v84
	s_nop 0
	v_add_f32_e32 v84, 1.0, v84
	v_div_scale_f32 v71, s[28:29], v84, v84, v223
	v_rcp_f32_e32 v82, v71
	s_nop 0
	v_fma_f32 v92, -v71, v82, 1.0
	v_fmac_f32_e32 v82, v92, v82
	v_div_scale_f32 v88, vcc, v223, v84, v223
	v_mul_f32_e32 v90, v88, v82
	v_fma_f32 v92, -v71, v90, v88
	v_fmac_f32_e32 v90, v92, v82
	v_fma_f32 v71, -v71, v90, v88
	v_div_fmas_f32 v71, v71, v82, v90
	v_div_fixup_f32 v223, v71, v84, v223
	v_mul_f32_e32 v70, v70, v223
	v_lshlrev_b32_e32 v221, 16, v221
	v_lshlrev_b32_e32 v222, 16, v222
	v_lshlrev_b32_e32 v197, 16, v197
	v_mul_f32_e32 v197, v16, v197
	v_fmac_f32_e32 v197, v14, v221
	v_fmac_f32_e32 v197, v17, v222
	v_add_f32_e32 v197, v12, v197
	v_fma_f32 v27, v57, v8, v5
	v_mul_f32_e32 v110, v27, v197
	v_lshlrev_b32_e32 v224, 16, v224
	v_mul_f32_e32 v84, 0xbfb8aa3b, v224
	v_exp_f32_e32 v84, v84
	s_nop 0
	v_add_f32_e32 v84, 1.0, v84
	v_div_scale_f32 v71, s[28:29], v84, v84, v224
	v_rcp_f32_e32 v82, v71
	s_nop 0
	v_fma_f32 v92, -v71, v82, 1.0
	v_fmac_f32_e32 v82, v92, v82
	v_div_scale_f32 v88, vcc, v224, v84, v224
	v_mul_f32_e32 v90, v88, v82
	v_fma_f32 v92, -v71, v90, v88
	v_fmac_f32_e32 v90, v92, v82
	v_fma_f32 v71, -v71, v90, v88
	v_div_fmas_f32 v71, v71, v82, v90
	v_div_fixup_f32 v224, v71, v84, v224
	v_mul_f32_e32 v110, v110, v224
	v_cvt_pk_bf16_f32 v210, v70, v110
	v_lshlrev_b32_e32 v226, 16, v226
	v_lshlrev_b32_e32 v227, 16, v227
	v_lshlrev_b32_e32 v225, 16, v225
	v_mul_f32_e32 v225, v16, v225
	v_fmac_f32_e32 v225, v14, v226
	v_fmac_f32_e32 v225, v17, v227
	v_add_f32_e32 v225, v12, v225
	v_fma_f32 v27, v54, v8, v6
	v_mul_f32_e32 v70, v27, v225
	v_lshlrev_b32_e32 v231, 16, v231
	v_mul_f32_e32 v84, 0xbfb8aa3b, v231
	v_exp_f32_e32 v84, v84
	s_nop 0
	v_add_f32_e32 v84, 1.0, v84
	v_div_scale_f32 v71, s[28:29], v84, v84, v231
	v_rcp_f32_e32 v82, v71
	s_nop 0
	v_fma_f32 v92, -v71, v82, 1.0
	v_fmac_f32_e32 v82, v92, v82
	v_div_scale_f32 v88, vcc, v231, v84, v231
	v_mul_f32_e32 v90, v88, v82
	v_fma_f32 v92, -v71, v90, v88
	v_fmac_f32_e32 v90, v92, v82
	v_fma_f32 v71, -v71, v90, v88
	v_div_fmas_f32 v71, v71, v82, v90
	v_div_fixup_f32 v231, v71, v84, v231
	v_mul_f32_e32 v70, v70, v231
	v_lshlrev_b32_e32 v229, 16, v229
	v_lshlrev_b32_e32 v230, 16, v230
	v_lshlrev_b32_e32 v228, 16, v228
	v_mul_f32_e32 v228, v16, v228
	v_fmac_f32_e32 v228, v14, v229
	v_fmac_f32_e32 v228, v17, v230
	v_add_f32_e32 v228, v12, v228
	v_fma_f32 v27, v56, v8, v7
	v_mul_f32_e32 v110, v27, v228
	v_lshlrev_b32_e32 v232, 16, v232
	v_mul_f32_e32 v84, 0xbfb8aa3b, v232
	v_exp_f32_e32 v84, v84
	s_nop 0
	v_add_f32_e32 v84, 1.0, v84
	v_div_scale_f32 v71, s[28:29], v84, v84, v232
	v_rcp_f32_e32 v82, v71
	s_nop 0
	v_fma_f32 v92, -v71, v82, 1.0
	v_fmac_f32_e32 v82, v92, v82
	v_div_scale_f32 v88, vcc, v232, v84, v232
	v_mul_f32_e32 v90, v88, v82
	v_fma_f32 v92, -v71, v90, v88
	v_fmac_f32_e32 v90, v92, v82
	v_fma_f32 v71, -v71, v90, v88
	v_div_fmas_f32 v71, v71, v82, v90
	v_div_fixup_f32 v232, v71, v84, v232
	v_mul_f32_e32 v110, v110, v232
	v_cvt_pk_bf16_f32 v211, v70, v110
	v_lshlrev_b32_e32 v234, 16, v234
	v_lshlrev_b32_e32 v235, 16, v235
	v_lshlrev_b32_e32 v233, 16, v233
	v_mul_f32_e32 v233, v16, v233
	v_fmac_f32_e32 v233, v14, v234
	v_fmac_f32_e32 v233, v17, v235
	v_add_f32_e32 v233, v12, v233
	v_fma_f32 v27, v59, v8, v0
	v_mul_f32_e32 v70, v27, v233
	v_lshlrev_b32_e32 v239, 16, v239
	v_mul_f32_e32 v84, 0xbfb8aa3b, v239
	v_exp_f32_e32 v84, v84
	s_nop 0
	v_add_f32_e32 v84, 1.0, v84
	v_div_scale_f32 v71, s[28:29], v84, v84, v239
	v_rcp_f32_e32 v82, v71
	s_nop 0
	v_fma_f32 v92, -v71, v82, 1.0
	v_fmac_f32_e32 v82, v92, v82
	v_div_scale_f32 v88, vcc, v239, v84, v239
	v_mul_f32_e32 v90, v88, v82
	v_fma_f32 v92, -v71, v90, v88
	v_fmac_f32_e32 v90, v92, v82
	v_fma_f32 v71, -v71, v90, v88
	v_div_fmas_f32 v71, v71, v82, v90
	v_div_fixup_f32 v239, v71, v84, v239
	v_mul_f32_e32 v70, v70, v239
	v_lshlrev_b32_e32 v237, 16, v237
	v_lshlrev_b32_e32 v238, 16, v238
	v_lshlrev_b32_e32 v236, 16, v236
	v_mul_f32_e32 v236, v16, v236
	v_fmac_f32_e32 v236, v14, v237
	v_fmac_f32_e32 v236, v17, v238
	v_add_f32_e32 v236, v12, v236
	v_fma_f32 v27, v61, v8, v1
	v_mul_f32_e32 v110, v27, v236
	v_lshlrev_b32_e32 v240, 16, v240
	v_mul_f32_e32 v84, 0xbfb8aa3b, v240
	v_exp_f32_e32 v84, v84
	s_nop 0
	v_add_f32_e32 v84, 1.0, v84
	v_div_scale_f32 v71, s[28:29], v84, v84, v240
	v_rcp_f32_e32 v82, v71
	s_nop 0
	v_fma_f32 v92, -v71, v82, 1.0
	v_fmac_f32_e32 v82, v92, v82
	v_div_scale_f32 v88, vcc, v240, v84, v240
	v_mul_f32_e32 v90, v88, v82
	v_fma_f32 v92, -v71, v90, v88
	v_fmac_f32_e32 v90, v92, v82
	v_fma_f32 v71, -v71, v90, v88
	v_div_fmas_f32 v71, v71, v82, v90
	v_div_fixup_f32 v240, v71, v84, v240
	v_mul_f32_e32 v110, v110, v240
	v_cvt_pk_bf16_f32 v212, v70, v110
	v_lshlrev_b32_e32 v242, 16, v242
	v_lshlrev_b32_e32 v243, 16, v243
	v_lshlrev_b32_e32 v241, 16, v241
	v_mul_f32_e32 v241, v16, v241
	v_mul_f32_e32 v243, v255, v243
	v_fmac_f32_e32 v241, v14, v242
	v_fmac_f32_e32 v241, v17, v243
	v_add_f32_e32 v241, v12, v241
	v_fma_f32 v27, v58, v8, v2
	v_mul_f32_e32 v70, v27, v241
	v_lshlrev_b32_e32 v247, 16, v247
	v_mul_f32_e32 v84, 0xbfb8aa3b, v247
	v_exp_f32_e32 v84, v84
	s_nop 0
	v_add_f32_e32 v84, 1.0, v84
	v_div_scale_f32 v71, s[28:29], v84, v84, v247
	v_rcp_f32_e32 v82, v71
	s_nop 0
	v_fma_f32 v92, -v71, v82, 1.0
	v_fmac_f32_e32 v82, v92, v82
	v_div_scale_f32 v88, vcc, v247, v84, v247
	v_mul_f32_e32 v90, v88, v82
	v_fma_f32 v92, -v71, v90, v88
	v_fmac_f32_e32 v90, v92, v82
	v_fma_f32 v71, -v71, v90, v88
	v_div_fmas_f32 v71, v71, v82, v90
	v_div_fixup_f32 v247, v71, v84, v247
	v_mul_f32_e32 v70, v70, v247
	v_lshlrev_b32_e32 v245, 16, v245
	v_lshlrev_b32_e32 v246, 16, v246
	v_lshlrev_b32_e32 v244, 16, v244
	v_mul_f32_e32 v244, v16, v244
	v_mul_f32_e32 v246, v255, v246
	v_fmac_f32_e32 v244, v14, v245
	v_fmac_f32_e32 v244, v17, v246
	v_add_f32_e32 v244, v12, v244
	v_fma_f32 v27, v60, v8, v3
	v_mul_f32_e32 v110, v27, v244
	v_lshlrev_b32_e32 v248, 16, v248
	v_mul_f32_e32 v84, 0xbfb8aa3b, v248
	v_exp_f32_e32 v84, v84
	s_nop 0
	v_add_f32_e32 v84, 1.0, v84
	v_div_scale_f32 v71, s[28:29], v84, v84, v248
	v_rcp_f32_e32 v82, v71
	s_nop 0
	v_fma_f32 v92, -v71, v82, 1.0
	v_fmac_f32_e32 v82, v92, v82
	v_div_scale_f32 v88, vcc, v248, v84, v248
	v_mul_f32_e32 v90, v88, v82
	v_fma_f32 v92, -v71, v90, v88
	v_fmac_f32_e32 v90, v92, v82
	v_fma_f32 v71, -v71, v90, v88
	v_div_fmas_f32 v71, v71, v82, v90
	v_div_fixup_f32 v248, v71, v84, v248
	v_mul_f32_e32 v110, v110, v248
	v_cvt_pk_bf16_f32 v213, v70, v110
	s_branch .Lhy_ep1_done_L0

.LBB0_910:
	s_lshl_b32 s0, s16, 11
	s_add_u32 s0, s45, s0
	s_addc_u32 s1, s24, 0
	global_load_dword v221, v145, s[0:1]
	s_lshl_b32 s4, s16, 9
	s_add_i32 s4, s4, 0x200
	s_add_i32 s0, s4, s62
	s_ashr_i32 s1, s0, 31
	s_lshl_b32 s6, s4, 2
	s_add_u32 s4, s64, s6
	s_addc_u32 s5, s65, 0
	s_lshl_b64 s[0:1], s[0:1], 14
	v_mov_b32_e32 v163, s6
	s_add_u32 s8, s26, s0
	s_addc_u32 s9, s27, s1
	s_add_u32 s10, s30, s0
	s_addc_u32 s11, s31, s1
	v_lshlrev_b32_e32 v232, 1, v146
	v_min_i32_e32 v233, 0x1ffe, v146
	v_max_i32_e32 v234, 1, v146
	global_load_dword v222, v163, s[64:65]
	global_load_dword v223, v151, s[4:5] offset:2048
	global_load_dword v224, v152, s[4:5]
	global_load_dword v225, v163, s[68:69]
	v_lshlrev_b32_e32 v233, 1, v233
	v_lshlrev_b32_e32 v234, 1, v234
	global_load_ushort v226, v232, s[8:9]
	global_load_ushort v227, v233, s[8:9] offset:2
	global_load_ushort v228, v234, s[8:9] offset:-2
	global_load_ushort v229, v232, s[10:11]
	global_load_ushort v230, v233, s[10:11] offset:2
	global_load_ushort v231, v234, s[10:11] offset:-2
	s_lshl_b32 s98, s16, 16
	s_mov_b32 s99, 0
	v_lshl_add_u64 v[196:197], s[98:99], 0, v[28:29]
	global_load_dwordx4 v[164:167], v[196:197], off offset:-4096
	global_load_dwordx4 v[168:171], v[196:197], off offset:-3072
	global_load_dwordx4 v[172:175], v[196:197], off offset:-2048
	global_load_dwordx4 v[176:179], v[196:197], off offset:-1024
	global_load_dwordx4 v[180:183], v[196:197], off
	global_load_dwordx4 v[184:187], v[196:197], off offset:1024
	global_load_dwordx4 v[188:191], v[196:197], off offset:2048
	global_load_dwordx4 v[192:195], v[196:197], off offset:3072
	v_mov_b32_e32 v20, v46
	v_mov_b32_e32 v21, v48
	v_mov_b32_e32 v22, v51
	v_mov_b32_e32 v23, v53
	v_pk_add_f32 v[88:89], v[20:21], 0 op_sel_hi:[1,0]
	v_pk_mul_f32 v[20:21], v[20:21], s[48:49] op_sel_hi:[1,0]
	v_xor_b32_e32 v91, 0x80000000, v46
	v_mov_b32_e32 v90, v48
	v_pk_add_f32 v[92:93], v[50:51], 0 neg_lo:[1,1] neg_hi:[1,1]
	v_mov_b32_e32 v24, v50
	v_mov_b32_e32 v25, v52
	v_pk_fma_f32 v[20:21], v[90:91], s[44:45], v[20:21] op_sel_hi:[1,0,1] neg_lo:[0,0,1] neg_hi:[0,0,1]
	v_pk_add_f32 v[90:91], v[22:23], 0 op_sel_hi:[1,0]
	v_pk_mul_f32 v[22:23], v[22:23], s[54:55] op_sel_hi:[1,0]
	v_mov_b32_e32 v92, v53
	v_mov_b32_e32 v26, v55
	v_mov_b32_e32 v27, v57
	v_pk_fma_f32 v[22:23], v[92:93], s[52:53], v[22:23] op_sel_hi:[1,0,1] neg_lo:[0,0,1] neg_hi:[0,0,1]
	v_pk_add_f32 v[92:93], v[24:25], 0 op_sel_hi:[1,0]
	v_pk_mul_f32 v[24:25], v[24:25], s[58:59] op_sel_hi:[1,0]
	v_xor_b32_e32 v95, 0x80000000, v50
	v_mov_b32_e32 v94, v52
	v_pk_add_f32 v[96:97], v[54:55], 0 neg_lo:[1,1] neg_hi:[1,1]
	v_mov_b32_e32 v64, v54
	v_mov_b32_e32 v65, v56
	v_pk_fma_f32 v[24:25], v[94:95], s[56:57], v[24:25] op_sel_hi:[1,0,1] neg_lo:[0,0,1] neg_hi:[0,0,1]
	v_pk_add_f32 v[94:95], v[26:27], 0 op_sel_hi:[1,0]
	v_pk_mul_f32 v[26:27], v[26:27], s[60:61] op_sel_hi:[1,0]
	v_mov_b32_e32 v96, v57
	v_mov_b32_e32 v66, v59
	v_mov_b32_e32 v67, v61
	v_pk_fma_f32 v[26:27], v[96:97], s[60:61], v[26:27] op_sel_hi:[1,0,1] neg_lo:[0,0,1] neg_hi:[0,0,1]
	v_pk_add_f32 v[96:97], v[64:65], 0 op_sel_hi:[1,0]
	v_pk_mul_f32 v[64:65], v[64:65], s[56:57] op_sel_hi:[1,0]
	v_xor_b32_e32 v99, 0x80000000, v54
	v_mov_b32_e32 v98, v56
	v_pk_add_f32 v[100:101], v[58:59], 0 neg_lo:[1,1] neg_hi:[1,1]
	v_mov_b32_e32 v2, v32
	v_mov_b32_e32 v3, v34
	v_mov_b32_e32 v4, v33
	v_mov_b32_e32 v5, v35
	v_mov_b32_e32 v18, v47
	v_mov_b32_e32 v19, v49
	v_mov_b32_e32 v68, v58
	v_mov_b32_e32 v69, v60
	v_pk_fma_f32 v[64:65], v[98:99], s[58:59], v[64:65] op_sel_hi:[1,0,1] neg_lo:[0,0,1] neg_hi:[0,0,1]
	v_pk_add_f32 v[98:99], v[66:67], 0 op_sel_hi:[1,0]
	v_pk_mul_f32 v[66:67], v[66:67], s[52:53] op_sel_hi:[1,0]
	v_mov_b32_e32 v100, v61
	v_pk_add_f32 v[70:71], v[2:3], 0 op_sel_hi:[1,0]
	v_pk_add_f32 v[72:73], v[4:5], 0 op_sel_hi:[1,0]
	v_pk_add_f32 v[74:75], v[32:33], 0 neg_lo:[1,1] neg_hi:[1,1]
	v_pk_add_f32 v[18:19], v[18:19], 0 op_sel_hi:[1,0]
	v_pk_fma_f32 v[66:67], v[100:101], s[54:55], v[66:67] op_sel_hi:[1,0,1] neg_lo:[0,0,1] neg_hi:[0,0,1]
	v_pk_add_f32 v[100:101], v[68:69], 0 op_sel_hi:[1,0]
	v_pk_mul_f32 v[68:69], v[68:69], s[44:45] op_sel_hi:[1,0]
	v_xor_b32_e32 v103, 0x80000000, v58
	v_mov_b32_e32 v102, v60
	v_mov_b32_e32 v74, v35
	v_pk_fma_f32 v[68:69], v[102:103], s[48:49], v[68:69] op_sel_hi:[1,0,1] neg_lo:[0,0,1] neg_hi:[0,0,1]
	v_pk_add_f32 v[102:103], v[18:19], v[70:71]
	v_pk_add_f32 v[18:19], v[70:71], v[18:19] neg_lo:[0,1] neg_hi:[0,1]
	v_pk_add_f32 v[70:71], v[88:89], v[72:73]
	v_pk_add_f32 v[72:73], v[72:73], v[88:89] neg_lo:[0,1] neg_hi:[0,1]
	v_mov_b32_e32 v6, v37
	v_mov_b32_e32 v7, v31
	v_pk_mul_f32 v[74:75], v[74:75], s[48:49] op_sel_hi:[1,0]
	s_nop 0
	v_pk_fma_f32 v[4:5], v[4:5], s[44:45], v[74:75] op_sel_hi:[1,0,1]
	v_pk_add_f32 v[74:75], v[6:7], 0 op_sel_hi:[1,0]
	v_pk_add_f32 v[76:77], v[36:37], 0 neg_lo:[1,1] neg_hi:[1,1]
	v_pk_mul_f32 v[88:89], v[72:73], s[54:55] op_sel:[1,0] op_sel_hi:[0,0] neg_hi:[1,0]
	v_mov_b32_e32 v76, v31
	v_pk_fma_f32 v[72:73], v[72:73], s[52:53], v[88:89] op_sel_hi:[1,0,1]
	v_pk_add_f32 v[88:89], v[90:91], v[74:75]
	v_pk_add_f32 v[74:75], v[74:75], v[90:91] neg_lo:[0,1] neg_hi:[0,1]
	v_mov_b32_e32 v8, v36
	v_mov_b32_e32 v9, v30
	v_pk_mul_f32 v[76:77], v[76:77], s[54:55] op_sel_hi:[1,0]
	s_nop 0
	v_pk_fma_f32 v[6:7], v[6:7], s[52:53], v[76:77] op_sel_hi:[1,0,1]
	v_pk_add_f32 v[76:77], v[8:9], 0 op_sel_hi:[1,0]
	v_pk_mul_f32 v[90:91], v[74:75], s[60:61] op_sel:[1,0] op_sel_hi:[0,0] neg_hi:[1,0]
	v_xor_b32_e32 v79, 0x80000000, v36
	v_mov_b32_e32 v78, v30
	v_pk_add_f32 v[80:81], v[38:39], 0 neg_lo:[1,1] neg_hi:[1,1]
	v_pk_fma_f32 v[74:75], v[74:75], s[60:61], v[90:91] op_sel_hi:[1,0,1]
	v_pk_add_f32 v[90:91], v[92:93], v[76:77]
	v_pk_add_f32 v[76:77], v[76:77], v[92:93] neg_lo:[0,1] neg_hi:[0,1]
	v_mov_b32_e32 v10, v39
	v_mov_b32_e32 v11, v41
	v_pk_mul_f32 v[78:79], v[78:79], s[58:59] op_sel_hi:[1,0]
	v_mov_b32_e32 v80, v41
	v_mov_b32_e32 v12, v38
	v_mov_b32_e32 v13, v40
	v_pk_fma_f32 v[8:9], v[8:9], s[56:57], v[78:79] op_sel_hi:[1,0,1]
	v_pk_add_f32 v[78:79], v[10:11], 0 op_sel_hi:[1,0]
	v_pk_mul_f32 v[80:81], v[80:81], s[60:61] op_sel_hi:[1,0]
	v_pk_mul_f32 v[92:93], v[76:77], s[52:53] op_sel:[1,0] op_sel_hi:[0,0] neg_hi:[1,0]
	v_pk_fma_f32 v[10:11], v[10:11], s[60:61], v[80:81] op_sel_hi:[1,0,1]
	v_pk_add_f32 v[80:81], v[12:13], 0 op_sel_hi:[1,0]
	v_xor_b32_e32 v83, 0x80000000, v38
	v_mov_b32_e32 v82, v40
	v_pk_fma_f32 v[76:77], v[76:77], s[54:55], v[92:93] op_sel_hi:[1,0,1]
	v_pk_add_f32 v[92:93], v[94:95], v[78:79]
	v_pk_add_f32 v[78:79], v[78:79], v[94:95] neg_lo:[0,1] neg_hi:[0,1]
	v_mov_b32_e32 v14, v43
	v_mov_b32_e32 v15, v45
	v_pk_mul_f32 v[82:83], v[82:83], s[56:57] op_sel_hi:[1,0]
	v_pk_add_f32 v[84:85], v[42:43], 0 neg_lo:[1,1] neg_hi:[1,1]
	v_xor_b32_e32 v95, 0x80000000, v78
	v_mov_b32_e32 v94, v79
	v_pk_add_f32 v[78:79], v[96:97], v[80:81]
	v_pk_add_f32 v[80:81], v[80:81], v[96:97] neg_lo:[0,1] neg_hi:[0,1]
	v_pk_fma_f32 v[12:13], v[12:13], s[58:59], v[82:83] op_sel_hi:[1,0,1]
	v_pk_add_f32 v[82:83], v[14:15], 0 op_sel_hi:[1,0]
	v_mov_b32_e32 v84, v45
	v_pk_mul_f32 v[96:97], v[80:81], s[54:55] op_sel_hi:[1,0]
	v_xor_b32_e32 v105, 0x80000000, v80
	v_mov_b32_e32 v104, v81
	v_mov_b32_e32 v16, v42
	v_mov_b32_e32 v17, v44
	v_pk_mul_f32 v[84:85], v[84:85], s[52:53] op_sel_hi:[1,0]
	v_xor_b32_e32 v87, 0x80000000, v42
	v_mov_b32_e32 v86, v44
	v_pk_fma_f32 v[80:81], v[104:105], s[52:53], v[96:97] op_sel_hi:[1,0,1] neg_lo:[0,0,1] neg_hi:[0,0,1]
	v_pk_add_f32 v[96:97], v[98:99], v[82:83]
	v_pk_add_f32 v[82:83], v[82:83], v[98:99] neg_lo:[0,1] neg_hi:[0,1]
	v_pk_fma_f32 v[14:15], v[14:15], s[54:55], v[84:85] op_sel_hi:[1,0,1]
	v_pk_add_f32 v[84:85], v[16:17], 0 op_sel_hi:[1,0]
	v_pk_mul_f32 v[86:87], v[86:87], s[44:45] op_sel_hi:[1,0]
	v_pk_mul_f32 v[98:99], v[82:83], s[60:61] op_sel_hi:[1,0]
	v_xor_b32_e32 v105, 0x80000000, v82
	v_mov_b32_e32 v104, v83
	v_pk_fma_f32 v[16:17], v[16:17], s[48:49], v[86:87] op_sel_hi:[1,0,1]
	v_pk_add_f32 v[86:87], v[46:47], 0 neg_lo:[1,1] neg_hi:[1,1]
	v_pk_fma_f32 v[82:83], v[104:105], s[60:61], v[98:99] op_sel_hi:[1,0,1] neg_lo:[0,0,1] neg_hi:[0,0,1]
	v_pk_add_f32 v[98:99], v[100:101], v[84:85]
	v_pk_add_f32 v[84:85], v[84:85], v[100:101] neg_lo:[0,1] neg_hi:[0,1]
	v_mov_b32_e32 v86, v49
	v_pk_mul_f32 v[100:101], v[84:85], s[52:53] op_sel_hi:[1,0]
	v_xor_b32_e32 v105, 0x80000000, v84
	v_mov_b32_e32 v104, v85
	v_pk_fma_f32 v[84:85], v[104:105], s[54:55], v[100:101] op_sel_hi:[1,0,1] neg_lo:[0,0,1] neg_hi:[0,0,1]
	v_pk_add_f32 v[100:101], v[86:87], v[2:3]
	v_pk_add_f32 v[2:3], v[2:3], v[86:87] neg_lo:[0,1] neg_hi:[0,1]
	v_pk_add_f32 v[86:87], v[20:21], v[4:5]
	v_pk_add_f32 v[4:5], v[4:5], v[20:21] neg_lo:[0,1] neg_hi:[0,1]
	v_mov_b32_e32 v63, v146
	v_pk_mul_f32 v[20:21], v[4:5], s[54:55] op_sel:[1,0] op_sel_hi:[0,0] neg_hi:[1,0]
	s_nop 0
	v_pk_fma_f32 v[4:5], v[4:5], s[52:53], v[20:21] op_sel_hi:[1,0,1]
	v_pk_add_f32 v[20:21], v[22:23], v[6:7]
	v_pk_add_f32 v[6:7], v[6:7], v[22:23] neg_lo:[0,1] neg_hi:[0,1]
	s_barrier
	v_pk_mul_f32 v[22:23], v[6:7], s[60:61] op_sel:[1,0] op_sel_hi:[0,0] neg_hi:[1,0]
	s_nop 0
	v_pk_fma_f32 v[6:7], v[6:7], s[60:61], v[22:23] op_sel_hi:[1,0,1]
	v_pk_add_f32 v[22:23], v[24:25], v[8:9]
	v_pk_add_f32 v[8:9], v[8:9], v[24:25] neg_lo:[0,1] neg_hi:[0,1]
	s_add_i32 s19, 16, 0x11000
	v_pk_mul_f32 v[24:25], v[8:9], s[52:53] op_sel:[1,0] op_sel_hi:[0,0] neg_hi:[1,0]
	s_add_i32 s18, 16, 0x12000
	v_pk_fma_f32 v[8:9], v[8:9], s[54:55], v[24:25] op_sel_hi:[1,0,1]
	v_pk_add_f32 v[24:25], v[26:27], v[10:11]
	v_pk_add_f32 v[10:11], v[10:11], v[26:27] neg_lo:[0,1] neg_hi:[0,1]
	s_add_i32 s17, 16, 0x13000
	v_xor_b32_e32 v27, 0x80000000, v10
	v_mov_b32_e32 v26, v11
	v_pk_add_f32 v[10:11], v[64:65], v[12:13]
	v_pk_add_f32 v[12:13], v[12:13], v[64:65] neg_lo:[0,1] neg_hi:[0,1]
	s_add_i32 s13, 16, 0x14000
	v_pk_mul_f32 v[64:65], v[12:13], s[54:55] op_sel_hi:[1,0]
	v_xor_b32_e32 v105, 0x80000000, v12
	v_mov_b32_e32 v104, v13
	v_pk_fma_f32 v[12:13], v[104:105], s[52:53], v[64:65] op_sel_hi:[1,0,1] neg_lo:[0,0,1] neg_hi:[0,0,1]
	v_pk_add_f32 v[64:65], v[66:67], v[14:15]
	v_pk_add_f32 v[14:15], v[14:15], v[66:67] neg_lo:[0,1] neg_hi:[0,1]
	s_add_i32 s12, 16, 0x15000
	v_pk_mul_f32 v[66:67], v[14:15], s[60:61] op_sel_hi:[1,0]
	v_xor_b32_e32 v105, 0x80000000, v14
	v_mov_b32_e32 v104, v15
	v_pk_fma_f32 v[14:15], v[104:105], s[60:61], v[66:67] op_sel_hi:[1,0,1] neg_lo:[0,0,1] neg_hi:[0,0,1]
	v_pk_add_f32 v[66:67], v[68:69], v[16:17]
	v_pk_add_f32 v[16:17], v[16:17], v[68:69] neg_lo:[0,1] neg_hi:[0,1]
	s_add_i32 s11, 16, 0x16000
	v_pk_mul_f32 v[68:69], v[16:17], s[52:53] op_sel_hi:[1,0]
	v_xor_b32_e32 v105, 0x80000000, v16
	v_mov_b32_e32 v104, v17
	v_pk_fma_f32 v[16:17], v[104:105], s[54:55], v[68:69] op_sel_hi:[1,0,1] neg_lo:[0,0,1] neg_hi:[0,0,1]
	v_pk_add_f32 v[68:69], v[92:93], v[102:103]
	v_pk_add_f32 v[92:93], v[102:103], v[92:93] neg_lo:[0,1] neg_hi:[0,1]
	v_pk_add_f32 v[102:103], v[78:79], v[70:71]
	v_pk_add_f32 v[70:71], v[70:71], v[78:79] neg_lo:[0,1] neg_hi:[0,1]
	s_add_i32 s10, 16, 0x17000
	v_pk_mul_f32 v[78:79], v[70:71], s[60:61] op_sel:[1,0] op_sel_hi:[0,0] neg_hi:[1,0]
	s_add_i32 s9, 16, 0x18000
	v_pk_fma_f32 v[70:71], v[70:71], s[60:61], v[78:79] op_sel_hi:[1,0,1]
	v_pk_add_f32 v[78:79], v[96:97], v[88:89]
	v_pk_add_f32 v[88:89], v[88:89], v[96:97] neg_lo:[0,1] neg_hi:[0,1]
	s_add_i32 s8, 16, 0x19000
	v_xor_b32_e32 v97, 0x80000000, v88
	v_mov_b32_e32 v96, v89
	v_pk_add_f32 v[88:89], v[98:99], v[90:91]
	v_pk_add_f32 v[90:91], v[90:91], v[98:99] neg_lo:[0,1] neg_hi:[0,1]
	s_add_i32 s7, 16, 0x1a000
	v_pk_mul_f32 v[98:99], v[90:91], s[60:61] op_sel_hi:[1,0]
	v_xor_b32_e32 v105, 0x80000000, v90
	v_mov_b32_e32 v104, v91
	v_pk_fma_f32 v[90:91], v[104:105], s[60:61], v[98:99] op_sel_hi:[1,0,1] neg_lo:[0,0,1] neg_hi:[0,0,1]
	v_pk_add_f32 v[98:99], v[94:95], v[18:19]
	v_pk_add_f32 v[18:19], v[18:19], v[94:95] neg_lo:[0,1] neg_hi:[0,1]
	v_pk_add_f32 v[94:95], v[80:81], v[72:73]
	v_pk_add_f32 v[72:73], v[72:73], v[80:81] neg_lo:[0,1] neg_hi:[0,1]
	s_add_i32 s6, 16, 0x1b000
	v_pk_mul_f32 v[80:81], v[72:73], s[60:61] op_sel:[1,0] op_sel_hi:[0,0] neg_hi:[1,0]
	s_add_i32 s5, 16, 0x1c000
	v_pk_fma_f32 v[72:73], v[72:73], s[60:61], v[80:81] op_sel_hi:[1,0,1]
	v_pk_add_f32 v[80:81], v[82:83], v[74:75]
	v_pk_add_f32 v[74:75], v[74:75], v[82:83] neg_lo:[0,1] neg_hi:[0,1]
	s_add_i32 s4, 16, 0x1d000
	v_xor_b32_e32 v83, 0x80000000, v74
	v_mov_b32_e32 v82, v75
	v_pk_add_f32 v[74:75], v[84:85], v[76:77]
	v_pk_add_f32 v[76:77], v[76:77], v[84:85] neg_lo:[0,1] neg_hi:[0,1]
	v_pk_add_f32 v[106:107], v[18:19], v[82:83]
	v_pk_mul_f32 v[84:85], v[76:77], s[60:61] op_sel_hi:[1,0]
	v_xor_b32_e32 v105, 0x80000000, v76
	v_mov_b32_e32 v104, v77
	v_pk_fma_f32 v[76:77], v[104:105], s[60:61], v[84:85] op_sel_hi:[1,0,1] neg_lo:[0,0,1] neg_hi:[0,0,1]
	v_pk_add_f32 v[84:85], v[24:25], v[100:101]
	v_pk_add_f32 v[24:25], v[100:101], v[24:25] neg_lo:[0,1] neg_hi:[0,1]
	v_pk_add_f32 v[100:101], v[10:11], v[86:87]
	v_pk_add_f32 v[10:11], v[86:87], v[10:11] neg_lo:[0,1] neg_hi:[0,1]
	v_pk_add_f32 v[18:19], v[18:19], v[82:83] neg_lo:[0,1] neg_hi:[0,1]
	v_pk_mul_f32 v[86:87], v[10:11], s[60:61] op_sel:[1,0] op_sel_hi:[0,0] neg_hi:[1,0]
	v_pk_add_f32 v[82:83], v[76:77], v[72:73]
	v_pk_fma_f32 v[10:11], v[10:11], s[60:61], v[86:87] op_sel_hi:[1,0,1]
	v_pk_add_f32 v[86:87], v[64:65], v[20:21]
	v_pk_add_f32 v[20:21], v[20:21], v[64:65] neg_lo:[0,1] neg_hi:[0,1]
	v_pk_add_f32 v[72:73], v[72:73], v[76:77] neg_lo:[0,1] neg_hi:[0,1]
	v_xor_b32_e32 v65, 0x80000000, v20
	v_mov_b32_e32 v64, v21
	v_pk_add_f32 v[20:21], v[66:67], v[22:23]
	v_pk_add_f32 v[22:23], v[22:23], v[66:67] neg_lo:[0,1] neg_hi:[0,1]
	v_xor_b32_e32 v77, 0x80000000, v72
	v_pk_mul_f32 v[66:67], v[22:23], s[60:61] op_sel_hi:[1,0]
	v_xor_b32_e32 v105, 0x80000000, v22
	v_mov_b32_e32 v104, v23
	v_pk_fma_f32 v[22:23], v[104:105], s[60:61], v[66:67] op_sel_hi:[1,0,1] neg_lo:[0,0,1] neg_hi:[0,0,1]
	v_pk_add_f32 v[66:67], v[2:3], v[26:27]
	v_pk_add_f32 v[2:3], v[2:3], v[26:27] neg_lo:[0,1] neg_hi:[0,1]
	v_pk_add_f32 v[26:27], v[12:13], v[4:5]
	v_pk_add_f32 v[4:5], v[4:5], v[12:13] neg_lo:[0,1] neg_hi:[0,1]
	v_mov_b32_e32 v76, v73
	v_pk_mul_f32 v[12:13], v[4:5], s[60:61] op_sel:[1,0] op_sel_hi:[0,0] neg_hi:[1,0]
	v_pk_add_f32 v[72:73], v[84:85], v[86:87]
	v_pk_fma_f32 v[4:5], v[4:5], s[60:61], v[12:13] op_sel_hi:[1,0,1]
	v_pk_add_f32 v[12:13], v[14:15], v[6:7]
	v_pk_add_f32 v[6:7], v[6:7], v[14:15] neg_lo:[0,1] neg_hi:[0,1]
	v_pk_add_f32 v[84:85], v[84:85], v[86:87] neg_lo:[0,1] neg_hi:[0,1]
	v_xor_b32_e32 v15, 0x80000000, v6
	v_mov_b32_e32 v14, v7
	v_pk_add_f32 v[6:7], v[16:17], v[8:9]
	v_pk_add_f32 v[8:9], v[8:9], v[16:17] neg_lo:[0,1] neg_hi:[0,1]
	v_pk_add_f32 v[86:87], v[20:21], v[100:101]
	v_pk_mul_f32 v[16:17], v[8:9], s[60:61] op_sel_hi:[1,0]
	s_nop 0
	v_pk_fma_f32 v[8:9], v[8:9], s[60:61], v[16:17] op_sel:[1,0,0] op_sel_hi:[0,0,1] neg_lo:[0,0,1] neg_hi:[1,0,1]
	v_pk_add_f32 v[104:105], v[92:93], v[96:97]
	v_pk_add_f32 v[92:93], v[92:93], v[96:97] neg_lo:[0,1] neg_hi:[0,1]
	v_pk_add_f32 v[96:97], v[90:91], v[70:71]
	v_pk_add_f32 v[70:71], v[70:71], v[90:91] neg_lo:[0,1] neg_hi:[0,1]
	v_pk_add_f32 v[16:17], v[78:79], v[68:69]
	v_pk_add_f32 v[68:69], v[68:69], v[78:79] neg_lo:[0,1] neg_hi:[0,1]
	v_pk_add_f32 v[78:79], v[88:89], v[102:103]
	v_pk_add_f32 v[88:89], v[102:103], v[88:89] neg_lo:[0,1] neg_hi:[0,1]
	v_xor_b32_e32 v91, 0x80000000, v70
	v_mov_b32_e32 v90, v71
	v_pk_add_f32 v[70:71], v[98:99], v[80:81]
	v_pk_add_f32 v[98:99], v[98:99], v[80:81] neg_lo:[0,1] neg_hi:[0,1]
	v_pk_add_f32 v[80:81], v[74:75], v[94:95]
	v_pk_add_f32 v[74:75], v[94:95], v[74:75] neg_lo:[0,1] neg_hi:[0,1]
	v_pk_add_f32 v[20:21], v[100:101], v[20:21] neg_lo:[0,1] neg_hi:[0,1]
	v_pk_add_f32 v[108:109], v[24:25], v[64:65]
	v_pk_add_f32 v[24:25], v[24:25], v[64:65] neg_lo:[0,1] neg_hi:[0,1]
	v_pk_add_f32 v[64:65], v[22:23], v[10:11]
	v_pk_add_f32 v[10:11], v[10:11], v[22:23] neg_lo:[0,1] neg_hi:[0,1]
	v_pk_add_f32 v[114:115], v[6:7], v[26:27]
	v_pk_add_f32 v[6:7], v[26:27], v[6:7] neg_lo:[0,1] neg_hi:[0,1]
	v_xor_b32_e32 v103, 0x80000000, v88
	v_mov_b32_e32 v102, v89
	v_xor_b32_e32 v95, 0x80000000, v74
	v_mov_b32_e32 v94, v75
	v_xor_b32_e32 v101, 0x80000000, v20
	v_mov_b32_e32 v100, v21
	v_xor_b32_e32 v27, 0x80000000, v6
	v_mov_b32_e32 v26, v7
	v_pk_add_f32 v[6:7], v[2:3], v[14:15]
	v_pk_add_f32 v[116:117], v[2:3], v[14:15] neg_lo:[0,1] neg_hi:[0,1]
	v_pk_add_f32 v[2:3], v[4:5], v[8:9] neg_lo:[0,1] neg_hi:[0,1]
	v_pk_add_f32 v[112:113], v[66:67], v[12:13]
	v_pk_add_f32 v[66:67], v[66:67], v[12:13] neg_lo:[0,1] neg_hi:[0,1]
	v_pk_add_f32 v[118:119], v[8:9], v[4:5]
	v_xor_b32_e32 v121, 0x80000000, v2
	v_mov_b32_e32 v120, v3
	v_pk_add_f32 v[2:3], v[78:79], v[16:17]
	v_pk_add_f32 v[88:89], v[16:17], v[78:79] neg_lo:[0,1] neg_hi:[0,1]
	v_pk_add_f32 v[122:123], v[68:69], v[102:103]
	v_pk_add_f32 v[20:21], v[68:69], v[102:103] neg_lo:[0,1] neg_hi:[0,1]
	v_pk_add_f32 v[78:79], v[104:105], v[96:97]
	v_pk_add_f32 v[74:75], v[104:105], v[96:97] neg_lo:[0,1] neg_hi:[0,1]
	v_pk_add_f32 v[96:97], v[92:93], v[90:91]
	v_pk_add_f32 v[8:9], v[92:93], v[90:91] neg_lo:[0,1] neg_hi:[0,1]
	v_pk_add_f32 v[102:103], v[98:99], v[94:95]
	v_pk_add_f32 v[12:13], v[98:99], v[94:95] neg_lo:[0,1] neg_hi:[0,1]
	v_pk_add_f32 v[98:99], v[18:19], v[76:77]
	v_pk_add_f32 v[4:5], v[18:19], v[76:77] neg_lo:[0,1] neg_hi:[0,1]
	v_pk_add_f32 v[18:19], v[72:73], v[86:87]
	v_pk_add_f32 v[92:93], v[72:73], v[86:87] neg_lo:[0,1] neg_hi:[0,1]
	v_pk_add_f32 v[86:87], v[84:85], v[100:101]
	v_pk_add_f32 v[22:23], v[84:85], v[100:101] neg_lo:[0,1] neg_hi:[0,1]
	v_pk_add_f32 v[100:101], v[24:25], v[10:11] op_sel:[0,1] op_sel_hi:[1,0] neg_hi:[0,1]
	v_pk_add_f32 v[10:11], v[24:25], v[10:11] op_sel:[0,1] op_sel_hi:[1,0] neg_lo:[0,1]
	v_mov_b32_e32 v24, v63
	v_pk_add_f32 v[84:85], v[108:109], v[64:65]
	v_cvt_f32_i32_e32 v24, v24
	v_pk_add_f32 v[76:77], v[108:109], v[64:65] neg_lo:[0,1] neg_hi:[0,1]
	v_pk_add_f32 v[104:105], v[66:67], v[26:27]
	v_pk_add_f32 v[14:15], v[66:67], v[26:27] neg_lo:[0,1] neg_hi:[0,1]
	v_mul_f32_e32 v25, 0x38800000, v24
	v_cos_f32_e32 v24, v25
	v_sin_f32_e32 v25, v25
	s_nop 0
	s_nop 0
	v_add_f32_e32 v62, v24, v24
	v_pk_mul_f32 v[26:27], v[24:25], v[24:25]
	v_mul_f32_e32 v62, v25, v62
	s_nop 0
	s_nop 0
	v_mov_b32_e32 v108, v25
	v_pk_add_f32 v[26:27], v[26:27], v[26:27] op_sel:[0,1] op_sel_hi:[0,1] neg_lo:[0,1] neg_hi:[0,1]
	v_pk_mul_f32 v[72:73], v[24:25], v[62:63] op_sel:[1,0] op_sel_hi:[0,0] neg_lo:[1,0]
	v_pk_mul_f32 v[94:95], v[18:19], v[108:109] op_sel:[1,0] op_sel_hi:[0,0] neg_hi:[1,0]
	v_pk_add_f32 v[16:17], v[70:71], v[80:81]
	v_pk_fma_f32 v[72:73], v[24:25], v[26:27], v[72:73]
	v_pk_fma_f32 v[18:19], v[18:19], v[24:25], v[94:95] op_sel_hi:[1,0,1]
	v_pk_mul_f32 v[24:25], v[62:63], s[46:47] op_sel_hi:[0,1]
	v_pk_fma_f32 v[94:95], v[26:27], s[40:41], v[24:25]
	s_nop 0
	v_pk_mul_f32 v[24:25], v[16:17], v[94:95] op_sel:[1,1] op_sel_hi:[0,1] neg_hi:[1,0]
	v_pk_add_f32 v[64:65], v[112:113], v[114:115]
	v_pk_fma_f32 v[24:25], v[16:17], v[94:95], v[24:25] op_sel_hi:[1,0,1]
	v_pk_mul_f32 v[16:17], v[62:63], v[72:73] op_sel:[0,1] op_sel_hi:[0,0] neg_lo:[0,1]
	v_pk_fma_f32 v[108:109], v[26:27], v[72:73], v[16:17]
	v_pk_mul_f32 v[16:17], v[64:65], v[72:73] op_sel:[1,1] op_sel_hi:[0,1] neg_hi:[1,0]
	v_pk_add_f32 v[90:91], v[106:107], v[82:83]
	v_pk_fma_f32 v[16:17], v[64:65], v[72:73], v[16:17] op_sel_hi:[1,0,1]
	v_pk_mul_f32 v[64:65], v[62:63], v[94:95] op_sel:[0,1] op_sel_hi:[0,0] neg_lo:[0,1]
	v_pk_fma_f32 v[94:95], v[26:27], v[94:95], v[64:65]
	s_nop 0
	v_pk_mul_f32 v[64:65], v[78:79], v[94:95] op_sel:[1,1] op_sel_hi:[0,1] neg_hi:[1,0]
	v_pk_add_f32 v[66:67], v[6:7], v[118:119]
	v_pk_fma_f32 v[72:73], v[78:79], v[94:95], v[64:65] op_sel_hi:[1,0,1]
	v_pk_mul_f32 v[64:65], v[62:63], v[108:109] op_sel:[0,1] op_sel_hi:[0,0] neg_lo:[0,1]
	v_pk_fma_f32 v[110:111], v[26:27], v[108:109], v[64:65]
	v_pk_mul_f32 v[64:65], v[84:85], v[108:109] op_sel:[1,1] op_sel_hi:[0,1] neg_hi:[1,0]
	v_pk_mul_f32 v[78:79], v[62:63], v[94:95] op_sel:[0,1] op_sel_hi:[0,0] neg_lo:[0,1]
	v_pk_fma_f32 v[64:65], v[84:85], v[108:109], v[64:65] op_sel_hi:[1,0,1]
	v_pk_fma_f32 v[84:85], v[26:27], v[94:95], v[78:79]
	s_nop 0
	v_pk_mul_f32 v[78:79], v[90:91], v[84:85] op_sel:[1,1] op_sel_hi:[0,1] neg_hi:[1,0]
	v_pk_add_f32 v[68:69], v[106:107], v[82:83] neg_lo:[0,1] neg_hi:[0,1]
	v_pk_fma_f32 v[78:79], v[90:91], v[84:85], v[78:79] op_sel_hi:[1,0,1]
	v_pk_mul_f32 v[90:91], v[62:63], v[110:111] op_sel:[0,1] op_sel_hi:[0,0] neg_lo:[0,1]
	v_pk_fma_f32 v[94:95], v[26:27], v[110:111], v[90:91]
	v_pk_mul_f32 v[90:91], v[66:67], v[110:111] op_sel:[1,1] op_sel_hi:[0,1] neg_hi:[1,0]
	v_pk_add_f32 v[106:107], v[116:117], v[120:121]
	v_pk_fma_f32 v[66:67], v[66:67], v[110:111], v[90:91] op_sel_hi:[1,0,1]
	v_pk_mul_f32 v[90:91], v[62:63], v[84:85] op_sel:[0,1] op_sel_hi:[0,0] neg_lo:[0,1]
	v_pk_fma_f32 v[108:109], v[26:27], v[84:85], v[90:91]
	s_nop 0
	v_pk_mul_f32 v[84:85], v[122:123], v[108:109] op_sel:[1,1] op_sel_hi:[0,1] neg_hi:[1,0]
	v_pk_add_f32 v[80:81], v[70:71], v[80:81] neg_lo:[0,1] neg_hi:[0,1]
	v_pk_fma_f32 v[90:91], v[122:123], v[108:109], v[84:85] op_sel_hi:[1,0,1]
	v_pk_mul_f32 v[84:85], v[62:63], v[94:95] op_sel:[0,1] op_sel_hi:[0,0] neg_lo:[0,1]
	v_pk_fma_f32 v[110:111], v[26:27], v[94:95], v[84:85]
	v_pk_mul_f32 v[84:85], v[86:87], v[94:95] op_sel:[1,1] op_sel_hi:[0,1] neg_hi:[1,0]
	v_pk_add_f32 v[82:83], v[112:113], v[114:115] neg_lo:[0,1] neg_hi:[0,1]
	v_pk_fma_f32 v[84:85], v[86:87], v[94:95], v[84:85] op_sel_hi:[1,0,1]
	v_pk_mul_f32 v[86:87], v[62:63], v[108:109] op_sel:[0,1] op_sel_hi:[0,0] neg_lo:[0,1]
	v_pk_fma_f32 v[108:109], v[26:27], v[108:109], v[86:87]
	s_nop 0
	v_pk_mul_f32 v[86:87], v[102:103], v[108:109] op_sel:[1,1] op_sel_hi:[0,1] neg_hi:[1,0]
	v_pk_add_f32 v[70:71], v[6:7], v[118:119] neg_lo:[0,1] neg_hi:[0,1]
	v_pk_fma_f32 v[94:95], v[102:103], v[108:109], v[86:87] op_sel_hi:[1,0,1]
	v_pk_mul_f32 v[86:87], v[62:63], v[110:111] op_sel:[0,1] op_sel_hi:[0,0] neg_lo:[0,1]
	v_pk_fma_f32 v[102:103], v[26:27], v[110:111], v[86:87]
	v_pk_mul_f32 v[86:87], v[104:105], v[110:111] op_sel:[1,1] op_sel_hi:[0,1] neg_hi:[1,0]
	v_pk_add_f32 v[6:7], v[116:117], v[120:121] neg_lo:[0,1] neg_hi:[0,1]
	v_pk_fma_f32 v[86:87], v[104:105], v[110:111], v[86:87] op_sel_hi:[1,0,1]
	v_pk_mul_f32 v[104:105], v[62:63], v[108:109] op_sel:[0,1] op_sel_hi:[0,0] neg_lo:[0,1]
	v_pk_fma_f32 v[104:105], v[26:27], v[108:109], v[104:105]
	s_nop 0
	v_pk_mul_f32 v[108:109], v[96:97], v[104:105] op_sel:[1,1] op_sel_hi:[0,1] neg_hi:[1,0]
	s_nop 0
	v_pk_fma_f32 v[96:97], v[96:97], v[104:105], v[108:109] op_sel_hi:[1,0,1]
	v_pk_mul_f32 v[108:109], v[62:63], v[102:103] op_sel:[0,1] op_sel_hi:[0,0] neg_lo:[0,1]
	v_pk_mul_f32 v[110:111], v[100:101], v[102:103] op_sel:[1,1] op_sel_hi:[0,1] neg_hi:[1,0]
	v_pk_fma_f32 v[108:109], v[26:27], v[102:103], v[108:109]
	v_pk_fma_f32 v[100:101], v[100:101], v[102:103], v[110:111] op_sel_hi:[1,0,1]
	v_pk_mul_f32 v[102:103], v[62:63], v[104:105] op_sel:[0,1] op_sel_hi:[0,0] neg_lo:[0,1]
	v_pk_fma_f32 v[102:103], v[26:27], v[104:105], v[102:103]
	s_nop 0
	v_pk_mul_f32 v[104:105], v[98:99], v[102:103] op_sel:[1,1] op_sel_hi:[0,1] neg_hi:[1,0]
	s_nop 0
	v_pk_fma_f32 v[98:99], v[98:99], v[102:103], v[104:105] op_sel_hi:[1,0,1]
	v_pk_mul_f32 v[104:105], v[62:63], v[108:109] op_sel:[0,1] op_sel_hi:[0,0] neg_lo:[0,1]
	v_pk_mul_f32 v[110:111], v[106:107], v[108:109] op_sel:[1,1] op_sel_hi:[0,1] neg_hi:[1,0]
	v_pk_fma_f32 v[104:105], v[26:27], v[108:109], v[104:105]
	v_pk_fma_f32 v[106:107], v[106:107], v[108:109], v[110:111] op_sel_hi:[1,0,1]
	v_pk_mul_f32 v[108:109], v[62:63], v[102:103] op_sel:[0,1] op_sel_hi:[0,0] neg_lo:[0,1]
	v_pk_fma_f32 v[102:103], v[26:27], v[102:103], v[108:109]
	s_nop 0
	v_pk_mul_f32 v[108:109], v[88:89], v[102:103] op_sel:[1,1] op_sel_hi:[0,1] neg_hi:[1,0]
	s_nop 0
	v_pk_fma_f32 v[88:89], v[88:89], v[102:103], v[108:109] op_sel_hi:[1,0,1]
	v_pk_mul_f32 v[108:109], v[62:63], v[104:105] op_sel:[0,1] op_sel_hi:[0,0] neg_lo:[0,1]
	v_pk_mul_f32 v[110:111], v[92:93], v[104:105] op_sel:[1,1] op_sel_hi:[0,1] neg_hi:[1,0]
	v_pk_fma_f32 v[108:109], v[26:27], v[104:105], v[108:109]
	v_pk_fma_f32 v[92:93], v[92:93], v[104:105], v[110:111] op_sel_hi:[1,0,1]
	v_pk_mul_f32 v[104:105], v[62:63], v[102:103] op_sel:[0,1] op_sel_hi:[0,0] neg_lo:[0,1]
	v_pk_fma_f32 v[102:103], v[26:27], v[102:103], v[104:105]
	s_nop 0
	v_pk_mul_f32 v[104:105], v[80:81], v[102:103] op_sel:[1,1] op_sel_hi:[0,1] neg_hi:[1,0]
	s_nop 0
	v_pk_fma_f32 v[80:81], v[80:81], v[102:103], v[104:105] op_sel_hi:[1,0,1]
	v_pk_mul_f32 v[104:105], v[62:63], v[108:109] op_sel:[0,1] op_sel_hi:[0,0] neg_lo:[0,1]
	v_pk_mul_f32 v[110:111], v[82:83], v[108:109] op_sel:[1,1] op_sel_hi:[0,1] neg_hi:[1,0]
	v_pk_fma_f32 v[104:105], v[26:27], v[108:109], v[104:105]
	v_pk_fma_f32 v[82:83], v[82:83], v[108:109], v[110:111] op_sel_hi:[1,0,1]
	v_pk_mul_f32 v[108:109], v[62:63], v[102:103] op_sel:[0,1] op_sel_hi:[0,0] neg_lo:[0,1]
	v_pk_fma_f32 v[102:103], v[26:27], v[102:103], v[108:109]
	s_nop 0
	v_pk_mul_f32 v[108:109], v[74:75], v[102:103] op_sel:[1,1] op_sel_hi:[0,1] neg_hi:[1,0]
	s_nop 0
	v_pk_fma_f32 v[74:75], v[74:75], v[102:103], v[108:109] op_sel_hi:[1,0,1]
	v_pk_mul_f32 v[108:109], v[62:63], v[104:105] op_sel:[0,1] op_sel_hi:[0,0] neg_lo:[0,1]
	v_pk_mul_f32 v[110:111], v[76:77], v[104:105] op_sel:[1,1] op_sel_hi:[0,1] neg_hi:[1,0]
	v_pk_fma_f32 v[108:109], v[26:27], v[104:105], v[108:109]
	v_pk_fma_f32 v[76:77], v[76:77], v[104:105], v[110:111] op_sel_hi:[1,0,1]
	v_pk_mul_f32 v[104:105], v[62:63], v[102:103] op_sel:[0,1] op_sel_hi:[0,0] neg_lo:[0,1]
	v_pk_fma_f32 v[102:103], v[26:27], v[102:103], v[104:105]
	s_nop 0
	v_pk_mul_f32 v[104:105], v[68:69], v[102:103] op_sel:[1,1] op_sel_hi:[0,1] neg_hi:[1,0]
	s_nop 0
	v_pk_fma_f32 v[68:69], v[68:69], v[102:103], v[104:105] op_sel_hi:[1,0,1]
	v_pk_mul_f32 v[104:105], v[62:63], v[108:109] op_sel:[0,1] op_sel_hi:[0,0] neg_lo:[0,1]
	v_pk_mul_f32 v[110:111], v[70:71], v[108:109] op_sel:[1,1] op_sel_hi:[0,1] neg_hi:[1,0]
	v_pk_fma_f32 v[104:105], v[26:27], v[108:109], v[104:105]
	v_pk_fma_f32 v[70:71], v[70:71], v[108:109], v[110:111] op_sel_hi:[1,0,1]
	v_pk_mul_f32 v[108:109], v[62:63], v[102:103] op_sel:[0,1] op_sel_hi:[0,0] neg_lo:[0,1]
	v_pk_fma_f32 v[102:103], v[26:27], v[102:103], v[108:109]
	s_nop 0
	v_pk_mul_f32 v[108:109], v[20:21], v[102:103] op_sel:[1,1] op_sel_hi:[0,1] neg_hi:[1,0]
	s_nop 0
	v_pk_fma_f32 v[20:21], v[20:21], v[102:103], v[108:109] op_sel_hi:[1,0,1]
	v_pk_mul_f32 v[108:109], v[62:63], v[104:105] op_sel:[0,1] op_sel_hi:[0,0] neg_lo:[0,1]
	v_pk_mul_f32 v[110:111], v[22:23], v[104:105] op_sel:[1,1] op_sel_hi:[0,1] neg_hi:[1,0]
	v_pk_fma_f32 v[108:109], v[26:27], v[104:105], v[108:109]
	v_pk_fma_f32 v[22:23], v[22:23], v[104:105], v[110:111] op_sel_hi:[1,0,1]
	v_pk_mul_f32 v[104:105], v[62:63], v[102:103] op_sel:[0,1] op_sel_hi:[0,0] neg_lo:[0,1]
	v_pk_fma_f32 v[102:103], v[26:27], v[102:103], v[104:105]
	s_nop 0
	v_pk_mul_f32 v[104:105], v[12:13], v[102:103] op_sel:[1,1] op_sel_hi:[0,1] neg_hi:[1,0]
	s_nop 0
	v_pk_fma_f32 v[12:13], v[12:13], v[102:103], v[104:105] op_sel_hi:[1,0,1]
	v_pk_mul_f32 v[104:105], v[62:63], v[108:109] op_sel:[0,1] op_sel_hi:[0,0] neg_lo:[0,1]
	v_pk_mul_f32 v[110:111], v[14:15], v[108:109] op_sel:[1,1] op_sel_hi:[0,1] neg_hi:[1,0]
	v_pk_fma_f32 v[104:105], v[26:27], v[108:109], v[104:105]
	v_pk_fma_f32 v[14:15], v[14:15], v[108:109], v[110:111] op_sel_hi:[1,0,1]
	v_pk_mul_f32 v[108:109], v[62:63], v[102:103] op_sel:[0,1] op_sel_hi:[0,0] neg_lo:[0,1]
	v_pk_fma_f32 v[102:103], v[26:27], v[102:103], v[108:109]
	s_nop 0
	v_pk_mul_f32 v[108:109], v[8:9], v[102:103] op_sel:[1,1] op_sel_hi:[0,1] neg_hi:[1,0]
	s_nop 0
	v_pk_fma_f32 v[8:9], v[8:9], v[102:103], v[108:109] op_sel_hi:[1,0,1]
	v_pk_mul_f32 v[108:109], v[62:63], v[104:105] op_sel:[0,1] op_sel_hi:[0,0] neg_lo:[0,1]
	v_pk_mul_f32 v[110:111], v[10:11], v[104:105] op_sel:[1,1] op_sel_hi:[0,1] neg_hi:[1,0]
	v_pk_fma_f32 v[108:109], v[26:27], v[104:105], v[108:109]
	v_pk_fma_f32 v[10:11], v[10:11], v[104:105], v[110:111] op_sel_hi:[1,0,1]
	v_pk_mul_f32 v[104:105], v[62:63], v[102:103] op_sel:[0,1] op_sel_hi:[0,0] neg_lo:[0,1]
	v_pk_fma_f32 v[26:27], v[26:27], v[102:103], v[104:105]
	s_nop 0
	v_pk_mul_f32 v[102:103], v[4:5], v[26:27] op_sel:[1,1] op_sel_hi:[0,1] neg_hi:[1,0]
	s_add_i32 s1, 16, 0x1e000
	v_pk_fma_f32 v[4:5], v[4:5], v[26:27], v[102:103] op_sel_hi:[1,0,1]
	s_nop 0
	s_nop 0
	v_pk_mul_f32 v[26:27], v[6:7], v[108:109] op_sel:[1,1] op_sel_hi:[0,1] neg_hi:[1,0]
	s_add_i32 s0, 16, 0x1f000
	v_pk_fma_f32 v[6:7], v[6:7], v[108:109], v[26:27] op_sel_hi:[1,0,1]
	v_lshrrev_b32_e32 v26, 5, v63
	v_bitop3_b32 v26, v26, v63, 15 bitop3:0x6c
	v_lshlrev_b32_e32 v26, 3, v26
	v_bfe_u32 v27, v63, 5, 4
	v_add_u32_e32 v62, 16, v26
	ds_write_b64 v62, v[2:3]
	v_bitop3_b32 v2, v27, v63, 16 bitop3:0x36
	v_lshlrev_b32_e32 v2, 3, v2
	v_add_u32_e32 v3, 16, v2
	ds_write_b64 v3, v[88:89] offset:4096
	ds_write_b64 v62, v[90:91] offset:8192
	ds_write_b64 v3, v[20:21] offset:12288
	ds_write_b64 v62, v[72:73] offset:16384
	ds_write_b64 v3, v[74:75] offset:20480
	ds_write_b64 v62, v[96:97] offset:24576
	ds_write_b64 v3, v[8:9] offset:28672
	ds_write_b64 v62, v[24:25] offset:32768
	ds_write_b64 v3, v[80:81] offset:36864
	ds_write_b64 v62, v[94:95] offset:40960
	ds_write_b64 v3, v[12:13] offset:45056
	ds_write_b64 v62, v[78:79] offset:49152
	ds_write_b64 v3, v[68:69] offset:53248
	ds_write_b64 v62, v[98:99] offset:57344
	ds_write_b64 v3, v[4:5] offset:61440
	v_add_u32_e32 v3, s79, v26
	ds_write_b64 v3, v[18:19]
	v_add_u32_e32 v3, s19, v2
	ds_write_b64 v3, v[92:93]
	v_add_u32_e32 v3, s18, v26
	ds_write_b64 v3, v[84:85]
	v_add_u32_e32 v3, s17, v2
	ds_write_b64 v3, v[22:23]
	v_add_u32_e32 v3, s13, v26
	ds_write_b64 v3, v[64:65]
	v_add_u32_e32 v3, s12, v2
	ds_write_b64 v3, v[76:77]
	v_add_u32_e32 v3, s11, v26
	ds_write_b64 v3, v[100:101]
	v_add_u32_e32 v3, s10, v2
	ds_write_b64 v3, v[10:11]
	v_add_u32_e32 v3, s9, v26
	ds_write_b64 v3, v[16:17]
	v_add_u32_e32 v3, s8, v2
	ds_write_b64 v3, v[82:83]
	v_add_u32_e32 v3, s7, v26
	ds_write_b64 v3, v[86:87]
	v_add_u32_e32 v3, s6, v2
	ds_write_b64 v3, v[14:15]
	v_add_u32_e32 v3, s5, v26
	ds_write_b64 v3, v[66:67]
	v_add_u32_e32 v3, s4, v2
	ds_write_b64 v3, v[70:71]
	v_add_u32_e32 v3, s1, v26
	v_add_u32_e32 v2, s0, v2
	v_mov_b32_e32 v21, v146
	ds_write_b64 v3, v[106:107]
	ds_write_b64 v2, v[6:7]
	s_waitcnt lgkmcnt(0)
	s_barrier
	s_lshl_b32 s42, s16, 14
	v_lshlrev_b32_e32 v2, 5, v21
	v_and_b32_e32 v4, 0xfffffe00, v2
	v_and_b32_e32 v20, 15, v21
	v_and_or_b32 v2, v21, 16, v4
	v_bitop3_b32 v4, v4, 16, v21 bitop3:0x34
	v_bitop3_b32 v72, v21, 8, 15 bitop3:0x6c
	v_lshl_add_u32 v26, v2, 3, 16
	v_lshlrev_b32_e32 v5, 3, v20
	v_lshl_add_u32 v126, v4, 3, 16
	v_lshlrev_b32_e32 v74, 3, v72
	v_add_u32_e32 v27, v26, v5
	v_add_u32_e32 v96, v126, v5
	v_add_u32_e32 v111, v26, v74
	v_add_u32_e32 v112, v126, v74
	ds_read_b64 v[2:3], v27
	ds_read_b64 v[4:5], v96
	v_bitop3_b32 v6, v21, 1, 15 bitop3:0x6c
	ds_read_b64 v[72:73], v111 offset:2048
	ds_read_b64 v[74:75], v112 offset:2048
	v_bitop3_b32 v76, v21, 9, 15 bitop3:0x6c
	v_lshlrev_b32_e32 v8, 3, v6
	v_lshlrev_b32_e32 v78, 3, v76
	v_add_u32_e32 v97, v26, v8
	v_add_u32_e32 v113, v26, v78
	ds_read_b64 v[6:7], v97 offset:256
	ds_read_b64 v[76:77], v113 offset:2304
	v_add_u32_e32 v98, v126, v8
	v_add_u32_e32 v114, v126, v78
	ds_read_b64 v[8:9], v98 offset:256
	ds_read_b64 v[78:79], v114 offset:2304
	s_waitcnt lgkmcnt(5)
	v_pk_add_f32 v[136:137], v[2:3], v[72:73]
	v_pk_add_f32 v[2:3], v[2:3], v[72:73] neg_lo:[0,1] neg_hi:[0,1]
	s_waitcnt lgkmcnt(4)
	v_pk_add_f32 v[72:73], v[4:5], v[74:75]
	v_pk_add_f32 v[4:5], v[4:5], v[74:75] neg_lo:[0,1] neg_hi:[0,1]
	v_bitop3_b32 v10, v21, 2, 15 bitop3:0x6c
	v_bitop3_b32 v80, v21, 10, 15 bitop3:0x6c
	v_lshlrev_b32_e32 v12, 3, v10
	v_lshlrev_b32_e32 v82, 3, v80
	v_pk_mul_f32 v[74:75], v[4:5], s[48:49] op_sel:[1,0] op_sel_hi:[0,0] neg_hi:[1,0]
	v_add_u32_e32 v99, v26, v12
	v_add_u32_e32 v115, v26, v82
	v_pk_fma_f32 v[4:5], v[4:5], s[44:45], v[74:75] op_sel_hi:[1,0,1]
	s_waitcnt lgkmcnt(2)
	v_pk_add_f32 v[74:75], v[6:7], v[76:77]
	v_pk_add_f32 v[6:7], v[6:7], v[76:77] neg_lo:[0,1] neg_hi:[0,1]
	ds_read_b64 v[10:11], v99 offset:512
	ds_read_b64 v[80:81], v115 offset:2560
	v_pk_mul_f32 v[76:77], v[6:7], s[54:55] op_sel:[1,0] op_sel_hi:[0,0] neg_hi:[1,0]
	v_add_u32_e32 v100, v126, v12
	v_bitop3_b32 v14, v21, 3, 15 bitop3:0x6c
	v_add_u32_e32 v116, v126, v82
	v_bitop3_b32 v84, v21, 11, 15 bitop3:0x6c
	v_pk_fma_f32 v[6:7], v[6:7], s[52:53], v[76:77] op_sel_hi:[1,0,1]
	s_waitcnt lgkmcnt(2)
	v_pk_add_f32 v[76:77], v[8:9], v[78:79]
	v_pk_add_f32 v[8:9], v[8:9], v[78:79] neg_lo:[0,1] neg_hi:[0,1]
	ds_read_b64 v[12:13], v100 offset:512
	v_lshlrev_b32_e32 v16, 3, v14
	ds_read_b64 v[82:83], v116 offset:2560
	v_lshlrev_b32_e32 v86, 3, v84
	v_add_u32_e32 v101, v26, v16
	v_add_u32_e32 v102, v126, v16
	v_add_u32_e32 v117, v26, v86
	v_add_u32_e32 v118, v126, v86
	v_pk_mul_f32 v[78:79], v[8:9], s[58:59] op_sel:[1,0] op_sel_hi:[0,0] neg_hi:[1,0]
	ds_read_b64 v[14:15], v101 offset:768
	ds_read_b64 v[16:17], v102 offset:768
	ds_read_b64 v[84:85], v117 offset:2816
	ds_read_b64 v[86:87], v118 offset:2816
	v_pk_fma_f32 v[8:9], v[8:9], s[56:57], v[78:79] op_sel_hi:[1,0,1]
	s_waitcnt lgkmcnt(6)
	v_pk_add_f32 v[78:79], v[10:11], v[80:81]
	v_pk_add_f32 v[10:11], v[10:11], v[80:81] neg_lo:[0,1] neg_hi:[0,1]
	v_bitop3_b32 v18, v21, 4, 15 bitop3:0x6c
	v_pk_mul_f32 v[80:81], v[10:11], s[60:61] op_sel:[1,0] op_sel_hi:[0,0] neg_hi:[1,0]
	v_bitop3_b32 v88, v21, 12, 15 bitop3:0x6c
	v_pk_fma_f32 v[10:11], v[10:11], s[60:61], v[80:81] op_sel_hi:[1,0,1]
	s_waitcnt lgkmcnt(4)
	v_pk_add_f32 v[80:81], v[12:13], v[82:83]
	v_pk_add_f32 v[12:13], v[12:13], v[82:83] neg_lo:[0,1] neg_hi:[0,1]
	v_lshlrev_b32_e32 v22, 3, v18
	v_lshlrev_b32_e32 v90, 3, v88
	v_pk_mul_f32 v[82:83], v[12:13], s[56:57] op_sel:[1,0] op_sel_hi:[0,0] neg_hi:[1,0]
	v_add_u32_e32 v103, v26, v22
	v_add_u32_e32 v119, v26, v90
	v_pk_fma_f32 v[12:13], v[12:13], s[58:59], v[82:83] op_sel_hi:[1,0,1]
	s_waitcnt lgkmcnt(1)
	v_pk_add_f32 v[82:83], v[14:15], v[84:85]
	v_pk_add_f32 v[14:15], v[14:15], v[84:85] neg_lo:[0,1] neg_hi:[0,1]
	ds_read_b64 v[18:19], v103 offset:1024
	v_add_u32_e32 v104, v126, v22
	v_bitop3_b32 v24, v21, 5, 15 bitop3:0x6c
	ds_read_b64 v[88:89], v119 offset:3072
	v_add_u32_e32 v120, v126, v90
	v_bitop3_b32 v92, v21, 13, 15 bitop3:0x6c
	ds_read_b64 v[22:23], v104 offset:1024
	v_lshlrev_b32_e32 v62, 3, v24
	ds_read_b64 v[90:91], v120 offset:3072
	v_lshlrev_b32_e32 v94, 3, v92
	v_pk_mul_f32 v[84:85], v[14:15], s[52:53] op_sel:[1,0] op_sel_hi:[0,0] neg_hi:[1,0]
	v_add_u32_e32 v105, v26, v62
	v_add_u32_e32 v121, v26, v94
	v_pk_fma_f32 v[14:15], v[14:15], s[54:55], v[84:85] op_sel_hi:[1,0,1]
	s_waitcnt lgkmcnt(4)
	v_pk_add_f32 v[84:85], v[16:17], v[86:87]
	v_pk_add_f32 v[16:17], v[16:17], v[86:87] neg_lo:[0,1] neg_hi:[0,1]
	ds_read_b64 v[24:25], v105 offset:1280
	ds_read_b64 v[92:93], v121 offset:3328
	v_add_u32_e32 v106, v126, v62
	v_bitop3_b32 v64, v21, 6, 15 bitop3:0x6c
	v_add_u32_e32 v122, v126, v94
	v_bitop3_b32 v123, v21, 14, 15 bitop3:0x6c
	v_pk_mul_f32 v[86:87], v[16:17], s[44:45] op_sel:[1,0] op_sel_hi:[0,0] neg_hi:[1,0]
	ds_read_b64 v[62:63], v106 offset:1280
	v_lshlrev_b32_e32 v66, 3, v64
	ds_read_b64 v[94:95], v122 offset:3328
	v_lshlrev_b32_e32 v124, 3, v123
	v_pk_fma_f32 v[16:17], v[16:17], s[48:49], v[86:87] op_sel_hi:[1,0,1]
	s_waitcnt lgkmcnt(6)
	v_pk_add_f32 v[86:87], v[18:19], v[88:89]
	v_pk_add_f32 v[18:19], v[18:19], v[88:89] neg_lo:[0,1] neg_hi:[0,1]
	v_add_u32_e32 v107, v26, v66
	v_add_u32_e32 v123, v26, v124
	v_xor_b32_e32 v89, 0x80000000, v18
	v_mov_b32_e32 v88, v19
	s_waitcnt lgkmcnt(4)
	v_pk_add_f32 v[18:19], v[22:23], v[90:91]
	v_pk_add_f32 v[22:23], v[22:23], v[90:91] neg_lo:[0,1] neg_hi:[0,1]
	ds_read_b64 v[64:65], v107 offset:1536
	ds_read_b64 v[128:129], v123 offset:3584
	v_pk_mul_f32 v[90:91], v[22:23], s[48:49] op_sel_hi:[1,0]
	v_xor_b32_e32 v139, 0x80000000, v22
	v_mov_b32_e32 v138, v23
	v_add_u32_e32 v108, v126, v66
	v_bitop3_b32 v68, v21, 7, 15 bitop3:0x6c
	v_add_u32_e32 v124, v126, v124
	v_bitop3_b32 v21, v21, 15, v21 bitop3:0xc
	v_pk_fma_f32 v[22:23], v[138:139], s[44:45], v[90:91] op_sel_hi:[1,0,1] neg_lo:[0,0,1] neg_hi:[0,0,1]
	s_waitcnt lgkmcnt(4)
	v_pk_add_f32 v[90:91], v[24:25], v[92:93]
	v_pk_add_f32 v[24:25], v[24:25], v[92:93] neg_lo:[0,1] neg_hi:[0,1]
	ds_read_b64 v[66:67], v108 offset:1536
	v_lshlrev_b32_e32 v70, 3, v68
	ds_read_b64 v[130:131], v124 offset:3584
	v_lshlrev_b32_e32 v21, 3, v21
	v_pk_mul_f32 v[92:93], v[24:25], s[54:55] op_sel_hi:[1,0]
	v_xor_b32_e32 v139, 0x80000000, v24
	v_mov_b32_e32 v138, v25
	v_add_u32_e32 v109, v26, v70
	v_add_u32_e32 v125, v26, v21
	v_pk_fma_f32 v[24:25], v[138:139], s[52:53], v[92:93] op_sel_hi:[1,0,1] neg_lo:[0,0,1] neg_hi:[0,0,1]
	s_waitcnt lgkmcnt(4)
	v_pk_add_f32 v[92:93], v[62:63], v[94:95]
	v_pk_add_f32 v[62:63], v[62:63], v[94:95] neg_lo:[0,1] neg_hi:[0,1]
	ds_read_b64 v[68:69], v109 offset:1792
	v_add_u32_e32 v110, v126, v70
	ds_read_b64 v[132:133], v125 offset:3840
	v_add_u32_e32 v126, v126, v21
	v_pk_mul_f32 v[94:95], v[62:63], s[58:59] op_sel_hi:[1,0]
	v_xor_b32_e32 v139, 0x80000000, v62
	v_mov_b32_e32 v138, v63
	ds_read_b64 v[70:71], v110 offset:1792
	ds_read_b64 v[134:135], v126 offset:3840
	v_pk_fma_f32 v[62:63], v[138:139], s[56:57], v[94:95] op_sel_hi:[1,0,1] neg_lo:[0,0,1] neg_hi:[0,0,1]
	s_waitcnt lgkmcnt(6)
	v_pk_add_f32 v[94:95], v[64:65], v[128:129]
	v_pk_add_f32 v[64:65], v[64:65], v[128:129] neg_lo:[0,1] neg_hi:[0,1]
	v_lshl_add_u64 v[0:1], s[42:43], 2, v[28:29]
	v_pk_mul_f32 v[128:129], v[64:65], s[60:61] op_sel_hi:[1,0]
	v_xor_b32_e32 v139, 0x80000000, v64
	v_mov_b32_e32 v138, v65
	v_pk_fma_f32 v[64:65], v[138:139], s[60:61], v[128:129] op_sel_hi:[1,0,1] neg_lo:[0,0,1] neg_hi:[0,0,1]
	s_waitcnt lgkmcnt(4)
	v_pk_add_f32 v[128:129], v[66:67], v[130:131]
	v_pk_add_f32 v[66:67], v[66:67], v[130:131] neg_lo:[0,1] neg_hi:[0,1]
	v_cvt_f32_i32_e32 v20, v20
	v_pk_mul_f32 v[130:131], v[66:67], s[56:57] op_sel_hi:[1,0]
	v_xor_b32_e32 v139, 0x80000000, v66
	v_mov_b32_e32 v138, v67
	v_pk_fma_f32 v[66:67], v[138:139], s[58:59], v[130:131] op_sel_hi:[1,0,1] neg_lo:[0,0,1] neg_hi:[0,0,1]
	s_waitcnt lgkmcnt(2)
	v_pk_add_f32 v[130:131], v[68:69], v[132:133]
	v_pk_add_f32 v[68:69], v[68:69], v[132:133] neg_lo:[0,1] neg_hi:[0,1]
	v_mul_f32_e32 v21, 0x3b000000, v20
	v_pk_mul_f32 v[132:133], v[68:69], s[52:53] op_sel_hi:[1,0]
	v_xor_b32_e32 v139, 0x80000000, v68
	v_mov_b32_e32 v138, v69
	v_pk_fma_f32 v[68:69], v[138:139], s[54:55], v[132:133] op_sel_hi:[1,0,1] neg_lo:[0,0,1] neg_hi:[0,0,1]
	s_waitcnt lgkmcnt(0)
	v_pk_add_f32 v[132:133], v[70:71], v[134:135]
	v_pk_add_f32 v[70:71], v[70:71], v[134:135] neg_lo:[0,1] neg_hi:[0,1]
	v_cos_f32_e32 v20, v21
	v_pk_mul_f32 v[134:135], v[70:71], s[44:45] op_sel_hi:[1,0]
	v_xor_b32_e32 v139, 0x80000000, v70
	v_mov_b32_e32 v138, v71
	v_pk_fma_f32 v[70:71], v[138:139], s[48:49], v[134:135] op_sel_hi:[1,0,1] neg_lo:[0,0,1] neg_hi:[0,0,1]
	v_pk_add_f32 v[134:135], v[136:137], v[86:87]
	v_pk_add_f32 v[86:87], v[136:137], v[86:87] neg_lo:[0,1] neg_hi:[0,1]
	v_pk_add_f32 v[136:137], v[72:73], v[18:19]
	v_pk_add_f32 v[18:19], v[72:73], v[18:19] neg_lo:[0,1] neg_hi:[0,1]
	v_sin_f32_e32 v21, v21
	s_nop 0
	s_nop 0
	v_pk_mul_f32 v[72:73], v[18:19], s[54:55] op_sel:[1,0] op_sel_hi:[0,0] neg_hi:[1,0]
	v_add_f32_e32 v26, v20, v20
	v_pk_fma_f32 v[18:19], v[18:19], s[52:53], v[72:73] op_sel_hi:[1,0,1]
	v_pk_add_f32 v[72:73], v[74:75], v[90:91]
	v_pk_add_f32 v[74:75], v[74:75], v[90:91] neg_lo:[0,1] neg_hi:[0,1]
	v_mul_f32_e32 v26, v21, v26
	s_nop 0
	s_nop 0
	v_pk_mul_f32 v[90:91], v[74:75], s[60:61] op_sel:[1,0] op_sel_hi:[0,0] neg_hi:[1,0]
	s_lshl_b32 s42, s16, 9
	v_pk_fma_f32 v[74:75], v[74:75], s[60:61], v[90:91] op_sel_hi:[1,0,1]
	v_pk_add_f32 v[90:91], v[76:77], v[92:93]
	v_pk_add_f32 v[76:77], v[76:77], v[92:93] neg_lo:[0,1] neg_hi:[0,1]
	s_mov_b64 s[74:75], -1
	s_nop 0
	s_nop 0
	v_pk_mul_f32 v[92:93], v[76:77], s[52:53] op_sel:[1,0] op_sel_hi:[0,0] neg_hi:[1,0]
	s_nop 0
	v_pk_fma_f32 v[76:77], v[76:77], s[54:55], v[92:93] op_sel_hi:[1,0,1]
	v_pk_add_f32 v[92:93], v[78:79], v[94:95]
	v_pk_add_f32 v[78:79], v[78:79], v[94:95] neg_lo:[0,1] neg_hi:[0,1]
	s_nop 0
	v_xor_b32_e32 v95, 0x80000000, v78
	v_mov_b32_e32 v94, v79
	v_pk_add_f32 v[78:79], v[80:81], v[128:129]
	v_pk_add_f32 v[80:81], v[80:81], v[128:129] neg_lo:[0,1] neg_hi:[0,1]
	s_nop 0
	v_pk_mul_f32 v[128:129], v[80:81], s[54:55] op_sel_hi:[1,0]
	v_xor_b32_e32 v139, 0x80000000, v80
	v_mov_b32_e32 v138, v81
	v_pk_fma_f32 v[80:81], v[138:139], s[52:53], v[128:129] op_sel_hi:[1,0,1] neg_lo:[0,0,1] neg_hi:[0,0,1]
	v_pk_add_f32 v[128:129], v[82:83], v[130:131]
	v_pk_add_f32 v[82:83], v[82:83], v[130:131] neg_lo:[0,1] neg_hi:[0,1]
	s_nop 0
	v_pk_mul_f32 v[130:131], v[82:83], s[60:61] op_sel_hi:[1,0]
	v_xor_b32_e32 v139, 0x80000000, v82
	v_mov_b32_e32 v138, v83
	v_pk_fma_f32 v[82:83], v[138:139], s[60:61], v[130:131] op_sel_hi:[1,0,1] neg_lo:[0,0,1] neg_hi:[0,0,1]
	v_pk_add_f32 v[130:131], v[84:85], v[132:133]
	v_pk_add_f32 v[84:85], v[84:85], v[132:133] neg_lo:[0,1] neg_hi:[0,1]
	s_nop 0
	v_pk_mul_f32 v[132:133], v[84:85], s[52:53] op_sel_hi:[1,0]
	v_xor_b32_e32 v139, 0x80000000, v84
	v_mov_b32_e32 v138, v85
	v_pk_fma_f32 v[84:85], v[138:139], s[54:55], v[132:133] op_sel_hi:[1,0,1] neg_lo:[0,0,1] neg_hi:[0,0,1]
	v_pk_add_f32 v[132:133], v[2:3], v[88:89]
	v_pk_add_f32 v[2:3], v[2:3], v[88:89] neg_lo:[0,1] neg_hi:[0,1]
	v_pk_add_f32 v[88:89], v[4:5], v[22:23]
	v_pk_add_f32 v[4:5], v[4:5], v[22:23] neg_lo:[0,1] neg_hi:[0,1]
	s_nop 0
	v_pk_mul_f32 v[22:23], v[4:5], s[54:55] op_sel:[1,0] op_sel_hi:[0,0] neg_hi:[1,0]
	s_nop 0
	v_pk_fma_f32 v[4:5], v[4:5], s[52:53], v[22:23] op_sel_hi:[1,0,1]
	v_pk_add_f32 v[22:23], v[6:7], v[24:25]
	v_pk_add_f32 v[6:7], v[6:7], v[24:25] neg_lo:[0,1] neg_hi:[0,1]
	s_nop 0
	v_pk_mul_f32 v[24:25], v[6:7], s[60:61] op_sel:[1,0] op_sel_hi:[0,0] neg_hi:[1,0]
	s_nop 0
	v_pk_fma_f32 v[6:7], v[6:7], s[60:61], v[24:25] op_sel_hi:[1,0,1]
	v_pk_add_f32 v[24:25], v[8:9], v[62:63]
	v_pk_add_f32 v[8:9], v[8:9], v[62:63] neg_lo:[0,1] neg_hi:[0,1]
	s_nop 0
	v_pk_mul_f32 v[62:63], v[8:9], s[52:53] op_sel:[1,0] op_sel_hi:[0,0] neg_hi:[1,0]
	s_nop 0
	v_pk_fma_f32 v[8:9], v[8:9], s[54:55], v[62:63] op_sel_hi:[1,0,1]
	v_pk_add_f32 v[62:63], v[10:11], v[64:65]
	v_pk_add_f32 v[10:11], v[10:11], v[64:65] neg_lo:[0,1] neg_hi:[0,1]
	s_nop 0
	v_xor_b32_e32 v65, 0x80000000, v10
	v_mov_b32_e32 v64, v11
	v_pk_add_f32 v[10:11], v[12:13], v[66:67]
	v_pk_add_f32 v[12:13], v[12:13], v[66:67] neg_lo:[0,1] neg_hi:[0,1]
	s_nop 0
	v_pk_mul_f32 v[66:67], v[12:13], s[54:55] op_sel_hi:[1,0]
	v_xor_b32_e32 v139, 0x80000000, v12
	v_mov_b32_e32 v138, v13
	v_pk_fma_f32 v[12:13], v[138:139], s[52:53], v[66:67] op_sel_hi:[1,0,1] neg_lo:[0,0,1] neg_hi:[0,0,1]
	v_pk_add_f32 v[66:67], v[14:15], v[68:69]
	v_pk_add_f32 v[14:15], v[14:15], v[68:69] neg_lo:[0,1] neg_hi:[0,1]
	s_nop 0
	v_pk_mul_f32 v[68:69], v[14:15], s[60:61] op_sel_hi:[1,0]
	v_xor_b32_e32 v139, 0x80000000, v14
	v_mov_b32_e32 v138, v15
	v_pk_fma_f32 v[14:15], v[138:139], s[60:61], v[68:69] op_sel_hi:[1,0,1] neg_lo:[0,0,1] neg_hi:[0,0,1]
	v_pk_add_f32 v[68:69], v[16:17], v[70:71]
	v_pk_add_f32 v[16:17], v[16:17], v[70:71] neg_lo:[0,1] neg_hi:[0,1]
	s_nop 0
	v_pk_mul_f32 v[70:71], v[16:17], s[52:53] op_sel_hi:[1,0]
	v_xor_b32_e32 v139, 0x80000000, v16
	v_mov_b32_e32 v138, v17
	v_pk_fma_f32 v[16:17], v[138:139], s[54:55], v[70:71] op_sel_hi:[1,0,1] neg_lo:[0,0,1] neg_hi:[0,0,1]
	v_pk_add_f32 v[70:71], v[134:135], v[92:93]
	v_pk_add_f32 v[92:93], v[134:135], v[92:93] neg_lo:[0,1] neg_hi:[0,1]
	v_pk_add_f32 v[134:135], v[136:137], v[78:79]
	v_pk_add_f32 v[78:79], v[136:137], v[78:79] neg_lo:[0,1] neg_hi:[0,1]
	s_nop 0
	v_pk_mul_f32 v[136:137], v[78:79], s[60:61] op_sel:[1,0] op_sel_hi:[0,0] neg_hi:[1,0]
	s_nop 0
	v_pk_fma_f32 v[78:79], v[78:79], s[60:61], v[136:137] op_sel_hi:[1,0,1]
	v_pk_add_f32 v[136:137], v[72:73], v[128:129]
	v_pk_add_f32 v[72:73], v[72:73], v[128:129] neg_lo:[0,1] neg_hi:[0,1]
	s_nop 0
	v_xor_b32_e32 v129, 0x80000000, v72
	v_mov_b32_e32 v128, v73
	v_pk_add_f32 v[72:73], v[90:91], v[130:131]
	v_pk_add_f32 v[90:91], v[90:91], v[130:131] neg_lo:[0,1] neg_hi:[0,1]
	s_nop 0
	v_pk_mul_f32 v[130:131], v[90:91], s[60:61] op_sel_hi:[1,0]
	v_xor_b32_e32 v139, 0x80000000, v90
	v_mov_b32_e32 v138, v91
	v_pk_fma_f32 v[90:91], v[138:139], s[60:61], v[130:131] op_sel_hi:[1,0,1] neg_lo:[0,0,1] neg_hi:[0,0,1]
	v_pk_add_f32 v[130:131], v[86:87], v[94:95]
	v_pk_add_f32 v[86:87], v[86:87], v[94:95] neg_lo:[0,1] neg_hi:[0,1]
	v_pk_add_f32 v[94:95], v[18:19], v[80:81]
	v_pk_add_f32 v[18:19], v[18:19], v[80:81] neg_lo:[0,1] neg_hi:[0,1]
	s_nop 0
	v_pk_mul_f32 v[80:81], v[18:19], s[60:61] op_sel:[1,0] op_sel_hi:[0,0] neg_hi:[1,0]
	s_nop 0
	v_pk_fma_f32 v[18:19], v[18:19], s[60:61], v[80:81] op_sel_hi:[1,0,1]
	v_pk_add_f32 v[80:81], v[74:75], v[82:83]
	v_pk_add_f32 v[74:75], v[74:75], v[82:83] neg_lo:[0,1] neg_hi:[0,1]
	s_nop 0
	v_xor_b32_e32 v83, 0x80000000, v74
	v_mov_b32_e32 v82, v75
	v_pk_add_f32 v[74:75], v[76:77], v[84:85]
	v_pk_add_f32 v[76:77], v[76:77], v[84:85] neg_lo:[0,1] neg_hi:[0,1]
	s_nop 0
	v_pk_mul_f32 v[84:85], v[76:77], s[60:61] op_sel_hi:[1,0]
	v_xor_b32_e32 v139, 0x80000000, v76
	v_mov_b32_e32 v138, v77
	v_pk_fma_f32 v[76:77], v[138:139], s[60:61], v[84:85] op_sel_hi:[1,0,1] neg_lo:[0,0,1] neg_hi:[0,0,1]
	v_pk_add_f32 v[84:85], v[132:133], v[62:63]
	v_pk_add_f32 v[62:63], v[132:133], v[62:63] neg_lo:[0,1] neg_hi:[0,1]
	v_pk_add_f32 v[132:133], v[88:89], v[10:11]
	v_pk_add_f32 v[10:11], v[88:89], v[10:11] neg_lo:[0,1] neg_hi:[0,1]
	s_nop 0
	v_pk_mul_f32 v[88:89], v[10:11], s[60:61] op_sel:[1,0] op_sel_hi:[0,0] neg_hi:[1,0]
	s_nop 0
	v_pk_fma_f32 v[10:11], v[10:11], s[60:61], v[88:89] op_sel_hi:[1,0,1]
	v_pk_add_f32 v[88:89], v[22:23], v[66:67]
	v_pk_add_f32 v[22:23], v[22:23], v[66:67] neg_lo:[0,1] neg_hi:[0,1]
	s_nop 0
	v_xor_b32_e32 v67, 0x80000000, v22
	v_mov_b32_e32 v66, v23
	v_pk_add_f32 v[22:23], v[24:25], v[68:69]
	v_pk_add_f32 v[24:25], v[24:25], v[68:69] neg_lo:[0,1] neg_hi:[0,1]
	s_nop 0
	v_pk_mul_f32 v[68:69], v[24:25], s[60:61] op_sel_hi:[1,0]
	v_xor_b32_e32 v139, 0x80000000, v24
	v_mov_b32_e32 v138, v25
	v_pk_fma_f32 v[24:25], v[138:139], s[60:61], v[68:69] op_sel_hi:[1,0,1] neg_lo:[0,0,1] neg_hi:[0,0,1]
	v_pk_add_f32 v[68:69], v[2:3], v[64:65]
	v_pk_add_f32 v[2:3], v[2:3], v[64:65] neg_lo:[0,1] neg_hi:[0,1]
	v_pk_add_f32 v[64:65], v[4:5], v[12:13]
	v_pk_add_f32 v[4:5], v[4:5], v[12:13] neg_lo:[0,1] neg_hi:[0,1]
	s_nop 0
	v_pk_mul_f32 v[12:13], v[4:5], s[60:61] op_sel:[1,0] op_sel_hi:[0,0] neg_hi:[1,0]
	s_nop 0
	v_pk_fma_f32 v[4:5], v[4:5], s[60:61], v[12:13] op_sel_hi:[1,0,1]
	v_pk_add_f32 v[12:13], v[6:7], v[14:15]
	v_pk_add_f32 v[6:7], v[6:7], v[14:15] neg_lo:[0,1] neg_hi:[0,1]
	v_pk_add_f32 v[140:141], v[68:69], v[12:13]
	v_xor_b32_e32 v15, 0x80000000, v6
	v_mov_b32_e32 v14, v7
	v_pk_add_f32 v[6:7], v[8:9], v[16:17]
	v_pk_add_f32 v[8:9], v[8:9], v[16:17] neg_lo:[0,1] neg_hi:[0,1]
	v_pk_add_f32 v[142:143], v[64:65], v[6:7]
	v_pk_mul_f32 v[16:17], v[8:9], s[60:61] op_sel_hi:[1,0]
	s_nop 0
	v_pk_fma_f32 v[8:9], v[8:9], s[60:61], v[16:17] op_sel:[1,0,0] op_sel_hi:[0,0,1] neg_lo:[0,0,1] neg_hi:[1,0,1]
	v_pk_add_f32 v[16:17], v[70:71], v[136:137]
	v_pk_add_f32 v[70:71], v[70:71], v[136:137] neg_lo:[0,1] neg_hi:[0,1]
	v_pk_add_f32 v[136:137], v[134:135], v[72:73]
	v_pk_add_f32 v[72:73], v[134:135], v[72:73] neg_lo:[0,1] neg_hi:[0,1]
	v_pk_add_f32 v[138:139], v[84:85], v[88:89] neg_lo:[0,1] neg_hi:[0,1]
	v_xor_b32_e32 v135, 0x80000000, v72
	v_mov_b32_e32 v134, v73
	v_pk_add_f32 v[72:73], v[92:93], v[128:129]
	v_pk_add_f32 v[92:93], v[92:93], v[128:129] neg_lo:[0,1] neg_hi:[0,1]
	v_pk_add_f32 v[128:129], v[78:79], v[90:91]
	v_pk_add_f32 v[78:79], v[78:79], v[90:91] neg_lo:[0,1] neg_hi:[0,1]
	v_pk_add_f32 v[6:7], v[64:65], v[6:7] neg_lo:[0,1] neg_hi:[0,1]
	v_xor_b32_e32 v91, 0x80000000, v78
	v_mov_b32_e32 v90, v79
	v_pk_add_f32 v[78:79], v[130:131], v[80:81]
	v_pk_add_f32 v[130:131], v[130:131], v[80:81] neg_lo:[0,1] neg_hi:[0,1]
	v_pk_add_f32 v[80:81], v[94:95], v[74:75]
	v_pk_add_f32 v[74:75], v[94:95], v[74:75] neg_lo:[0,1] neg_hi:[0,1]
	v_xor_b32_e32 v149, 0x80000000, v6
	v_xor_b32_e32 v95, 0x80000000, v74
	v_mov_b32_e32 v94, v75
	v_pk_add_f32 v[74:75], v[86:87], v[82:83]
	v_pk_add_f32 v[82:83], v[86:87], v[82:83] neg_lo:[0,1] neg_hi:[0,1]
	v_pk_add_f32 v[86:87], v[18:19], v[76:77]
	v_pk_add_f32 v[18:19], v[18:19], v[76:77] neg_lo:[0,1] neg_hi:[0,1]
	v_mov_b32_e32 v148, v7
	v_xor_b32_e32 v77, 0x80000000, v18
	v_mov_b32_e32 v76, v19
	v_pk_add_f32 v[18:19], v[84:85], v[88:89]
	v_pk_add_f32 v[88:89], v[132:133], v[22:23]
	v_pk_add_f32 v[22:23], v[132:133], v[22:23] neg_lo:[0,1] neg_hi:[0,1]
	v_pk_add_f32 v[6:7], v[2:3], v[14:15]
	v_xor_b32_e32 v133, 0x80000000, v22
	v_mov_b32_e32 v132, v23
	v_pk_add_f32 v[22:23], v[62:63], v[66:67]
	v_pk_add_f32 v[62:63], v[62:63], v[66:67] neg_lo:[0,1] neg_hi:[0,1]
	v_pk_add_f32 v[66:67], v[10:11], v[24:25]
	v_pk_add_f32 v[10:11], v[10:11], v[24:25] neg_lo:[0,1] neg_hi:[0,1]
	v_pk_add_f32 v[154:155], v[2:3], v[14:15] neg_lo:[0,1] neg_hi:[0,1]
	v_pk_add_f32 v[2:3], v[4:5], v[8:9] neg_lo:[0,1] neg_hi:[0,1]
	v_pk_add_f32 v[68:69], v[68:69], v[12:13] neg_lo:[0,1] neg_hi:[0,1]
	v_pk_add_f32 v[156:157], v[4:5], v[8:9]
	v_xor_b32_e32 v159, 0x80000000, v2
	v_mov_b32_e32 v158, v3
	v_pk_add_f32 v[2:3], v[16:17], v[136:137]
	v_pk_add_f32 v[84:85], v[16:17], v[136:137] neg_lo:[0,1] neg_hi:[0,1]
	v_pk_add_f32 v[136:137], v[70:71], v[134:135]
	v_pk_add_f32 v[16:17], v[70:71], v[134:135] neg_lo:[0,1] neg_hi:[0,1]
	v_pk_add_f32 v[134:135], v[72:73], v[128:129]
	v_pk_add_f32 v[70:71], v[72:73], v[128:129] neg_lo:[0,1] neg_hi:[0,1]
	v_pk_add_f32 v[128:129], v[92:93], v[90:91]
	v_pk_add_f32 v[8:9], v[92:93], v[90:91] neg_lo:[0,1] neg_hi:[0,1]
	v_pk_add_f32 v[72:73], v[78:79], v[80:81]
	v_pk_add_f32 v[80:81], v[78:79], v[80:81] neg_lo:[0,1] neg_hi:[0,1]
	v_pk_add_f32 v[92:93], v[130:131], v[94:95]
	v_pk_add_f32 v[12:13], v[130:131], v[94:95] neg_lo:[0,1] neg_hi:[0,1]
	v_pk_add_f32 v[78:79], v[74:75], v[86:87]
	v_pk_add_f32 v[64:65], v[74:75], v[86:87] neg_lo:[0,1] neg_hi:[0,1]
	v_pk_add_f32 v[130:131], v[82:83], v[76:77]
	v_pk_add_f32 v[4:5], v[82:83], v[76:77] neg_lo:[0,1] neg_hi:[0,1]
	v_pk_add_f32 v[76:77], v[18:19], v[88:89]
	v_pk_add_f32 v[88:89], v[18:19], v[88:89] neg_lo:[0,1] neg_hi:[0,1]
	v_pk_add_f32 v[86:87], v[138:139], v[132:133]
	v_pk_add_f32 v[18:19], v[138:139], v[132:133] neg_lo:[0,1] neg_hi:[0,1]
	v_pk_add_f32 v[132:133], v[62:63], v[10:11] op_sel:[0,1] op_sel_hi:[1,0] neg_hi:[0,1]
	v_pk_add_f32 v[10:11], v[62:63], v[10:11] op_sel:[0,1] op_sel_hi:[1,0] neg_lo:[0,1]
	v_pk_mul_f32 v[24:25], v[20:21], v[20:21]
	s_nop 0
	v_pk_add_f32 v[24:25], v[24:25], v[24:25] op_sel:[0,1] op_sel_hi:[0,1] neg_lo:[0,1] neg_hi:[0,1]
	v_pk_mul_f32 v[62:63], v[20:21], v[26:27] op_sel:[1,0] op_sel_hi:[0,0] neg_lo:[1,0]
	v_pk_add_f32 v[90:91], v[22:23], v[66:67]
	v_pk_add_f32 v[74:75], v[22:23], v[66:67] neg_lo:[0,1] neg_hi:[0,1]
	v_pk_add_f32 v[22:23], v[140:141], v[142:143]
	v_pk_add_f32 v[82:83], v[140:141], v[142:143] neg_lo:[0,1] neg_hi:[0,1]
	v_pk_add_f32 v[138:139], v[68:69], v[148:149]
	v_pk_add_f32 v[14:15], v[68:69], v[148:149] neg_lo:[0,1] neg_hi:[0,1]
	v_pk_fma_f32 v[68:69], v[20:21], v[24:25], v[62:63]
	v_mov_b32_e32 v142, v21
	s_nop 0
	v_pk_mul_f32 v[62:63], v[142:143], v[76:77] op_sel:[0,1] op_sel_hi:[0,0] neg_hi:[0,1]
	v_pk_fma_f32 v[20:21], v[20:21], v[76:77], v[62:63] op_sel_hi:[0,1,1]
	v_pk_mul_f32 v[62:63], v[26:27], s[46:47] op_sel_hi:[0,1]
	v_pk_fma_f32 v[76:77], v[24:25], s[40:41], v[62:63]
	s_nop 0
	v_pk_mul_f32 v[62:63], v[76:77], v[72:73] op_sel:[1,1] op_sel_hi:[1,0] neg_hi:[0,1]
	v_pk_add_f32 v[94:95], v[6:7], v[156:157]
	v_pk_fma_f32 v[62:63], v[72:73], v[76:77], v[62:63] op_sel_hi:[1,0,1]
	v_pk_mul_f32 v[72:73], v[26:27], v[68:69] op_sel:[0,1] op_sel_hi:[0,0] neg_lo:[0,1]
	v_pk_fma_f32 v[142:143], v[24:25], v[68:69], v[72:73]
	v_pk_mul_f32 v[72:73], v[68:69], v[22:23] op_sel:[1,1] op_sel_hi:[1,0] neg_hi:[0,1]
	v_pk_add_f32 v[140:141], v[154:155], v[158:159]
	v_pk_fma_f32 v[22:23], v[68:69], v[22:23], v[72:73] op_sel_hi:[0,1,1]
	v_pk_mul_f32 v[68:69], v[26:27], v[76:77] op_sel:[0,1] op_sel_hi:[0,0] neg_lo:[0,1]
	v_pk_fma_f32 v[76:77], v[24:25], v[76:77], v[68:69]
	s_nop 0
	v_pk_mul_f32 v[68:69], v[134:135], v[76:77] op_sel:[1,1] op_sel_hi:[0,1] neg_hi:[1,0]
	v_pk_add_f32 v[66:67], v[6:7], v[156:157] neg_lo:[0,1] neg_hi:[0,1]
	v_pk_fma_f32 v[72:73], v[134:135], v[76:77], v[68:69] op_sel_hi:[1,0,1]
	v_pk_mul_f32 v[68:69], v[26:27], v[142:143] op_sel:[0,1] op_sel_hi:[0,0] neg_lo:[0,1]
	v_pk_fma_f32 v[134:135], v[24:25], v[142:143], v[68:69]
	v_pk_mul_f32 v[68:69], v[142:143], v[90:91] op_sel:[1,1] op_sel_hi:[1,0] neg_hi:[0,1]
	v_pk_add_f32 v[6:7], v[154:155], v[158:159] neg_lo:[0,1] neg_hi:[0,1]
	v_pk_fma_f32 v[68:69], v[90:91], v[142:143], v[68:69] op_sel_hi:[1,0,1]
	v_pk_mul_f32 v[90:91], v[26:27], v[76:77] op_sel:[0,1] op_sel_hi:[0,0] neg_lo:[0,1]
	v_pk_fma_f32 v[90:91], v[24:25], v[76:77], v[90:91]
	s_nop 0
	v_pk_mul_f32 v[76:77], v[78:79], v[90:91] op_sel:[1,1] op_sel_hi:[0,1] neg_hi:[1,0]
	s_nop 0
	v_pk_fma_f32 v[78:79], v[78:79], v[90:91], v[76:77] op_sel_hi:[1,0,1]
	v_pk_mul_f32 v[76:77], v[26:27], v[134:135] op_sel:[0,1] op_sel_hi:[0,0] neg_lo:[0,1]
	v_pk_fma_f32 v[142:143], v[24:25], v[134:135], v[76:77]
	v_pk_mul_f32 v[76:77], v[134:135], v[94:95] op_sel:[1,1] op_sel_hi:[1,0] neg_hi:[0,1]
	s_nop 0
	v_pk_fma_f32 v[76:77], v[94:95], v[134:135], v[76:77] op_sel_hi:[1,0,1]
	v_pk_mul_f32 v[94:95], v[26:27], v[90:91] op_sel:[0,1] op_sel_hi:[0,0] neg_lo:[0,1]
	v_pk_fma_f32 v[94:95], v[24:25], v[90:91], v[94:95]
	s_nop 0
	v_pk_mul_f32 v[90:91], v[136:137], v[94:95] op_sel:[1,1] op_sel_hi:[0,1] neg_hi:[1,0]
	v_xor_b32_e32 v134, 0x80000000, v143
	v_pk_fma_f32 v[90:91], v[136:137], v[94:95], v[90:91] op_sel_hi:[1,0,1]
	v_pk_mul_f32 v[136:137], v[86:87], v[142:143] op_sel:[1,1] op_sel_hi:[0,1] neg_hi:[1,0]
	v_mov_b32_e32 v135, v142
	v_pk_fma_f32 v[86:87], v[86:87], v[142:143], v[136:137] op_sel_hi:[1,0,1]
	v_pk_mul_f32 v[136:137], v[26:27], v[94:95] op_sel:[0,1] op_sel_hi:[0,0] neg_lo:[0,1]
	v_pk_mul_f32 v[134:135], v[26:27], v[134:135] op_sel_hi:[0,1]
	v_pk_fma_f32 v[136:137], v[24:25], v[94:95], v[136:137]
	v_pk_fma_f32 v[134:135], v[24:25], v[142:143], v[134:135]
	v_pk_mul_f32 v[94:95], v[92:93], v[136:137] op_sel:[1,1] op_sel_hi:[0,1] neg_hi:[1,0]
	s_nop 0
	v_pk_fma_f32 v[94:95], v[92:93], v[136:137], v[94:95] op_sel_hi:[1,0,1]
	v_pk_mul_f32 v[92:93], v[26:27], v[134:135] op_sel:[0,1] op_sel_hi:[0,0] neg_lo:[0,1]
	v_pk_fma_f32 v[142:143], v[24:25], v[134:135], v[92:93]
	v_pk_mul_f32 v[92:93], v[138:139], v[134:135] op_sel:[1,1] op_sel_hi:[0,1] neg_hi:[1,0]
	s_nop 0
	v_pk_fma_f32 v[92:93], v[138:139], v[134:135], v[92:93] op_sel_hi:[1,0,1]
	v_pk_mul_f32 v[134:135], v[26:27], v[136:137] op_sel:[0,1] op_sel_hi:[0,0] neg_lo:[0,1]
	s_nop 0
	v_pk_fma_f32 v[134:135], v[24:25], v[136:137], v[134:135]
	v_pk_mul_f32 v[138:139], v[132:133], v[142:143] op_sel:[1,1] op_sel_hi:[0,1] neg_hi:[1,0]
	v_pk_mul_f32 v[136:137], v[128:129], v[134:135] op_sel:[1,1] op_sel_hi:[0,1] neg_hi:[1,0]
	v_pk_fma_f32 v[132:133], v[132:133], v[142:143], v[138:139] op_sel_hi:[1,0,1]
	v_pk_fma_f32 v[128:129], v[128:129], v[134:135], v[136:137] op_sel_hi:[1,0,1]
	v_pk_mul_f32 v[138:139], v[26:27], v[134:135] op_sel:[0,1] op_sel_hi:[0,0] neg_lo:[0,1]
	v_pk_mul_f32 v[136:137], v[26:27], v[142:143] op_sel:[0,1] op_sel_hi:[0,0] neg_lo:[0,1]
	v_pk_fma_f32 v[134:135], v[24:25], v[134:135], v[138:139]
	v_pk_fma_f32 v[136:137], v[24:25], v[142:143], v[136:137]
	v_pk_mul_f32 v[138:139], v[130:131], v[134:135] op_sel:[1,1] op_sel_hi:[0,1] neg_hi:[1,0]
	s_nop 0
	v_pk_fma_f32 v[130:131], v[130:131], v[134:135], v[138:139] op_sel_hi:[1,0,1]
	v_pk_mul_f32 v[138:139], v[26:27], v[136:137] op_sel:[0,1] op_sel_hi:[0,0] neg_lo:[0,1]
	v_pk_mul_f32 v[142:143], v[140:141], v[136:137] op_sel:[1,1] op_sel_hi:[0,1] neg_hi:[1,0]
	v_pk_fma_f32 v[138:139], v[24:25], v[136:137], v[138:139]
	v_pk_fma_f32 v[136:137], v[140:141], v[136:137], v[142:143] op_sel_hi:[1,0,1]
	v_pk_mul_f32 v[140:141], v[26:27], v[134:135] op_sel:[0,1] op_sel_hi:[0,0] neg_lo:[0,1]
	v_pk_fma_f32 v[134:135], v[24:25], v[134:135], v[140:141]
	s_nop 0
	v_pk_mul_f32 v[140:141], v[84:85], v[134:135] op_sel:[1,1] op_sel_hi:[0,1] neg_hi:[1,0]
	s_nop 0
	v_pk_fma_f32 v[84:85], v[84:85], v[134:135], v[140:141] op_sel_hi:[1,0,1]
	v_pk_mul_f32 v[140:141], v[26:27], v[138:139] op_sel:[0,1] op_sel_hi:[0,0] neg_lo:[0,1]
	v_pk_mul_f32 v[142:143], v[88:89], v[138:139] op_sel:[1,1] op_sel_hi:[0,1] neg_hi:[1,0]
	v_pk_fma_f32 v[140:141], v[24:25], v[138:139], v[140:141]
	v_pk_fma_f32 v[88:89], v[88:89], v[138:139], v[142:143] op_sel_hi:[1,0,1]
	v_pk_mul_f32 v[138:139], v[26:27], v[134:135] op_sel:[0,1] op_sel_hi:[0,0] neg_lo:[0,1]
	v_pk_fma_f32 v[134:135], v[24:25], v[134:135], v[138:139]
	s_nop 0
	v_pk_mul_f32 v[138:139], v[80:81], v[134:135] op_sel:[1,1] op_sel_hi:[0,1] neg_hi:[1,0]
	s_nop 0
	v_pk_fma_f32 v[80:81], v[80:81], v[134:135], v[138:139] op_sel_hi:[1,0,1]
	v_pk_mul_f32 v[138:139], v[26:27], v[140:141] op_sel:[0,1] op_sel_hi:[0,0] neg_lo:[0,1]
	v_pk_mul_f32 v[142:143], v[82:83], v[140:141] op_sel:[1,1] op_sel_hi:[0,1] neg_hi:[1,0]
	v_pk_fma_f32 v[138:139], v[24:25], v[140:141], v[138:139]
	v_pk_fma_f32 v[82:83], v[82:83], v[140:141], v[142:143] op_sel_hi:[1,0,1]
	v_pk_mul_f32 v[140:141], v[26:27], v[134:135] op_sel:[0,1] op_sel_hi:[0,0] neg_lo:[0,1]
	v_pk_fma_f32 v[134:135], v[24:25], v[134:135], v[140:141]
	s_nop 0
	v_pk_mul_f32 v[140:141], v[70:71], v[134:135] op_sel:[1,1] op_sel_hi:[0,1] neg_hi:[1,0]
	s_nop 0
	v_pk_fma_f32 v[70:71], v[70:71], v[134:135], v[140:141] op_sel_hi:[1,0,1]
	v_pk_mul_f32 v[140:141], v[26:27], v[138:139] op_sel:[0,1] op_sel_hi:[0,0] neg_lo:[0,1]
	v_pk_mul_f32 v[142:143], v[74:75], v[138:139] op_sel:[1,1] op_sel_hi:[0,1] neg_hi:[1,0]
	v_pk_fma_f32 v[140:141], v[24:25], v[138:139], v[140:141]
	v_pk_fma_f32 v[74:75], v[74:75], v[138:139], v[142:143] op_sel_hi:[1,0,1]
	v_pk_mul_f32 v[138:139], v[26:27], v[134:135] op_sel:[0,1] op_sel_hi:[0,0] neg_lo:[0,1]
	v_pk_fma_f32 v[134:135], v[24:25], v[134:135], v[138:139]
	s_nop 0
	v_pk_mul_f32 v[138:139], v[64:65], v[134:135] op_sel:[1,1] op_sel_hi:[0,1] neg_hi:[1,0]
	s_nop 0
	v_pk_fma_f32 v[64:65], v[64:65], v[134:135], v[138:139] op_sel_hi:[1,0,1]
	v_pk_mul_f32 v[138:139], v[26:27], v[140:141] op_sel:[0,1] op_sel_hi:[0,0] neg_lo:[0,1]
	v_pk_mul_f32 v[142:143], v[66:67], v[140:141] op_sel:[1,1] op_sel_hi:[0,1] neg_hi:[1,0]
	v_pk_fma_f32 v[138:139], v[24:25], v[140:141], v[138:139]
	v_pk_fma_f32 v[66:67], v[66:67], v[140:141], v[142:143] op_sel_hi:[1,0,1]
	v_pk_mul_f32 v[140:141], v[26:27], v[134:135] op_sel:[0,1] op_sel_hi:[0,0] neg_lo:[0,1]
	v_pk_fma_f32 v[134:135], v[24:25], v[134:135], v[140:141]
	s_nop 0
	v_pk_mul_f32 v[140:141], v[16:17], v[134:135] op_sel:[1,1] op_sel_hi:[0,1] neg_hi:[1,0]
	s_nop 0
	v_pk_fma_f32 v[16:17], v[16:17], v[134:135], v[140:141] op_sel_hi:[1,0,1]
	v_pk_mul_f32 v[140:141], v[26:27], v[138:139] op_sel:[0,1] op_sel_hi:[0,0] neg_lo:[0,1]
	v_pk_mul_f32 v[142:143], v[18:19], v[138:139] op_sel:[1,1] op_sel_hi:[0,1] neg_hi:[1,0]
	v_pk_fma_f32 v[140:141], v[24:25], v[138:139], v[140:141]
	v_pk_fma_f32 v[18:19], v[18:19], v[138:139], v[142:143] op_sel_hi:[1,0,1]
	v_pk_mul_f32 v[138:139], v[26:27], v[134:135] op_sel:[0,1] op_sel_hi:[0,0] neg_lo:[0,1]
	v_pk_fma_f32 v[134:135], v[24:25], v[134:135], v[138:139]
	s_nop 0
	v_pk_mul_f32 v[138:139], v[12:13], v[134:135] op_sel:[1,1] op_sel_hi:[0,1] neg_hi:[1,0]
	s_nop 0
	v_pk_fma_f32 v[12:13], v[12:13], v[134:135], v[138:139] op_sel_hi:[1,0,1]
	v_pk_mul_f32 v[138:139], v[26:27], v[140:141] op_sel:[0,1] op_sel_hi:[0,0] neg_lo:[0,1]
	v_pk_mul_f32 v[142:143], v[14:15], v[140:141] op_sel:[1,1] op_sel_hi:[0,1] neg_hi:[1,0]
	v_pk_fma_f32 v[138:139], v[24:25], v[140:141], v[138:139]
	v_pk_fma_f32 v[14:15], v[14:15], v[140:141], v[142:143] op_sel_hi:[1,0,1]
	v_pk_mul_f32 v[140:141], v[26:27], v[134:135] op_sel:[0,1] op_sel_hi:[0,0] neg_lo:[0,1]
	v_pk_fma_f32 v[134:135], v[24:25], v[134:135], v[140:141]
	s_nop 0
	v_pk_mul_f32 v[140:141], v[8:9], v[134:135] op_sel:[1,1] op_sel_hi:[0,1] neg_hi:[1,0]
	s_nop 0
	v_pk_fma_f32 v[8:9], v[8:9], v[134:135], v[140:141] op_sel_hi:[1,0,1]
	v_pk_mul_f32 v[140:141], v[26:27], v[138:139] op_sel:[0,1] op_sel_hi:[0,0] neg_lo:[0,1]
	v_pk_mul_f32 v[142:143], v[10:11], v[138:139] op_sel:[1,1] op_sel_hi:[0,1] neg_hi:[1,0]
	v_pk_fma_f32 v[140:141], v[24:25], v[138:139], v[140:141]
	v_pk_fma_f32 v[10:11], v[10:11], v[138:139], v[142:143] op_sel_hi:[1,0,1]
	v_pk_mul_f32 v[138:139], v[26:27], v[134:135] op_sel:[0,1] op_sel_hi:[0,0] neg_lo:[0,1]
	v_pk_fma_f32 v[24:25], v[24:25], v[134:135], v[138:139]
	s_nop 0
	v_pk_mul_f32 v[134:135], v[4:5], v[24:25] op_sel:[1,1] op_sel_hi:[0,1] neg_hi:[1,0]
	s_nop 0
	v_pk_fma_f32 v[4:5], v[4:5], v[24:25], v[134:135] op_sel_hi:[1,0,1]
	v_pk_mul_f32 v[24:25], v[6:7], v[140:141] op_sel:[1,1] op_sel_hi:[0,1] neg_hi:[1,0]
	s_nop 0
	v_pk_fma_f32 v[6:7], v[6:7], v[140:141], v[24:25] op_sel_hi:[1,0,1]
	ds_write_b64 v27, v[2:3]
	ds_write_b64 v96, v[84:85]
	ds_write_b64 v97, v[90:91] offset:256
	ds_write_b64 v98, v[16:17] offset:256
	ds_write_b64 v99, v[72:73] offset:512
	ds_write_b64 v100, v[70:71] offset:512
	ds_write_b64 v101, v[128:129] offset:768
	ds_write_b64 v102, v[8:9] offset:768
	ds_write_b64 v103, v[62:63] offset:1024
	ds_write_b64 v104, v[80:81] offset:1024
	ds_write_b64 v105, v[94:95] offset:1280
	ds_write_b64 v106, v[12:13] offset:1280
	ds_write_b64 v107, v[78:79] offset:1536
	ds_write_b64 v108, v[64:65] offset:1536
	ds_write_b64 v109, v[130:131] offset:1792
	ds_write_b64 v110, v[4:5] offset:1792
	ds_write_b64 v111, v[20:21] offset:2048
	ds_write_b64 v112, v[88:89] offset:2048
	ds_write_b64 v113, v[86:87] offset:2304
	ds_write_b64 v114, v[18:19] offset:2304
	ds_write_b64 v115, v[68:69] offset:2560
	ds_write_b64 v116, v[74:75] offset:2560
	ds_write_b64 v117, v[132:133] offset:2816
	ds_write_b64 v118, v[10:11] offset:2816
	ds_write_b64 v119, v[22:23] offset:3072
	ds_write_b64 v120, v[82:83] offset:3072
	ds_write_b64 v121, v[92:93] offset:3328
	ds_write_b64 v122, v[14:15] offset:3328
	ds_write_b64 v123, v[76:77] offset:3584
	ds_write_b64 v124, v[66:67] offset:3584
	ds_write_b64 v125, v[136:137] offset:3840
	ds_write_b64 v126, v[6:7] offset:3840
	v_mov_b32_e32 v2, v146
	s_waitcnt lgkmcnt(0)
	s_barrier
	s_nop 0
	v_lshlrev_b32_e32 v3, 4, v2
	v_lshrrev_b32_e32 v4, 1, v2
	v_bfe_u32 v2, v2, 1, 4
	v_bitop3_b32 v5, v4, v3, 16 bitop3:0x6c
	v_lshl_add_u32 v5, v5, 3, 16
	v_lshlrev_b32_e32 v2, 3, v2
	v_add_u32_e32 v6, v5, v2
	ds_read_b64 v[12:13], v6
	v_bitop3_b32 v6, v4, 1, 15 bitop3:0x6c
	v_lshlrev_b32_e32 v8, 3, v6
	v_add_u32_e32 v6, v5, v8
	ds_read_b64 v[14:15], v6
	v_bitop3_b32 v6, v4, 2, 15 bitop3:0x6c
	v_lshlrev_b32_e32 v9, 3, v6
	v_add_u32_e32 v6, v5, v9
	ds_read_b64 v[16:17], v6
	v_bitop3_b32 v6, v4, 3, 15 bitop3:0x6c
	v_lshlrev_b32_e32 v10, 3, v6
	v_add_u32_e32 v6, v5, v10
	ds_read_b64 v[18:19], v6
	v_bitop3_b32 v6, v4, 4, 15 bitop3:0x6c
	v_lshlrev_b32_e32 v11, 3, v6
	v_add_u32_e32 v6, v5, v11
	ds_read_b64 v[20:21], v6
	v_bitop3_b32 v6, v4, 5, 15 bitop3:0x6c
	v_lshlrev_b32_e32 v82, 3, v6
	v_add_u32_e32 v6, v5, v82
	ds_read_b64 v[22:23], v6
	v_bitop3_b32 v6, v4, 6, 15 bitop3:0x6c
	v_lshlrev_b32_e32 v83, 3, v6
	v_add_u32_e32 v6, v5, v83
	ds_read_b64 v[24:25], v6
	v_bitop3_b32 v6, v4, 7, 15 bitop3:0x6c
	v_lshlrev_b32_e32 v84, 3, v6
	v_add_u32_e32 v6, v5, v84
	ds_read_b64 v[26:27], v6
	v_bitop3_b32 v6, v4, 8, 15 bitop3:0x6c
	v_lshlrev_b32_e32 v85, 3, v6
	v_add_u32_e32 v6, v5, v85
	ds_read_b64 v[62:63], v6
	v_bitop3_b32 v6, v4, 9, 15 bitop3:0x6c
	v_lshlrev_b32_e32 v86, 3, v6
	v_add_u32_e32 v6, v5, v86
	ds_read_b64 v[64:65], v6
	v_bitop3_b32 v6, v4, 10, 15 bitop3:0x6c
	v_lshlrev_b32_e32 v87, 3, v6
	v_add_u32_e32 v6, v5, v87
	ds_read_b64 v[66:67], v6
	v_bitop3_b32 v6, v4, 11, 15 bitop3:0x6c
	v_lshlrev_b32_e32 v88, 3, v6
	v_add_u32_e32 v6, v5, v88
	ds_read_b64 v[68:69], v6
	v_bitop3_b32 v6, v4, 12, 15 bitop3:0x6c
	v_lshlrev_b32_e32 v89, 3, v6
	v_add_u32_e32 v6, v5, v89
	ds_read_b64 v[70:71], v6
	v_bitop3_b32 v6, v4, 13, 15 bitop3:0x6c
	v_lshlrev_b32_e32 v90, 3, v6
	v_add_u32_e32 v6, v5, v90
	ds_read_b64 v[72:73], v6
	v_bitop3_b32 v6, v4, 14, 15 bitop3:0x6c
	v_lshlrev_b32_e32 v91, 3, v6
	v_add_u32_e32 v6, v5, v91
	v_add_u32_e32 v3, 0x2000, v3
	ds_read_b64 v[74:75], v6
	v_bitop3_b32 v6, v4, 15, v4 bitop3:0xc
	v_bitop3_b32 v3, v3, v4, 16 bitop3:0x78
	v_lshlrev_b32_e32 v106, 3, v6
	v_lshl_add_u32 v107, v3, 3, 16
	v_add_u32_e32 v5, v5, v106
	v_add_u32_e32 v2, v107, v2
	ds_read_b64 v[76:77], v5
	ds_read_b64 v[6:7], v2
	v_add_u32_e32 v2, v107, v8
	ds_read_b64 v[78:79], v2
	v_add_u32_e32 v2, v107, v9
	ds_read_b64 v[8:9], v2
	v_add_u32_e32 v2, v107, v10
	ds_read_b64 v[80:81], v2
	v_add_u32_e32 v2, v107, v11
	ds_read_b64 v[10:11], v2
	v_add_u32_e32 v2, v107, v82
	v_add_u32_e32 v82, v107, v84
	v_add_u32_e32 v84, v107, v85
	ds_read_b64 v[4:5], v2
	ds_read_b64 v[92:93], v84
	v_add_u32_e32 v2, v107, v83
	v_add_u32_e32 v84, v107, v86
	ds_read_b64 v[2:3], v2
	ds_read_b64 v[82:83], v82
	ds_read_b64 v[94:95], v84
	v_add_u32_e32 v84, v107, v87
	ds_read_b64 v[96:97], v84
	v_add_u32_e32 v84, v107, v88
	ds_read_b64 v[98:99], v84
	v_add_u32_e32 v84, v107, v89
	ds_read_b64 v[100:101], v84
	v_add_u32_e32 v84, v107, v90
	ds_read_b64 v[102:103], v84
	v_add_u32_e32 v84, v107, v91
	ds_read_b64 v[104:105], v84
	v_add_u32_e32 v84, v107, v106
	ds_read_b64 v[106:107], v84
	s_waitcnt lgkmcnt(14)
	v_pk_add_f32 v[84:85], v[12:13], v[62:63]
	v_pk_add_f32 v[12:13], v[12:13], v[62:63] neg_lo:[0,1] neg_hi:[0,1]
	v_pk_add_f32 v[62:63], v[14:15], v[64:65]
	v_pk_add_f32 v[14:15], v[14:15], v[64:65] neg_lo:[0,1] neg_hi:[0,1]
	s_nop 0
	v_pk_mul_f32 v[64:65], v[14:15], s[54:55] op_sel:[1,0] op_sel_hi:[0,0] neg_hi:[1,0]
	s_nop 0
	v_pk_fma_f32 v[14:15], v[14:15], s[52:53], v[64:65] op_sel_hi:[1,0,1]
	v_pk_add_f32 v[64:65], v[16:17], v[66:67]
	v_pk_add_f32 v[16:17], v[16:17], v[66:67] neg_lo:[0,1] neg_hi:[0,1]
	s_nop 0
	v_pk_mul_f32 v[66:67], v[16:17], s[60:61] op_sel:[1,0] op_sel_hi:[0,0] neg_hi:[1,0]
	s_nop 0
	v_pk_fma_f32 v[16:17], v[16:17], s[60:61], v[66:67] op_sel_hi:[1,0,1]
	v_pk_add_f32 v[66:67], v[18:19], v[68:69]
	v_pk_add_f32 v[18:19], v[18:19], v[68:69] neg_lo:[0,1] neg_hi:[0,1]
	s_nop 0
	v_pk_mul_f32 v[68:69], v[18:19], s[52:53] op_sel:[1,0] op_sel_hi:[0,0] neg_hi:[1,0]
	s_nop 0
	v_pk_fma_f32 v[18:19], v[18:19], s[54:55], v[68:69] op_sel_hi:[1,0,1]
	v_pk_add_f32 v[68:69], v[20:21], v[70:71]
	v_pk_add_f32 v[20:21], v[20:21], v[70:71] neg_lo:[0,1] neg_hi:[0,1]
	s_nop 0
	v_xor_b32_e32 v71, 0x80000000, v20
	v_mov_b32_e32 v70, v21
	v_pk_add_f32 v[20:21], v[22:23], v[72:73]
	v_pk_add_f32 v[22:23], v[22:23], v[72:73] neg_lo:[0,1] neg_hi:[0,1]
	s_nop 0
	v_pk_mul_f32 v[72:73], v[22:23], s[54:55] op_sel_hi:[1,0]
	v_xor_b32_e32 v87, 0x80000000, v22
	v_mov_b32_e32 v86, v23
	v_pk_fma_f32 v[22:23], v[86:87], s[52:53], v[72:73] op_sel_hi:[1,0,1] neg_lo:[0,0,1] neg_hi:[0,0,1]
	v_pk_add_f32 v[72:73], v[24:25], v[74:75]
	v_pk_add_f32 v[24:25], v[24:25], v[74:75] neg_lo:[0,1] neg_hi:[0,1]
	s_nop 0
	v_pk_mul_f32 v[74:75], v[24:25], s[60:61] op_sel_hi:[1,0]
	v_xor_b32_e32 v87, 0x80000000, v24
	v_mov_b32_e32 v86, v25
	v_pk_fma_f32 v[24:25], v[86:87], s[60:61], v[74:75] op_sel_hi:[1,0,1] neg_lo:[0,0,1] neg_hi:[0,0,1]
	v_pk_add_f32 v[74:75], v[26:27], v[76:77]
	v_pk_add_f32 v[26:27], v[26:27], v[76:77] neg_lo:[0,1] neg_hi:[0,1]
	s_nop 0
	v_pk_mul_f32 v[76:77], v[26:27], s[52:53] op_sel_hi:[1,0]
	v_xor_b32_e32 v87, 0x80000000, v26
	v_mov_b32_e32 v86, v27
	v_pk_fma_f32 v[26:27], v[86:87], s[54:55], v[76:77] op_sel_hi:[1,0,1] neg_lo:[0,0,1] neg_hi:[0,0,1]
	v_pk_add_f32 v[76:77], v[84:85], v[68:69]
	v_pk_add_f32 v[68:69], v[84:85], v[68:69] neg_lo:[0,1] neg_hi:[0,1]
	v_pk_add_f32 v[84:85], v[62:63], v[20:21]
	v_pk_add_f32 v[20:21], v[62:63], v[20:21] neg_lo:[0,1] neg_hi:[0,1]
	s_nop 0
	v_pk_mul_f32 v[62:63], v[20:21], s[60:61] op_sel:[1,0] op_sel_hi:[0,0] neg_hi:[1,0]
	s_nop 0
	v_pk_fma_f32 v[20:21], v[20:21], s[60:61], v[62:63] op_sel_hi:[1,0,1]
	v_pk_add_f32 v[62:63], v[64:65], v[72:73]
	v_pk_add_f32 v[64:65], v[64:65], v[72:73] neg_lo:[0,1] neg_hi:[0,1]
	s_nop 0
	v_xor_b32_e32 v73, 0x80000000, v64
	v_mov_b32_e32 v72, v65
	v_pk_add_f32 v[64:65], v[66:67], v[74:75]
	v_pk_add_f32 v[66:67], v[66:67], v[74:75] neg_lo:[0,1] neg_hi:[0,1]
	s_nop 0
	v_pk_mul_f32 v[74:75], v[66:67], s[60:61] op_sel_hi:[1,0]
	v_xor_b32_e32 v87, 0x80000000, v66
	v_mov_b32_e32 v86, v67
	v_pk_fma_f32 v[66:67], v[86:87], s[60:61], v[74:75] op_sel_hi:[1,0,1] neg_lo:[0,0,1] neg_hi:[0,0,1]
	v_pk_add_f32 v[74:75], v[12:13], v[70:71]
	v_pk_add_f32 v[12:13], v[12:13], v[70:71] neg_lo:[0,1] neg_hi:[0,1]
	v_pk_add_f32 v[70:71], v[14:15], v[22:23]
	v_pk_add_f32 v[14:15], v[14:15], v[22:23] neg_lo:[0,1] neg_hi:[0,1]
	s_nop 0
	v_pk_mul_f32 v[22:23], v[14:15], s[60:61] op_sel:[1,0] op_sel_hi:[0,0] neg_hi:[1,0]
	s_nop 0
	v_pk_fma_f32 v[14:15], v[14:15], s[60:61], v[22:23] op_sel_hi:[1,0,1]
	v_pk_add_f32 v[22:23], v[16:17], v[24:25]
	v_pk_add_f32 v[16:17], v[16:17], v[24:25] neg_lo:[0,1] neg_hi:[0,1]
	s_nop 0
	v_xor_b32_e32 v25, 0x80000000, v16
	v_mov_b32_e32 v24, v17
	v_pk_add_f32 v[16:17], v[18:19], v[26:27]
	v_pk_add_f32 v[18:19], v[18:19], v[26:27] neg_lo:[0,1] neg_hi:[0,1]
	v_pk_add_f32 v[108:109], v[12:13], v[24:25]
	v_pk_mul_f32 v[26:27], v[18:19], s[60:61] op_sel_hi:[1,0]
	s_nop 0
	v_pk_fma_f32 v[18:19], v[18:19], s[60:61], v[26:27] op_sel:[1,0,0] op_sel_hi:[0,0,1] neg_lo:[0,0,1] neg_hi:[1,0,1]
	v_pk_add_f32 v[26:27], v[76:77], v[62:63]
	v_pk_add_f32 v[62:63], v[76:77], v[62:63] neg_lo:[0,1] neg_hi:[0,1]
	v_pk_add_f32 v[76:77], v[84:85], v[64:65]
	v_pk_add_f32 v[64:65], v[84:85], v[64:65] neg_lo:[0,1] neg_hi:[0,1]
	v_pk_add_f32 v[110:111], v[12:13], v[24:25] neg_lo:[0,1] neg_hi:[0,1]
	v_xor_b32_e32 v85, 0x80000000, v64
	v_mov_b32_e32 v84, v65
	v_pk_add_f32 v[64:65], v[68:69], v[72:73]
	v_pk_add_f32 v[68:69], v[68:69], v[72:73] neg_lo:[0,1] neg_hi:[0,1]
	v_pk_add_f32 v[72:73], v[20:21], v[66:67]
	v_pk_add_f32 v[20:21], v[20:21], v[66:67] neg_lo:[0,1] neg_hi:[0,1]
	v_pk_add_f32 v[12:13], v[14:15], v[18:19] neg_lo:[0,1] neg_hi:[0,1]
	v_pk_add_f32 v[112:113], v[14:15], v[18:19]
	v_xor_b32_e32 v115, 0x80000000, v12
	v_mov_b32_e32 v114, v13
	v_pk_add_f32 v[12:13], v[26:27], v[76:77]
	v_pk_add_f32 v[14:15], v[26:27], v[76:77] neg_lo:[0,1] neg_hi:[0,1]
	v_pk_add_f32 v[24:25], v[68:69], v[20:21] op_sel:[0,1] op_sel_hi:[1,0] neg_hi:[0,1]
	v_pk_add_f32 v[26:27], v[68:69], v[20:21] op_sel:[0,1] op_sel_hi:[1,0] neg_lo:[0,1]
	s_waitcnt lgkmcnt(6)
	v_pk_add_f32 v[66:67], v[78:79], v[94:95] neg_lo:[0,1] neg_hi:[0,1]
	v_pk_add_f32 v[86:87], v[74:75], v[22:23]
	v_pk_mul_f32 v[76:77], v[66:67], s[54:55] op_sel:[1,0] op_sel_hi:[0,0] neg_hi:[1,0]
	v_pk_add_f32 v[74:75], v[74:75], v[22:23] neg_lo:[0,1] neg_hi:[0,1]
	v_pk_fma_f32 v[66:67], v[66:67], s[52:53], v[76:77] op_sel_hi:[1,0,1]
	s_waitcnt lgkmcnt(5)
	v_pk_add_f32 v[76:77], v[8:9], v[96:97]
	v_pk_add_f32 v[8:9], v[8:9], v[96:97] neg_lo:[0,1] neg_hi:[0,1]
	v_pk_add_f32 v[20:21], v[64:65], v[72:73]
	v_pk_add_f32 v[22:23], v[64:65], v[72:73] neg_lo:[0,1] neg_hi:[0,1]
	v_pk_add_f32 v[64:65], v[78:79], v[94:95]
	v_pk_mul_f32 v[78:79], v[8:9], s[60:61] op_sel:[1,0] op_sel_hi:[0,0] neg_hi:[1,0]
	v_pk_add_f32 v[88:89], v[70:71], v[16:17]
	v_pk_add_f32 v[16:17], v[70:71], v[16:17] neg_lo:[0,1] neg_hi:[0,1]
	v_pk_fma_f32 v[8:9], v[8:9], s[60:61], v[78:79] op_sel_hi:[1,0,1]
	s_waitcnt lgkmcnt(4)
	v_pk_add_f32 v[78:79], v[80:81], v[98:99]
	v_pk_add_f32 v[80:81], v[80:81], v[98:99] neg_lo:[0,1] neg_hi:[0,1]
	v_xor_b32_e32 v91, 0x80000000, v16
	v_mov_b32_e32 v90, v17
	v_pk_add_f32 v[16:17], v[62:63], v[84:85]
	v_pk_add_f32 v[18:19], v[62:63], v[84:85] neg_lo:[0,1] neg_hi:[0,1]
	v_pk_add_f32 v[62:63], v[6:7], v[92:93]
	v_pk_add_f32 v[6:7], v[6:7], v[92:93] neg_lo:[0,1] neg_hi:[0,1]
	v_pk_mul_f32 v[92:93], v[80:81], s[52:53] op_sel:[1,0] op_sel_hi:[0,0] neg_hi:[1,0]
	v_pk_add_f32 v[68:69], v[86:87], v[88:89]
	v_pk_fma_f32 v[80:81], v[80:81], s[54:55], v[92:93] op_sel_hi:[1,0,1]
	s_waitcnt lgkmcnt(3)
	v_pk_add_f32 v[92:93], v[10:11], v[100:101]
	v_pk_add_f32 v[10:11], v[10:11], v[100:101] neg_lo:[0,1] neg_hi:[0,1]
	v_pk_add_f32 v[70:71], v[86:87], v[88:89] neg_lo:[0,1] neg_hi:[0,1]
	v_xor_b32_e32 v95, 0x80000000, v10
	v_mov_b32_e32 v94, v11
	s_waitcnt lgkmcnt(2)
	v_pk_add_f32 v[10:11], v[4:5], v[102:103]
	v_pk_add_f32 v[4:5], v[4:5], v[102:103] neg_lo:[0,1] neg_hi:[0,1]
	v_pk_add_f32 v[84:85], v[108:109], v[112:113]
	v_pk_mul_f32 v[96:97], v[4:5], s[54:55] op_sel_hi:[1,0]
	s_nop 0
	v_pk_fma_f32 v[4:5], v[4:5], s[52:53], v[96:97] op_sel:[1,0,0] op_sel_hi:[0,0,1] neg_lo:[0,0,1] neg_hi:[1,0,1]
	s_waitcnt lgkmcnt(1)
	v_pk_add_f32 v[96:97], v[2:3], v[104:105]
	v_pk_add_f32 v[2:3], v[2:3], v[104:105] neg_lo:[0,1] neg_hi:[0,1]
	v_pk_add_f32 v[86:87], v[108:109], v[112:113] neg_lo:[0,1] neg_hi:[0,1]
	v_pk_mul_f32 v[98:99], v[2:3], s[60:61] op_sel_hi:[1,0]
	s_nop 0
	v_pk_fma_f32 v[2:3], v[2:3], s[60:61], v[98:99] op_sel:[1,0,0] op_sel_hi:[0,0,1] neg_lo:[0,0,1] neg_hi:[1,0,1]
	s_waitcnt lgkmcnt(0)
	v_pk_add_f32 v[98:99], v[82:83], v[106:107]
	v_pk_add_f32 v[82:83], v[82:83], v[106:107] neg_lo:[0,1] neg_hi:[0,1]
	v_pk_add_f32 v[72:73], v[74:75], v[90:91]
	v_pk_mul_f32 v[100:101], v[82:83], s[52:53] op_sel_hi:[1,0]
	v_xor_b32_e32 v103, 0x80000000, v82
	v_mov_b32_e32 v102, v83
	v_pk_fma_f32 v[82:83], v[102:103], s[54:55], v[100:101] op_sel_hi:[1,0,1] neg_lo:[0,0,1] neg_hi:[0,0,1]
	v_pk_add_f32 v[100:101], v[62:63], v[92:93]
	v_pk_add_f32 v[62:63], v[62:63], v[92:93] neg_lo:[0,1] neg_hi:[0,1]
	v_pk_add_f32 v[92:93], v[64:65], v[10:11]
	v_pk_add_f32 v[10:11], v[64:65], v[10:11] neg_lo:[0,1] neg_hi:[0,1]
	v_pk_add_f32 v[74:75], v[74:75], v[90:91] neg_lo:[0,1] neg_hi:[0,1]
	v_pk_mul_f32 v[64:65], v[10:11], s[60:61] op_sel:[1,0] op_sel_hi:[0,0] neg_hi:[1,0]
	v_pk_add_f32 v[88:89], v[110:111], v[114:115]
	v_pk_fma_f32 v[10:11], v[10:11], s[60:61], v[64:65] op_sel_hi:[1,0,1]
	v_pk_add_f32 v[64:65], v[76:77], v[96:97]
	v_pk_add_f32 v[76:77], v[76:77], v[96:97] neg_lo:[0,1] neg_hi:[0,1]
	v_pk_add_f32 v[90:91], v[110:111], v[114:115] neg_lo:[0,1] neg_hi:[0,1]
	v_xor_b32_e32 v97, 0x80000000, v76
	v_mov_b32_e32 v96, v77
	v_pk_add_f32 v[76:77], v[78:79], v[98:99]
	v_pk_add_f32 v[78:79], v[78:79], v[98:99] neg_lo:[0,1] neg_hi:[0,1]
	s_nop 0
	v_pk_mul_f32 v[98:99], v[78:79], s[60:61] op_sel_hi:[1,0]
	v_xor_b32_e32 v103, 0x80000000, v78
	v_mov_b32_e32 v102, v79
	v_pk_fma_f32 v[78:79], v[102:103], s[60:61], v[98:99] op_sel_hi:[1,0,1] neg_lo:[0,0,1] neg_hi:[0,0,1]
	v_pk_add_f32 v[98:99], v[6:7], v[94:95]
	v_pk_add_f32 v[6:7], v[6:7], v[94:95] neg_lo:[0,1] neg_hi:[0,1]
	v_pk_add_f32 v[94:95], v[66:67], v[4:5]
	v_pk_add_f32 v[4:5], v[66:67], v[4:5] neg_lo:[0,1] neg_hi:[0,1]
	s_nop 0
	v_pk_mul_f32 v[66:67], v[4:5], s[60:61] op_sel:[1,0] op_sel_hi:[0,0] neg_hi:[1,0]
	s_nop 0
	v_pk_fma_f32 v[4:5], v[4:5], s[60:61], v[66:67] op_sel_hi:[1,0,1]
	v_pk_add_f32 v[66:67], v[8:9], v[2:3]
	v_pk_add_f32 v[2:3], v[8:9], v[2:3] neg_lo:[0,1] neg_hi:[0,1]
	v_pk_add_f32 v[106:107], v[98:99], v[66:67] neg_lo:[0,1] neg_hi:[0,1]
	v_xor_b32_e32 v9, 0x80000000, v2
	v_mov_b32_e32 v8, v3
	v_pk_add_f32 v[2:3], v[80:81], v[82:83]
	v_pk_add_f32 v[80:81], v[80:81], v[82:83] neg_lo:[0,1] neg_hi:[0,1]
	v_pk_add_f32 v[108:109], v[94:95], v[2:3]
	v_pk_mul_f32 v[82:83], v[80:81], s[60:61] op_sel_hi:[1,0]
	s_nop 0
	v_pk_fma_f32 v[80:81], v[80:81], s[60:61], v[82:83] op_sel:[1,0,0] op_sel_hi:[0,0,1] neg_lo:[0,0,1] neg_hi:[1,0,1]
	v_pk_add_f32 v[82:83], v[100:101], v[64:65]
	v_pk_add_f32 v[64:65], v[100:101], v[64:65] neg_lo:[0,1] neg_hi:[0,1]
	v_pk_add_f32 v[100:101], v[92:93], v[76:77]
	v_pk_add_f32 v[76:77], v[92:93], v[76:77] neg_lo:[0,1] neg_hi:[0,1]
	v_pk_add_f32 v[102:103], v[10:11], v[78:79]
	v_xor_b32_e32 v93, 0x80000000, v76
	v_mov_b32_e32 v92, v77
	v_pk_add_f32 v[76:77], v[62:63], v[96:97]
	v_pk_add_f32 v[10:11], v[10:11], v[78:79] neg_lo:[0,1] neg_hi:[0,1]
	v_pk_add_f32 v[2:3], v[94:95], v[2:3] neg_lo:[0,1] neg_hi:[0,1]
	v_pk_add_f32 v[62:63], v[62:63], v[96:97] neg_lo:[0,1] neg_hi:[0,1]
	v_xor_b32_e32 v105, 0x80000000, v10
	v_mov_b32_e32 v104, v11
	v_pk_add_f32 v[10:11], v[98:99], v[66:67]
	v_xor_b32_e32 v111, 0x80000000, v2
	v_mov_b32_e32 v110, v3
	v_pk_add_f32 v[112:113], v[6:7], v[8:9]
	v_pk_add_f32 v[114:115], v[6:7], v[8:9] neg_lo:[0,1] neg_hi:[0,1]
	v_pk_add_f32 v[6:7], v[4:5], v[80:81]
	v_pk_add_f32 v[2:3], v[4:5], v[80:81] neg_lo:[0,1] neg_hi:[0,1]
	v_pk_add_f32 v[98:99], v[82:83], v[100:101]
	v_pk_add_f32 v[96:97], v[82:83], v[100:101] neg_lo:[0,1] neg_hi:[0,1]
	v_pk_add_f32 v[82:83], v[76:77], v[102:103]
	v_pk_add_f32 v[80:81], v[76:77], v[102:103] neg_lo:[0,1] neg_hi:[0,1]
	s_waitcnt vmcnt(7)
	v_mov_b64 v[100:101], v[164:165]
	v_mov_b64 v[102:103], v[166:167]
	v_pk_add_f32 v[78:79], v[62:63], v[104:105]
	v_pk_add_f32 v[76:77], v[62:63], v[104:105] neg_lo:[0,1] neg_hi:[0,1]
	v_xor_b32_e32 v5, 0x80000000, v2
	v_mov_b32_e32 v4, v3
	v_pk_add_f32 v[62:63], v[106:107], v[110:111]
	v_pk_add_f32 v[2:3], v[106:107], v[110:111] neg_lo:[0,1] neg_hi:[0,1]
	v_pk_add_f32 v[94:95], v[64:65], v[92:93]
	v_pk_add_f32 v[92:93], v[64:65], v[92:93] neg_lo:[0,1] neg_hi:[0,1]
	v_pk_add_f32 v[66:67], v[10:11], v[108:109]
	v_pk_add_f32 v[64:65], v[10:11], v[108:109] neg_lo:[0,1] neg_hi:[0,1]
	v_pk_add_f32 v[10:11], v[112:113], v[6:7]
	v_pk_add_f32 v[8:9], v[112:113], v[6:7] neg_lo:[0,1] neg_hi:[0,1]
	v_pk_add_f32 v[6:7], v[114:115], v[4:5]
	v_pk_add_f32 v[4:5], v[114:115], v[4:5] neg_lo:[0,1] neg_hi:[0,1]
	v_cvt_f32_f16_e32 v104, v100
	v_cvt_f32_f16_sdwa v100, v100 dst_sel:DWORD dst_unused:UNUSED_PAD src0_sel:WORD_1
	v_mul_f32_e32 v104, 0x38800000, v104
	v_mul_f32_e32 v100, 0x38800000, v100
	s_nop 0
	v_pk_mul_f32 v[106:107], v[12:13], v[100:101] op_sel:[1,0] op_sel_hi:[0,0] neg_lo:[1,0]
	v_cvt_f32_f16_e32 v100, v101
	v_cvt_f32_f16_sdwa v101, v101 dst_sel:DWORD dst_unused:UNUSED_PAD src0_sel:WORD_1
	v_pk_fma_f32 v[12:13], v[12:13], v[104:105], v[106:107] op_sel_hi:[1,0,1]
	v_xor_b32_e32 v106, 0x80000000, v15
	v_mov_b32_e32 v107, v14
	v_mul_f32_e32 v104, 0x38800000, v101
	v_mul_f32_e32 v100, 0x38800000, v100
	v_pk_mul_f32 v[104:105], v[106:107], v[104:105] op_sel_hi:[1,0]
	v_xor_b32_e32 v106, 0x80000000, v21
	v_pk_fma_f32 v[14:15], v[14:15], v[100:101], v[104:105] op_sel_hi:[1,0,1]
	v_cvt_f32_f16_sdwa v101, v102 dst_sel:DWORD dst_unused:UNUSED_PAD src0_sel:WORD_1
	v_cvt_f32_f16_e32 v100, v102
	s_nop 0
	s_nop 0
	v_mul_f32_e32 v102, 0x38800000, v101
	v_mul_f32_e32 v100, 0x38800000, v100
	v_pk_mul_f32 v[104:105], v[16:17], v[102:103] op_sel:[1,0] op_sel_hi:[0,0] neg_lo:[1,0]
	v_mov_b32_e32 v107, v20
	v_pk_fma_f32 v[16:17], v[16:17], v[100:101], v[104:105] op_sel_hi:[1,0,1]
	v_cvt_f32_f16_sdwa v101, v103 dst_sel:DWORD dst_unused:UNUSED_PAD src0_sel:WORD_1
	v_cvt_f32_f16_e32 v100, v103
	v_xor_b32_e32 v104, 0x80000000, v19
	v_mov_b32_e32 v105, v18
	v_mul_f32_e32 v102, 0x38800000, v101
	v_mul_f32_e32 v100, 0x38800000, v100
	v_pk_mul_f32 v[102:103], v[104:105], v[102:103] op_sel_hi:[1,0]
	s_nop 0
	v_pk_fma_f32 v[18:19], v[18:19], v[100:101], v[102:103] op_sel_hi:[1,0,1]
	s_waitcnt vmcnt(6)
	v_mov_b64 v[100:101], v[168:169]
	v_mov_b64 v[102:103], v[170:171]
	v_cvt_f32_f16_e32 v104, v100
	v_cvt_f32_f16_sdwa v100, v100 dst_sel:DWORD dst_unused:UNUSED_PAD src0_sel:WORD_1
	v_mul_f32_e32 v104, 0x38800000, v104
	v_mul_f32_e32 v100, 0x38800000, v100
	v_pk_mul_f32 v[106:107], v[106:107], v[100:101] op_sel_hi:[1,0]
	v_cvt_f32_f16_e32 v100, v101
	v_cvt_f32_f16_sdwa v101, v101 dst_sel:DWORD dst_unused:UNUSED_PAD src0_sel:WORD_1
	v_pk_fma_f32 v[20:21], v[20:21], v[104:105], v[106:107] op_sel_hi:[1,0,1]
	v_xor_b32_e32 v106, 0x80000000, v23
	v_mov_b32_e32 v107, v22
	v_mul_f32_e32 v104, 0x38800000, v101
	v_mul_f32_e32 v100, 0x38800000, v100
	v_pk_mul_f32 v[104:105], v[106:107], v[104:105] op_sel_hi:[1,0]
	v_xor_b32_e32 v106, 0x80000000, v69
	v_pk_fma_f32 v[22:23], v[22:23], v[100:101], v[104:105] op_sel_hi:[1,0,1]
	v_cvt_f32_f16_sdwa v101, v102 dst_sel:DWORD dst_unused:UNUSED_PAD src0_sel:WORD_1
	v_cvt_f32_f16_e32 v100, v102
	s_nop 0
	s_nop 0
	v_mul_f32_e32 v102, 0x38800000, v101
	v_mul_f32_e32 v100, 0x38800000, v100
	v_pk_mul_f32 v[104:105], v[24:25], v[102:103] op_sel:[1,0] op_sel_hi:[0,0] neg_lo:[1,0]
	v_mov_b32_e32 v107, v68
	v_pk_fma_f32 v[24:25], v[24:25], v[100:101], v[104:105] op_sel_hi:[1,0,1]
	v_cvt_f32_f16_sdwa v101, v103 dst_sel:DWORD dst_unused:UNUSED_PAD src0_sel:WORD_1
	v_cvt_f32_f16_e32 v100, v103
	v_xor_b32_e32 v104, 0x80000000, v27
	v_mov_b32_e32 v105, v26
	v_mul_f32_e32 v102, 0x38800000, v101
	v_mul_f32_e32 v100, 0x38800000, v100
	v_pk_mul_f32 v[102:103], v[104:105], v[102:103] op_sel_hi:[1,0]
	s_nop 0
	v_pk_fma_f32 v[26:27], v[26:27], v[100:101], v[102:103] op_sel_hi:[1,0,1]
	s_waitcnt vmcnt(5)
	v_mov_b64 v[100:101], v[172:173]
	v_mov_b64 v[102:103], v[174:175]
	v_cvt_f32_f16_e32 v104, v100
	v_cvt_f32_f16_sdwa v100, v100 dst_sel:DWORD dst_unused:UNUSED_PAD src0_sel:WORD_1
	v_mul_f32_e32 v104, 0x38800000, v104
	v_mul_f32_e32 v100, 0x38800000, v100
	v_pk_mul_f32 v[106:107], v[106:107], v[100:101] op_sel_hi:[1,0]
	v_cvt_f32_f16_e32 v100, v101
	v_cvt_f32_f16_sdwa v101, v101 dst_sel:DWORD dst_unused:UNUSED_PAD src0_sel:WORD_1
	v_pk_fma_f32 v[68:69], v[68:69], v[104:105], v[106:107] op_sel_hi:[1,0,1]
	v_xor_b32_e32 v106, 0x80000000, v71
	v_mov_b32_e32 v107, v70
	v_mul_f32_e32 v104, 0x38800000, v101
	v_mul_f32_e32 v100, 0x38800000, v100
	v_pk_mul_f32 v[104:105], v[106:107], v[104:105] op_sel_hi:[1,0]
	v_xor_b32_e32 v106, 0x80000000, v85
	v_pk_fma_f32 v[70:71], v[70:71], v[100:101], v[104:105] op_sel_hi:[1,0,1]
	v_cvt_f32_f16_sdwa v101, v102 dst_sel:DWORD dst_unused:UNUSED_PAD src0_sel:WORD_1
	v_cvt_f32_f16_e32 v100, v102
	s_nop 0
	s_nop 0
	v_mul_f32_e32 v102, 0x38800000, v101
	v_mul_f32_e32 v100, 0x38800000, v100
	v_pk_mul_f32 v[104:105], v[72:73], v[102:103] op_sel:[1,0] op_sel_hi:[0,0] neg_lo:[1,0]
	v_mov_b32_e32 v107, v84
	v_pk_fma_f32 v[72:73], v[72:73], v[100:101], v[104:105] op_sel_hi:[1,0,1]
	v_cvt_f32_f16_sdwa v101, v103 dst_sel:DWORD dst_unused:UNUSED_PAD src0_sel:WORD_1
	v_cvt_f32_f16_e32 v100, v103
	v_xor_b32_e32 v104, 0x80000000, v75
	v_mov_b32_e32 v105, v74
	v_mul_f32_e32 v102, 0x38800000, v101
	v_mul_f32_e32 v100, 0x38800000, v100
	v_pk_mul_f32 v[102:103], v[104:105], v[102:103] op_sel_hi:[1,0]
	s_nop 0
	v_pk_fma_f32 v[74:75], v[74:75], v[100:101], v[102:103] op_sel_hi:[1,0,1]
	s_waitcnt vmcnt(4)
	v_mov_b64 v[100:101], v[176:177]
	v_mov_b64 v[102:103], v[178:179]
	v_cvt_f32_f16_e32 v104, v100
	v_cvt_f32_f16_sdwa v100, v100 dst_sel:DWORD dst_unused:UNUSED_PAD src0_sel:WORD_1
	v_mul_f32_e32 v104, 0x38800000, v104
	v_mul_f32_e32 v100, 0x38800000, v100
	v_pk_mul_f32 v[106:107], v[106:107], v[100:101] op_sel_hi:[1,0]
	v_cvt_f32_f16_e32 v100, v101
	v_cvt_f32_f16_sdwa v101, v101 dst_sel:DWORD dst_unused:UNUSED_PAD src0_sel:WORD_1
	v_pk_fma_f32 v[84:85], v[84:85], v[104:105], v[106:107] op_sel_hi:[1,0,1]
	v_xor_b32_e32 v106, 0x80000000, v87
	v_mov_b32_e32 v107, v86
	v_mul_f32_e32 v104, 0x38800000, v101
	v_mul_f32_e32 v100, 0x38800000, v100
	v_pk_mul_f32 v[104:105], v[106:107], v[104:105] op_sel_hi:[1,0]
	v_xor_b32_e32 v106, 0x80000000, v99
	v_pk_fma_f32 v[86:87], v[86:87], v[100:101], v[104:105] op_sel_hi:[1,0,1]
	v_cvt_f32_f16_sdwa v101, v102 dst_sel:DWORD dst_unused:UNUSED_PAD src0_sel:WORD_1
	v_cvt_f32_f16_e32 v100, v102
	s_nop 0
	s_nop 0
	v_mul_f32_e32 v102, 0x38800000, v101
	v_mul_f32_e32 v100, 0x38800000, v100
	v_pk_mul_f32 v[104:105], v[88:89], v[102:103] op_sel:[1,0] op_sel_hi:[0,0] neg_lo:[1,0]
	v_mov_b32_e32 v107, v98
	v_pk_fma_f32 v[88:89], v[88:89], v[100:101], v[104:105] op_sel_hi:[1,0,1]
	v_cvt_f32_f16_sdwa v101, v103 dst_sel:DWORD dst_unused:UNUSED_PAD src0_sel:WORD_1
	v_cvt_f32_f16_e32 v100, v103
	v_xor_b32_e32 v104, 0x80000000, v91
	v_mov_b32_e32 v105, v90
	v_mul_f32_e32 v102, 0x38800000, v101
	v_mul_f32_e32 v100, 0x38800000, v100
	v_pk_mul_f32 v[102:103], v[104:105], v[102:103] op_sel_hi:[1,0]
	s_nop 0
	v_pk_fma_f32 v[90:91], v[90:91], v[100:101], v[102:103] op_sel_hi:[1,0,1]
	s_waitcnt vmcnt(3)
	v_mov_b64 v[100:101], v[180:181]
	v_mov_b64 v[102:103], v[182:183]
	v_cvt_f32_f16_e32 v104, v100
	v_cvt_f32_f16_sdwa v100, v100 dst_sel:DWORD dst_unused:UNUSED_PAD src0_sel:WORD_1
	v_mul_f32_e32 v104, 0x38800000, v104
	v_mul_f32_e32 v100, 0x38800000, v100
	v_pk_mul_f32 v[106:107], v[106:107], v[100:101] op_sel_hi:[1,0]
	v_cvt_f32_f16_e32 v100, v101
	v_cvt_f32_f16_sdwa v101, v101 dst_sel:DWORD dst_unused:UNUSED_PAD src0_sel:WORD_1
	v_pk_fma_f32 v[98:99], v[98:99], v[104:105], v[106:107] op_sel_hi:[1,0,1]
	v_xor_b32_e32 v106, 0x80000000, v97
	v_mov_b32_e32 v107, v96
	v_mul_f32_e32 v104, 0x38800000, v101
	v_mul_f32_e32 v100, 0x38800000, v100
	v_pk_mul_f32 v[104:105], v[106:107], v[104:105] op_sel_hi:[1,0]
	v_xor_b32_e32 v106, 0x80000000, v83
	v_pk_fma_f32 v[96:97], v[96:97], v[100:101], v[104:105] op_sel_hi:[1,0,1]
	v_cvt_f32_f16_sdwa v101, v102 dst_sel:DWORD dst_unused:UNUSED_PAD src0_sel:WORD_1
	v_cvt_f32_f16_e32 v100, v102
	s_nop 0
	s_nop 0
	v_mul_f32_e32 v102, 0x38800000, v101
	v_mul_f32_e32 v100, 0x38800000, v100
	v_pk_mul_f32 v[104:105], v[94:95], v[102:103] op_sel:[1,0] op_sel_hi:[0,0] neg_lo:[1,0]
	v_mov_b32_e32 v107, v82
	v_pk_fma_f32 v[94:95], v[94:95], v[100:101], v[104:105] op_sel_hi:[1,0,1]
	v_cvt_f32_f16_sdwa v101, v103 dst_sel:DWORD dst_unused:UNUSED_PAD src0_sel:WORD_1
	v_cvt_f32_f16_e32 v100, v103
	v_xor_b32_e32 v104, 0x80000000, v93
	v_mov_b32_e32 v105, v92
	v_mul_f32_e32 v102, 0x38800000, v101
	v_mul_f32_e32 v100, 0x38800000, v100
	v_pk_mul_f32 v[102:103], v[104:105], v[102:103] op_sel_hi:[1,0]
	s_nop 0
	v_pk_fma_f32 v[92:93], v[92:93], v[100:101], v[102:103] op_sel_hi:[1,0,1]
	s_waitcnt vmcnt(2)
	v_mov_b64 v[100:101], v[184:185]
	v_mov_b64 v[102:103], v[186:187]
	v_cvt_f32_f16_e32 v104, v100
	v_cvt_f32_f16_sdwa v100, v100 dst_sel:DWORD dst_unused:UNUSED_PAD src0_sel:WORD_1
	v_mul_f32_e32 v104, 0x38800000, v104
	v_mul_f32_e32 v100, 0x38800000, v100
	v_pk_mul_f32 v[106:107], v[106:107], v[100:101] op_sel_hi:[1,0]
	v_cvt_f32_f16_e32 v100, v101
	v_cvt_f32_f16_sdwa v101, v101 dst_sel:DWORD dst_unused:UNUSED_PAD src0_sel:WORD_1
	v_pk_fma_f32 v[82:83], v[82:83], v[104:105], v[106:107] op_sel_hi:[1,0,1]
	v_xor_b32_e32 v106, 0x80000000, v81
	v_mov_b32_e32 v107, v80
	v_mul_f32_e32 v104, 0x38800000, v101
	v_mul_f32_e32 v100, 0x38800000, v100
	v_pk_mul_f32 v[104:105], v[106:107], v[104:105] op_sel_hi:[1,0]
	v_xor_b32_e32 v106, 0x80000000, v67
	v_pk_fma_f32 v[80:81], v[80:81], v[100:101], v[104:105] op_sel_hi:[1,0,1]
	v_cvt_f32_f16_sdwa v101, v102 dst_sel:DWORD dst_unused:UNUSED_PAD src0_sel:WORD_1
	v_cvt_f32_f16_e32 v100, v102
	s_nop 0
	s_nop 0
	v_mul_f32_e32 v102, 0x38800000, v101
	v_mul_f32_e32 v100, 0x38800000, v100
	v_pk_mul_f32 v[104:105], v[78:79], v[102:103] op_sel:[1,0] op_sel_hi:[0,0] neg_lo:[1,0]
	v_mov_b32_e32 v107, v66
	v_pk_fma_f32 v[78:79], v[78:79], v[100:101], v[104:105] op_sel_hi:[1,0,1]
	v_cvt_f32_f16_sdwa v101, v103 dst_sel:DWORD dst_unused:UNUSED_PAD src0_sel:WORD_1
	v_cvt_f32_f16_e32 v100, v103
	v_xor_b32_e32 v104, 0x80000000, v77
	v_mov_b32_e32 v105, v76
	v_mul_f32_e32 v102, 0x38800000, v101
	v_mul_f32_e32 v100, 0x38800000, v100
	v_pk_mul_f32 v[102:103], v[104:105], v[102:103] op_sel_hi:[1,0]
	s_nop 0
	v_pk_fma_f32 v[76:77], v[76:77], v[100:101], v[102:103] op_sel_hi:[1,0,1]
	s_waitcnt vmcnt(1)
	v_mov_b64 v[100:101], v[188:189]
	v_mov_b64 v[102:103], v[190:191]
	v_cvt_f32_f16_e32 v104, v100
	v_cvt_f32_f16_sdwa v100, v100 dst_sel:DWORD dst_unused:UNUSED_PAD src0_sel:WORD_1
	v_mul_f32_e32 v104, 0x38800000, v104
	v_mul_f32_e32 v100, 0x38800000, v100
	v_pk_mul_f32 v[106:107], v[106:107], v[100:101] op_sel_hi:[1,0]
	v_cvt_f32_f16_e32 v100, v101
	v_cvt_f32_f16_sdwa v101, v101 dst_sel:DWORD dst_unused:UNUSED_PAD src0_sel:WORD_1
	v_pk_fma_f32 v[66:67], v[66:67], v[104:105], v[106:107] op_sel_hi:[1,0,1]
	v_xor_b32_e32 v106, 0x80000000, v65
	v_mov_b32_e32 v107, v64
	v_mul_f32_e32 v104, 0x38800000, v101
	v_mul_f32_e32 v100, 0x38800000, v100
	v_pk_mul_f32 v[104:105], v[106:107], v[104:105] op_sel_hi:[1,0]
	s_nop 0
	v_pk_fma_f32 v[64:65], v[64:65], v[100:101], v[104:105] op_sel_hi:[1,0,1]
	v_cvt_f32_f16_sdwa v101, v102 dst_sel:DWORD dst_unused:UNUSED_PAD src0_sel:WORD_1
	v_cvt_f32_f16_e32 v100, v102
	s_nop 0
	s_nop 0
	v_mul_f32_e32 v102, 0x38800000, v101
	v_mul_f32_e32 v100, 0x38800000, v100
	v_pk_mul_f32 v[104:105], v[62:63], v[102:103] op_sel:[1,0] op_sel_hi:[0,0] neg_lo:[1,0]
	s_nop 0
	v_pk_fma_f32 v[62:63], v[62:63], v[100:101], v[104:105] op_sel_hi:[1,0,1]
	v_cvt_f32_f16_sdwa v101, v103 dst_sel:DWORD dst_unused:UNUSED_PAD src0_sel:WORD_1
	v_cvt_f32_f16_e32 v100, v103
	v_xor_b32_e32 v104, 0x80000000, v3
	v_mov_b32_e32 v105, v2
	v_mul_f32_e32 v102, 0x38800000, v101
	v_mul_f32_e32 v100, 0x38800000, v100
	v_pk_mul_f32 v[102:103], v[104:105], v[102:103] op_sel_hi:[1,0]
	v_xor_b32_e32 v104, 0x80000000, v11
	v_pk_fma_f32 v[100:101], v[2:3], v[100:101], v[102:103] op_sel_hi:[1,0,1]
	s_waitcnt vmcnt(0)
	v_mov_b64 v[0:1], v[192:193]
	v_mov_b64 v[2:3], v[194:195]
	v_mov_b32_e32 v105, v10
	v_cvt_f32_f16_e32 v102, v0
	v_cvt_f32_f16_sdwa v0, v0 dst_sel:DWORD dst_unused:UNUSED_PAD src0_sel:WORD_1
	v_mul_f32_e32 v102, 0x38800000, v102
	v_mul_f32_e32 v0, 0x38800000, v0
	v_pk_mul_f32 v[104:105], v[104:105], v[0:1] op_sel_hi:[1,0]
	v_cvt_f32_f16_e32 v0, v1
	v_cvt_f32_f16_sdwa v1, v1 dst_sel:DWORD dst_unused:UNUSED_PAD src0_sel:WORD_1
	v_pk_fma_f32 v[10:11], v[10:11], v[102:103], v[104:105] op_sel_hi:[1,0,1]
	v_xor_b32_e32 v104, 0x80000000, v9
	v_mov_b32_e32 v105, v8
	v_mul_f32_e32 v102, 0x38800000, v1
	v_mul_f32_e32 v0, 0x38800000, v0
	v_pk_mul_f32 v[102:103], v[104:105], v[102:103] op_sel_hi:[1,0]
	s_nop 0
	v_pk_fma_f32 v[0:1], v[8:9], v[0:1], v[102:103] op_sel_hi:[1,0,1]
	v_cvt_f32_f16_e32 v8, v2
	v_cvt_f32_f16_sdwa v2, v2 dst_sel:DWORD dst_unused:UNUSED_PAD src0_sel:WORD_1
	s_nop 0
	s_nop 0
	v_mul_f32_e32 v8, 0x38800000, v8
	v_mul_f32_e32 v2, 0x38800000, v2
	s_nop 0
	v_pk_mul_f32 v[102:103], v[6:7], v[2:3] op_sel:[1,0] op_sel_hi:[0,0] neg_lo:[1,0]
	v_cvt_f32_f16_e32 v2, v3
	v_cvt_f32_f16_sdwa v3, v3 dst_sel:DWORD dst_unused:UNUSED_PAD src0_sel:WORD_1
	v_pk_fma_f32 v[6:7], v[6:7], v[8:9], v[102:103] op_sel_hi:[1,0,1]
	v_xor_b32_e32 v102, 0x80000000, v5
	v_mov_b32_e32 v103, v4
	v_mul_f32_e32 v8, 0x38800000, v3
	v_mul_f32_e32 v2, 0x38800000, v2
	v_pk_mul_f32 v[8:9], v[102:103], v[8:9] op_sel_hi:[1,0]
	v_mov_b32_e32 v102, v146
	v_pk_fma_f32 v[2:3], v[4:5], v[2:3], v[8:9] op_sel_hi:[1,0,1]
	v_pk_add_f32 v[4:5], v[12:13], v[14:15]
	v_pk_add_f32 v[8:9], v[12:13], v[14:15] neg_lo:[0,1] neg_hi:[0,1]
	v_pk_add_f32 v[12:13], v[16:17], v[18:19]
	v_pk_add_f32 v[14:15], v[16:17], v[18:19] neg_lo:[0,1] neg_hi:[0,1]
	v_pk_add_f32 v[16:17], v[20:21], v[22:23]
	v_pk_add_f32 v[18:19], v[20:21], v[22:23] neg_lo:[0,1] neg_hi:[0,1]
	v_pk_add_f32 v[20:21], v[24:25], v[26:27]
	v_pk_add_f32 v[22:23], v[24:25], v[26:27] neg_lo:[0,1] neg_hi:[0,1]
	v_pk_add_f32 v[24:25], v[68:69], v[70:71]
	v_pk_add_f32 v[26:27], v[68:69], v[70:71] neg_lo:[0,1] neg_hi:[0,1]
	v_pk_add_f32 v[68:69], v[72:73], v[74:75]
	v_pk_add_f32 v[70:71], v[72:73], v[74:75] neg_lo:[0,1] neg_hi:[0,1]
	v_pk_add_f32 v[72:73], v[84:85], v[86:87]
	v_pk_add_f32 v[74:75], v[84:85], v[86:87] neg_lo:[0,1] neg_hi:[0,1]
	v_pk_add_f32 v[84:85], v[88:89], v[90:91]
	v_pk_add_f32 v[86:87], v[88:89], v[90:91] neg_lo:[0,1] neg_hi:[0,1]
	v_pk_add_f32 v[88:89], v[4:5], v[12:13]
	v_pk_add_f32 v[4:5], v[4:5], v[12:13] neg_lo:[0,1] neg_hi:[0,1]
	v_xor_b32_e32 v12, 0x80000000, v15
	v_mov_b32_e32 v13, v14
	v_pk_add_f32 v[14:15], v[8:9], v[12:13]
	v_pk_add_f32 v[8:9], v[8:9], v[12:13] neg_lo:[0,1] neg_hi:[0,1]
	v_pk_add_f32 v[12:13], v[16:17], v[20:21]
	v_pk_add_f32 v[16:17], v[16:17], v[20:21] neg_lo:[0,1] neg_hi:[0,1]
	v_xor_b32_e32 v20, 0x80000000, v23
	v_mov_b32_e32 v21, v22
	v_pk_add_f32 v[22:23], v[18:19], v[20:21]
	v_pk_add_f32 v[18:19], v[18:19], v[20:21] neg_lo:[0,1] neg_hi:[0,1]
	v_pk_add_f32 v[20:21], v[24:25], v[68:69]
	v_pk_add_f32 v[24:25], v[24:25], v[68:69] neg_lo:[0,1] neg_hi:[0,1]
	v_xor_b32_e32 v68, 0x80000000, v71
	v_mov_b32_e32 v69, v70
	v_pk_add_f32 v[70:71], v[26:27], v[68:69]
	v_pk_add_f32 v[26:27], v[26:27], v[68:69] neg_lo:[0,1] neg_hi:[0,1]
	v_pk_add_f32 v[68:69], v[72:73], v[84:85]
	v_pk_add_f32 v[72:73], v[72:73], v[84:85] neg_lo:[0,1] neg_hi:[0,1]
	v_xor_b32_e32 v84, 0x80000000, v87
	v_mov_b32_e32 v85, v86
	v_pk_add_f32 v[86:87], v[74:75], v[84:85]
	v_pk_add_f32 v[74:75], v[74:75], v[84:85] neg_lo:[0,1] neg_hi:[0,1]
	v_pk_add_f32 v[84:85], v[88:89], v[12:13]
	v_pk_add_f32 v[12:13], v[88:89], v[12:13] neg_lo:[0,1] neg_hi:[0,1]
	v_pk_mul_f32 v[88:89], v[22:23], s[60:61] op_sel:[1,0] op_sel_hi:[0,0] neg_lo:[1,0]
	v_xor_b32_e32 v90, 0x80000000, v19
	v_pk_fma_f32 v[22:23], v[22:23], s[60:61], v[88:89] op_sel_hi:[1,0,1]
	v_mov_b32_e32 v91, v18
	v_pk_add_f32 v[88:89], v[14:15], v[22:23]
	v_pk_add_f32 v[14:15], v[14:15], v[22:23] neg_lo:[0,1] neg_hi:[0,1]
	v_xor_b32_e32 v22, 0x80000000, v17
	v_mov_b32_e32 v23, v16
	v_pk_add_f32 v[16:17], v[4:5], v[22:23]
	v_pk_add_f32 v[4:5], v[4:5], v[22:23] neg_lo:[0,1] neg_hi:[0,1]
	v_pk_mul_f32 v[22:23], v[18:19], s[60:61] op_sel_hi:[1,0]
	s_nop 0
	v_pk_fma_f32 v[18:19], v[90:91], s[60:61], v[22:23] op_sel_hi:[1,0,1] neg_lo:[0,0,1] neg_hi:[0,0,1]
	v_xor_b32_e32 v90, 0x80000000, v75
	v_pk_add_f32 v[22:23], v[8:9], v[18:19]
	v_pk_add_f32 v[8:9], v[8:9], v[18:19] neg_lo:[0,1] neg_hi:[0,1]
	v_pk_add_f32 v[18:19], v[20:21], v[68:69]
	v_pk_add_f32 v[20:21], v[20:21], v[68:69] neg_lo:[0,1] neg_hi:[0,1]
	v_pk_mul_f32 v[68:69], v[86:87], s[60:61] op_sel:[1,0] op_sel_hi:[0,0] neg_lo:[1,0]
	v_mov_b32_e32 v91, v74
	v_pk_fma_f32 v[68:69], v[86:87], s[60:61], v[68:69] op_sel_hi:[1,0,1]
	s_nop 0
	v_pk_add_f32 v[86:87], v[70:71], v[68:69]
	v_pk_add_f32 v[68:69], v[70:71], v[68:69] neg_lo:[0,1] neg_hi:[0,1]
	v_xor_b32_e32 v70, 0x80000000, v73
	v_mov_b32_e32 v71, v72
	v_pk_add_f32 v[72:73], v[24:25], v[70:71]
	v_pk_add_f32 v[24:25], v[24:25], v[70:71] neg_lo:[0,1] neg_hi:[0,1]
	v_pk_mul_f32 v[70:71], v[74:75], s[60:61] op_sel_hi:[1,0]
	s_nop 0
	v_pk_fma_f32 v[70:71], v[90:91], s[60:61], v[70:71] op_sel_hi:[1,0,1] neg_lo:[0,0,1] neg_hi:[0,0,1]
	v_xor_b32_e32 v90, 0x80000000, v69
	v_pk_add_f32 v[74:75], v[26:27], v[70:71]
	v_pk_add_f32 v[26:27], v[26:27], v[70:71] neg_lo:[0,1] neg_hi:[0,1]
	v_pk_add_f32 v[70:71], v[84:85], v[18:19]
	v_pk_add_f32 v[18:19], v[84:85], v[18:19] neg_lo:[0,1] neg_hi:[0,1]
	v_pk_mul_f32 v[84:85], v[86:87], s[54:55] op_sel:[1,0] op_sel_hi:[0,0] neg_lo:[1,0]
	v_mov_b32_e32 v91, v68
	v_pk_fma_f32 v[84:85], v[86:87], s[52:53], v[84:85] op_sel_hi:[1,0,1]
	s_nop 0
	v_pk_add_f32 v[86:87], v[88:89], v[84:85]
	v_pk_add_f32 v[84:85], v[88:89], v[84:85] neg_lo:[0,1] neg_hi:[0,1]
	v_pk_mul_f32 v[88:89], v[72:73], s[60:61] op_sel:[1,0] op_sel_hi:[0,0] neg_lo:[1,0]
	s_nop 0
	v_pk_fma_f32 v[72:73], v[72:73], s[60:61], v[88:89] op_sel_hi:[1,0,1]
	s_nop 0
	v_pk_add_f32 v[88:89], v[16:17], v[72:73]
	v_pk_add_f32 v[16:17], v[16:17], v[72:73] neg_lo:[0,1] neg_hi:[0,1]
	v_pk_mul_f32 v[72:73], v[74:75], s[52:53] op_sel:[1,0] op_sel_hi:[0,0] neg_lo:[1,0]
	s_nop 0
	v_pk_fma_f32 v[72:73], v[74:75], s[54:55], v[72:73] op_sel_hi:[1,0,1]
	s_nop 0
	v_pk_add_f32 v[74:75], v[22:23], v[72:73]
	v_pk_add_f32 v[22:23], v[22:23], v[72:73] neg_lo:[0,1] neg_hi:[0,1]
	v_xor_b32_e32 v72, 0x80000000, v21
	v_mov_b32_e32 v73, v20
	v_pk_add_f32 v[20:21], v[12:13], v[72:73]
	v_pk_add_f32 v[12:13], v[12:13], v[72:73] neg_lo:[0,1] neg_hi:[0,1]
	v_pk_mul_f32 v[72:73], v[68:69], s[54:55] op_sel_hi:[1,0]
	s_nop 0
	v_pk_fma_f32 v[68:69], v[90:91], s[52:53], v[72:73] op_sel_hi:[1,0,1] neg_lo:[0,0,1] neg_hi:[0,0,1]
	v_xor_b32_e32 v90, 0x80000000, v25
	v_pk_add_f32 v[72:73], v[14:15], v[68:69]
	v_pk_add_f32 v[14:15], v[14:15], v[68:69] neg_lo:[0,1] neg_hi:[0,1]
	v_pk_mul_f32 v[68:69], v[24:25], s[60:61] op_sel_hi:[1,0]
	v_mov_b32_e32 v91, v24
	v_pk_fma_f32 v[24:25], v[90:91], s[60:61], v[68:69] op_sel_hi:[1,0,1] neg_lo:[0,0,1] neg_hi:[0,0,1]
	s_nop 0
	v_pk_add_f32 v[68:69], v[4:5], v[24:25]
	v_pk_add_f32 v[4:5], v[4:5], v[24:25] neg_lo:[0,1] neg_hi:[0,1]
	v_pk_mul_f32 v[24:25], v[26:27], s[52:53] op_sel_hi:[1,0]
	s_nop 0
	v_pk_fma_f32 v[24:25], v[26:27], s[54:55], v[24:25] op_sel:[1,0,0] op_sel_hi:[0,0,1] neg_lo:[1,0,1] neg_hi:[0,0,1]
	v_pk_add_f32 v[90:91], v[98:99], v[96:97] neg_lo:[0,1] neg_hi:[0,1]
	v_pk_add_f32 v[26:27], v[8:9], v[24:25]
	v_pk_add_f32 v[8:9], v[8:9], v[24:25] neg_lo:[0,1] neg_hi:[0,1]
	v_pk_add_f32 v[24:25], v[98:99], v[96:97]
	v_pk_add_f32 v[96:97], v[94:95], v[92:93]
	v_pk_add_f32 v[92:93], v[94:95], v[92:93] neg_lo:[0,1] neg_hi:[0,1]
	v_pk_add_f32 v[94:95], v[82:83], v[80:81]
	v_pk_add_f32 v[80:81], v[82:83], v[80:81] neg_lo:[0,1] neg_hi:[0,1]
	v_pk_add_f32 v[82:83], v[78:79], v[76:77]
	v_pk_add_f32 v[76:77], v[78:79], v[76:77] neg_lo:[0,1] neg_hi:[0,1]
	v_pk_add_f32 v[98:99], v[10:11], v[0:1]
	v_pk_add_f32 v[0:1], v[10:11], v[0:1] neg_lo:[0,1] neg_hi:[0,1]
	v_pk_add_f32 v[10:11], v[6:7], v[2:3]
	v_pk_add_f32 v[2:3], v[6:7], v[2:3] neg_lo:[0,1] neg_hi:[0,1]
	v_pk_add_f32 v[6:7], v[24:25], v[96:97]
	v_pk_add_f32 v[24:25], v[24:25], v[96:97] neg_lo:[0,1] neg_hi:[0,1]
	v_xor_b32_e32 v96, 0x80000000, v93
	v_mov_b32_e32 v97, v92
	v_pk_add_f32 v[78:79], v[66:67], v[64:65]
	v_pk_add_f32 v[64:65], v[66:67], v[64:65] neg_lo:[0,1] neg_hi:[0,1]
	v_pk_add_f32 v[66:67], v[62:63], v[100:101]
	v_pk_add_f32 v[62:63], v[62:63], v[100:101] neg_lo:[0,1] neg_hi:[0,1]
	v_pk_add_f32 v[92:93], v[90:91], v[96:97]
	v_pk_add_f32 v[90:91], v[90:91], v[96:97] neg_lo:[0,1] neg_hi:[0,1]
	v_pk_add_f32 v[96:97], v[94:95], v[82:83]
	v_pk_add_f32 v[82:83], v[94:95], v[82:83] neg_lo:[0,1] neg_hi:[0,1]
	v_xor_b32_e32 v94, 0x80000000, v77
	v_mov_b32_e32 v95, v76
	v_pk_add_f32 v[76:77], v[80:81], v[94:95]
	v_pk_add_f32 v[80:81], v[80:81], v[94:95] neg_lo:[0,1] neg_hi:[0,1]
	v_pk_add_f32 v[94:95], v[78:79], v[66:67]
	v_pk_add_f32 v[66:67], v[78:79], v[66:67] neg_lo:[0,1] neg_hi:[0,1]
	v_xor_b32_e32 v78, 0x80000000, v63
	v_mov_b32_e32 v79, v62
	v_pk_add_f32 v[62:63], v[64:65], v[78:79]
	v_pk_add_f32 v[64:65], v[64:65], v[78:79] neg_lo:[0,1] neg_hi:[0,1]
	v_pk_add_f32 v[78:79], v[98:99], v[10:11]
	v_pk_add_f32 v[10:11], v[98:99], v[10:11] neg_lo:[0,1] neg_hi:[0,1]
	v_xor_b32_e32 v98, 0x80000000, v3
	v_mov_b32_e32 v99, v2
	v_pk_add_f32 v[2:3], v[0:1], v[98:99]
	v_pk_add_f32 v[0:1], v[0:1], v[98:99] neg_lo:[0,1] neg_hi:[0,1]
	v_pk_add_f32 v[98:99], v[6:7], v[96:97]
	v_pk_add_f32 v[6:7], v[6:7], v[96:97] neg_lo:[0,1] neg_hi:[0,1]
	v_pk_mul_f32 v[96:97], v[76:77], s[60:61] op_sel:[1,0] op_sel_hi:[0,0] neg_lo:[1,0]
	v_xor_b32_e32 v100, 0x80000000, v81
	v_pk_fma_f32 v[76:77], v[76:77], s[60:61], v[96:97] op_sel_hi:[1,0,1]
	v_mov_b32_e32 v101, v80
	v_pk_add_f32 v[96:97], v[92:93], v[76:77]
	v_pk_add_f32 v[76:77], v[92:93], v[76:77] neg_lo:[0,1] neg_hi:[0,1]
	v_xor_b32_e32 v92, 0x80000000, v83
	v_mov_b32_e32 v93, v82
	v_pk_add_f32 v[82:83], v[24:25], v[92:93]
	v_pk_add_f32 v[24:25], v[24:25], v[92:93] neg_lo:[0,1] neg_hi:[0,1]
	v_pk_mul_f32 v[92:93], v[80:81], s[60:61] op_sel_hi:[1,0]
	s_nop 0
	v_pk_fma_f32 v[80:81], v[100:101], s[60:61], v[92:93] op_sel_hi:[1,0,1] neg_lo:[0,0,1] neg_hi:[0,0,1]
	v_xor_b32_e32 v100, 0x80000000, v1
	v_pk_add_f32 v[92:93], v[90:91], v[80:81]
	v_pk_add_f32 v[80:81], v[90:91], v[80:81] neg_lo:[0,1] neg_hi:[0,1]
	v_pk_add_f32 v[90:91], v[94:95], v[78:79]
	v_pk_add_f32 v[78:79], v[94:95], v[78:79] neg_lo:[0,1] neg_hi:[0,1]
	v_pk_mul_f32 v[94:95], v[2:3], s[60:61] op_sel:[1,0] op_sel_hi:[0,0] neg_lo:[1,0]
	v_mov_b32_e32 v101, v0
	v_pk_fma_f32 v[2:3], v[2:3], s[60:61], v[94:95] op_sel_hi:[1,0,1]
	s_nop 0
	v_pk_add_f32 v[94:95], v[62:63], v[2:3]
	v_pk_add_f32 v[2:3], v[62:63], v[2:3] neg_lo:[0,1] neg_hi:[0,1]
	v_xor_b32_e32 v62, 0x80000000, v11
	v_mov_b32_e32 v63, v10
	v_pk_add_f32 v[10:11], v[66:67], v[62:63]
	v_pk_add_f32 v[62:63], v[66:67], v[62:63] neg_lo:[0,1] neg_hi:[0,1]
	v_pk_mul_f32 v[66:67], v[0:1], s[60:61] op_sel_hi:[1,0]
	s_nop 0
	v_pk_fma_f32 v[0:1], v[100:101], s[60:61], v[66:67] op_sel_hi:[1,0,1] neg_lo:[0,0,1] neg_hi:[0,0,1]
	v_xor_b32_e32 v100, 0x80000000, v3
	v_pk_add_f32 v[66:67], v[64:65], v[0:1]
	v_pk_add_f32 v[0:1], v[64:65], v[0:1] neg_lo:[0,1] neg_hi:[0,1]
	v_pk_add_f32 v[64:65], v[98:99], v[90:91]
	v_pk_add_f32 v[90:91], v[98:99], v[90:91] neg_lo:[0,1] neg_hi:[0,1]
	v_pk_mul_f32 v[98:99], v[94:95], s[54:55] op_sel:[1,0] op_sel_hi:[0,0] neg_lo:[1,0]
	v_mov_b32_e32 v101, v2
	v_pk_fma_f32 v[94:95], v[94:95], s[52:53], v[98:99] op_sel_hi:[1,0,1]
	s_nop 0
	v_pk_add_f32 v[98:99], v[96:97], v[94:95]
	v_pk_add_f32 v[94:95], v[96:97], v[94:95] neg_lo:[0,1] neg_hi:[0,1]
	v_pk_mul_f32 v[96:97], v[10:11], s[60:61] op_sel:[1,0] op_sel_hi:[0,0] neg_lo:[1,0]
	s_nop 0
	v_pk_fma_f32 v[10:11], v[10:11], s[60:61], v[96:97] op_sel_hi:[1,0,1]
	s_nop 0
	v_pk_add_f32 v[96:97], v[82:83], v[10:11]
	v_pk_add_f32 v[10:11], v[82:83], v[10:11] neg_lo:[0,1] neg_hi:[0,1]
	v_pk_mul_f32 v[82:83], v[66:67], s[52:53] op_sel:[1,0] op_sel_hi:[0,0] neg_lo:[1,0]
	s_nop 0
	v_pk_fma_f32 v[66:67], v[66:67], s[54:55], v[82:83] op_sel_hi:[1,0,1]
	s_nop 0
	v_pk_add_f32 v[82:83], v[92:93], v[66:67]
	v_pk_add_f32 v[66:67], v[92:93], v[66:67] neg_lo:[0,1] neg_hi:[0,1]
	v_xor_b32_e32 v92, 0x80000000, v79
	v_mov_b32_e32 v93, v78
	v_pk_add_f32 v[78:79], v[6:7], v[92:93]
	v_pk_add_f32 v[6:7], v[6:7], v[92:93] neg_lo:[0,1] neg_hi:[0,1]
	v_pk_mul_f32 v[92:93], v[2:3], s[54:55] op_sel_hi:[1,0]
	s_nop 0
	v_pk_fma_f32 v[2:3], v[100:101], s[52:53], v[92:93] op_sel_hi:[1,0,1] neg_lo:[0,0,1] neg_hi:[0,0,1]
	v_xor_b32_e32 v100, 0x80000000, v63
	v_pk_add_f32 v[92:93], v[76:77], v[2:3]
	v_pk_add_f32 v[2:3], v[76:77], v[2:3] neg_lo:[0,1] neg_hi:[0,1]
	v_pk_mul_f32 v[76:77], v[62:63], s[60:61] op_sel_hi:[1,0]
	v_mov_b32_e32 v101, v62
	v_pk_fma_f32 v[62:63], v[100:101], s[60:61], v[76:77] op_sel_hi:[1,0,1] neg_lo:[0,0,1] neg_hi:[0,0,1]
	v_xor_b32_e32 v100, 0x80000000, v1
	v_pk_add_f32 v[76:77], v[24:25], v[62:63]
	v_pk_add_f32 v[24:25], v[24:25], v[62:63] neg_lo:[0,1] neg_hi:[0,1]
	v_pk_mul_f32 v[62:63], v[0:1], s[52:53] op_sel_hi:[1,0]
	v_mov_b32_e32 v101, v0
	v_pk_fma_f32 v[0:1], v[100:101], s[54:55], v[62:63] op_sel_hi:[1,0,1] neg_lo:[0,0,1] neg_hi:[0,0,1]
	v_bfe_u32 v100, v102, 1, 4
	v_pk_add_f32 v[62:63], v[80:81], v[0:1]
	v_pk_add_f32 v[0:1], v[80:81], v[0:1] neg_lo:[0,1] neg_hi:[0,1]
	v_lshlrev_b32_e32 v80, 4, v102
	v_lshrrev_b32_e32 v81, 1, v102
	v_bitop3_b32 v101, v81, v80, 16 bitop3:0x6c
	v_lshl_add_u32 v101, v101, 3, 16
	v_lshlrev_b32_e32 v100, 3, v100
	v_add_u32_e32 v102, v101, v100
	ds_write_b64 v102, v[70:71]
	v_bitop3_b32 v70, v81, 1, 15 bitop3:0x6c
	v_lshlrev_b32_e32 v70, 3, v70
	v_add_u32_e32 v71, v101, v70
	ds_write_b64 v71, v[86:87]
	v_bitop3_b32 v71, v81, 2, 15 bitop3:0x6c
	v_lshlrev_b32_e32 v71, 3, v71
	v_add_u32_e32 v86, v101, v71
	ds_write_b64 v86, v[88:89]
	v_bitop3_b32 v86, v81, 3, 15 bitop3:0x6c
	v_lshlrev_b32_e32 v86, 3, v86
	v_add_u32_e32 v87, v101, v86
	ds_write_b64 v87, v[74:75]
	v_bitop3_b32 v74, v81, 4, 15 bitop3:0x6c
	v_lshlrev_b32_e32 v74, 3, v74
	v_add_u32_e32 v75, v101, v74
	ds_write_b64 v75, v[20:21]
	v_bitop3_b32 v20, v81, 5, 15 bitop3:0x6c
	v_lshlrev_b32_e32 v20, 3, v20
	v_add_u32_e32 v21, v101, v20
	ds_write_b64 v21, v[72:73]
	v_bitop3_b32 v21, v81, 6, 15 bitop3:0x6c
	v_lshlrev_b32_e32 v21, 3, v21
	v_add_u32_e32 v72, v101, v21
	ds_write_b64 v72, v[68:69]
	v_bitop3_b32 v68, v81, 7, 15 bitop3:0x6c
	v_lshlrev_b32_e32 v68, 3, v68
	v_add_u32_e32 v69, v101, v68
	ds_write_b64 v69, v[26:27]
	v_bitop3_b32 v26, v81, 8, 15 bitop3:0x6c
	v_lshlrev_b32_e32 v26, 3, v26
	v_add_u32_e32 v27, v101, v26
	ds_write_b64 v27, v[18:19]
	v_bitop3_b32 v18, v81, 9, 15 bitop3:0x6c
	v_lshlrev_b32_e32 v18, 3, v18
	v_add_u32_e32 v19, v101, v18
	ds_write_b64 v19, v[84:85]
	v_bitop3_b32 v19, v81, 10, 15 bitop3:0x6c
	v_lshlrev_b32_e32 v19, 3, v19
	v_add_u32_e32 v27, v101, v19
	ds_write_b64 v27, v[16:17]
	v_bitop3_b32 v16, v81, 11, 15 bitop3:0x6c
	v_lshlrev_b32_e32 v16, 3, v16
	v_add_u32_e32 v17, v101, v16
	ds_write_b64 v17, v[22:23]
	v_bitop3_b32 v17, v81, 12, 15 bitop3:0x6c
	v_lshlrev_b32_e32 v17, 3, v17
	v_add_u32_e32 v22, v101, v17
	ds_write_b64 v22, v[12:13]
	v_bitop3_b32 v12, v81, 13, 15 bitop3:0x6c
	v_lshlrev_b32_e32 v12, 3, v12
	v_add_u32_e32 v13, v101, v12
	ds_write_b64 v13, v[14:15]
	v_bitop3_b32 v13, v81, 14, 15 bitop3:0x6c
	v_lshlrev_b32_e32 v13, 3, v13
	v_add_u32_e32 v14, v101, v13
	ds_write_b64 v14, v[4:5]
	v_bitop3_b32 v4, v81, 15, v81 bitop3:0xc
	v_lshlrev_b32_e32 v4, 3, v4
	v_add_u32_e32 v5, v101, v4
	ds_write_b64 v5, v[8:9]
	v_add_u32_e32 v5, 0x2000, v80
	v_bitop3_b32 v5, v5, v81, 16 bitop3:0x78
	v_lshl_add_u32 v5, v5, 3, 16
	v_add_u32_e32 v8, v5, v100
	ds_write_b64 v8, v[64:65]
	v_add_u32_e32 v8, v5, v70
	ds_write_b64 v8, v[98:99]
	v_add_u32_e32 v8, v5, v71
	ds_write_b64 v8, v[96:97]
	v_add_u32_e32 v8, v5, v86
	ds_write_b64 v8, v[82:83]
	v_add_u32_e32 v8, v5, v74
	ds_write_b64 v8, v[78:79]
	v_add_u32_e32 v8, v5, v20
	ds_write_b64 v8, v[92:93]
	v_add_u32_e32 v8, v5, v21
	ds_write_b64 v8, v[76:77]
	v_add_u32_e32 v8, v5, v68
	ds_write_b64 v8, v[62:63]
	v_add_u32_e32 v8, v5, v26
	ds_write_b64 v8, v[90:91]
	v_add_u32_e32 v8, v5, v18
	ds_write_b64 v8, v[94:95]
	v_add_u32_e32 v8, v5, v19
	ds_write_b64 v8, v[10:11]
	v_add_u32_e32 v8, v5, v16
	ds_write_b64 v8, v[66:67]
	v_add_u32_e32 v8, v5, v17
	ds_write_b64 v8, v[6:7]
	v_add_u32_e32 v6, v5, v12
	ds_write_b64 v6, v[2:3]
	v_add_u32_e32 v2, v5, v13
	ds_write_b64 v2, v[24:25]
	v_add_u32_e32 v2, v5, v4
	v_mov_b32_e32 v22, v146
	ds_write_b64 v2, v[0:1]
	s_waitcnt lgkmcnt(0)
	s_barrier
	s_nop 0
	v_lshlrev_b32_e32 v0, 5, v22
	v_and_b32_e32 v2, 0xfffffe00, v0
	v_and_or_b32 v0, v22, 16, v2
	v_bitop3_b32 v2, v2, 16, v22 bitop3:0x34
	v_bitop3_b32 v6, v22, 4, 15 bitop3:0x6c
	v_bitop3_b32 v14, v22, 8, 15 bitop3:0x6c
	v_lshl_add_u32 v23, v0, 3, 16
	v_lshl_add_u32 v65, v2, 3, 16
	v_lshlrev_b32_e32 v6, 3, v6
	v_lshlrev_b32_e32 v14, 3, v14
	v_bitop3_b32 v2, v22, 1, 15 bitop3:0x6c
	v_add_u32_e32 v105, v23, v6
	v_add_u32_e32 v106, v65, v6
	v_bitop3_b32 v6, v22, 5, 15 bitop3:0x6c
	v_add_u32_e32 v113, v23, v14
	v_add_u32_e32 v114, v65, v14
	v_bitop3_b32 v14, v22, 9, 15 bitop3:0x6c
	v_lshlrev_b32_e32 v2, 3, v2
	v_lshlrev_b32_e32 v6, 3, v6
	v_lshlrev_b32_e32 v14, 3, v14
	v_add_u32_e32 v99, v23, v2
	v_add_u32_e32 v100, v65, v2
	v_bitop3_b32 v2, v22, 2, 15 bitop3:0x6c
	v_add_u32_e32 v107, v23, v6
	v_add_u32_e32 v108, v65, v6
	v_bitop3_b32 v6, v22, 6, 15 bitop3:0x6c
	v_add_u32_e32 v115, v23, v14
	v_add_u32_e32 v116, v65, v14
	v_bitop3_b32 v14, v22, 10, 15 bitop3:0x6c
	v_bitop3_b32 v26, v22, 12, 15 bitop3:0x6c
	v_lshlrev_b32_e32 v2, 3, v2
	v_lshlrev_b32_e32 v6, 3, v6
	v_lshlrev_b32_e32 v14, 3, v14
	v_lshlrev_b32_e32 v26, 3, v26
	v_and_b32_e32 v64, 15, v22
	v_add_u32_e32 v101, v23, v2
	v_add_u32_e32 v102, v65, v2
	v_bitop3_b32 v2, v22, 3, 15 bitop3:0x6c
	v_add_u32_e32 v109, v23, v6
	v_add_u32_e32 v110, v65, v6
	v_bitop3_b32 v6, v22, 7, 15 bitop3:0x6c
	v_add_u32_e32 v117, v23, v14
	v_add_u32_e32 v118, v65, v14
	v_bitop3_b32 v14, v22, 11, 15 bitop3:0x6c
	v_add_u32_e32 v121, v23, v26
	v_add_u32_e32 v122, v65, v26
	v_bitop3_b32 v26, v22, 13, 15 bitop3:0x6c
	v_bitop3_b32 v66, v22, 14, 15 bitop3:0x6c
	v_bitop3_b32 v22, v22, 15, v22 bitop3:0xc
	v_lshlrev_b32_e32 v3, 3, v64
	v_lshlrev_b32_e32 v2, 3, v2
	v_lshlrev_b32_e32 v6, 3, v6
	v_lshlrev_b32_e32 v14, 3, v14
	v_lshlrev_b32_e32 v26, 3, v26
	v_lshlrev_b32_e32 v66, 3, v66
	v_lshlrev_b32_e32 v22, 3, v22
	v_add_u32_e32 v67, v23, v3
	v_add_u32_e32 v98, v65, v3
	v_add_u32_e32 v103, v23, v2
	v_add_u32_e32 v104, v65, v2
	v_add_u32_e32 v111, v23, v6
	v_add_u32_e32 v112, v65, v6
	v_add_u32_e32 v119, v23, v14
	v_add_u32_e32 v120, v65, v14
	v_add_u32_e32 v123, v23, v26
	v_add_u32_e32 v124, v65, v26
	v_add_u32_e32 v125, v23, v66
	v_add_u32_e32 v126, v65, v66
	v_add_u32_e32 v127, v23, v22
	v_add_u32_e32 v128, v65, v22
	ds_read_b64 v[0:1], v67
	ds_read_b64 v[12:13], v98
	ds_read_b64 v[74:75], v99 offset:256
	ds_read_b64 v[4:5], v100 offset:256
	ds_read_b64 v[76:77], v101 offset:512
	ds_read_b64 v[10:11], v102 offset:512
	ds_read_b64 v[70:71], v103 offset:768
	ds_read_b64 v[2:3], v104 offset:768
	ds_read_b64 v[62:63], v105 offset:1024
	ds_read_b64 v[20:21], v106 offset:1024
	ds_read_b64 v[90:91], v107 offset:1280
	ds_read_b64 v[8:9], v108 offset:1280
	ds_read_b64 v[84:85], v109 offset:1536
	ds_read_b64 v[16:17], v110 offset:1536
	ds_read_b64 v[82:83], v111 offset:1792
	ds_read_b64 v[6:7], v112 offset:1792
	ds_read_b64 v[24:25], v113 offset:2048
	ds_read_b64 v[78:79], v114 offset:2048
	ds_read_b64 v[96:97], v115 offset:2304
	ds_read_b64 v[18:19], v116 offset:2304
	ds_read_b64 v[86:87], v117 offset:2560
	ds_read_b64 v[72:73], v118 offset:2560
	ds_read_b64 v[130:131], v119 offset:2816
	ds_read_b64 v[14:15], v120 offset:2816
	ds_read_b64 v[80:81], v121 offset:3072
	ds_read_b64 v[92:93], v122 offset:3072
	ds_read_b64 v[132:133], v123 offset:3328
	ds_read_b64 v[26:27], v124 offset:3328
	ds_read_b64 v[94:95], v125 offset:3584
	ds_read_b64 v[88:89], v126 offset:3584
	ds_read_b64 v[134:135], v127 offset:3840
	ds_read_b64 v[22:23], v128 offset:3840
	s_waitcnt lgkmcnt(14)
	s_nop 0
	v_cvt_f32_i32_e32 v64, v64
	s_nop 0
	v_mul_f32_e32 v64, 0x3b000000, v64
	v_cos_f32_e32 v68, v64
	v_sin_f32_e32 v69, v64
	v_add_f32_e32 v66, v68, v68
	v_pk_mul_f32 v[64:65], v[68:69], v[68:69]
	v_mul_f32_e32 v66, v69, v66
	s_nop 0
	s_nop 0
	v_mov_b32_e32 v140, v69
	v_pk_add_f32 v[64:65], v[64:65], v[64:65] op_sel:[0,1] op_sel_hi:[0,1] neg_lo:[0,1] neg_hi:[0,1]
	v_pk_mul_f32 v[136:137], v[68:69], v[66:67] op_sel:[1,0] op_sel_hi:[0,0] neg_lo:[1,0]
	v_pk_mul_f32 v[138:139], v[24:25], v[140:141] op_sel:[1,0] op_sel_hi:[0,0] neg_lo:[1,0]
	v_pk_fma_f32 v[136:137], v[68:69], v[64:65], v[136:137]
	v_pk_fma_f32 v[24:25], v[24:25], v[68:69], v[138:139] op_sel_hi:[1,0,1]
	v_pk_mul_f32 v[68:69], v[66:67], s[46:47] op_sel_hi:[0,1]
	v_pk_fma_f32 v[138:139], v[64:65], s[40:41], v[68:69]
	s_nop 0
	v_pk_mul_f32 v[68:69], v[62:63], v[138:139] op_sel:[1,1] op_sel_hi:[0,1] neg_lo:[1,0]
	s_nop 0
	v_pk_fma_f32 v[68:69], v[62:63], v[138:139], v[68:69] op_sel_hi:[1,0,1]
	v_pk_mul_f32 v[62:63], v[66:67], v[136:137] op_sel:[0,1] op_sel_hi:[0,0] neg_lo:[0,1]
	v_pk_fma_f32 v[140:141], v[64:65], v[136:137], v[62:63]
	s_waitcnt lgkmcnt(7)
	v_pk_mul_f32 v[62:63], v[80:81], v[136:137] op_sel:[1,1] op_sel_hi:[0,1] neg_lo:[1,0]
	s_nop 0
	v_pk_fma_f32 v[62:63], v[80:81], v[136:137], v[62:63] op_sel_hi:[1,0,1]
	v_pk_mul_f32 v[80:81], v[66:67], v[138:139] op_sel:[0,1] op_sel_hi:[0,0] neg_lo:[0,1]
	v_pk_fma_f32 v[136:137], v[64:65], v[138:139], v[80:81]
	s_nop 0
	v_pk_mul_f32 v[80:81], v[76:77], v[136:137] op_sel:[1,1] op_sel_hi:[0,1] neg_lo:[1,0]
	s_nop 0
	v_pk_fma_f32 v[80:81], v[76:77], v[136:137], v[80:81] op_sel_hi:[1,0,1]
	v_pk_mul_f32 v[76:77], v[66:67], v[140:141] op_sel:[0,1] op_sel_hi:[0,0] neg_lo:[0,1]
	v_pk_fma_f32 v[138:139], v[64:65], v[140:141], v[76:77]
	v_pk_mul_f32 v[76:77], v[86:87], v[140:141] op_sel:[1,1] op_sel_hi:[0,1] neg_lo:[1,0]
	s_nop 0
	v_pk_fma_f32 v[76:77], v[86:87], v[140:141], v[76:77] op_sel_hi:[1,0,1]
	v_pk_mul_f32 v[86:87], v[66:67], v[136:137] op_sel:[0,1] op_sel_hi:[0,0] neg_lo:[0,1]
	v_pk_fma_f32 v[136:137], v[64:65], v[136:137], v[86:87]
	s_nop 0
	v_pk_mul_f32 v[86:87], v[84:85], v[136:137] op_sel:[1,1] op_sel_hi:[0,1] neg_lo:[1,0]
	s_nop 0
	v_pk_fma_f32 v[86:87], v[84:85], v[136:137], v[86:87] op_sel_hi:[1,0,1]
	v_pk_mul_f32 v[84:85], v[66:67], v[138:139] op_sel:[0,1] op_sel_hi:[0,0] neg_lo:[0,1]
	v_pk_fma_f32 v[140:141], v[64:65], v[138:139], v[84:85]
	s_waitcnt lgkmcnt(3)
	v_pk_mul_f32 v[84:85], v[94:95], v[138:139] op_sel:[1,1] op_sel_hi:[0,1] neg_lo:[1,0]
	s_nop 0
	v_pk_fma_f32 v[84:85], v[94:95], v[138:139], v[84:85] op_sel_hi:[1,0,1]
	v_pk_mul_f32 v[94:95], v[66:67], v[136:137] op_sel:[0,1] op_sel_hi:[0,0] neg_lo:[0,1]
	v_pk_fma_f32 v[136:137], v[64:65], v[136:137], v[94:95]
	s_nop 0
	v_pk_mul_f32 v[94:95], v[74:75], v[136:137] op_sel:[1,1] op_sel_hi:[0,1] neg_lo:[1,0]
	s_nop 0
	v_pk_fma_f32 v[94:95], v[74:75], v[136:137], v[94:95] op_sel_hi:[1,0,1]
	v_pk_mul_f32 v[74:75], v[66:67], v[140:141] op_sel:[0,1] op_sel_hi:[0,0] neg_lo:[0,1]
	v_pk_fma_f32 v[138:139], v[64:65], v[140:141], v[74:75]
	v_pk_mul_f32 v[74:75], v[96:97], v[140:141] op_sel:[1,1] op_sel_hi:[0,1] neg_lo:[1,0]
	s_nop 0
	v_pk_fma_f32 v[74:75], v[96:97], v[140:141], v[74:75] op_sel_hi:[1,0,1]
	v_pk_mul_f32 v[96:97], v[66:67], v[136:137] op_sel:[0,1] op_sel_hi:[0,0] neg_lo:[0,1]
	v_pk_fma_f32 v[136:137], v[64:65], v[136:137], v[96:97]
	s_nop 0
	v_pk_mul_f32 v[96:97], v[90:91], v[136:137] op_sel:[1,1] op_sel_hi:[0,1] neg_lo:[1,0]
	s_nop 0
	v_pk_fma_f32 v[96:97], v[90:91], v[136:137], v[96:97] op_sel_hi:[1,0,1]
	v_pk_mul_f32 v[90:91], v[66:67], v[138:139] op_sel:[0,1] op_sel_hi:[0,0] neg_lo:[0,1]
	v_pk_fma_f32 v[140:141], v[64:65], v[138:139], v[90:91]
	v_pk_mul_f32 v[90:91], v[132:133], v[138:139] op_sel:[1,1] op_sel_hi:[0,1] neg_lo:[1,0]
	s_nop 0
	v_pk_fma_f32 v[90:91], v[132:133], v[138:139], v[90:91] op_sel_hi:[1,0,1]
	v_pk_mul_f32 v[132:133], v[66:67], v[136:137] op_sel:[0,1] op_sel_hi:[0,0] neg_lo:[0,1]
	s_nop 0
	v_pk_fma_f32 v[132:133], v[64:65], v[136:137], v[132:133]
	v_pk_mul_f32 v[138:139], v[130:131], v[140:141] op_sel:[1,1] op_sel_hi:[0,1] neg_lo:[1,0]
	v_pk_mul_f32 v[136:137], v[70:71], v[132:133] op_sel:[1,1] op_sel_hi:[0,1] neg_lo:[1,0]
	v_pk_fma_f32 v[130:131], v[130:131], v[140:141], v[138:139] op_sel_hi:[1,0,1]
	v_pk_fma_f32 v[70:71], v[70:71], v[132:133], v[136:137] op_sel_hi:[1,0,1]
	v_pk_mul_f32 v[138:139], v[66:67], v[132:133] op_sel:[0,1] op_sel_hi:[0,0] neg_lo:[0,1]
	v_pk_mul_f32 v[136:137], v[66:67], v[140:141] op_sel:[0,1] op_sel_hi:[0,0] neg_lo:[0,1]
	v_pk_fma_f32 v[132:133], v[64:65], v[132:133], v[138:139]
	v_pk_fma_f32 v[136:137], v[64:65], v[140:141], v[136:137]
	v_pk_mul_f32 v[138:139], v[82:83], v[132:133] op_sel:[1,1] op_sel_hi:[0,1] neg_lo:[1,0]
	s_waitcnt lgkmcnt(1)
	v_pk_fma_f32 v[82:83], v[82:83], v[132:133], v[138:139] op_sel_hi:[1,0,1]
	v_pk_mul_f32 v[138:139], v[66:67], v[136:137] op_sel:[0,1] op_sel_hi:[0,0] neg_lo:[0,1]
	v_pk_mul_f32 v[140:141], v[134:135], v[136:137] op_sel:[1,1] op_sel_hi:[0,1] neg_lo:[1,0]
	v_pk_fma_f32 v[138:139], v[64:65], v[136:137], v[138:139]
	v_pk_fma_f32 v[134:135], v[134:135], v[136:137], v[140:141] op_sel_hi:[1,0,1]
	v_pk_mul_f32 v[136:137], v[66:67], v[132:133] op_sel:[0,1] op_sel_hi:[0,0] neg_lo:[0,1]
	v_pk_fma_f32 v[132:133], v[64:65], v[132:133], v[136:137]
	s_nop 0
	v_pk_mul_f32 v[136:137], v[12:13], v[132:133] op_sel:[1,1] op_sel_hi:[0,1] neg_lo:[1,0]
	s_nop 0
	v_pk_fma_f32 v[12:13], v[12:13], v[132:133], v[136:137] op_sel_hi:[1,0,1]
	v_pk_mul_f32 v[136:137], v[66:67], v[138:139] op_sel:[0,1] op_sel_hi:[0,0] neg_lo:[0,1]
	v_pk_mul_f32 v[140:141], v[78:79], v[138:139] op_sel:[1,1] op_sel_hi:[0,1] neg_lo:[1,0]
	v_pk_fma_f32 v[136:137], v[64:65], v[138:139], v[136:137]
	v_pk_fma_f32 v[78:79], v[78:79], v[138:139], v[140:141] op_sel_hi:[1,0,1]
	v_pk_mul_f32 v[138:139], v[66:67], v[132:133] op_sel:[0,1] op_sel_hi:[0,0] neg_lo:[0,1]
	v_pk_fma_f32 v[132:133], v[64:65], v[132:133], v[138:139]
	s_nop 0
	v_pk_mul_f32 v[138:139], v[20:21], v[132:133] op_sel:[1,1] op_sel_hi:[0,1] neg_lo:[1,0]
	s_nop 0
	v_pk_fma_f32 v[20:21], v[20:21], v[132:133], v[138:139] op_sel_hi:[1,0,1]
	v_pk_mul_f32 v[138:139], v[66:67], v[136:137] op_sel:[0,1] op_sel_hi:[0,0] neg_lo:[0,1]
	v_pk_mul_f32 v[140:141], v[92:93], v[136:137] op_sel:[1,1] op_sel_hi:[0,1] neg_lo:[1,0]
	v_pk_fma_f32 v[138:139], v[64:65], v[136:137], v[138:139]
	v_pk_fma_f32 v[92:93], v[92:93], v[136:137], v[140:141] op_sel_hi:[1,0,1]
	v_pk_mul_f32 v[136:137], v[66:67], v[132:133] op_sel:[0,1] op_sel_hi:[0,0] neg_lo:[0,1]
	v_pk_fma_f32 v[132:133], v[64:65], v[132:133], v[136:137]
	s_nop 0
	v_pk_mul_f32 v[136:137], v[10:11], v[132:133] op_sel:[1,1] op_sel_hi:[0,1] neg_lo:[1,0]
	s_nop 0
	v_pk_fma_f32 v[10:11], v[10:11], v[132:133], v[136:137] op_sel_hi:[1,0,1]
	v_pk_mul_f32 v[136:137], v[66:67], v[138:139] op_sel:[0,1] op_sel_hi:[0,0] neg_lo:[0,1]
	v_pk_mul_f32 v[140:141], v[72:73], v[138:139] op_sel:[1,1] op_sel_hi:[0,1] neg_lo:[1,0]
	v_pk_fma_f32 v[136:137], v[64:65], v[138:139], v[136:137]
	v_pk_fma_f32 v[72:73], v[72:73], v[138:139], v[140:141] op_sel_hi:[1,0,1]
	v_pk_mul_f32 v[138:139], v[66:67], v[132:133] op_sel:[0,1] op_sel_hi:[0,0] neg_lo:[0,1]
	v_pk_fma_f32 v[132:133], v[64:65], v[132:133], v[138:139]
	s_nop 0
	v_pk_mul_f32 v[138:139], v[16:17], v[132:133] op_sel:[1,1] op_sel_hi:[0,1] neg_lo:[1,0]
	s_nop 0
	v_pk_fma_f32 v[16:17], v[16:17], v[132:133], v[138:139] op_sel_hi:[1,0,1]
	v_pk_mul_f32 v[138:139], v[66:67], v[136:137] op_sel:[0,1] op_sel_hi:[0,0] neg_lo:[0,1]
	v_pk_mul_f32 v[140:141], v[88:89], v[136:137] op_sel:[1,1] op_sel_hi:[0,1] neg_lo:[1,0]
	v_pk_fma_f32 v[138:139], v[64:65], v[136:137], v[138:139]
	v_pk_fma_f32 v[88:89], v[88:89], v[136:137], v[140:141] op_sel_hi:[1,0,1]
	v_pk_mul_f32 v[136:137], v[66:67], v[132:133] op_sel:[0,1] op_sel_hi:[0,0] neg_lo:[0,1]
	v_pk_fma_f32 v[132:133], v[64:65], v[132:133], v[136:137]
	s_nop 0
	v_pk_mul_f32 v[136:137], v[4:5], v[132:133] op_sel:[1,1] op_sel_hi:[0,1] neg_lo:[1,0]
	s_nop 0
	v_pk_fma_f32 v[4:5], v[4:5], v[132:133], v[136:137] op_sel_hi:[1,0,1]
	v_pk_mul_f32 v[136:137], v[66:67], v[138:139] op_sel:[0,1] op_sel_hi:[0,0] neg_lo:[0,1]
	v_pk_mul_f32 v[140:141], v[18:19], v[138:139] op_sel:[1,1] op_sel_hi:[0,1] neg_lo:[1,0]
	v_pk_fma_f32 v[136:137], v[64:65], v[138:139], v[136:137]
	v_pk_fma_f32 v[18:19], v[18:19], v[138:139], v[140:141] op_sel_hi:[1,0,1]
	v_pk_mul_f32 v[138:139], v[66:67], v[132:133] op_sel:[0,1] op_sel_hi:[0,0] neg_lo:[0,1]
	v_pk_fma_f32 v[132:133], v[64:65], v[132:133], v[138:139]
	s_nop 0
	v_pk_mul_f32 v[138:139], v[8:9], v[132:133] op_sel:[1,1] op_sel_hi:[0,1] neg_lo:[1,0]
	s_nop 0
	v_pk_fma_f32 v[8:9], v[8:9], v[132:133], v[138:139] op_sel_hi:[1,0,1]
	v_pk_mul_f32 v[138:139], v[66:67], v[136:137] op_sel:[0,1] op_sel_hi:[0,0] neg_lo:[0,1]
	v_pk_mul_f32 v[140:141], v[26:27], v[136:137] op_sel:[1,1] op_sel_hi:[0,1] neg_lo:[1,0]
	v_pk_fma_f32 v[138:139], v[64:65], v[136:137], v[138:139]
	v_pk_fma_f32 v[26:27], v[26:27], v[136:137], v[140:141] op_sel_hi:[1,0,1]
	v_pk_mul_f32 v[136:137], v[66:67], v[132:133] op_sel:[0,1] op_sel_hi:[0,0] neg_lo:[0,1]
	v_pk_fma_f32 v[132:133], v[64:65], v[132:133], v[136:137]
	s_nop 0
	v_pk_mul_f32 v[136:137], v[2:3], v[132:133] op_sel:[1,1] op_sel_hi:[0,1] neg_lo:[1,0]
	s_nop 0
	v_pk_fma_f32 v[2:3], v[2:3], v[132:133], v[136:137] op_sel_hi:[1,0,1]
	v_pk_mul_f32 v[136:137], v[66:67], v[138:139] op_sel:[0,1] op_sel_hi:[0,0] neg_lo:[0,1]
	v_pk_mul_f32 v[140:141], v[14:15], v[138:139] op_sel:[1,1] op_sel_hi:[0,1] neg_lo:[1,0]
	v_pk_fma_f32 v[136:137], v[64:65], v[138:139], v[136:137]
	v_pk_fma_f32 v[14:15], v[14:15], v[138:139], v[140:141] op_sel_hi:[1,0,1]
	v_pk_mul_f32 v[138:139], v[66:67], v[132:133] op_sel:[0,1] op_sel_hi:[0,0] neg_lo:[0,1]
	v_pk_fma_f32 v[64:65], v[64:65], v[132:133], v[138:139]
	s_nop 0
	v_pk_mul_f32 v[132:133], v[6:7], v[64:65] op_sel:[1,1] op_sel_hi:[0,1] neg_lo:[1,0]
	s_nop 0
	v_pk_fma_f32 v[6:7], v[6:7], v[64:65], v[132:133] op_sel_hi:[1,0,1]
	s_waitcnt lgkmcnt(0)
	v_pk_mul_f32 v[64:65], v[22:23], v[136:137] op_sel:[1,1] op_sel_hi:[0,1] neg_lo:[1,0]
	s_nop 0
	v_pk_fma_f32 v[22:23], v[22:23], v[136:137], v[64:65] op_sel_hi:[1,0,1]
	v_pk_add_f32 v[64:65], v[0:1], v[12:13]
	v_pk_add_f32 v[0:1], v[0:1], v[12:13] neg_lo:[0,1] neg_hi:[0,1]
	v_pk_add_f32 v[12:13], v[94:95], v[4:5]
	v_pk_add_f32 v[4:5], v[94:95], v[4:5] neg_lo:[0,1] neg_hi:[0,1]
	v_pk_add_f32 v[94:95], v[80:81], v[10:11]
	v_pk_add_f32 v[10:11], v[80:81], v[10:11] neg_lo:[0,1] neg_hi:[0,1]
	v_pk_add_f32 v[80:81], v[70:71], v[2:3]
	v_pk_add_f32 v[2:3], v[70:71], v[2:3] neg_lo:[0,1] neg_hi:[0,1]
	v_pk_add_f32 v[132:133], v[64:65], v[12:13]
	v_pk_add_f32 v[12:13], v[64:65], v[12:13] neg_lo:[0,1] neg_hi:[0,1]
	v_xor_b32_e32 v64, 0x80000000, v5
	v_mov_b32_e32 v65, v4
	v_pk_add_f32 v[70:71], v[68:69], v[20:21]
	v_pk_add_f32 v[20:21], v[68:69], v[20:21] neg_lo:[0,1] neg_hi:[0,1]
	v_pk_add_f32 v[68:69], v[96:97], v[8:9]
	v_pk_add_f32 v[8:9], v[96:97], v[8:9] neg_lo:[0,1] neg_hi:[0,1]
	v_pk_add_f32 v[4:5], v[0:1], v[64:65]
	v_pk_add_f32 v[0:1], v[0:1], v[64:65] neg_lo:[0,1] neg_hi:[0,1]
	v_pk_add_f32 v[64:65], v[94:95], v[80:81]
	v_pk_add_f32 v[80:81], v[94:95], v[80:81] neg_lo:[0,1] neg_hi:[0,1]
	v_xor_b32_e32 v94, 0x80000000, v3
	v_mov_b32_e32 v95, v2
	v_pk_add_f32 v[96:97], v[86:87], v[16:17]
	v_pk_add_f32 v[16:17], v[86:87], v[16:17] neg_lo:[0,1] neg_hi:[0,1]
	v_pk_add_f32 v[86:87], v[82:83], v[6:7]
	v_pk_add_f32 v[6:7], v[82:83], v[6:7] neg_lo:[0,1] neg_hi:[0,1]
	v_pk_add_f32 v[2:3], v[10:11], v[94:95]
	v_pk_add_f32 v[10:11], v[10:11], v[94:95] neg_lo:[0,1] neg_hi:[0,1]
	v_pk_add_f32 v[94:95], v[70:71], v[68:69]
	v_pk_add_f32 v[68:69], v[70:71], v[68:69] neg_lo:[0,1] neg_hi:[0,1]
	v_xor_b32_e32 v70, 0x80000000, v9
	v_mov_b32_e32 v71, v8
	v_pk_add_f32 v[82:83], v[24:25], v[78:79]
	v_pk_add_f32 v[24:25], v[24:25], v[78:79] neg_lo:[0,1] neg_hi:[0,1]
	v_pk_add_f32 v[78:79], v[74:75], v[18:19]
	v_pk_add_f32 v[18:19], v[74:75], v[18:19] neg_lo:[0,1] neg_hi:[0,1]
	v_pk_add_f32 v[8:9], v[20:21], v[70:71]
	v_pk_add_f32 v[20:21], v[20:21], v[70:71] neg_lo:[0,1] neg_hi:[0,1]
	v_pk_add_f32 v[70:71], v[96:97], v[86:87]
	v_pk_add_f32 v[86:87], v[96:97], v[86:87] neg_lo:[0,1] neg_hi:[0,1]
	v_xor_b32_e32 v96, 0x80000000, v7
	v_mov_b32_e32 v97, v6
	v_pk_add_f32 v[74:75], v[76:77], v[72:73]
	v_pk_add_f32 v[72:73], v[76:77], v[72:73] neg_lo:[0,1] neg_hi:[0,1]
	v_pk_add_f32 v[76:77], v[130:131], v[14:15]
	v_pk_add_f32 v[14:15], v[130:131], v[14:15] neg_lo:[0,1] neg_hi:[0,1]
	v_pk_add_f32 v[6:7], v[16:17], v[96:97]
	v_pk_add_f32 v[16:17], v[16:17], v[96:97] neg_lo:[0,1] neg_hi:[0,1]
	v_pk_add_f32 v[96:97], v[82:83], v[78:79]
	v_pk_add_f32 v[78:79], v[82:83], v[78:79] neg_lo:[0,1] neg_hi:[0,1]
	v_xor_b32_e32 v82, 0x80000000, v19
	v_mov_b32_e32 v83, v18
	v_pk_add_f32 v[130:131], v[62:63], v[92:93]
	v_pk_add_f32 v[62:63], v[62:63], v[92:93] neg_lo:[0,1] neg_hi:[0,1]
	v_pk_add_f32 v[92:93], v[90:91], v[26:27]
	v_pk_add_f32 v[26:27], v[90:91], v[26:27] neg_lo:[0,1] neg_hi:[0,1]
	v_pk_add_f32 v[18:19], v[24:25], v[82:83]
	v_pk_add_f32 v[24:25], v[24:25], v[82:83] neg_lo:[0,1] neg_hi:[0,1]
	v_pk_add_f32 v[82:83], v[74:75], v[76:77]
	v_pk_add_f32 v[74:75], v[74:75], v[76:77] neg_lo:[0,1] neg_hi:[0,1]
	v_xor_b32_e32 v76, 0x80000000, v15
	v_mov_b32_e32 v77, v14
	v_pk_add_f32 v[90:91], v[84:85], v[88:89]
	v_pk_add_f32 v[84:85], v[84:85], v[88:89] neg_lo:[0,1] neg_hi:[0,1]
	v_pk_add_f32 v[88:89], v[134:135], v[22:23]
	v_pk_add_f32 v[22:23], v[134:135], v[22:23] neg_lo:[0,1] neg_hi:[0,1]
	v_pk_add_f32 v[14:15], v[72:73], v[76:77]
	v_pk_add_f32 v[72:73], v[72:73], v[76:77] neg_lo:[0,1] neg_hi:[0,1]
	v_pk_add_f32 v[76:77], v[130:131], v[92:93]
	v_pk_add_f32 v[92:93], v[130:131], v[92:93] neg_lo:[0,1] neg_hi:[0,1]
	v_xor_b32_e32 v130, 0x80000000, v27
	v_mov_b32_e32 v131, v26
	v_pk_add_f32 v[26:27], v[62:63], v[130:131]
	v_pk_add_f32 v[62:63], v[62:63], v[130:131] neg_lo:[0,1] neg_hi:[0,1]
	v_pk_add_f32 v[130:131], v[90:91], v[88:89]
	v_pk_add_f32 v[88:89], v[90:91], v[88:89] neg_lo:[0,1] neg_hi:[0,1]
	v_xor_b32_e32 v90, 0x80000000, v23
	v_mov_b32_e32 v91, v22
	v_pk_add_f32 v[22:23], v[84:85], v[90:91]
	v_pk_add_f32 v[84:85], v[84:85], v[90:91] neg_lo:[0,1] neg_hi:[0,1]
	v_pk_add_f32 v[90:91], v[132:133], v[64:65]
	v_pk_add_f32 v[64:65], v[132:133], v[64:65] neg_lo:[0,1] neg_hi:[0,1]
	v_pk_mul_f32 v[132:133], v[2:3], s[60:61] op_sel:[1,0] op_sel_hi:[0,0] neg_lo:[1,0]
	v_xor_b32_e32 v134, 0x80000000, v11
	v_pk_fma_f32 v[2:3], v[2:3], s[60:61], v[132:133] op_sel_hi:[1,0,1]
	v_mov_b32_e32 v135, v10
	v_pk_add_f32 v[132:133], v[4:5], v[2:3]
	v_pk_add_f32 v[2:3], v[4:5], v[2:3] neg_lo:[0,1] neg_hi:[0,1]
	v_xor_b32_e32 v4, 0x80000000, v81
	v_mov_b32_e32 v5, v80
	v_pk_add_f32 v[80:81], v[12:13], v[4:5]
	v_pk_add_f32 v[4:5], v[12:13], v[4:5] neg_lo:[0,1] neg_hi:[0,1]
	v_pk_mul_f32 v[12:13], v[10:11], s[60:61] op_sel_hi:[1,0]
	s_nop 0
	v_pk_fma_f32 v[10:11], v[134:135], s[60:61], v[12:13] op_sel_hi:[1,0,1] neg_lo:[0,0,1] neg_hi:[0,0,1]
	v_xor_b32_e32 v134, 0x80000000, v17
	v_pk_add_f32 v[12:13], v[0:1], v[10:11]
	v_pk_add_f32 v[0:1], v[0:1], v[10:11] neg_lo:[0,1] neg_hi:[0,1]
	v_pk_add_f32 v[10:11], v[94:95], v[70:71]
	v_pk_add_f32 v[70:71], v[94:95], v[70:71] neg_lo:[0,1] neg_hi:[0,1]
	v_pk_mul_f32 v[94:95], v[6:7], s[60:61] op_sel:[1,0] op_sel_hi:[0,0] neg_lo:[1,0]
	v_mov_b32_e32 v135, v16
	v_pk_fma_f32 v[6:7], v[6:7], s[60:61], v[94:95] op_sel_hi:[1,0,1]
	s_nop 0
	v_pk_add_f32 v[94:95], v[8:9], v[6:7]
	v_pk_add_f32 v[6:7], v[8:9], v[6:7] neg_lo:[0,1] neg_hi:[0,1]
	v_xor_b32_e32 v8, 0x80000000, v87
	v_mov_b32_e32 v9, v86
	v_pk_add_f32 v[86:87], v[68:69], v[8:9]
	v_pk_add_f32 v[8:9], v[68:69], v[8:9] neg_lo:[0,1] neg_hi:[0,1]
	v_pk_mul_f32 v[68:69], v[16:17], s[60:61] op_sel_hi:[1,0]
	s_nop 0
	v_pk_fma_f32 v[16:17], v[134:135], s[60:61], v[68:69] op_sel_hi:[1,0,1] neg_lo:[0,0,1] neg_hi:[0,0,1]
	v_xor_b32_e32 v134, 0x80000000, v73
	v_pk_add_f32 v[68:69], v[20:21], v[16:17]
	v_pk_add_f32 v[16:17], v[20:21], v[16:17] neg_lo:[0,1] neg_hi:[0,1]
	v_pk_add_f32 v[20:21], v[96:97], v[82:83]
	v_pk_add_f32 v[82:83], v[96:97], v[82:83] neg_lo:[0,1] neg_hi:[0,1]
	v_pk_mul_f32 v[96:97], v[14:15], s[60:61] op_sel:[1,0] op_sel_hi:[0,0] neg_lo:[1,0]
	v_mov_b32_e32 v135, v72
	v_pk_fma_f32 v[14:15], v[14:15], s[60:61], v[96:97] op_sel_hi:[1,0,1]
	s_nop 0
	v_pk_add_f32 v[96:97], v[18:19], v[14:15]
	v_pk_add_f32 v[14:15], v[18:19], v[14:15] neg_lo:[0,1] neg_hi:[0,1]
	v_xor_b32_e32 v18, 0x80000000, v75
	v_mov_b32_e32 v19, v74
	v_pk_add_f32 v[74:75], v[78:79], v[18:19]
	v_pk_add_f32 v[18:19], v[78:79], v[18:19] neg_lo:[0,1] neg_hi:[0,1]
	v_pk_mul_f32 v[78:79], v[72:73], s[60:61] op_sel_hi:[1,0]
	s_nop 0
	v_pk_fma_f32 v[72:73], v[134:135], s[60:61], v[78:79] op_sel_hi:[1,0,1] neg_lo:[0,0,1] neg_hi:[0,0,1]
	v_xor_b32_e32 v134, 0x80000000, v85
	v_pk_add_f32 v[78:79], v[24:25], v[72:73]
	v_pk_add_f32 v[24:25], v[24:25], v[72:73] neg_lo:[0,1] neg_hi:[0,1]
	v_pk_add_f32 v[72:73], v[76:77], v[130:131]
	v_pk_add_f32 v[76:77], v[76:77], v[130:131] neg_lo:[0,1] neg_hi:[0,1]
	v_pk_mul_f32 v[130:131], v[22:23], s[60:61] op_sel:[1,0] op_sel_hi:[0,0] neg_lo:[1,0]
	v_mov_b32_e32 v135, v84
	v_pk_fma_f32 v[22:23], v[22:23], s[60:61], v[130:131] op_sel_hi:[1,0,1]
	s_nop 0
	v_pk_add_f32 v[130:131], v[26:27], v[22:23]
	v_pk_add_f32 v[22:23], v[26:27], v[22:23] neg_lo:[0,1] neg_hi:[0,1]
	v_xor_b32_e32 v26, 0x80000000, v89
	v_mov_b32_e32 v27, v88
	v_pk_add_f32 v[88:89], v[92:93], v[26:27]
	v_pk_add_f32 v[26:27], v[92:93], v[26:27] neg_lo:[0,1] neg_hi:[0,1]
	v_pk_mul_f32 v[92:93], v[84:85], s[60:61] op_sel_hi:[1,0]
	s_nop 0
	v_pk_fma_f32 v[84:85], v[134:135], s[60:61], v[92:93] op_sel_hi:[1,0,1] neg_lo:[0,0,1] neg_hi:[0,0,1]
	v_xor_b32_e32 v134, 0x80000000, v7
	v_pk_add_f32 v[92:93], v[62:63], v[84:85]
	v_pk_add_f32 v[62:63], v[62:63], v[84:85] neg_lo:[0,1] neg_hi:[0,1]
	v_pk_add_f32 v[84:85], v[90:91], v[10:11]
	v_pk_add_f32 v[10:11], v[90:91], v[10:11] neg_lo:[0,1] neg_hi:[0,1]
	v_pk_mul_f32 v[90:91], v[94:95], s[54:55] op_sel:[1,0] op_sel_hi:[0,0] neg_lo:[1,0]
	v_mov_b32_e32 v135, v6
	v_pk_fma_f32 v[90:91], v[94:95], s[52:53], v[90:91] op_sel_hi:[1,0,1]
	s_nop 0
	v_pk_add_f32 v[94:95], v[132:133], v[90:91]
	v_pk_add_f32 v[90:91], v[132:133], v[90:91] neg_lo:[0,1] neg_hi:[0,1]
	v_pk_mul_f32 v[132:133], v[86:87], s[60:61] op_sel:[1,0] op_sel_hi:[0,0] neg_lo:[1,0]
	s_nop 0
	v_pk_fma_f32 v[86:87], v[86:87], s[60:61], v[132:133] op_sel_hi:[1,0,1]
	s_nop 0
	v_pk_add_f32 v[132:133], v[80:81], v[86:87]
	v_pk_add_f32 v[80:81], v[80:81], v[86:87] neg_lo:[0,1] neg_hi:[0,1]
	v_pk_mul_f32 v[86:87], v[68:69], s[52:53] op_sel:[1,0] op_sel_hi:[0,0] neg_lo:[1,0]
	s_nop 0
	v_pk_fma_f32 v[68:69], v[68:69], s[54:55], v[86:87] op_sel_hi:[1,0,1]
	s_nop 0
	v_pk_add_f32 v[86:87], v[12:13], v[68:69]
	v_pk_add_f32 v[12:13], v[12:13], v[68:69] neg_lo:[0,1] neg_hi:[0,1]
	v_xor_b32_e32 v68, 0x80000000, v71
	v_mov_b32_e32 v69, v70
	v_pk_add_f32 v[70:71], v[64:65], v[68:69]
	v_pk_add_f32 v[64:65], v[64:65], v[68:69] neg_lo:[0,1] neg_hi:[0,1]
	v_pk_mul_f32 v[68:69], v[6:7], s[54:55] op_sel_hi:[1,0]
	s_nop 0
	v_pk_fma_f32 v[6:7], v[134:135], s[52:53], v[68:69] op_sel_hi:[1,0,1] neg_lo:[0,0,1] neg_hi:[0,0,1]
	v_xor_b32_e32 v134, 0x80000000, v9
	v_pk_add_f32 v[68:69], v[2:3], v[6:7]
	v_pk_add_f32 v[2:3], v[2:3], v[6:7] neg_lo:[0,1] neg_hi:[0,1]
	v_pk_mul_f32 v[6:7], v[8:9], s[60:61] op_sel_hi:[1,0]
	v_mov_b32_e32 v135, v8
	v_pk_fma_f32 v[6:7], v[134:135], s[60:61], v[6:7] op_sel_hi:[1,0,1] neg_lo:[0,0,1] neg_hi:[0,0,1]
	v_xor_b32_e32 v134, 0x80000000, v17
	v_pk_add_f32 v[8:9], v[4:5], v[6:7]
	v_pk_add_f32 v[4:5], v[4:5], v[6:7] neg_lo:[0,1] neg_hi:[0,1]
	v_pk_mul_f32 v[6:7], v[16:17], s[52:53] op_sel_hi:[1,0]
	v_mov_b32_e32 v135, v16
	v_pk_fma_f32 v[6:7], v[134:135], s[54:55], v[6:7] op_sel_hi:[1,0,1] neg_lo:[0,0,1] neg_hi:[0,0,1]
	v_xor_b32_e32 v134, 0x80000000, v23
	v_pk_add_f32 v[16:17], v[0:1], v[6:7]
	v_pk_add_f32 v[0:1], v[0:1], v[6:7] neg_lo:[0,1] neg_hi:[0,1]
	v_pk_add_f32 v[6:7], v[20:21], v[72:73]
	v_pk_add_f32 v[20:21], v[20:21], v[72:73] neg_lo:[0,1] neg_hi:[0,1]
	v_pk_mul_f32 v[72:73], v[130:131], s[54:55] op_sel:[1,0] op_sel_hi:[0,0] neg_lo:[1,0]
	v_mov_b32_e32 v135, v22
	v_pk_fma_f32 v[72:73], v[130:131], s[52:53], v[72:73] op_sel_hi:[1,0,1]
	s_nop 0
	v_pk_add_f32 v[130:131], v[96:97], v[72:73]
	v_pk_add_f32 v[72:73], v[96:97], v[72:73] neg_lo:[0,1] neg_hi:[0,1]
	v_pk_mul_f32 v[96:97], v[88:89], s[60:61] op_sel:[1,0] op_sel_hi:[0,0] neg_lo:[1,0]
	s_nop 0
	v_pk_fma_f32 v[88:89], v[88:89], s[60:61], v[96:97] op_sel_hi:[1,0,1]
	s_nop 0
	v_pk_add_f32 v[96:97], v[74:75], v[88:89]
	v_pk_add_f32 v[74:75], v[74:75], v[88:89] neg_lo:[0,1] neg_hi:[0,1]
	v_pk_mul_f32 v[88:89], v[92:93], s[52:53] op_sel:[1,0] op_sel_hi:[0,0] neg_lo:[1,0]
	s_nop 0
	v_pk_fma_f32 v[88:89], v[92:93], s[54:55], v[88:89] op_sel_hi:[1,0,1]
	s_nop 0
	v_pk_add_f32 v[92:93], v[78:79], v[88:89]
	v_pk_add_f32 v[78:79], v[78:79], v[88:89] neg_lo:[0,1] neg_hi:[0,1]
	v_xor_b32_e32 v88, 0x80000000, v77
	v_mov_b32_e32 v89, v76
	v_pk_add_f32 v[76:77], v[82:83], v[88:89]
	v_pk_add_f32 v[82:83], v[82:83], v[88:89] neg_lo:[0,1] neg_hi:[0,1]
	v_pk_mul_f32 v[88:89], v[22:23], s[54:55] op_sel_hi:[1,0]
	s_nop 0
	v_pk_fma_f32 v[22:23], v[134:135], s[52:53], v[88:89] op_sel_hi:[1,0,1] neg_lo:[0,0,1] neg_hi:[0,0,1]
	v_xor_b32_e32 v134, 0x80000000, v27
	v_pk_add_f32 v[88:89], v[14:15], v[22:23]
	v_pk_add_f32 v[14:15], v[14:15], v[22:23] neg_lo:[0,1] neg_hi:[0,1]
	v_pk_mul_f32 v[22:23], v[26:27], s[60:61] op_sel_hi:[1,0]
	v_mov_b32_e32 v135, v26
	v_pk_fma_f32 v[22:23], v[134:135], s[60:61], v[22:23] op_sel_hi:[1,0,1] neg_lo:[0,0,1] neg_hi:[0,0,1]
	v_xor_b32_e32 v134, 0x80000000, v63
	v_pk_add_f32 v[26:27], v[18:19], v[22:23]
	v_pk_add_f32 v[18:19], v[18:19], v[22:23] neg_lo:[0,1] neg_hi:[0,1]
	v_pk_mul_f32 v[22:23], v[62:63], s[52:53] op_sel_hi:[1,0]
	v_mov_b32_e32 v135, v62
	v_pk_fma_f32 v[22:23], v[134:135], s[54:55], v[22:23] op_sel_hi:[1,0,1] neg_lo:[0,0,1] neg_hi:[0,0,1]
	v_xor_b32_e32 v134, 0x80000000, v73
	v_pk_add_f32 v[62:63], v[24:25], v[22:23]
	v_pk_add_f32 v[22:23], v[24:25], v[22:23] neg_lo:[0,1] neg_hi:[0,1]
	v_pk_add_f32 v[24:25], v[84:85], v[6:7]
	v_pk_add_f32 v[6:7], v[84:85], v[6:7] neg_lo:[0,1] neg_hi:[0,1]
	v_pk_mul_f32 v[84:85], v[130:131], s[48:49] op_sel:[1,0] op_sel_hi:[0,0] neg_lo:[1,0]
	v_mov_b32_e32 v135, v72
	v_pk_fma_f32 v[84:85], v[130:131], s[44:45], v[84:85] op_sel_hi:[1,0,1]
	s_nop 0
	v_pk_add_f32 v[130:131], v[94:95], v[84:85]
	v_pk_add_f32 v[84:85], v[94:95], v[84:85] neg_lo:[0,1] neg_hi:[0,1]
	v_pk_mul_f32 v[94:95], v[96:97], s[54:55] op_sel:[1,0] op_sel_hi:[0,0] neg_lo:[1,0]
	s_nop 0
	v_pk_fma_f32 v[94:95], v[96:97], s[52:53], v[94:95] op_sel_hi:[1,0,1]
	s_nop 0
	v_pk_add_f32 v[96:97], v[132:133], v[94:95]
	v_pk_add_f32 v[94:95], v[132:133], v[94:95] neg_lo:[0,1] neg_hi:[0,1]
	v_pk_mul_f32 v[132:133], v[92:93], s[58:59] op_sel:[1,0] op_sel_hi:[0,0] neg_lo:[1,0]
	s_nop 0
	v_pk_fma_f32 v[92:93], v[92:93], s[56:57], v[132:133] op_sel_hi:[1,0,1]
	s_nop 0
	v_pk_add_f32 v[132:133], v[86:87], v[92:93]
	v_pk_add_f32 v[86:87], v[86:87], v[92:93] neg_lo:[0,1] neg_hi:[0,1]
	v_pk_mul_f32 v[92:93], v[76:77], s[60:61] op_sel:[1,0] op_sel_hi:[0,0] neg_lo:[1,0]
	s_nop 0
	v_pk_fma_f32 v[76:77], v[76:77], s[60:61], v[92:93] op_sel_hi:[1,0,1]
	s_nop 0
	v_pk_add_f32 v[92:93], v[70:71], v[76:77]
	v_pk_add_f32 v[70:71], v[70:71], v[76:77] neg_lo:[0,1] neg_hi:[0,1]
	v_pk_mul_f32 v[76:77], v[88:89], s[56:57] op_sel:[1,0] op_sel_hi:[0,0] neg_lo:[1,0]
	s_nop 0
	v_pk_fma_f32 v[76:77], v[88:89], s[58:59], v[76:77] op_sel_hi:[1,0,1]
	s_nop 0
	v_pk_add_f32 v[88:89], v[68:69], v[76:77]
	v_pk_add_f32 v[68:69], v[68:69], v[76:77] neg_lo:[0,1] neg_hi:[0,1]
	v_pk_mul_f32 v[76:77], v[26:27], s[52:53] op_sel:[1,0] op_sel_hi:[0,0] neg_lo:[1,0]
	s_nop 0
	v_pk_fma_f32 v[26:27], v[26:27], s[54:55], v[76:77] op_sel_hi:[1,0,1]
	s_nop 0
	v_pk_add_f32 v[76:77], v[8:9], v[26:27]
	v_pk_add_f32 v[8:9], v[8:9], v[26:27] neg_lo:[0,1] neg_hi:[0,1]
	v_pk_mul_f32 v[26:27], v[62:63], s[44:45] op_sel:[1,0] op_sel_hi:[0,0] neg_lo:[1,0]
	s_nop 0
	v_pk_fma_f32 v[26:27], v[62:63], s[48:49], v[26:27] op_sel_hi:[1,0,1]
	s_nop 0
	v_pk_add_f32 v[62:63], v[16:17], v[26:27]
	v_pk_add_f32 v[16:17], v[16:17], v[26:27] neg_lo:[0,1] neg_hi:[0,1]
	v_xor_b32_e32 v26, 0x80000000, v21
	v_mov_b32_e32 v27, v20
	v_pk_add_f32 v[20:21], v[10:11], v[26:27]
	v_pk_add_f32 v[10:11], v[10:11], v[26:27] neg_lo:[0,1] neg_hi:[0,1]
	v_pk_mul_f32 v[26:27], v[72:73], s[48:49] op_sel_hi:[1,0]
	s_nop 0
	v_pk_fma_f32 v[26:27], v[134:135], s[44:45], v[26:27] op_sel_hi:[1,0,1] neg_lo:[0,0,1] neg_hi:[0,0,1]
	v_xor_b32_e32 v134, 0x80000000, v75
	v_pk_add_f32 v[72:73], v[90:91], v[26:27]
	v_pk_add_f32 v[26:27], v[90:91], v[26:27] neg_lo:[0,1] neg_hi:[0,1]
	v_pk_mul_f32 v[90:91], v[74:75], s[54:55] op_sel_hi:[1,0]
	v_mov_b32_e32 v135, v74
	v_pk_fma_f32 v[74:75], v[134:135], s[52:53], v[90:91] op_sel_hi:[1,0,1] neg_lo:[0,0,1] neg_hi:[0,0,1]
	v_xor_b32_e32 v134, 0x80000000, v79
	v_pk_add_f32 v[90:91], v[80:81], v[74:75]
	v_pk_add_f32 v[74:75], v[80:81], v[74:75] neg_lo:[0,1] neg_hi:[0,1]
	v_pk_mul_f32 v[80:81], v[78:79], s[58:59] op_sel_hi:[1,0]
	v_mov_b32_e32 v135, v78
	v_pk_fma_f32 v[78:79], v[134:135], s[56:57], v[80:81] op_sel_hi:[1,0,1] neg_lo:[0,0,1] neg_hi:[0,0,1]
	v_xor_b32_e32 v134, 0x80000000, v83
	v_pk_add_f32 v[80:81], v[12:13], v[78:79]
	v_pk_add_f32 v[12:13], v[12:13], v[78:79] neg_lo:[0,1] neg_hi:[0,1]
	v_pk_mul_f32 v[78:79], v[82:83], s[60:61] op_sel_hi:[1,0]
	v_mov_b32_e32 v135, v82
	v_pk_fma_f32 v[78:79], v[134:135], s[60:61], v[78:79] op_sel_hi:[1,0,1] neg_lo:[0,0,1] neg_hi:[0,0,1]
	v_xor_b32_e32 v134, 0x80000000, v15
	v_pk_add_f32 v[82:83], v[64:65], v[78:79]
	v_pk_add_f32 v[64:65], v[64:65], v[78:79] neg_lo:[0,1] neg_hi:[0,1]
	v_pk_mul_f32 v[78:79], v[14:15], s[56:57] op_sel_hi:[1,0]
	v_mov_b32_e32 v135, v14
	v_pk_fma_f32 v[14:15], v[134:135], s[58:59], v[78:79] op_sel_hi:[1,0,1] neg_lo:[0,0,1] neg_hi:[0,0,1]
	v_xor_b32_e32 v134, 0x80000000, v19
	v_pk_add_f32 v[78:79], v[2:3], v[14:15]
	v_pk_add_f32 v[2:3], v[2:3], v[14:15] neg_lo:[0,1] neg_hi:[0,1]
	v_pk_mul_f32 v[14:15], v[18:19], s[52:53] op_sel_hi:[1,0]
	v_mov_b32_e32 v135, v18
	v_pk_fma_f32 v[14:15], v[134:135], s[54:55], v[14:15] op_sel_hi:[1,0,1] neg_lo:[0,0,1] neg_hi:[0,0,1]
	v_xor_b32_e32 v134, 0x80000000, v23
	v_pk_add_f32 v[18:19], v[4:5], v[14:15]
	v_pk_add_f32 v[4:5], v[4:5], v[14:15] neg_lo:[0,1] neg_hi:[0,1]
	v_pk_mul_f32 v[14:15], v[22:23], s[44:45] op_sel_hi:[1,0]
	v_mov_b32_e32 v135, v22
	v_pk_fma_f32 v[14:15], v[134:135], s[48:49], v[14:15] op_sel_hi:[1,0,1] neg_lo:[0,0,1] neg_hi:[0,0,1]
	s_nop 0
	v_pk_add_f32 v[22:23], v[0:1], v[14:15]
	v_pk_add_f32 v[0:1], v[0:1], v[14:15] neg_lo:[0,1] neg_hi:[0,1]
	ds_write_b64 v67, v[24:25]
	ds_write_b64 v98, v[130:131]
	ds_write_b64 v99, v[96:97] offset:256
	ds_write_b64 v100, v[132:133] offset:256
	ds_write_b64 v101, v[92:93] offset:512
	ds_write_b64 v102, v[88:89] offset:512
	ds_write_b64 v103, v[76:77] offset:768
	ds_write_b64 v104, v[62:63] offset:768
	ds_write_b64 v105, v[20:21] offset:1024
	ds_write_b64 v106, v[72:73] offset:1024
	ds_write_b64 v107, v[90:91] offset:1280
	ds_write_b64 v108, v[80:81] offset:1280
	ds_write_b64 v109, v[82:83] offset:1536
	ds_write_b64 v110, v[78:79] offset:1536
	ds_write_b64 v111, v[18:19] offset:1792
	ds_write_b64 v112, v[22:23] offset:1792
	ds_write_b64 v113, v[6:7] offset:2048
	ds_write_b64 v114, v[84:85] offset:2048
	ds_write_b64 v115, v[94:95] offset:2304
	ds_write_b64 v116, v[86:87] offset:2304
	ds_write_b64 v117, v[70:71] offset:2560
	ds_write_b64 v118, v[68:69] offset:2560
	ds_write_b64 v119, v[8:9] offset:2816
	ds_write_b64 v120, v[16:17] offset:2816
	ds_write_b64 v121, v[10:11] offset:3072
	ds_write_b64 v122, v[26:27] offset:3072
	ds_write_b64 v123, v[74:75] offset:3328
	ds_write_b64 v124, v[12:13] offset:3328
	ds_write_b64 v125, v[64:65] offset:3584
	ds_write_b64 v126, v[2:3] offset:3584
	ds_write_b64 v127, v[4:5] offset:3840
	ds_write_b64 v128, v[0:1] offset:3840
	v_mov_b32_e32 v74, v146
	s_waitcnt lgkmcnt(0)
	s_barrier
	s_nop 0
	v_lshrrev_b32_e32 v0, 5, v74
	v_bfe_u32 v4, v74, 5, 4
	v_bitop3_b32 v0, v0, v74, 15 bitop3:0x6c
	v_bitop3_b32 v4, v4, v74, 16 bitop3:0x36
	v_lshlrev_b32_e32 v66, 3, v0
	v_lshlrev_b32_e32 v67, 3, v4
	v_add_u32_e32 v5, 16, v66
	v_add_u32_e32 v4, 16, v67
	v_add_u32_e32 v62, s79, v66
	v_add_u32_e32 v70, s9, v66
	ds_read2st64_b64 v[0:3], v5 offset1:16
	ds_read2st64_b64 v[16:19], v4 offset0:8 offset1:24
	ds_read2st64_b64 v[24:27], v5 offset0:32 offset1:48
	ds_read2st64_b64 v[8:11], v4 offset0:40 offset1:56
	ds_read2st64_b64 v[92:95], v5 offset0:64 offset1:80
	ds_read2st64_b64 v[12:15], v4 offset0:72 offset1:88
	ds_read2st64_b64 v[20:23], v5 offset0:96 offset1:112
	ds_read2st64_b64 v[4:7], v4 offset0:104 offset1:120
	ds_read_b64 v[68:69], v62
	ds_read_b64 v[72:73], v70
	v_add_u32_e32 v62, s19, v67
	v_add_u32_e32 v70, s8, v67
	ds_read_b64 v[84:85], v62
	ds_read_b64 v[90:91], v70
	v_add_u32_e32 v62, s18, v66
	v_add_u32_e32 v70, s7, v66
	ds_read_b64 v[96:97], v62
	ds_read_b64 v[100:101], v70
	v_add_u32_e32 v62, s17, v67
	v_add_u32_e32 v70, s6, v67
	ds_read_b64 v[64:65], v62
	ds_read_b64 v[70:71], v70
	v_add_u32_e32 v62, s13, v66
	v_add_u32_e32 v75, s5, v66
	ds_read_b64 v[86:87], v62
	ds_read_b64 v[102:103], v75
	v_add_u32_e32 v62, s12, v67
	v_add_u32_e32 v75, s4, v67
	ds_read_b64 v[80:81], v62
	ds_read_b64 v[88:89], v75
	v_add_u32_e32 v62, s11, v66
	v_add_u32_e32 v66, s1, v66
	ds_read_b64 v[98:99], v62
	ds_read_b64 v[104:105], v66
	v_add_u32_e32 v62, s10, v67
	v_add_u32_e32 v66, s0, v67
	ds_read_b64 v[62:63], v62
	ds_read_b64 v[66:67], v66
	s_waitcnt lgkmcnt(14)
	s_nop 0
	v_cvt_f32_i32_e32 v74, v74
	s_nop 0
	s_lshl_b64 s[0:1], s[42:43], 2
	s_add_u32 s0, s45, s0
	v_mul_f32_e32 v74, 0x38800000, v74
	v_cos_f32_e32 v78, v74
	v_sin_f32_e32 v79, v74
	s_addc_u32 s1, s24, s1
	s_and_b64 vcc, s[14:15], exec
	v_add_f32_e32 v76, v78, v78
	v_pk_mul_f32 v[74:75], v[78:79], v[78:79]
	v_mul_f32_e32 v76, v79, v76
	s_nop 0
	s_nop 0
	v_mov_b32_e32 v108, v79
	v_pk_add_f32 v[74:75], v[74:75], v[74:75] op_sel:[0,1] op_sel_hi:[0,1] neg_lo:[0,1] neg_hi:[0,1]
	v_pk_mul_f32 v[82:83], v[78:79], v[76:77] op_sel:[1,0] op_sel_hi:[0,0] neg_lo:[1,0]
	v_pk_mul_f32 v[106:107], v[68:69], v[108:109] op_sel:[1,0] op_sel_hi:[0,0] neg_lo:[1,0]
	v_pk_fma_f32 v[82:83], v[78:79], v[74:75], v[82:83]
	v_pk_fma_f32 v[68:69], v[68:69], v[78:79], v[106:107] op_sel_hi:[1,0,1]
	v_pk_mul_f32 v[78:79], v[76:77], s[46:47] op_sel_hi:[0,1]
	v_pk_fma_f32 v[106:107], v[74:75], s[40:41], v[78:79]
	s_nop 0
	v_pk_mul_f32 v[78:79], v[92:93], v[106:107] op_sel:[1,1] op_sel_hi:[0,1] neg_lo:[1,0]
	s_nop 0
	v_pk_fma_f32 v[78:79], v[92:93], v[106:107], v[78:79] op_sel_hi:[1,0,1]
	v_pk_mul_f32 v[92:93], v[76:77], v[82:83] op_sel:[0,1] op_sel_hi:[0,0] neg_lo:[0,1]
	v_pk_mul_f32 v[108:109], v[72:73], v[82:83] op_sel:[1,1] op_sel_hi:[0,1] neg_lo:[1,0]
	v_pk_fma_f32 v[92:93], v[74:75], v[82:83], v[92:93]
	v_pk_fma_f32 v[72:73], v[72:73], v[82:83], v[108:109] op_sel_hi:[1,0,1]
	v_pk_mul_f32 v[82:83], v[76:77], v[106:107] op_sel:[0,1] op_sel_hi:[0,0] neg_lo:[0,1]
	v_pk_fma_f32 v[106:107], v[74:75], v[106:107], v[82:83]
	s_nop 0
	v_pk_mul_f32 v[82:83], v[24:25], v[106:107] op_sel:[1,1] op_sel_hi:[0,1] neg_lo:[1,0]
	s_nop 0
	v_pk_fma_f32 v[82:83], v[24:25], v[106:107], v[82:83] op_sel_hi:[1,0,1]
	v_pk_mul_f32 v[24:25], v[76:77], v[92:93] op_sel:[0,1] op_sel_hi:[0,0] neg_lo:[0,1]
	v_pk_fma_f32 v[108:109], v[74:75], v[92:93], v[24:25]
	s_waitcnt lgkmcnt(7)
	v_pk_mul_f32 v[24:25], v[86:87], v[92:93] op_sel:[1,1] op_sel_hi:[0,1] neg_lo:[1,0]
	s_nop 0
	v_pk_fma_f32 v[24:25], v[86:87], v[92:93], v[24:25] op_sel_hi:[1,0,1]
	v_pk_mul_f32 v[86:87], v[76:77], v[106:107] op_sel:[0,1] op_sel_hi:[0,0] neg_lo:[0,1]
	v_pk_fma_f32 v[92:93], v[74:75], v[106:107], v[86:87]
	s_nop 0
	v_pk_mul_f32 v[86:87], v[20:21], v[92:93] op_sel:[1,1] op_sel_hi:[0,1] neg_lo:[1,0]
	s_nop 0
	v_pk_fma_f32 v[86:87], v[20:21], v[92:93], v[86:87] op_sel_hi:[1,0,1]
	v_pk_mul_f32 v[20:21], v[76:77], v[108:109] op_sel:[0,1] op_sel_hi:[0,0] neg_lo:[0,1]
	v_pk_fma_f32 v[106:107], v[74:75], v[108:109], v[20:21]
	s_waitcnt lgkmcnt(6)
	v_pk_mul_f32 v[20:21], v[102:103], v[108:109] op_sel:[1,1] op_sel_hi:[0,1] neg_lo:[1,0]
	s_nop 0
	v_pk_fma_f32 v[20:21], v[102:103], v[108:109], v[20:21] op_sel_hi:[1,0,1]
	v_pk_mul_f32 v[102:103], v[76:77], v[92:93] op_sel:[0,1] op_sel_hi:[0,0] neg_lo:[0,1]
	v_pk_fma_f32 v[102:103], v[74:75], v[92:93], v[102:103]
	s_nop 0
	v_pk_mul_f32 v[92:93], v[2:3], v[102:103] op_sel:[1,1] op_sel_hi:[0,1] neg_lo:[1,0]
	s_nop 0
	v_pk_fma_f32 v[92:93], v[2:3], v[102:103], v[92:93] op_sel_hi:[1,0,1]
	v_pk_mul_f32 v[2:3], v[76:77], v[106:107] op_sel:[0,1] op_sel_hi:[0,0] neg_lo:[0,1]
	v_pk_fma_f32 v[108:109], v[74:75], v[106:107], v[2:3]
	v_pk_mul_f32 v[2:3], v[96:97], v[106:107] op_sel:[1,1] op_sel_hi:[0,1] neg_lo:[1,0]
	s_nop 0
	v_pk_fma_f32 v[2:3], v[96:97], v[106:107], v[2:3] op_sel_hi:[1,0,1]
	v_pk_mul_f32 v[96:97], v[76:77], v[102:103] op_sel:[0,1] op_sel_hi:[0,0] neg_lo:[0,1]
	v_pk_fma_f32 v[102:103], v[74:75], v[102:103], v[96:97]
	s_nop 0
	v_pk_mul_f32 v[96:97], v[94:95], v[102:103] op_sel:[1,1] op_sel_hi:[0,1] neg_lo:[1,0]
	s_nop 0
	v_pk_fma_f32 v[96:97], v[94:95], v[102:103], v[96:97] op_sel_hi:[1,0,1]
	v_pk_mul_f32 v[94:95], v[76:77], v[108:109] op_sel:[0,1] op_sel_hi:[0,0] neg_lo:[0,1]
	v_pk_fma_f32 v[106:107], v[74:75], v[108:109], v[94:95]
	v_pk_mul_f32 v[94:95], v[100:101], v[108:109] op_sel:[1,1] op_sel_hi:[0,1] neg_lo:[1,0]
	s_nop 0
	v_pk_fma_f32 v[94:95], v[100:101], v[108:109], v[94:95] op_sel_hi:[1,0,1]
	v_pk_mul_f32 v[100:101], v[76:77], v[102:103] op_sel:[0,1] op_sel_hi:[0,0] neg_lo:[0,1]
	v_pk_fma_f32 v[100:101], v[74:75], v[102:103], v[100:101]
	s_nop 0
	v_pk_mul_f32 v[102:103], v[26:27], v[100:101] op_sel:[1,1] op_sel_hi:[0,1] neg_lo:[1,0]
	s_waitcnt lgkmcnt(3)
	v_pk_fma_f32 v[26:27], v[26:27], v[100:101], v[102:103] op_sel_hi:[1,0,1]
	v_pk_mul_f32 v[102:103], v[76:77], v[106:107] op_sel:[0,1] op_sel_hi:[0,0] neg_lo:[0,1]
	v_pk_mul_f32 v[108:109], v[98:99], v[106:107] op_sel:[1,1] op_sel_hi:[0,1] neg_lo:[1,0]
	v_pk_fma_f32 v[102:103], v[74:75], v[106:107], v[102:103]
	v_pk_fma_f32 v[98:99], v[98:99], v[106:107], v[108:109] op_sel_hi:[1,0,1]
	v_pk_mul_f32 v[106:107], v[76:77], v[100:101] op_sel:[0,1] op_sel_hi:[0,0] neg_lo:[0,1]
	v_pk_fma_f32 v[100:101], v[74:75], v[100:101], v[106:107]
	s_nop 0
	v_pk_mul_f32 v[106:107], v[22:23], v[100:101] op_sel:[1,1] op_sel_hi:[0,1] neg_lo:[1,0]
	s_waitcnt lgkmcnt(2)
	v_pk_fma_f32 v[22:23], v[22:23], v[100:101], v[106:107] op_sel_hi:[1,0,1]
	v_pk_mul_f32 v[106:107], v[76:77], v[102:103] op_sel:[0,1] op_sel_hi:[0,0] neg_lo:[0,1]
	v_pk_mul_f32 v[108:109], v[104:105], v[102:103] op_sel:[1,1] op_sel_hi:[0,1] neg_lo:[1,0]
	v_pk_fma_f32 v[106:107], v[74:75], v[102:103], v[106:107]
	v_pk_fma_f32 v[102:103], v[104:105], v[102:103], v[108:109] op_sel_hi:[1,0,1]
	v_pk_mul_f32 v[104:105], v[76:77], v[100:101] op_sel:[0,1] op_sel_hi:[0,0] neg_lo:[0,1]
	v_pk_fma_f32 v[100:101], v[74:75], v[100:101], v[104:105]
	s_nop 0
	v_pk_mul_f32 v[104:105], v[16:17], v[100:101] op_sel:[1,1] op_sel_hi:[0,1] neg_lo:[1,0]
	s_nop 0
	v_pk_fma_f32 v[16:17], v[16:17], v[100:101], v[104:105] op_sel_hi:[1,0,1]
	v_pk_mul_f32 v[104:105], v[76:77], v[106:107] op_sel:[0,1] op_sel_hi:[0,0] neg_lo:[0,1]
	v_pk_mul_f32 v[108:109], v[84:85], v[106:107] op_sel:[1,1] op_sel_hi:[0,1] neg_lo:[1,0]
	v_pk_fma_f32 v[104:105], v[74:75], v[106:107], v[104:105]
	v_pk_fma_f32 v[84:85], v[84:85], v[106:107], v[108:109] op_sel_hi:[1,0,1]
	v_pk_mul_f32 v[106:107], v[76:77], v[100:101] op_sel:[0,1] op_sel_hi:[0,0] neg_lo:[0,1]
	v_pk_fma_f32 v[100:101], v[74:75], v[100:101], v[106:107]
	s_nop 0
	v_pk_mul_f32 v[106:107], v[12:13], v[100:101] op_sel:[1,1] op_sel_hi:[0,1] neg_lo:[1,0]
	s_nop 0
	v_pk_fma_f32 v[12:13], v[12:13], v[100:101], v[106:107] op_sel_hi:[1,0,1]
	v_pk_mul_f32 v[106:107], v[76:77], v[104:105] op_sel:[0,1] op_sel_hi:[0,0] neg_lo:[0,1]
	v_pk_mul_f32 v[108:109], v[90:91], v[104:105] op_sel:[1,1] op_sel_hi:[0,1] neg_lo:[1,0]
	v_pk_fma_f32 v[106:107], v[74:75], v[104:105], v[106:107]
	v_pk_fma_f32 v[90:91], v[90:91], v[104:105], v[108:109] op_sel_hi:[1,0,1]
	v_pk_mul_f32 v[104:105], v[76:77], v[100:101] op_sel:[0,1] op_sel_hi:[0,0] neg_lo:[0,1]
	v_pk_fma_f32 v[100:101], v[74:75], v[100:101], v[104:105]
	s_nop 0
	v_pk_mul_f32 v[104:105], v[8:9], v[100:101] op_sel:[1,1] op_sel_hi:[0,1] neg_lo:[1,0]
	s_nop 0
	v_pk_fma_f32 v[8:9], v[8:9], v[100:101], v[104:105] op_sel_hi:[1,0,1]
	v_pk_mul_f32 v[104:105], v[76:77], v[106:107] op_sel:[0,1] op_sel_hi:[0,0] neg_lo:[0,1]
	v_pk_mul_f32 v[108:109], v[80:81], v[106:107] op_sel:[1,1] op_sel_hi:[0,1] neg_lo:[1,0]
	v_pk_fma_f32 v[104:105], v[74:75], v[106:107], v[104:105]
	v_pk_fma_f32 v[80:81], v[80:81], v[106:107], v[108:109] op_sel_hi:[1,0,1]
	v_pk_mul_f32 v[106:107], v[76:77], v[100:101] op_sel:[0,1] op_sel_hi:[0,0] neg_lo:[0,1]
	v_pk_fma_f32 v[100:101], v[74:75], v[100:101], v[106:107]
	s_nop 0
	v_pk_mul_f32 v[106:107], v[4:5], v[100:101] op_sel:[1,1] op_sel_hi:[0,1] neg_lo:[1,0]
	s_nop 0
	v_pk_fma_f32 v[4:5], v[4:5], v[100:101], v[106:107] op_sel_hi:[1,0,1]
	v_pk_mul_f32 v[106:107], v[76:77], v[104:105] op_sel:[0,1] op_sel_hi:[0,0] neg_lo:[0,1]
	v_pk_mul_f32 v[108:109], v[88:89], v[104:105] op_sel:[1,1] op_sel_hi:[0,1] neg_lo:[1,0]
	v_pk_fma_f32 v[106:107], v[74:75], v[104:105], v[106:107]
	v_pk_fma_f32 v[88:89], v[88:89], v[104:105], v[108:109] op_sel_hi:[1,0,1]
	v_pk_mul_f32 v[104:105], v[76:77], v[100:101] op_sel:[0,1] op_sel_hi:[0,0] neg_lo:[0,1]
	v_pk_fma_f32 v[100:101], v[74:75], v[100:101], v[104:105]
	s_nop 0
	v_pk_mul_f32 v[104:105], v[18:19], v[100:101] op_sel:[1,1] op_sel_hi:[0,1] neg_lo:[1,0]
	s_nop 0
	v_pk_fma_f32 v[18:19], v[18:19], v[100:101], v[104:105] op_sel_hi:[1,0,1]
	v_pk_mul_f32 v[104:105], v[76:77], v[106:107] op_sel:[0,1] op_sel_hi:[0,0] neg_lo:[0,1]
	v_pk_mul_f32 v[108:109], v[64:65], v[106:107] op_sel:[1,1] op_sel_hi:[0,1] neg_lo:[1,0]
	v_pk_fma_f32 v[104:105], v[74:75], v[106:107], v[104:105]
	v_pk_fma_f32 v[64:65], v[64:65], v[106:107], v[108:109] op_sel_hi:[1,0,1]
	v_pk_mul_f32 v[106:107], v[76:77], v[100:101] op_sel:[0,1] op_sel_hi:[0,0] neg_lo:[0,1]
	v_pk_fma_f32 v[100:101], v[74:75], v[100:101], v[106:107]
	s_nop 0
	v_pk_mul_f32 v[106:107], v[14:15], v[100:101] op_sel:[1,1] op_sel_hi:[0,1] neg_lo:[1,0]
	s_nop 0
	v_pk_fma_f32 v[14:15], v[14:15], v[100:101], v[106:107] op_sel_hi:[1,0,1]
	v_pk_mul_f32 v[106:107], v[76:77], v[104:105] op_sel:[0,1] op_sel_hi:[0,0] neg_lo:[0,1]
	v_pk_mul_f32 v[108:109], v[70:71], v[104:105] op_sel:[1,1] op_sel_hi:[0,1] neg_lo:[1,0]
	v_pk_fma_f32 v[106:107], v[74:75], v[104:105], v[106:107]
	v_pk_fma_f32 v[70:71], v[70:71], v[104:105], v[108:109] op_sel_hi:[1,0,1]
	v_pk_mul_f32 v[104:105], v[76:77], v[100:101] op_sel:[0,1] op_sel_hi:[0,0] neg_lo:[0,1]
	v_pk_fma_f32 v[100:101], v[74:75], v[100:101], v[104:105]
	s_nop 0
	v_pk_mul_f32 v[104:105], v[10:11], v[100:101] op_sel:[1,1] op_sel_hi:[0,1] neg_lo:[1,0]
	s_waitcnt lgkmcnt(1)
	v_pk_fma_f32 v[10:11], v[10:11], v[100:101], v[104:105] op_sel_hi:[1,0,1]
	v_pk_mul_f32 v[104:105], v[76:77], v[106:107] op_sel:[0,1] op_sel_hi:[0,0] neg_lo:[0,1]
	v_pk_mul_f32 v[108:109], v[62:63], v[106:107] op_sel:[1,1] op_sel_hi:[0,1] neg_lo:[1,0]
	v_pk_fma_f32 v[104:105], v[74:75], v[106:107], v[104:105]
	v_pk_fma_f32 v[62:63], v[62:63], v[106:107], v[108:109] op_sel_hi:[1,0,1]
	v_pk_mul_f32 v[76:77], v[76:77], v[100:101] op_sel:[0,1] op_sel_hi:[0,0] neg_lo:[0,1]
	v_pk_fma_f32 v[74:75], v[74:75], v[100:101], v[76:77]
	s_nop 0
	v_pk_mul_f32 v[76:77], v[6:7], v[74:75] op_sel:[1,1] op_sel_hi:[0,1] neg_lo:[1,0]
	s_nop 0
	v_pk_fma_f32 v[6:7], v[6:7], v[74:75], v[76:77] op_sel_hi:[1,0,1]
	s_waitcnt lgkmcnt(0)
	v_pk_mul_f32 v[74:75], v[66:67], v[104:105] op_sel:[1,1] op_sel_hi:[0,1] neg_lo:[1,0]
	v_pk_add_f32 v[76:77], v[82:83], v[8:9]
	v_pk_fma_f32 v[66:67], v[66:67], v[104:105], v[74:75] op_sel_hi:[1,0,1]
	v_pk_add_f32 v[74:75], v[0:1], v[16:17]
	v_pk_add_f32 v[0:1], v[0:1], v[16:17] neg_lo:[0,1] neg_hi:[0,1]
	v_pk_add_f32 v[16:17], v[92:93], v[18:19]
	v_pk_add_f32 v[18:19], v[92:93], v[18:19] neg_lo:[0,1] neg_hi:[0,1]
	v_pk_add_f32 v[8:9], v[82:83], v[8:9] neg_lo:[0,1] neg_hi:[0,1]
	v_pk_add_f32 v[82:83], v[26:27], v[10:11]
	v_pk_add_f32 v[10:11], v[26:27], v[10:11] neg_lo:[0,1] neg_hi:[0,1]
	v_pk_add_f32 v[92:93], v[86:87], v[4:5]
	v_pk_add_f32 v[4:5], v[86:87], v[4:5] neg_lo:[0,1] neg_hi:[0,1]
	v_pk_add_f32 v[86:87], v[22:23], v[6:7]
	v_pk_add_f32 v[6:7], v[22:23], v[6:7] neg_lo:[0,1] neg_hi:[0,1]
	v_pk_add_f32 v[22:23], v[68:69], v[84:85]
	v_pk_add_f32 v[68:69], v[68:69], v[84:85] neg_lo:[0,1] neg_hi:[0,1]
	v_pk_add_f32 v[84:85], v[2:3], v[64:65]
	v_pk_add_f32 v[2:3], v[2:3], v[64:65] neg_lo:[0,1] neg_hi:[0,1]
	v_pk_add_f32 v[64:65], v[24:25], v[80:81]
	v_pk_add_f32 v[24:25], v[24:25], v[80:81] neg_lo:[0,1] neg_hi:[0,1]
	v_pk_add_f32 v[80:81], v[98:99], v[62:63]
	v_pk_add_f32 v[62:63], v[98:99], v[62:63] neg_lo:[0,1] neg_hi:[0,1]
	v_pk_add_f32 v[98:99], v[74:75], v[16:17]
	v_pk_add_f32 v[16:17], v[74:75], v[16:17] neg_lo:[0,1] neg_hi:[0,1]
	v_xor_b32_e32 v74, 0x80000000, v19
	v_mov_b32_e32 v75, v18
	v_pk_add_f32 v[26:27], v[78:79], v[12:13]
	v_pk_add_f32 v[12:13], v[78:79], v[12:13] neg_lo:[0,1] neg_hi:[0,1]
	v_pk_add_f32 v[78:79], v[96:97], v[14:15]
	v_pk_add_f32 v[14:15], v[96:97], v[14:15] neg_lo:[0,1] neg_hi:[0,1]
	v_pk_add_f32 v[18:19], v[0:1], v[74:75]
	v_pk_add_f32 v[0:1], v[0:1], v[74:75] neg_lo:[0,1] neg_hi:[0,1]
	v_pk_add_f32 v[74:75], v[76:77], v[82:83]
	v_pk_add_f32 v[76:77], v[76:77], v[82:83] neg_lo:[0,1] neg_hi:[0,1]
	v_xor_b32_e32 v82, 0x80000000, v11
	v_mov_b32_e32 v83, v10
	v_pk_add_f32 v[10:11], v[8:9], v[82:83]
	v_pk_add_f32 v[8:9], v[8:9], v[82:83] neg_lo:[0,1] neg_hi:[0,1]
	v_pk_add_f32 v[82:83], v[26:27], v[78:79]
	v_pk_add_f32 v[26:27], v[26:27], v[78:79] neg_lo:[0,1] neg_hi:[0,1]
	v_xor_b32_e32 v78, 0x80000000, v15
	v_mov_b32_e32 v79, v14
	v_pk_add_f32 v[14:15], v[12:13], v[78:79]
	v_pk_add_f32 v[12:13], v[12:13], v[78:79] neg_lo:[0,1] neg_hi:[0,1]
	v_pk_add_f32 v[78:79], v[92:93], v[86:87]
	v_pk_add_f32 v[86:87], v[92:93], v[86:87] neg_lo:[0,1] neg_hi:[0,1]
	v_xor_b32_e32 v92, 0x80000000, v7
	v_mov_b32_e32 v93, v6
	v_pk_add_f32 v[6:7], v[4:5], v[92:93]
	v_pk_add_f32 v[4:5], v[4:5], v[92:93] neg_lo:[0,1] neg_hi:[0,1]
	v_pk_add_f32 v[92:93], v[22:23], v[84:85]
	v_pk_add_f32 v[22:23], v[22:23], v[84:85] neg_lo:[0,1] neg_hi:[0,1]
	v_xor_b32_e32 v84, 0x80000000, v3
	v_mov_b32_e32 v85, v2
	v_pk_add_f32 v[96:97], v[72:73], v[90:91]
	v_pk_add_f32 v[72:73], v[72:73], v[90:91] neg_lo:[0,1] neg_hi:[0,1]
	v_pk_add_f32 v[90:91], v[94:95], v[70:71]
	v_pk_add_f32 v[70:71], v[94:95], v[70:71] neg_lo:[0,1] neg_hi:[0,1]
	v_pk_add_f32 v[2:3], v[68:69], v[84:85]
	v_pk_add_f32 v[68:69], v[68:69], v[84:85] neg_lo:[0,1] neg_hi:[0,1]
	v_pk_add_f32 v[84:85], v[64:65], v[80:81]
	v_pk_add_f32 v[64:65], v[64:65], v[80:81] neg_lo:[0,1] neg_hi:[0,1]
	v_xor_b32_e32 v80, 0x80000000, v63
	v_mov_b32_e32 v81, v62
	v_pk_add_f32 v[94:95], v[20:21], v[88:89]
	v_pk_add_f32 v[20:21], v[20:21], v[88:89] neg_lo:[0,1] neg_hi:[0,1]
	v_pk_add_f32 v[88:89], v[102:103], v[66:67]
	v_pk_add_f32 v[66:67], v[102:103], v[66:67] neg_lo:[0,1] neg_hi:[0,1]
	v_pk_add_f32 v[62:63], v[24:25], v[80:81]
	v_pk_add_f32 v[24:25], v[24:25], v[80:81] neg_lo:[0,1] neg_hi:[0,1]
	v_pk_add_f32 v[80:81], v[96:97], v[90:91]
	v_pk_add_f32 v[90:91], v[96:97], v[90:91] neg_lo:[0,1] neg_hi:[0,1]
	v_xor_b32_e32 v96, 0x80000000, v71
	v_mov_b32_e32 v97, v70
	v_pk_add_f32 v[70:71], v[72:73], v[96:97]
	v_pk_add_f32 v[72:73], v[72:73], v[96:97] neg_lo:[0,1] neg_hi:[0,1]
	v_pk_add_f32 v[96:97], v[94:95], v[88:89]
	v_pk_add_f32 v[88:89], v[94:95], v[88:89] neg_lo:[0,1] neg_hi:[0,1]
	v_xor_b32_e32 v94, 0x80000000, v67
	v_mov_b32_e32 v95, v66
	v_pk_add_f32 v[66:67], v[20:21], v[94:95]
	v_pk_add_f32 v[20:21], v[20:21], v[94:95] neg_lo:[0,1] neg_hi:[0,1]
	v_pk_add_f32 v[94:95], v[98:99], v[74:75]
	v_pk_add_f32 v[74:75], v[98:99], v[74:75] neg_lo:[0,1] neg_hi:[0,1]
	v_pk_mul_f32 v[98:99], v[10:11], s[60:61] op_sel:[1,0] op_sel_hi:[0,0] neg_lo:[1,0]
	v_xor_b32_e32 v100, 0x80000000, v9
	v_pk_fma_f32 v[10:11], v[10:11], s[60:61], v[98:99] op_sel_hi:[1,0,1]
	v_mov_b32_e32 v101, v8
	v_pk_add_f32 v[98:99], v[18:19], v[10:11]
	v_pk_add_f32 v[10:11], v[18:19], v[10:11] neg_lo:[0,1] neg_hi:[0,1]
	v_xor_b32_e32 v18, 0x80000000, v77
	v_mov_b32_e32 v19, v76
	v_pk_add_f32 v[76:77], v[16:17], v[18:19]
	v_pk_add_f32 v[16:17], v[16:17], v[18:19] neg_lo:[0,1] neg_hi:[0,1]
	v_pk_mul_f32 v[18:19], v[8:9], s[60:61] op_sel_hi:[1,0]
	s_nop 0
	v_pk_fma_f32 v[8:9], v[100:101], s[60:61], v[18:19] op_sel_hi:[1,0,1] neg_lo:[0,0,1] neg_hi:[0,0,1]
	v_xor_b32_e32 v100, 0x80000000, v5
	v_pk_add_f32 v[18:19], v[0:1], v[8:9]
	v_pk_add_f32 v[0:1], v[0:1], v[8:9] neg_lo:[0,1] neg_hi:[0,1]
	v_pk_add_f32 v[8:9], v[82:83], v[78:79]
	v_pk_add_f32 v[78:79], v[82:83], v[78:79] neg_lo:[0,1] neg_hi:[0,1]
	v_pk_mul_f32 v[82:83], v[6:7], s[60:61] op_sel:[1,0] op_sel_hi:[0,0] neg_lo:[1,0]
	v_mov_b32_e32 v101, v4
	v_pk_fma_f32 v[6:7], v[6:7], s[60:61], v[82:83] op_sel_hi:[1,0,1]
	s_nop 0
	v_pk_add_f32 v[82:83], v[14:15], v[6:7]
	v_pk_add_f32 v[6:7], v[14:15], v[6:7] neg_lo:[0,1] neg_hi:[0,1]
	v_xor_b32_e32 v14, 0x80000000, v87
	v_mov_b32_e32 v15, v86
	v_pk_add_f32 v[86:87], v[26:27], v[14:15]
	v_pk_add_f32 v[14:15], v[26:27], v[14:15] neg_lo:[0,1] neg_hi:[0,1]
	v_pk_mul_f32 v[26:27], v[4:5], s[60:61] op_sel_hi:[1,0]
	s_nop 0
	v_pk_fma_f32 v[4:5], v[100:101], s[60:61], v[26:27] op_sel_hi:[1,0,1] neg_lo:[0,0,1] neg_hi:[0,0,1]
	v_xor_b32_e32 v100, 0x80000000, v25
	v_pk_add_f32 v[26:27], v[12:13], v[4:5]
	v_pk_add_f32 v[4:5], v[12:13], v[4:5] neg_lo:[0,1] neg_hi:[0,1]
	v_pk_add_f32 v[12:13], v[92:93], v[84:85]
	v_pk_add_f32 v[84:85], v[92:93], v[84:85] neg_lo:[0,1] neg_hi:[0,1]
	v_pk_mul_f32 v[92:93], v[62:63], s[60:61] op_sel:[1,0] op_sel_hi:[0,0] neg_lo:[1,0]
	v_mov_b32_e32 v101, v24
	v_pk_fma_f32 v[62:63], v[62:63], s[60:61], v[92:93] op_sel_hi:[1,0,1]
	s_nop 0
	v_pk_add_f32 v[92:93], v[2:3], v[62:63]
	v_pk_add_f32 v[2:3], v[2:3], v[62:63] neg_lo:[0,1] neg_hi:[0,1]
	v_xor_b32_e32 v62, 0x80000000, v65
	v_mov_b32_e32 v63, v64
	v_pk_add_f32 v[64:65], v[22:23], v[62:63]
	v_pk_add_f32 v[22:23], v[22:23], v[62:63] neg_lo:[0,1] neg_hi:[0,1]
	v_pk_mul_f32 v[62:63], v[24:25], s[60:61] op_sel_hi:[1,0]
	s_nop 0
	v_pk_fma_f32 v[24:25], v[100:101], s[60:61], v[62:63] op_sel_hi:[1,0,1] neg_lo:[0,0,1] neg_hi:[0,0,1]
	v_xor_b32_e32 v100, 0x80000000, v21
	v_pk_add_f32 v[62:63], v[68:69], v[24:25]
	v_pk_add_f32 v[24:25], v[68:69], v[24:25] neg_lo:[0,1] neg_hi:[0,1]
	v_pk_add_f32 v[68:69], v[80:81], v[96:97]
	v_pk_add_f32 v[80:81], v[80:81], v[96:97] neg_lo:[0,1] neg_hi:[0,1]
	v_pk_mul_f32 v[96:97], v[66:67], s[60:61] op_sel:[1,0] op_sel_hi:[0,0] neg_lo:[1,0]
	v_mov_b32_e32 v101, v20
	v_pk_fma_f32 v[66:67], v[66:67], s[60:61], v[96:97] op_sel_hi:[1,0,1]
	s_nop 0
	v_pk_add_f32 v[96:97], v[70:71], v[66:67]
	v_pk_add_f32 v[66:67], v[70:71], v[66:67] neg_lo:[0,1] neg_hi:[0,1]
	v_xor_b32_e32 v70, 0x80000000, v89
	v_mov_b32_e32 v71, v88
	v_pk_add_f32 v[88:89], v[90:91], v[70:71]
	v_pk_add_f32 v[70:71], v[90:91], v[70:71] neg_lo:[0,1] neg_hi:[0,1]
	v_pk_mul_f32 v[90:91], v[20:21], s[60:61] op_sel_hi:[1,0]
	s_nop 0
	v_pk_fma_f32 v[20:21], v[100:101], s[60:61], v[90:91] op_sel_hi:[1,0,1] neg_lo:[0,0,1] neg_hi:[0,0,1]
	s_nop 0
	v_pk_add_f32 v[90:91], v[72:73], v[20:21]
	v_pk_add_f32 v[20:21], v[72:73], v[20:21] neg_lo:[0,1] neg_hi:[0,1]
	v_pk_add_f32 v[72:73], v[94:95], v[8:9]
	v_pk_add_f32 v[8:9], v[94:95], v[8:9] neg_lo:[0,1] neg_hi:[0,1]
	v_pk_mul_f32 v[94:95], v[82:83], s[54:55] op_sel:[1,0] op_sel_hi:[0,0] neg_lo:[1,0]
	s_nop 0
	v_pk_fma_f32 v[82:83], v[82:83], s[52:53], v[94:95] op_sel_hi:[1,0,1]
	s_nop 0
	v_pk_add_f32 v[94:95], v[98:99], v[82:83]
	v_pk_add_f32 v[82:83], v[98:99], v[82:83] neg_lo:[0,1] neg_hi:[0,1]
	v_pk_mul_f32 v[98:99], v[86:87], s[60:61] op_sel:[1,0] op_sel_hi:[0,0] neg_lo:[1,0]
	s_nop 0
	v_pk_fma_f32 v[86:87], v[86:87], s[60:61], v[98:99] op_sel_hi:[1,0,1]
	s_nop 0
	v_pk_add_f32 v[98:99], v[76:77], v[86:87]
	v_pk_add_f32 v[86:87], v[76:77], v[86:87] neg_lo:[0,1] neg_hi:[0,1]
	v_pk_mul_f32 v[76:77], v[26:27], s[52:53] op_sel:[1,0] op_sel_hi:[0,0] neg_lo:[1,0]
	s_nop 0
	v_pk_fma_f32 v[26:27], v[26:27], s[54:55], v[76:77] op_sel_hi:[1,0,1]
	v_xor_b32_e32 v76, 0x80000000, v67
	v_pk_add_f32 v[100:101], v[18:19], v[26:27]
	v_pk_add_f32 v[26:27], v[18:19], v[26:27] neg_lo:[0,1] neg_hi:[0,1]
	v_pk_add_f32 v[102:103], v[74:75], v[78:79] op_sel:[0,1] op_sel_hi:[1,0] neg_lo:[0,1]
	v_pk_add_f32 v[104:105], v[74:75], v[78:79] op_sel:[0,1] op_sel_hi:[1,0] neg_hi:[0,1]
	v_pk_mul_f32 v[18:19], v[6:7], s[54:55] op_sel_hi:[1,0]
	v_xor_b32_e32 v74, 0x80000000, v7
	v_mov_b32_e32 v75, v6
	v_pk_fma_f32 v[6:7], v[74:75], s[52:53], v[18:19] op_sel_hi:[1,0,1] neg_lo:[0,0,1] neg_hi:[0,0,1]
	v_xor_b32_e32 v74, 0x80000000, v15
	v_pk_add_f32 v[18:19], v[10:11], v[6:7]
	v_pk_add_f32 v[6:7], v[10:11], v[6:7] neg_lo:[0,1] neg_hi:[0,1]
	v_pk_mul_f32 v[10:11], v[14:15], s[60:61] op_sel_hi:[1,0]
	v_mov_b32_e32 v75, v14
	v_pk_fma_f32 v[10:11], v[74:75], s[60:61], v[10:11] op_sel_hi:[1,0,1] neg_lo:[0,0,1] neg_hi:[0,0,1]
	v_xor_b32_e32 v74, 0x80000000, v5
	v_pk_add_f32 v[14:15], v[16:17], v[10:11]
	v_pk_add_f32 v[10:11], v[16:17], v[10:11] neg_lo:[0,1] neg_hi:[0,1]
	v_pk_mul_f32 v[16:17], v[4:5], s[52:53] op_sel_hi:[1,0]
	v_mov_b32_e32 v75, v4
	v_pk_fma_f32 v[4:5], v[74:75], s[54:55], v[16:17] op_sel_hi:[1,0,1] neg_lo:[0,0,1] neg_hi:[0,0,1]
	v_xor_b32_e32 v74, 0x80000000, v89
	v_pk_add_f32 v[16:17], v[0:1], v[4:5]
	v_pk_add_f32 v[106:107], v[0:1], v[4:5] neg_lo:[0,1] neg_hi:[0,1]
	v_pk_add_f32 v[0:1], v[12:13], v[68:69]
	v_pk_add_f32 v[4:5], v[12:13], v[68:69] neg_lo:[0,1] neg_hi:[0,1]
	v_mov_b32_e32 v75, v88
	v_pk_mul_f32 v[12:13], v[96:97], s[54:55] op_sel:[1,0] op_sel_hi:[0,0] neg_lo:[1,0]
	v_pk_mul_f32 v[74:75], v[74:75], s[60:61] op_sel_hi:[1,0]
	v_pk_fma_f32 v[12:13], v[96:97], s[52:53], v[12:13] op_sel_hi:[1,0,1]
	v_pk_fma_f32 v[74:75], v[88:89], s[60:61], v[74:75] op_sel_hi:[1,0,1]
	v_pk_add_f32 v[68:69], v[92:93], v[12:13]
	v_pk_add_f32 v[12:13], v[92:93], v[12:13] neg_lo:[0,1] neg_hi:[0,1]
	v_pk_add_f32 v[88:89], v[64:65], v[74:75]
	v_pk_add_f32 v[92:93], v[64:65], v[74:75] neg_lo:[0,1] neg_hi:[0,1]
	v_pk_mul_f32 v[64:65], v[90:91], s[52:53] op_sel:[1,0] op_sel_hi:[0,0] neg_lo:[1,0]
	v_pk_add_f32 v[78:79], v[72:73], v[0:1]
	v_pk_fma_f32 v[64:65], v[90:91], s[54:55], v[64:65] op_sel_hi:[1,0,1]
	s_nop 0
	v_pk_add_f32 v[74:75], v[62:63], v[64:65]
	v_pk_add_f32 v[90:91], v[62:63], v[64:65] neg_lo:[0,1] neg_hi:[0,1]
	v_pk_mul_f32 v[0:1], v[68:69], s[48:49] op_sel:[1,0] op_sel_hi:[0,0] neg_lo:[1,0]
	v_pk_add_f32 v[64:65], v[84:85], v[80:81] op_sel:[0,1] op_sel_hi:[1,0] neg_lo:[0,1]
	v_pk_add_f32 v[80:81], v[84:85], v[80:81] op_sel:[0,1] op_sel_hi:[1,0] neg_hi:[0,1]
	v_pk_mul_f32 v[62:63], v[66:67], s[54:55] op_sel_hi:[1,0]
	v_mov_b32_e32 v77, v66
	v_pk_fma_f32 v[0:1], v[68:69], s[44:45], v[0:1] op_sel_hi:[1,0,1]
	v_pk_fma_f32 v[62:63], v[76:77], s[52:53], v[62:63] op_sel_hi:[1,0,1] neg_lo:[0,0,1] neg_hi:[0,0,1]
	v_pk_add_f32 v[76:77], v[94:95], v[0:1]
	v_pk_mul_f32 v[0:1], v[88:89], s[54:55] op_sel:[1,0] op_sel_hi:[0,0] neg_lo:[1,0]
	v_pk_add_f32 v[84:85], v[2:3], v[62:63]
	v_pk_fma_f32 v[0:1], v[88:89], s[52:53], v[0:1] op_sel_hi:[1,0,1]
	v_pk_add_f32 v[2:3], v[2:3], v[62:63] neg_lo:[0,1] neg_hi:[0,1]
	v_pk_add_f32 v[72:73], v[98:99], v[0:1]
	v_pk_mul_f32 v[0:1], v[74:75], s[58:59] op_sel:[1,0] op_sel_hi:[0,0] neg_lo:[1,0]
	v_pk_mul_f32 v[62:63], v[70:71], s[60:61] op_sel_hi:[1,0]
	v_pk_fma_f32 v[0:1], v[74:75], s[56:57], v[0:1] op_sel_hi:[1,0,1]
	v_xor_b32_e32 v66, 0x80000000, v71
	v_pk_add_f32 v[74:75], v[100:101], v[0:1]
	v_pk_mul_f32 v[0:1], v[64:65], s[60:61] op_sel:[1,0] op_sel_hi:[0,0] neg_lo:[1,0]
	v_mov_b32_e32 v67, v70
	v_pk_fma_f32 v[0:1], v[64:65], s[60:61], v[0:1] op_sel_hi:[1,0,1]
	v_pk_fma_f32 v[62:63], v[66:67], s[60:61], v[62:63] op_sel_hi:[1,0,1] neg_lo:[0,0,1] neg_hi:[0,0,1]
	v_pk_add_f32 v[66:67], v[102:103], v[0:1]
	v_pk_mul_f32 v[0:1], v[84:85], s[56:57] op_sel:[1,0] op_sel_hi:[0,0] neg_lo:[1,0]
	v_pk_add_f32 v[70:71], v[22:23], v[62:63]
	v_pk_fma_f32 v[0:1], v[84:85], s[58:59], v[0:1] op_sel_hi:[1,0,1]
	v_pk_add_f32 v[96:97], v[22:23], v[62:63] neg_lo:[0,1] neg_hi:[0,1]
	v_pk_mul_f32 v[22:23], v[20:21], s[52:53] op_sel_hi:[1,0]
	v_pk_add_f32 v[68:69], v[18:19], v[0:1]
	v_pk_fma_f32 v[20:21], v[20:21], s[54:55], v[22:23] op_sel:[1,0,0] op_sel_hi:[0,0,1] neg_lo:[1,0,1] neg_hi:[0,0,1]
	v_pk_mul_f32 v[0:1], v[70:71], s[52:53] op_sel:[1,0] op_sel_hi:[0,0] neg_lo:[1,0]
	v_pk_add_f32 v[22:23], v[24:25], v[20:21]
	v_pk_fma_f32 v[0:1], v[70:71], s[54:55], v[0:1] op_sel_hi:[1,0,1]
	v_pk_add_f32 v[108:109], v[24:25], v[20:21] neg_lo:[0,1] neg_hi:[0,1]
	v_pk_add_f32 v[62:63], v[14:15], v[0:1]
	v_pk_mul_f32 v[0:1], v[22:23], s[44:45] op_sel:[1,0] op_sel_hi:[0,0] neg_lo:[1,0]
	s_nop 0
	v_pk_fma_f32 v[0:1], v[22:23], s[48:49], v[0:1] op_sel_hi:[1,0,1]
	s_nop 0
	v_pk_add_f32 v[64:65], v[16:17], v[0:1]
	v_pk_add_f32 v[22:23], v[8:9], v[4:5] op_sel:[0,1] op_sel_hi:[1,0] neg_lo:[0,1]
	v_pk_mul_f32 v[0:1], v[12:13], s[48:49] op_sel_hi:[1,0]
	v_xor_b32_e32 v4, 0x80000000, v13
	v_mov_b32_e32 v5, v12
	v_pk_fma_f32 v[0:1], v[4:5], s[44:45], v[0:1] op_sel_hi:[1,0,1] neg_lo:[0,0,1] neg_hi:[0,0,1]
	v_xor_b32_e32 v4, 0x80000000, v93
	v_pk_add_f32 v[24:25], v[82:83], v[0:1]
	v_pk_mul_f32 v[0:1], v[92:93], s[54:55] op_sel_hi:[1,0]
	v_mov_b32_e32 v5, v92
	v_pk_fma_f32 v[0:1], v[4:5], s[52:53], v[0:1] op_sel_hi:[1,0,1] neg_lo:[0,0,1] neg_hi:[0,0,1]
	v_xor_b32_e32 v4, 0x80000000, v91
	v_pk_add_f32 v[18:19], v[86:87], v[0:1]
	v_pk_mul_f32 v[0:1], v[90:91], s[58:59] op_sel_hi:[1,0]
	v_mov_b32_e32 v5, v90
	v_pk_fma_f32 v[0:1], v[4:5], s[56:57], v[0:1] op_sel_hi:[1,0,1] neg_lo:[0,0,1] neg_hi:[0,0,1]
	s_nop 0
	v_pk_add_f32 v[20:21], v[26:27], v[0:1]
	v_pk_mul_f32 v[0:1], v[80:81], s[60:61] op_sel_hi:[1,0]
	s_nop 0
	v_pk_fma_f32 v[0:1], v[80:81], s[60:61], v[0:1] op_sel:[1,0,0] op_sel_hi:[0,0,1] neg_lo:[1,0,1] neg_hi:[0,0,1]
	v_xor_b32_e32 v8, 0x80000000, v3
	v_pk_add_f32 v[4:5], v[104:105], v[0:1]
	v_pk_mul_f32 v[0:1], v[2:3], s[56:57] op_sel_hi:[1,0]
	v_mov_b32_e32 v9, v2
	v_pk_fma_f32 v[0:1], v[8:9], s[58:59], v[0:1] op_sel_hi:[1,0,1] neg_lo:[0,0,1] neg_hi:[0,0,1]
	s_nop 0
	v_pk_add_f32 v[6:7], v[6:7], v[0:1]
	v_pk_mul_f32 v[0:1], v[96:97], s[52:53] op_sel_hi:[1,0]
	s_nop 0
	v_pk_fma_f32 v[0:1], v[96:97], s[54:55], v[0:1] op_sel:[1,0,0] op_sel_hi:[0,0,1] neg_lo:[1,0,1] neg_hi:[0,0,1]
	v_pk_mul_f32 v[2:3], v[108:109], s[44:45] op_sel_hi:[1,0]
	v_pk_add_f32 v[0:1], v[10:11], v[0:1]
	v_xor_b32_e32 v8, 0x80000000, v109
	v_mov_b32_e32 v9, v108
	v_mov_b32_e32 v10, v146
	v_pk_fma_f32 v[2:3], v[8:9], s[48:49], v[2:3] op_sel_hi:[1,0,1] neg_lo:[0,0,1] neg_hi:[0,0,1]
	v_mov_b32_e32 v8, v221
	s_movk_i32 s0, 0x200
	s_cselect_b32 s4, s0, 0x400
	s_add_i32 s0, s4, s62
	s_ashr_i32 s1, s0, 31
	s_lshl_b32 s6, s4, 2
	s_add_u32 s4, s64, s6
	s_addc_u32 s5, s65, 0
	s_lshl_b64 s[0:1], s[0:1], 14
	v_min_i32_e32 v70, 0x1ffe, v10
	v_mov_b32_e32 v9, s6
	s_add_u32 s36, s26, s0
	v_ashrrev_i32_e32 v11, 31, v10
	v_ashrrev_i32_e32 v71, 31, v70
	v_mov_b32_e32 v16, v222
	v_mov_b32_e32 v14, v223
	v_mov_b32_e32 v17, v224
	v_mov_b32_e32 v12, v225
	s_addc_u32 s37, s27, s1
	v_max_i32_e32 v9, 1, v10
	v_lshlrev_b64 v[82:83], 1, v[10:11]
	v_lshlrev_b64 v[84:85], 1, v[70:71]
	v_lshl_add_u64 v[26:27], s[36:37], 0, v[82:83]
	v_lshlrev_b32_e32 v9, 1, v9
	v_lshl_add_u64 v[70:71], s[36:37], 0, v[84:85]
	v_mov_b32_e32 v13, v226
	s_add_u32 s72, s30, s0
	v_mov_b32_e32 v70, v227
	s_addc_u32 s73, s31, s1
	v_mov_b32_e32 v15, v228
	v_cmp_lt_i32_e64 s[0:1], 0, v10
	v_cmp_gt_i32_e64 s[4:5], s88, v10
	v_pk_add_f32 v[2:3], v[106:107], v[2:3]
	v_cndmask_b32_e64 v81, 0, 1.0, s[0:1]
	v_cndmask_b32_e64 v86, 0, 1.0, s[4:5]
	v_add_u32_e32 v92, 0x200, v10
	v_cmp_lt_i32_e64 s[20:21], s33, v10
	v_cmp_gt_i32_e64 s[18:19], s92, v10
	v_add_u32_e32 v90, 0x400, v10
	v_cmp_lt_i32_e64 s[16:17], s81, v10
	v_cmp_gt_i32_e64 s[0:1], s38, v10
	v_add_u32_e32 v88, 0x600, v10
	v_cmp_lt_i32_e64 s[12:13], s93, v10
	v_cmp_gt_i32_e64 s[10:11], s3, v10
	v_cmp_lt_i32_e64 s[8:9], s50, v10
	v_cmp_gt_i32_e64 s[6:7], s90, v10
	v_cmp_lt_i32_e64 s[4:5], s39, v10
	v_cmp_gt_i32_e64 s[22:23], s51, v10
	s_waitcnt vmcnt(2)
	v_lshlrev_b32_e32 v13, 16, v13
	s_waitcnt vmcnt(1)
	v_lshlrev_b32_e32 v70, 16, v70
	v_mul_f32_e32 v70, v86, v70
	s_waitcnt vmcnt(0)
	v_lshlrev_b32_e32 v15, 16, v15
	v_mul_f32_e32 v15, v81, v15
	v_mul_f32_e32 v15, v16, v15
	v_fmac_f32_e32 v15, v14, v13
	v_fmac_f32_e32 v15, v17, v70
	v_lshl_add_u64 v[70:71], s[72:73], 0, v[82:83]
	v_lshl_add_u64 v[82:83], s[72:73], 0, v[84:85]
	v_add_f32_e32 v80, v12, v15
	v_mov_b32_e32 v13, v229
	v_mov_b32_e32 v15, v230
	v_add_u32_e32 v84, 0x800, v10
	v_mov_b32_e32 v9, v231
	v_add_u32_e32 v82, 0xa00, v10
	s_waitcnt vmcnt(2)
	v_lshlrev_b32_e32 v13, 16, v13
	s_waitcnt vmcnt(1)
	v_lshlrev_b32_e32 v15, 16, v15
	v_mul_f32_e32 v15, v86, v15
	s_waitcnt vmcnt(0)
	v_lshlrev_b32_e32 v9, 16, v9
	v_mul_f32_e32 v9, v81, v9
	v_mul_f32_e32 v9, v16, v9
	v_fmac_f32_e32 v9, v14, v13
	v_fmac_f32_e32 v9, v17, v15
	v_add_f32_e32 v86, v12, v9
	s_cbranch_vccnz .LBB0_912
	s_mov_b32 s98, s29
	s_lshl_b64 s[0:1], s[66:67], 1
	s_add_u32 s4, s0, s30
	s_addc_u32 s5, s1, s31
	s_add_u32 s0, s0, s26
	s_addc_u32 s1, s1, s27
	s_add_u32 s18, s70, 0x800000
	s_addc_u32 s19, s71, 0
	s_cmpk_gt_i32 s98, 0xff
	s_cbranch_scc1 .Lhy_ep1_comb_L1
	v_lshlrev_b32_e32 v109, 1, v10
	v_add_u32_e32 v254, 0x1e00, v10
	v_add_u32_e32 v253, 0x1000, v109
	v_cmp_gt_i32_e32 vcc, 0x1fff, v254
	v_add_u32_e32 v251, 0x2000, v109
	v_add_u32_e32 v250, 0x3000, v109
	v_min_i32_e32 v254, 0x1ffe, v254
	v_cndmask_b32_e64 v255, 0, 1.0, vcc
	v_lshlrev_b32_e32 v254, 1, v254
	global_load_ushort v9, v109, s[0:1]
	global_load_ushort v11, v109, s[4:5]
	global_load_ushort v13, v109, s[36:37] offset:1022
	global_load_ushort v15, v109, s[36:37] offset:1024
	global_load_ushort v81, v109, s[36:37] offset:1026
	global_load_ushort v83, v109, s[72:73] offset:1022
	global_load_ushort v85, v109, s[72:73] offset:1024
	global_load_ushort v87, v109, s[72:73] offset:1026
	global_load_ushort v89, v109, s[0:1] offset:1024
	global_load_ushort v91, v109, s[4:5] offset:1024
	global_load_ushort v93, v109, s[36:37] offset:2046
	global_load_ushort v94, v109, s[36:37] offset:2048
	global_load_ushort v95, v109, s[36:37] offset:2050
	global_load_ushort v96, v109, s[72:73] offset:2046
	global_load_ushort v97, v109, s[72:73] offset:2048
	global_load_ushort v98, v109, s[72:73] offset:2050
	global_load_ushort v99, v109, s[0:1] offset:2048
	global_load_ushort v100, v109, s[4:5] offset:2048
	global_load_ushort v101, v109, s[36:37] offset:3070
	global_load_ushort v102, v109, s[36:37] offset:3072
	global_load_ushort v103, v109, s[36:37] offset:3074
	global_load_ushort v104, v109, s[72:73] offset:3070
	global_load_ushort v105, v109, s[72:73] offset:3072
	global_load_ushort v106, v109, s[72:73] offset:3074
	global_load_ushort v107, v109, s[0:1] offset:3072
	global_load_ushort v108, v109, s[4:5] offset:3072
	global_load_ushort v111, v253, s[36:37] offset:-2
	global_load_ushort v112, v253, s[36:37]
	global_load_ushort v113, v253, s[36:37] offset:2
	global_load_ushort v114, v253, s[72:73] offset:-2
	global_load_ushort v115, v253, s[72:73]
	global_load_ushort v116, v253, s[72:73] offset:2
	global_load_ushort v117, v253, s[0:1]
	global_load_ushort v118, v253, s[4:5]
	global_load_ushort v119, v253, s[36:37] offset:1022
	global_load_ushort v120, v253, s[36:37] offset:1024
	global_load_ushort v121, v253, s[36:37] offset:1026
	global_load_ushort v122, v253, s[72:73] offset:1022
	global_load_ushort v123, v253, s[72:73] offset:1024
	global_load_ushort v124, v253, s[72:73] offset:1026
	global_load_ushort v125, v253, s[0:1] offset:1024
	global_load_ushort v126, v253, s[4:5] offset:1024
	global_load_ushort v127, v253, s[36:37] offset:2046
	global_load_ushort v128, v253, s[36:37] offset:2048
	global_load_ushort v129, v253, s[36:37] offset:2050
	global_load_ushort v130, v253, s[72:73] offset:2046
	global_load_ushort v131, v253, s[72:73] offset:2048
	global_load_ushort v132, v253, s[72:73] offset:2050
	global_load_ushort v133, v253, s[0:1] offset:2048
	global_load_ushort v134, v253, s[4:5] offset:2048
	global_load_ushort v135, v253, s[36:37] offset:3070
	global_load_ushort v136, v253, s[36:37] offset:3072
	global_load_ushort v137, v253, s[36:37] offset:3074
	global_load_ushort v138, v253, s[72:73] offset:3070
	global_load_ushort v139, v253, s[72:73] offset:3072
	global_load_ushort v140, v253, s[72:73] offset:3074
	global_load_ushort v141, v253, s[0:1] offset:3072
	global_load_ushort v142, v253, s[4:5] offset:3072
	global_load_ushort v143, v251, s[36:37] offset:-2
	global_load_ushort v163, v251, s[36:37]
	global_load_ushort v164, v251, s[36:37] offset:2
	global_load_ushort v165, v251, s[72:73] offset:-2
	global_load_ushort v166, v251, s[72:73]
	global_load_ushort v167, v251, s[72:73] offset:2
	global_load_ushort v168, v251, s[0:1]
	global_load_ushort v169, v251, s[4:5]
	global_load_ushort v170, v251, s[36:37] offset:1022
	global_load_ushort v171, v251, s[36:37] offset:1024
	global_load_ushort v172, v251, s[36:37] offset:1026
	global_load_ushort v173, v251, s[72:73] offset:1022
	global_load_ushort v174, v251, s[72:73] offset:1024
	global_load_ushort v175, v251, s[72:73] offset:1026
	global_load_ushort v176, v251, s[0:1] offset:1024
	global_load_ushort v177, v251, s[4:5] offset:1024
	global_load_ushort v178, v251, s[36:37] offset:2046
	global_load_ushort v179, v251, s[36:37] offset:2048
	global_load_ushort v180, v251, s[36:37] offset:2050
	global_load_ushort v181, v251, s[72:73] offset:2046
	global_load_ushort v182, v251, s[72:73] offset:2048
	global_load_ushort v183, v251, s[72:73] offset:2050
	global_load_ushort v184, v251, s[0:1] offset:2048
	global_load_ushort v185, v251, s[4:5] offset:2048
	global_load_ushort v186, v251, s[36:37] offset:3070
	global_load_ushort v187, v251, s[36:37] offset:3072
	global_load_ushort v188, v251, s[36:37] offset:3074
	global_load_ushort v189, v251, s[72:73] offset:3070
	global_load_ushort v190, v251, s[72:73] offset:3072
	global_load_ushort v191, v251, s[72:73] offset:3074
	global_load_ushort v192, v251, s[0:1] offset:3072
	global_load_ushort v193, v251, s[4:5] offset:3072
	global_load_ushort v194, v250, s[36:37] offset:-2
	global_load_ushort v195, v250, s[36:37]
	global_load_ushort v196, v250, s[36:37] offset:2
	global_load_ushort v197, v250, s[72:73] offset:-2
	global_load_ushort v221, v250, s[72:73]
	global_load_ushort v222, v250, s[72:73] offset:2
	global_load_ushort v223, v250, s[0:1]
	global_load_ushort v224, v250, s[4:5]
	global_load_ushort v225, v250, s[36:37] offset:1022
	global_load_ushort v226, v250, s[36:37] offset:1024
	global_load_ushort v227, v250, s[36:37] offset:1026
	global_load_ushort v228, v250, s[72:73] offset:1022
	global_load_ushort v229, v250, s[72:73] offset:1024
	global_load_ushort v230, v250, s[72:73] offset:1026
	global_load_ushort v231, v250, s[0:1] offset:1024
	global_load_ushort v232, v250, s[4:5] offset:1024
	global_load_ushort v233, v250, s[36:37] offset:2046
	global_load_ushort v234, v250, s[36:37] offset:2048
	global_load_ushort v235, v250, s[36:37] offset:2050
	global_load_ushort v236, v250, s[72:73] offset:2046
	global_load_ushort v237, v250, s[72:73] offset:2048
	global_load_ushort v238, v250, s[72:73] offset:2050
	global_load_ushort v239, v250, s[0:1] offset:2048
	global_load_ushort v240, v250, s[4:5] offset:2048
	global_load_ushort v241, v250, s[36:37] offset:3070
	global_load_ushort v242, v250, s[36:37] offset:3072
	global_load_ushort v243, v254, s[36:37] offset:2
	global_load_ushort v244, v250, s[72:73] offset:3070
	global_load_ushort v245, v250, s[72:73] offset:3072
	global_load_ushort v246, v254, s[72:73] offset:2
	global_load_ushort v247, v250, s[0:1] offset:3072
	global_load_ushort v248, v250, s[4:5] offset:3072
	s_waitcnt vmcnt(63)
	v_fma_f32 v27, v32, v8, v78
	v_mul_f32_e32 v70, v80, v27
	v_lshlrev_b32_e32 v9, 16, v9
	v_mul_f32_e32 v84, 0xbfb8aa3b, v9
	v_exp_f32_e32 v84, v84
	s_nop 0
	v_add_f32_e32 v84, 1.0, v84
	v_div_scale_f32 v71, s[74:75], v84, v84, v9
	v_rcp_f32_e32 v82, v71
	s_nop 0
	v_fma_f32 v92, -v71, v82, 1.0
	v_fmac_f32_e32 v82, v92, v82
	v_div_scale_f32 v88, vcc, v9, v84, v9
	v_mul_f32_e32 v90, v88, v82
	v_fma_f32 v92, -v71, v90, v88
	v_fmac_f32_e32 v90, v92, v82
	v_fma_f32 v71, -v71, v90, v88
	v_div_fmas_f32 v71, v71, v82, v90
	v_div_fixup_f32 v9, v71, v84, v9
	v_mul_f32_e32 v70, v70, v9
	v_fma_f32 v27, v34, v8, v79
	v_mul_f32_e32 v110, v86, v27
	v_lshlrev_b32_e32 v11, 16, v11
	v_mul_f32_e32 v84, 0xbfb8aa3b, v11
	v_exp_f32_e32 v84, v84
	s_nop 0
	v_add_f32_e32 v84, 1.0, v84
	v_div_scale_f32 v71, s[74:75], v84, v84, v11
	v_rcp_f32_e32 v82, v71
	s_nop 0
	v_fma_f32 v92, -v71, v82, 1.0
	v_fmac_f32_e32 v82, v92, v82
	v_div_scale_f32 v88, vcc, v11, v84, v11
	v_mul_f32_e32 v90, v88, v82
	v_fma_f32 v92, -v71, v90, v88
	v_fmac_f32_e32 v90, v92, v82
	v_fma_f32 v71, -v71, v90, v88
	v_div_fmas_f32 v71, v71, v82, v90
	v_div_fixup_f32 v11, v71, v84, v11
	v_mul_f32_e32 v110, v110, v11
	v_cvt_pk_bf16_f32 v198, v70, v110
	v_lshlrev_b32_e32 v15, 16, v15
	v_lshlrev_b32_e32 v81, 16, v81
	v_lshlrev_b32_e32 v13, 16, v13
	v_mul_f32_e32 v13, v16, v13
	v_fmac_f32_e32 v13, v14, v15
	v_fmac_f32_e32 v13, v17, v81
	v_add_f32_e32 v13, v12, v13
	v_fma_f32 v27, v33, v8, v76
	v_mul_f32_e32 v70, v27, v13
	v_lshlrev_b32_e32 v89, 16, v89
	v_mul_f32_e32 v84, 0xbfb8aa3b, v89
	v_exp_f32_e32 v84, v84
	s_nop 0
	v_add_f32_e32 v84, 1.0, v84
	v_div_scale_f32 v71, s[74:75], v84, v84, v89
	v_rcp_f32_e32 v82, v71
	s_nop 0
	v_fma_f32 v92, -v71, v82, 1.0
	v_fmac_f32_e32 v82, v92, v82
	v_div_scale_f32 v88, vcc, v89, v84, v89
	v_mul_f32_e32 v90, v88, v82
	v_fma_f32 v92, -v71, v90, v88
	v_fmac_f32_e32 v90, v92, v82
	v_fma_f32 v71, -v71, v90, v88
	v_div_fmas_f32 v71, v71, v82, v90
	v_div_fixup_f32 v89, v71, v84, v89
	v_mul_f32_e32 v70, v70, v89
	v_lshlrev_b32_e32 v85, 16, v85
	v_lshlrev_b32_e32 v87, 16, v87
	v_lshlrev_b32_e32 v83, 16, v83
	v_mul_f32_e32 v83, v16, v83
	v_fmac_f32_e32 v83, v14, v85
	v_fmac_f32_e32 v83, v17, v87
	v_add_f32_e32 v83, v12, v83
	v_fma_f32 v27, v35, v8, v77
	v_mul_f32_e32 v110, v27, v83
	v_lshlrev_b32_e32 v91, 16, v91
	v_mul_f32_e32 v84, 0xbfb8aa3b, v91
	v_exp_f32_e32 v84, v84
	s_nop 0
	v_add_f32_e32 v84, 1.0, v84
	v_div_scale_f32 v71, s[74:75], v84, v84, v91
	v_rcp_f32_e32 v82, v71
	s_nop 0
	v_fma_f32 v92, -v71, v82, 1.0
	v_fmac_f32_e32 v82, v92, v82
	v_div_scale_f32 v88, vcc, v91, v84, v91
	v_mul_f32_e32 v90, v88, v82
	v_fma_f32 v92, -v71, v90, v88
	v_fmac_f32_e32 v90, v92, v82
	v_fma_f32 v71, -v71, v90, v88
	v_div_fmas_f32 v71, v71, v82, v90
	v_div_fixup_f32 v91, v71, v84, v91
	v_mul_f32_e32 v110, v110, v91
	v_cvt_pk_bf16_f32 v199, v70, v110
	v_lshlrev_b32_e32 v94, 16, v94
	v_lshlrev_b32_e32 v95, 16, v95
	v_lshlrev_b32_e32 v93, 16, v93
	v_mul_f32_e32 v93, v16, v93
	v_fmac_f32_e32 v93, v14, v94
	v_fmac_f32_e32 v93, v17, v95
	v_add_f32_e32 v93, v12, v93
	v_fma_f32 v27, v37, v8, v72
	v_mul_f32_e32 v70, v27, v93
	v_lshlrev_b32_e32 v99, 16, v99
	v_mul_f32_e32 v84, 0xbfb8aa3b, v99
	v_exp_f32_e32 v84, v84
	s_nop 0
	v_add_f32_e32 v84, 1.0, v84
	v_div_scale_f32 v71, s[74:75], v84, v84, v99
	v_rcp_f32_e32 v82, v71
	s_nop 0
	v_fma_f32 v92, -v71, v82, 1.0
	v_fmac_f32_e32 v82, v92, v82
	v_div_scale_f32 v88, vcc, v99, v84, v99
	v_mul_f32_e32 v90, v88, v82
	v_fma_f32 v92, -v71, v90, v88
	v_fmac_f32_e32 v90, v92, v82
	v_fma_f32 v71, -v71, v90, v88
	v_div_fmas_f32 v71, v71, v82, v90
	v_div_fixup_f32 v99, v71, v84, v99
	v_mul_f32_e32 v70, v70, v99
	v_lshlrev_b32_e32 v97, 16, v97
	v_lshlrev_b32_e32 v98, 16, v98
	v_lshlrev_b32_e32 v96, 16, v96
	v_mul_f32_e32 v96, v16, v96
	v_fmac_f32_e32 v96, v14, v97
	v_fmac_f32_e32 v96, v17, v98
	v_add_f32_e32 v96, v12, v96
	v_fma_f32 v27, v31, v8, v73
	v_mul_f32_e32 v110, v27, v96
	v_lshlrev_b32_e32 v100, 16, v100
	v_mul_f32_e32 v84, 0xbfb8aa3b, v100
	v_exp_f32_e32 v84, v84
	s_nop 0
	v_add_f32_e32 v84, 1.0, v84
	v_div_scale_f32 v71, s[74:75], v84, v84, v100
	v_rcp_f32_e32 v82, v71
	s_nop 0
	v_fma_f32 v92, -v71, v82, 1.0
	v_fmac_f32_e32 v82, v92, v82
	v_div_scale_f32 v88, vcc, v100, v84, v100
	v_mul_f32_e32 v90, v88, v82
	v_fma_f32 v92, -v71, v90, v88
	v_fmac_f32_e32 v90, v92, v82
	v_fma_f32 v71, -v71, v90, v88
	v_div_fmas_f32 v71, v71, v82, v90
	v_div_fixup_f32 v100, v71, v84, v100
	v_mul_f32_e32 v110, v110, v100
	v_cvt_pk_bf16_f32 v200, v70, v110
	v_lshlrev_b32_e32 v102, 16, v102
	v_lshlrev_b32_e32 v103, 16, v103
	v_lshlrev_b32_e32 v101, 16, v101
	v_mul_f32_e32 v101, v16, v101
	v_fmac_f32_e32 v101, v14, v102
	v_fmac_f32_e32 v101, v17, v103
	v_add_f32_e32 v101, v12, v101
	v_fma_f32 v27, v36, v8, v74
	v_mul_f32_e32 v70, v27, v101
	v_lshlrev_b32_e32 v107, 16, v107
	v_mul_f32_e32 v84, 0xbfb8aa3b, v107
	v_exp_f32_e32 v84, v84
	s_nop 0
	v_add_f32_e32 v84, 1.0, v84
	v_div_scale_f32 v71, s[74:75], v84, v84, v107
	v_rcp_f32_e32 v82, v71
	s_nop 0
	v_fma_f32 v92, -v71, v82, 1.0
	v_fmac_f32_e32 v82, v92, v82
	v_div_scale_f32 v88, vcc, v107, v84, v107
	v_mul_f32_e32 v90, v88, v82
	v_fma_f32 v92, -v71, v90, v88
	v_fmac_f32_e32 v90, v92, v82
	v_fma_f32 v71, -v71, v90, v88
	v_div_fmas_f32 v71, v71, v82, v90
	v_div_fixup_f32 v107, v71, v84, v107
	v_mul_f32_e32 v70, v70, v107
	v_lshlrev_b32_e32 v105, 16, v105
	v_lshlrev_b32_e32 v106, 16, v106
	v_lshlrev_b32_e32 v104, 16, v104
	v_mul_f32_e32 v104, v16, v104
	v_fmac_f32_e32 v104, v14, v105
	v_fmac_f32_e32 v104, v17, v106
	v_add_f32_e32 v104, v12, v104
	v_fma_f32 v27, v30, v8, v75
	v_mul_f32_e32 v110, v27, v104
	v_lshlrev_b32_e32 v108, 16, v108
	v_mul_f32_e32 v84, 0xbfb8aa3b, v108
	v_exp_f32_e32 v84, v84
	s_nop 0
	v_add_f32_e32 v84, 1.0, v84
	v_div_scale_f32 v71, s[74:75], v84, v84, v108
	v_rcp_f32_e32 v82, v71
	s_nop 0
	v_fma_f32 v92, -v71, v82, 1.0
	v_fmac_f32_e32 v82, v92, v82
	v_div_scale_f32 v88, vcc, v108, v84, v108
	v_mul_f32_e32 v90, v88, v82
	v_fma_f32 v92, -v71, v90, v88
	v_fmac_f32_e32 v90, v92, v82
	v_fma_f32 v71, -v71, v90, v88
	v_div_fmas_f32 v71, v71, v82, v90
	v_div_fixup_f32 v108, v71, v84, v108
	v_mul_f32_e32 v110, v110, v108
	v_cvt_pk_bf16_f32 v201, v70, v110
	s_waitcnt vmcnt(63)
	v_lshlrev_b32_e32 v112, 16, v112
	v_lshlrev_b32_e32 v113, 16, v113
	v_lshlrev_b32_e32 v111, 16, v111
	v_mul_f32_e32 v111, v16, v111
	v_fmac_f32_e32 v111, v14, v112
	v_fmac_f32_e32 v111, v17, v113
	v_add_f32_e32 v111, v12, v111
	v_fma_f32 v27, v39, v8, v66
	v_mul_f32_e32 v70, v27, v111
	v_lshlrev_b32_e32 v117, 16, v117
	v_mul_f32_e32 v84, 0xbfb8aa3b, v117
	v_exp_f32_e32 v84, v84
	s_nop 0
	v_add_f32_e32 v84, 1.0, v84
	v_div_scale_f32 v71, s[74:75], v84, v84, v117
	v_rcp_f32_e32 v82, v71
	s_nop 0
	v_fma_f32 v92, -v71, v82, 1.0
	v_fmac_f32_e32 v82, v92, v82
	v_div_scale_f32 v88, vcc, v117, v84, v117
	v_mul_f32_e32 v90, v88, v82
	v_fma_f32 v92, -v71, v90, v88
	v_fmac_f32_e32 v90, v92, v82
	v_fma_f32 v71, -v71, v90, v88
	v_div_fmas_f32 v71, v71, v82, v90
	v_div_fixup_f32 v117, v71, v84, v117
	v_mul_f32_e32 v70, v70, v117
	v_lshlrev_b32_e32 v115, 16, v115
	v_lshlrev_b32_e32 v116, 16, v116
	v_lshlrev_b32_e32 v114, 16, v114
	v_mul_f32_e32 v114, v16, v114
	v_fmac_f32_e32 v114, v14, v115
	v_fmac_f32_e32 v114, v17, v116
	v_add_f32_e32 v114, v12, v114
	v_fma_f32 v27, v41, v8, v67
	v_mul_f32_e32 v110, v27, v114
	v_lshlrev_b32_e32 v118, 16, v118
	v_mul_f32_e32 v84, 0xbfb8aa3b, v118
	v_exp_f32_e32 v84, v84
	s_nop 0
	v_add_f32_e32 v84, 1.0, v84
	v_div_scale_f32 v71, s[74:75], v84, v84, v118
	v_rcp_f32_e32 v82, v71
	s_nop 0
	v_fma_f32 v92, -v71, v82, 1.0
	v_fmac_f32_e32 v82, v92, v82
	v_div_scale_f32 v88, vcc, v118, v84, v118
	v_mul_f32_e32 v90, v88, v82
	v_fma_f32 v92, -v71, v90, v88
	v_fmac_f32_e32 v90, v92, v82
	v_fma_f32 v71, -v71, v90, v88
	v_div_fmas_f32 v71, v71, v82, v90
	v_div_fixup_f32 v118, v71, v84, v118
	v_mul_f32_e32 v110, v110, v118
	v_cvt_pk_bf16_f32 v202, v70, v110
	v_lshlrev_b32_e32 v120, 16, v120
	v_lshlrev_b32_e32 v121, 16, v121
	v_lshlrev_b32_e32 v119, 16, v119
	v_mul_f32_e32 v119, v16, v119
	v_fmac_f32_e32 v119, v14, v120
	v_fmac_f32_e32 v119, v17, v121
	v_add_f32_e32 v119, v12, v119
	v_fma_f32 v27, v38, v8, v68
	v_mul_f32_e32 v70, v27, v119
	v_lshlrev_b32_e32 v125, 16, v125
	v_mul_f32_e32 v84, 0xbfb8aa3b, v125
	v_exp_f32_e32 v84, v84
	s_nop 0
	v_add_f32_e32 v84, 1.0, v84
	v_div_scale_f32 v71, s[74:75], v84, v84, v125
	v_rcp_f32_e32 v82, v71
	s_nop 0
	v_fma_f32 v92, -v71, v82, 1.0
	v_fmac_f32_e32 v82, v92, v82
	v_div_scale_f32 v88, vcc, v125, v84, v125
	v_mul_f32_e32 v90, v88, v82
	v_fma_f32 v92, -v71, v90, v88
	v_fmac_f32_e32 v90, v92, v82
	v_fma_f32 v71, -v71, v90, v88
	v_div_fmas_f32 v71, v71, v82, v90
	v_div_fixup_f32 v125, v71, v84, v125
	v_mul_f32_e32 v70, v70, v125
	v_lshlrev_b32_e32 v123, 16, v123
	v_lshlrev_b32_e32 v124, 16, v124
	v_lshlrev_b32_e32 v122, 16, v122
	v_mul_f32_e32 v122, v16, v122
	v_fmac_f32_e32 v122, v14, v123
	v_fmac_f32_e32 v122, v17, v124
	v_add_f32_e32 v122, v12, v122
	v_fma_f32 v27, v40, v8, v69
	v_mul_f32_e32 v110, v27, v122
	v_lshlrev_b32_e32 v126, 16, v126
	v_mul_f32_e32 v84, 0xbfb8aa3b, v126
	v_exp_f32_e32 v84, v84
	s_nop 0
	v_add_f32_e32 v84, 1.0, v84
	v_div_scale_f32 v71, s[74:75], v84, v84, v126
	v_rcp_f32_e32 v82, v71
	s_nop 0
	v_fma_f32 v92, -v71, v82, 1.0
	v_fmac_f32_e32 v82, v92, v82
	v_div_scale_f32 v88, vcc, v126, v84, v126
	v_mul_f32_e32 v90, v88, v82
	v_fma_f32 v92, -v71, v90, v88
	v_fmac_f32_e32 v90, v92, v82
	v_fma_f32 v71, -v71, v90, v88
	v_div_fmas_f32 v71, v71, v82, v90
	v_div_fixup_f32 v126, v71, v84, v126
	v_mul_f32_e32 v110, v110, v126
	v_cvt_pk_bf16_f32 v203, v70, v110
	v_lshlrev_b32_e32 v128, 16, v128
	v_lshlrev_b32_e32 v129, 16, v129
	v_lshlrev_b32_e32 v127, 16, v127
	v_mul_f32_e32 v127, v16, v127
	v_fmac_f32_e32 v127, v14, v128
	v_fmac_f32_e32 v127, v17, v129
	v_add_f32_e32 v127, v12, v127
	v_fma_f32 v27, v43, v8, v62
	v_mul_f32_e32 v70, v27, v127
	v_lshlrev_b32_e32 v133, 16, v133
	v_mul_f32_e32 v84, 0xbfb8aa3b, v133
	v_exp_f32_e32 v84, v84
	s_nop 0
	v_add_f32_e32 v84, 1.0, v84
	v_div_scale_f32 v71, s[74:75], v84, v84, v133
	v_rcp_f32_e32 v82, v71
	s_nop 0
	v_fma_f32 v92, -v71, v82, 1.0
	v_fmac_f32_e32 v82, v92, v82
	v_div_scale_f32 v88, vcc, v133, v84, v133
	v_mul_f32_e32 v90, v88, v82
	v_fma_f32 v92, -v71, v90, v88
	v_fmac_f32_e32 v90, v92, v82
	v_fma_f32 v71, -v71, v90, v88
	v_div_fmas_f32 v71, v71, v82, v90
	v_div_fixup_f32 v133, v71, v84, v133
	v_mul_f32_e32 v70, v70, v133
	v_lshlrev_b32_e32 v131, 16, v131
	v_lshlrev_b32_e32 v132, 16, v132
	v_lshlrev_b32_e32 v130, 16, v130
	v_mul_f32_e32 v130, v16, v130
	v_fmac_f32_e32 v130, v14, v131
	v_fmac_f32_e32 v130, v17, v132
	v_add_f32_e32 v130, v12, v130
	v_fma_f32 v27, v45, v8, v63
	v_mul_f32_e32 v110, v27, v130
	v_lshlrev_b32_e32 v134, 16, v134
	v_mul_f32_e32 v84, 0xbfb8aa3b, v134
	v_exp_f32_e32 v84, v84
	s_nop 0
	v_add_f32_e32 v84, 1.0, v84
	v_div_scale_f32 v71, s[74:75], v84, v84, v134
	v_rcp_f32_e32 v82, v71
	s_nop 0
	v_fma_f32 v92, -v71, v82, 1.0
	v_fmac_f32_e32 v82, v92, v82
	v_div_scale_f32 v88, vcc, v134, v84, v134
	v_mul_f32_e32 v90, v88, v82
	v_fma_f32 v92, -v71, v90, v88
	v_fmac_f32_e32 v90, v92, v82
	v_fma_f32 v71, -v71, v90, v88
	v_div_fmas_f32 v71, v71, v82, v90
	v_div_fixup_f32 v134, v71, v84, v134
	v_mul_f32_e32 v110, v110, v134
	v_cvt_pk_bf16_f32 v204, v70, v110
	v_lshlrev_b32_e32 v136, 16, v136
	v_lshlrev_b32_e32 v137, 16, v137
	v_lshlrev_b32_e32 v135, 16, v135
	v_mul_f32_e32 v135, v16, v135
	v_fmac_f32_e32 v135, v14, v136
	v_fmac_f32_e32 v135, v17, v137
	v_add_f32_e32 v135, v12, v135
	v_fma_f32 v27, v42, v8, v64
	v_mul_f32_e32 v70, v27, v135
	v_lshlrev_b32_e32 v141, 16, v141
	v_mul_f32_e32 v84, 0xbfb8aa3b, v141
	v_exp_f32_e32 v84, v84
	s_nop 0
	v_add_f32_e32 v84, 1.0, v84
	v_div_scale_f32 v71, s[74:75], v84, v84, v141
	v_rcp_f32_e32 v82, v71
	s_nop 0
	v_fma_f32 v92, -v71, v82, 1.0
	v_fmac_f32_e32 v82, v92, v82
	v_div_scale_f32 v88, vcc, v141, v84, v141
	v_mul_f32_e32 v90, v88, v82
	v_fma_f32 v92, -v71, v90, v88
	v_fmac_f32_e32 v90, v92, v82
	v_fma_f32 v71, -v71, v90, v88
	v_div_fmas_f32 v71, v71, v82, v90
	v_div_fixup_f32 v141, v71, v84, v141
	v_mul_f32_e32 v70, v70, v141
	v_lshlrev_b32_e32 v139, 16, v139
	v_lshlrev_b32_e32 v140, 16, v140
	v_lshlrev_b32_e32 v138, 16, v138
	v_mul_f32_e32 v138, v16, v138
	v_fmac_f32_e32 v138, v14, v139
	v_fmac_f32_e32 v138, v17, v140
	v_add_f32_e32 v138, v12, v138
	v_fma_f32 v27, v44, v8, v65
	v_mul_f32_e32 v110, v27, v138
	v_lshlrev_b32_e32 v142, 16, v142
	v_mul_f32_e32 v84, 0xbfb8aa3b, v142
	v_exp_f32_e32 v84, v84
	s_nop 0
	v_add_f32_e32 v84, 1.0, v84
	v_div_scale_f32 v71, s[74:75], v84, v84, v142
	v_rcp_f32_e32 v82, v71
	s_nop 0
	v_fma_f32 v92, -v71, v82, 1.0
	v_fmac_f32_e32 v82, v92, v82
	v_div_scale_f32 v88, vcc, v142, v84, v142
	v_mul_f32_e32 v90, v88, v82
	v_fma_f32 v92, -v71, v90, v88
	v_fmac_f32_e32 v90, v92, v82
	v_fma_f32 v71, -v71, v90, v88
	v_div_fmas_f32 v71, v71, v82, v90
	v_div_fixup_f32 v142, v71, v84, v142
	v_mul_f32_e32 v110, v110, v142
	v_cvt_pk_bf16_f32 v205, v70, v110
	s_waitcnt vmcnt(32)
	v_lshlrev_b32_e32 v163, 16, v163
	v_lshlrev_b32_e32 v164, 16, v164
	v_lshlrev_b32_e32 v143, 16, v143
	v_mul_f32_e32 v143, v16, v143
	v_fmac_f32_e32 v143, v14, v163
	v_fmac_f32_e32 v143, v17, v164
	v_add_f32_e32 v143, v12, v143
	v_fma_f32 v27, v47, v8, v22
	v_mul_f32_e32 v70, v27, v143
	v_lshlrev_b32_e32 v168, 16, v168
	v_mul_f32_e32 v84, 0xbfb8aa3b, v168
	v_exp_f32_e32 v84, v84
	s_nop 0
	v_add_f32_e32 v84, 1.0, v84
	v_div_scale_f32 v71, s[74:75], v84, v84, v168
	v_rcp_f32_e32 v82, v71
	s_nop 0
	v_fma_f32 v92, -v71, v82, 1.0
	v_fmac_f32_e32 v82, v92, v82
	v_div_scale_f32 v88, vcc, v168, v84, v168
	v_mul_f32_e32 v90, v88, v82
	v_fma_f32 v92, -v71, v90, v88
	v_fmac_f32_e32 v90, v92, v82
	v_fma_f32 v71, -v71, v90, v88
	v_div_fmas_f32 v71, v71, v82, v90
	v_div_fixup_f32 v168, v71, v84, v168
	v_mul_f32_e32 v70, v70, v168
	v_lshlrev_b32_e32 v166, 16, v166
	v_lshlrev_b32_e32 v167, 16, v167
	v_lshlrev_b32_e32 v165, 16, v165
	v_mul_f32_e32 v165, v16, v165
	v_fmac_f32_e32 v165, v14, v166
	v_fmac_f32_e32 v165, v17, v167
	v_add_f32_e32 v165, v12, v165
	v_fma_f32 v27, v49, v8, v23
	v_mul_f32_e32 v110, v27, v165
	v_lshlrev_b32_e32 v169, 16, v169
	v_mul_f32_e32 v84, 0xbfb8aa3b, v169
	v_exp_f32_e32 v84, v84
	s_nop 0
	v_add_f32_e32 v84, 1.0, v84
	v_div_scale_f32 v71, s[74:75], v84, v84, v169
	v_rcp_f32_e32 v82, v71
	s_nop 0
	v_fma_f32 v92, -v71, v82, 1.0
	v_fmac_f32_e32 v82, v92, v82
	v_div_scale_f32 v88, vcc, v169, v84, v169
	v_mul_f32_e32 v90, v88, v82
	v_fma_f32 v92, -v71, v90, v88
	v_fmac_f32_e32 v90, v92, v82
	v_fma_f32 v71, -v71, v90, v88
	v_div_fmas_f32 v71, v71, v82, v90
	v_div_fixup_f32 v169, v71, v84, v169
	v_mul_f32_e32 v110, v110, v169
	v_cvt_pk_bf16_f32 v206, v70, v110
	v_lshlrev_b32_e32 v171, 16, v171
	v_lshlrev_b32_e32 v172, 16, v172
	v_lshlrev_b32_e32 v170, 16, v170
	v_mul_f32_e32 v170, v16, v170
	v_fmac_f32_e32 v170, v14, v171
	v_fmac_f32_e32 v170, v17, v172
	v_add_f32_e32 v170, v12, v170
	v_fma_f32 v27, v46, v8, v24
	v_mul_f32_e32 v70, v27, v170
	v_lshlrev_b32_e32 v176, 16, v176
	v_mul_f32_e32 v84, 0xbfb8aa3b, v176
	v_exp_f32_e32 v84, v84
	s_nop 0
	v_add_f32_e32 v84, 1.0, v84
	v_div_scale_f32 v71, s[74:75], v84, v84, v176
	v_rcp_f32_e32 v82, v71
	s_nop 0
	v_fma_f32 v92, -v71, v82, 1.0
	v_fmac_f32_e32 v82, v92, v82
	v_div_scale_f32 v88, vcc, v176, v84, v176
	v_mul_f32_e32 v90, v88, v82
	v_fma_f32 v92, -v71, v90, v88
	v_fmac_f32_e32 v90, v92, v82
	v_fma_f32 v71, -v71, v90, v88
	v_div_fmas_f32 v71, v71, v82, v90
	v_div_fixup_f32 v176, v71, v84, v176
	v_mul_f32_e32 v70, v70, v176
	v_lshlrev_b32_e32 v174, 16, v174
	v_lshlrev_b32_e32 v175, 16, v175
	v_lshlrev_b32_e32 v173, 16, v173
	v_mul_f32_e32 v173, v16, v173
	v_fmac_f32_e32 v173, v14, v174
	v_fmac_f32_e32 v173, v17, v175
	v_add_f32_e32 v173, v12, v173
	v_fma_f32 v27, v48, v8, v25
	v_mul_f32_e32 v110, v27, v173
	v_lshlrev_b32_e32 v177, 16, v177
	v_mul_f32_e32 v84, 0xbfb8aa3b, v177
	v_exp_f32_e32 v84, v84
	s_nop 0
	v_add_f32_e32 v84, 1.0, v84
	v_div_scale_f32 v71, s[74:75], v84, v84, v177
	v_rcp_f32_e32 v82, v71
	s_nop 0
	v_fma_f32 v92, -v71, v82, 1.0
	v_fmac_f32_e32 v82, v92, v82
	v_div_scale_f32 v88, vcc, v177, v84, v177
	v_mul_f32_e32 v90, v88, v82
	v_fma_f32 v92, -v71, v90, v88
	v_fmac_f32_e32 v90, v92, v82
	v_fma_f32 v71, -v71, v90, v88
	v_div_fmas_f32 v71, v71, v82, v90
	v_div_fixup_f32 v177, v71, v84, v177
	v_mul_f32_e32 v110, v110, v177
	v_cvt_pk_bf16_f32 v207, v70, v110
	v_lshlrev_b32_e32 v179, 16, v179
	v_lshlrev_b32_e32 v180, 16, v180
	v_lshlrev_b32_e32 v178, 16, v178
	v_mul_f32_e32 v178, v16, v178
	v_fmac_f32_e32 v178, v14, v179
	v_fmac_f32_e32 v178, v17, v180
	v_add_f32_e32 v178, v12, v178
	v_fma_f32 v27, v51, v8, v18
	v_mul_f32_e32 v70, v27, v178
	v_lshlrev_b32_e32 v184, 16, v184
	v_mul_f32_e32 v84, 0xbfb8aa3b, v184
	v_exp_f32_e32 v84, v84
	s_nop 0
	v_add_f32_e32 v84, 1.0, v84
	v_div_scale_f32 v71, s[74:75], v84, v84, v184
	v_rcp_f32_e32 v82, v71
	s_nop 0
	v_fma_f32 v92, -v71, v82, 1.0
	v_fmac_f32_e32 v82, v92, v82
	v_div_scale_f32 v88, vcc, v184, v84, v184
	v_mul_f32_e32 v90, v88, v82
	v_fma_f32 v92, -v71, v90, v88
	v_fmac_f32_e32 v90, v92, v82
	v_fma_f32 v71, -v71, v90, v88
	v_div_fmas_f32 v71, v71, v82, v90
	v_div_fixup_f32 v184, v71, v84, v184
	v_mul_f32_e32 v70, v70, v184
	v_lshlrev_b32_e32 v182, 16, v182
	v_lshlrev_b32_e32 v183, 16, v183
	v_lshlrev_b32_e32 v181, 16, v181
	v_mul_f32_e32 v181, v16, v181
	v_fmac_f32_e32 v181, v14, v182
	v_fmac_f32_e32 v181, v17, v183
	v_add_f32_e32 v181, v12, v181
	v_fma_f32 v27, v53, v8, v19
	v_mul_f32_e32 v110, v27, v181
	v_lshlrev_b32_e32 v185, 16, v185
	v_mul_f32_e32 v84, 0xbfb8aa3b, v185
	v_exp_f32_e32 v84, v84
	s_nop 0
	v_add_f32_e32 v84, 1.0, v84
	v_div_scale_f32 v71, s[74:75], v84, v84, v185
	v_rcp_f32_e32 v82, v71
	s_nop 0
	v_fma_f32 v92, -v71, v82, 1.0
	v_fmac_f32_e32 v82, v92, v82
	v_div_scale_f32 v88, vcc, v185, v84, v185
	v_mul_f32_e32 v90, v88, v82
	v_fma_f32 v92, -v71, v90, v88
	v_fmac_f32_e32 v90, v92, v82
	v_fma_f32 v71, -v71, v90, v88
	v_div_fmas_f32 v71, v71, v82, v90
	v_div_fixup_f32 v185, v71, v84, v185
	v_mul_f32_e32 v110, v110, v185
	v_cvt_pk_bf16_f32 v208, v70, v110
	v_lshlrev_b32_e32 v187, 16, v187
	v_lshlrev_b32_e32 v188, 16, v188
	v_lshlrev_b32_e32 v186, 16, v186
	v_mul_f32_e32 v186, v16, v186
	v_fmac_f32_e32 v186, v14, v187
	v_fmac_f32_e32 v186, v17, v188
	v_add_f32_e32 v186, v12, v186
	v_fma_f32 v27, v50, v8, v20
	v_mul_f32_e32 v70, v27, v186
	v_lshlrev_b32_e32 v192, 16, v192
	v_mul_f32_e32 v84, 0xbfb8aa3b, v192
	v_exp_f32_e32 v84, v84
	s_nop 0
	v_add_f32_e32 v84, 1.0, v84
	v_div_scale_f32 v71, s[74:75], v84, v84, v192
	v_rcp_f32_e32 v82, v71
	s_nop 0
	v_fma_f32 v92, -v71, v82, 1.0
	v_fmac_f32_e32 v82, v92, v82
	v_div_scale_f32 v88, vcc, v192, v84, v192
	v_mul_f32_e32 v90, v88, v82
	v_fma_f32 v92, -v71, v90, v88
	v_fmac_f32_e32 v90, v92, v82
	v_fma_f32 v71, -v71, v90, v88
	v_div_fmas_f32 v71, v71, v82, v90
	v_div_fixup_f32 v192, v71, v84, v192
	v_mul_f32_e32 v70, v70, v192
	v_lshlrev_b32_e32 v190, 16, v190
	v_lshlrev_b32_e32 v191, 16, v191
	v_lshlrev_b32_e32 v189, 16, v189
	v_mul_f32_e32 v189, v16, v189
	v_fmac_f32_e32 v189, v14, v190
	v_fmac_f32_e32 v189, v17, v191
	v_add_f32_e32 v189, v12, v189
	v_fma_f32 v27, v52, v8, v21
	v_mul_f32_e32 v110, v27, v189
	v_lshlrev_b32_e32 v193, 16, v193
	v_mul_f32_e32 v84, 0xbfb8aa3b, v193
	v_exp_f32_e32 v84, v84
	s_nop 0
	v_add_f32_e32 v84, 1.0, v84
	v_div_scale_f32 v71, s[74:75], v84, v84, v193
	v_rcp_f32_e32 v82, v71
	s_nop 0
	v_fma_f32 v92, -v71, v82, 1.0
	v_fmac_f32_e32 v82, v92, v82
	v_div_scale_f32 v88, vcc, v193, v84, v193
	v_mul_f32_e32 v90, v88, v82
	v_fma_f32 v92, -v71, v90, v88
	v_fmac_f32_e32 v90, v92, v82
	v_fma_f32 v71, -v71, v90, v88
	v_div_fmas_f32 v71, v71, v82, v90
	v_div_fixup_f32 v193, v71, v84, v193
	v_mul_f32_e32 v110, v110, v193
	v_cvt_pk_bf16_f32 v209, v70, v110
	s_waitcnt vmcnt(0)
	v_lshlrev_b32_e32 v195, 16, v195
	v_lshlrev_b32_e32 v196, 16, v196
	v_lshlrev_b32_e32 v194, 16, v194
	v_mul_f32_e32 v194, v16, v194
	v_fmac_f32_e32 v194, v14, v195
	v_fmac_f32_e32 v194, v17, v196
	v_add_f32_e32 v194, v12, v194
	v_fma_f32 v27, v55, v8, v4
	v_mul_f32_e32 v70, v27, v194
	v_lshlrev_b32_e32 v223, 16, v223
	v_mul_f32_e32 v84, 0xbfb8aa3b, v223
	v_exp_f32_e32 v84, v84
	s_nop 0
	v_add_f32_e32 v84, 1.0, v84
	v_div_scale_f32 v71, s[74:75], v84, v84, v223
	v_rcp_f32_e32 v82, v71
	s_nop 0
	v_fma_f32 v92, -v71, v82, 1.0
	v_fmac_f32_e32 v82, v92, v82
	v_div_scale_f32 v88, vcc, v223, v84, v223
	v_mul_f32_e32 v90, v88, v82
	v_fma_f32 v92, -v71, v90, v88
	v_fmac_f32_e32 v90, v92, v82
	v_fma_f32 v71, -v71, v90, v88
	v_div_fmas_f32 v71, v71, v82, v90
	v_div_fixup_f32 v223, v71, v84, v223
	v_mul_f32_e32 v70, v70, v223
	v_lshlrev_b32_e32 v221, 16, v221
	v_lshlrev_b32_e32 v222, 16, v222
	v_lshlrev_b32_e32 v197, 16, v197
	v_mul_f32_e32 v197, v16, v197
	v_fmac_f32_e32 v197, v14, v221
	v_fmac_f32_e32 v197, v17, v222
	v_add_f32_e32 v197, v12, v197
	v_fma_f32 v27, v57, v8, v5
	v_mul_f32_e32 v110, v27, v197
	v_lshlrev_b32_e32 v224, 16, v224
	v_mul_f32_e32 v84, 0xbfb8aa3b, v224
	v_exp_f32_e32 v84, v84
	s_nop 0
	v_add_f32_e32 v84, 1.0, v84
	v_div_scale_f32 v71, s[74:75], v84, v84, v224
	v_rcp_f32_e32 v82, v71
	s_nop 0
	v_fma_f32 v92, -v71, v82, 1.0
	v_fmac_f32_e32 v82, v92, v82
	v_div_scale_f32 v88, vcc, v224, v84, v224
	v_mul_f32_e32 v90, v88, v82
	v_fma_f32 v92, -v71, v90, v88
	v_fmac_f32_e32 v90, v92, v82
	v_fma_f32 v71, -v71, v90, v88
	v_div_fmas_f32 v71, v71, v82, v90
	v_div_fixup_f32 v224, v71, v84, v224
	v_mul_f32_e32 v110, v110, v224
	v_cvt_pk_bf16_f32 v210, v70, v110
	v_lshlrev_b32_e32 v226, 16, v226
	v_lshlrev_b32_e32 v227, 16, v227
	v_lshlrev_b32_e32 v225, 16, v225
	v_mul_f32_e32 v225, v16, v225
	v_fmac_f32_e32 v225, v14, v226
	v_fmac_f32_e32 v225, v17, v227
	v_add_f32_e32 v225, v12, v225
	v_fma_f32 v27, v54, v8, v6
	v_mul_f32_e32 v70, v27, v225
	v_lshlrev_b32_e32 v231, 16, v231
	v_mul_f32_e32 v84, 0xbfb8aa3b, v231
	v_exp_f32_e32 v84, v84
	s_nop 0
	v_add_f32_e32 v84, 1.0, v84
	v_div_scale_f32 v71, s[74:75], v84, v84, v231
	v_rcp_f32_e32 v82, v71
	s_nop 0
	v_fma_f32 v92, -v71, v82, 1.0
	v_fmac_f32_e32 v82, v92, v82
	v_div_scale_f32 v88, vcc, v231, v84, v231
	v_mul_f32_e32 v90, v88, v82
	v_fma_f32 v92, -v71, v90, v88
	v_fmac_f32_e32 v90, v92, v82
	v_fma_f32 v71, -v71, v90, v88
	v_div_fmas_f32 v71, v71, v82, v90
	v_div_fixup_f32 v231, v71, v84, v231
	v_mul_f32_e32 v70, v70, v231
	v_lshlrev_b32_e32 v229, 16, v229
	v_lshlrev_b32_e32 v230, 16, v230
	v_lshlrev_b32_e32 v228, 16, v228
	v_mul_f32_e32 v228, v16, v228
	v_fmac_f32_e32 v228, v14, v229
	v_fmac_f32_e32 v228, v17, v230
	v_add_f32_e32 v228, v12, v228
	v_fma_f32 v27, v56, v8, v7
	v_mul_f32_e32 v110, v27, v228
	v_lshlrev_b32_e32 v232, 16, v232
	v_mul_f32_e32 v84, 0xbfb8aa3b, v232
	v_exp_f32_e32 v84, v84
	s_nop 0
	v_add_f32_e32 v84, 1.0, v84
	v_div_scale_f32 v71, s[74:75], v84, v84, v232
	v_rcp_f32_e32 v82, v71
	s_nop 0
	v_fma_f32 v92, -v71, v82, 1.0
	v_fmac_f32_e32 v82, v92, v82
	v_div_scale_f32 v88, vcc, v232, v84, v232
	v_mul_f32_e32 v90, v88, v82
	v_fma_f32 v92, -v71, v90, v88
	v_fmac_f32_e32 v90, v92, v82
	v_fma_f32 v71, -v71, v90, v88
	v_div_fmas_f32 v71, v71, v82, v90
	v_div_fixup_f32 v232, v71, v84, v232
	v_mul_f32_e32 v110, v110, v232
	v_cvt_pk_bf16_f32 v211, v70, v110
	v_lshlrev_b32_e32 v234, 16, v234
	v_lshlrev_b32_e32 v235, 16, v235
	v_lshlrev_b32_e32 v233, 16, v233
	v_mul_f32_e32 v233, v16, v233
	v_fmac_f32_e32 v233, v14, v234
	v_fmac_f32_e32 v233, v17, v235
	v_add_f32_e32 v233, v12, v233
	v_fma_f32 v27, v59, v8, v0
	v_mul_f32_e32 v70, v27, v233
	v_lshlrev_b32_e32 v239, 16, v239
	v_mul_f32_e32 v84, 0xbfb8aa3b, v239
	v_exp_f32_e32 v84, v84
	s_nop 0
	v_add_f32_e32 v84, 1.0, v84
	v_div_scale_f32 v71, s[74:75], v84, v84, v239
	v_rcp_f32_e32 v82, v71
	s_nop 0
	v_fma_f32 v92, -v71, v82, 1.0
	v_fmac_f32_e32 v82, v92, v82
	v_div_scale_f32 v88, vcc, v239, v84, v239
	v_mul_f32_e32 v90, v88, v82
	v_fma_f32 v92, -v71, v90, v88
	v_fmac_f32_e32 v90, v92, v82
	v_fma_f32 v71, -v71, v90, v88
	v_div_fmas_f32 v71, v71, v82, v90
	v_div_fixup_f32 v239, v71, v84, v239
	v_mul_f32_e32 v70, v70, v239
	v_lshlrev_b32_e32 v237, 16, v237
	v_lshlrev_b32_e32 v238, 16, v238
	v_lshlrev_b32_e32 v236, 16, v236
	v_mul_f32_e32 v236, v16, v236
	v_fmac_f32_e32 v236, v14, v237
	v_fmac_f32_e32 v236, v17, v238
	v_add_f32_e32 v236, v12, v236
	v_fma_f32 v27, v61, v8, v1
	v_mul_f32_e32 v110, v27, v236
	v_lshlrev_b32_e32 v240, 16, v240
	v_mul_f32_e32 v84, 0xbfb8aa3b, v240
	v_exp_f32_e32 v84, v84
	s_nop 0
	v_add_f32_e32 v84, 1.0, v84
	v_div_scale_f32 v71, s[74:75], v84, v84, v240
	v_rcp_f32_e32 v82, v71
	s_nop 0
	v_fma_f32 v92, -v71, v82, 1.0
	v_fmac_f32_e32 v82, v92, v82
	v_div_scale_f32 v88, vcc, v240, v84, v240
	v_mul_f32_e32 v90, v88, v82
	v_fma_f32 v92, -v71, v90, v88
	v_fmac_f32_e32 v90, v92, v82
	v_fma_f32 v71, -v71, v90, v88
	v_div_fmas_f32 v71, v71, v82, v90
	v_div_fixup_f32 v240, v71, v84, v240
	v_mul_f32_e32 v110, v110, v240
	v_cvt_pk_bf16_f32 v212, v70, v110
	v_lshlrev_b32_e32 v242, 16, v242
	v_lshlrev_b32_e32 v243, 16, v243
	v_lshlrev_b32_e32 v241, 16, v241
	v_mul_f32_e32 v241, v16, v241
	v_mul_f32_e32 v243, v255, v243
	v_fmac_f32_e32 v241, v14, v242
	v_fmac_f32_e32 v241, v17, v243
	v_add_f32_e32 v241, v12, v241
	v_fma_f32 v27, v58, v8, v2
	v_mul_f32_e32 v70, v27, v241
	v_lshlrev_b32_e32 v247, 16, v247
	v_mul_f32_e32 v84, 0xbfb8aa3b, v247
	v_exp_f32_e32 v84, v84
	s_nop 0
	v_add_f32_e32 v84, 1.0, v84
	v_div_scale_f32 v71, s[74:75], v84, v84, v247
	v_rcp_f32_e32 v82, v71
	s_nop 0
	v_fma_f32 v92, -v71, v82, 1.0
	v_fmac_f32_e32 v82, v92, v82
	v_div_scale_f32 v88, vcc, v247, v84, v247
	v_mul_f32_e32 v90, v88, v82
	v_fma_f32 v92, -v71, v90, v88
	v_fmac_f32_e32 v90, v92, v82
	v_fma_f32 v71, -v71, v90, v88
	v_div_fmas_f32 v71, v71, v82, v90
	v_div_fixup_f32 v247, v71, v84, v247
	v_mul_f32_e32 v70, v70, v247
	v_lshlrev_b32_e32 v245, 16, v245
	v_lshlrev_b32_e32 v246, 16, v246
	v_lshlrev_b32_e32 v244, 16, v244
	v_mul_f32_e32 v244, v16, v244
	v_mul_f32_e32 v246, v255, v246
	v_fmac_f32_e32 v244, v14, v245
	v_fmac_f32_e32 v244, v17, v246
	v_add_f32_e32 v244, v12, v244
	v_fma_f32 v27, v60, v8, v3
	v_mul_f32_e32 v110, v27, v244
	v_lshlrev_b32_e32 v248, 16, v248
	v_mul_f32_e32 v84, 0xbfb8aa3b, v248
	v_exp_f32_e32 v84, v84
	s_nop 0
	v_add_f32_e32 v84, 1.0, v84
	v_div_scale_f32 v71, s[74:75], v84, v84, v248
	v_rcp_f32_e32 v82, v71
	s_nop 0
	v_fma_f32 v92, -v71, v82, 1.0
	v_fmac_f32_e32 v82, v92, v82
	v_div_scale_f32 v88, vcc, v248, v84, v248
	v_mul_f32_e32 v90, v88, v82
	v_fma_f32 v92, -v71, v90, v88
	v_fmac_f32_e32 v90, v92, v82
	v_fma_f32 v71, -v71, v90, v88
	v_div_fmas_f32 v71, v71, v82, v90
	v_div_fixup_f32 v248, v71, v84, v248
	v_mul_f32_e32 v110, v110, v248
	v_cvt_pk_bf16_f32 v213, v70, v110
	s_branch .Lhy_ep1_done_L1
